# P9: workgroup barrier at the start of each routing unit (re-aligns the 8 waves that share one head's sub-keys through L1), on top of the P2 pair offset
# baseline (speedup 1.0000x reference)
.LBB0_796:
	s_barrier
	s_bitcmp1_b32 s98, 0
	s_cselect_b32 s52, s94, s92
	s_cselect_b32 s53, s95, s93
	s_cselect_b32 s54, s48, s46
	s_cselect_b32 s55, s49, s47
	s_mov_b32 s96, 0x42580000
	s_cselect_b32 s96, 0x40b66666, s96
	s_add_i32 s98, s98, 1
	v_mbcnt_lo_u32_b32 v248, -1, 0
	v_mbcnt_hi_u32_b32 v248, -1, v248
	v_lshlrev_b32_e32 v236, 6, v248
	v_mov_b32_e32 v237, 0
	v_lshl_add_u64 v[236:237], s[52:53], 0, v[236:237]
	v_lshl_add_u64 v[238:239], v[236:237], 0, v[250:251]
	v_lshlrev_b32_e32 v240, 4, v248
	v_mov_b32_e32 v241, 0
	v_lshl_add_u64 v[240:241], s[54:55], 0, v[240:241]
	s_lshr_b32 s14, s34, 3
	s_and_b32 s14, s14, 0x7fffff8
	v_mov_b32_e32 v87, v1
	s_or_b32 s14, s14, s20
	s_lshl_b32 s36, s14, 5
	v_and_b32_e32 v4, 31, v87
	v_or_b32_e32 v2, s36, v4
	v_ashrrev_i32_e32 v3, 31, v2
	v_ashrrev_i32_e32 v118, 5, v87
	v_lshlrev_b64 v[2:3], 12, v[2:3]
	v_lshl_add_u64 v[6:7], s[2:3], 0, v[2:3]
	v_lshlrev_b32_e32 v2, 3, v118
	v_ashrrev_i32_e32 v3, 31, v2
	s_bfe_u32 s35, s34, 0x30003
	v_lshlrev_b64 v[8:9], 1, v[2:3]
	v_lshlrev_b32_e32 v4, 8, v4
	v_lshl_add_u64 v[2:3], s[6:7], 0, v[8:9]
	v_lshl_or_b32 v78, s35, 16, v4
	v_lshl_add_u64 v[80:81], v[2:3], 0, v[78:79]
	global_load_dwordx4 v[2:5], v[80:81], off
	s_lshl_b32 s14, s35, 9
	v_lshl_add_u64 v[6:7], v[6:7], 0, s[14:15]
	v_lshl_add_u64 v[82:83], v[6:7], 0, v[8:9]
	global_load_dwordx4 v[34:37], v[82:83], off
	global_load_dwordx4 v[88:91], v[80:81], off offset:32
	global_load_dwordx4 v[92:95], v[80:81], off offset:64
	global_load_dwordx4 v[96:99], v[80:81], off offset:96
	global_load_dwordx4 v[100:103], v[80:81], off offset:128
	global_load_dwordx4 v[104:107], v[80:81], off offset:160
	global_load_dwordx4 v[108:111], v[80:81], off offset:192
	global_load_dwordx4 v[66:69], v[80:81], off offset:224
	global_load_dwordx4 v[62:65], v[82:83], off offset:32
	global_load_dwordx4 v[58:61], v[82:83], off offset:64
	global_load_dwordx4 v[54:57], v[82:83], off offset:96
	global_load_dwordx4 v[50:53], v[82:83], off offset:128
	global_load_dwordx4 v[46:49], v[82:83], off offset:160
	global_load_dwordx4 v[42:45], v[82:83], off offset:192
	global_load_dwordx4 v[38:41], v[82:83], off offset:224
	v_add_co_u32_e32 v116, vcc, s24, v80
	v_lshlrev_b32_e32 v146, 2, v118
	s_nop 0
	v_addc_co_u32_e32 v117, vcc, 0, v81, vcc
	global_load_dwordx4 v[6:9], v[116:117], off
	global_load_dwordx4 v[112:115], v[116:117], off offset:32
	v_add_co_u32_e32 v136, vcc, s25, v80
	v_sub_u32_e32 v78, 0x66, v146
	s_nop 0
	v_addc_co_u32_e32 v137, vcc, 0, v81, vcc
	v_sub_u32_e32 v144, 6, v146
	v_sub_u32_e32 v145, 5, v146
	s_waitcnt vmcnt(0)
	v_mfma_f32_32x32x16_bf16 v[18:33], v[2:5], v[34:37], 0
	v_mfma_f32_32x32x16_bf16 v[18:33], v[88:91], v[62:65], v[18:33]
	global_load_dwordx4 v[88:91], v[116:117], off offset:64
	v_mfma_f32_32x32x16_bf16 v[2:17], v[6:9], v[34:37], 0
	v_mfma_f32_32x32x16_bf16 v[2:17], v[112:115], v[62:65], v[2:17]
	global_load_dwordx4 v[112:115], v[116:117], off offset:160
	v_mfma_f32_32x32x16_bf16 v[18:33], v[92:95], v[58:61], v[18:33]
	global_load_dwordx4 v[92:95], v[116:117], off offset:96
	s_waitcnt vmcnt(0)
	v_mfma_f32_32x32x16_bf16 v[2:17], v[88:91], v[58:61], v[2:17]
	global_load_dwordx4 v[88:91], v[116:117], off offset:128
	v_mfma_f32_32x32x16_bf16 v[18:33], v[96:99], v[54:57], v[18:33]
	v_sub_u32_e32 v98, 0x7e, v146
	v_or_b32_e32 v99, 3, v146
	v_sub_u32_e32 v97, 0x77, v146
	v_sub_u32_e32 v96, 0x76, v146
	v_sub_u32_e32 v99, 0x7f, v99
	v_mfma_f32_32x32x16_bf16 v[18:33], v[100:103], v[50:53], v[18:33]
	v_sub_u32_e32 v100, 0x7f, v146
	v_mfma_f32_32x32x16_bf16 v[18:33], v[104:107], v[46:49], v[18:33]
	v_mfma_f32_32x32x16_bf16 v[18:33], v[108:111], v[42:45], v[18:33]
	global_load_dwordx4 v[104:107], v[116:117], off offset:192
	global_load_dwordx4 v[108:111], v[116:117], off offset:224
	v_mfma_f32_32x32x16_bf16 v[2:17], v[92:95], v[54:57], v[2:17]
	v_sub_u32_e32 v95, 0x75, v146
	v_sub_u32_e32 v94, 0x74, v146
	v_sub_u32_e32 v93, 0x6f, v146
	v_sub_u32_e32 v92, 0x6e, v146
	v_mfma_f32_32x32x16_bf16 v[18:33], v[66:69], v[38:41], v[18:33]
	s_waitcnt vmcnt(0)
	v_mfma_f32_32x32x16_bf16 v[2:17], v[88:91], v[50:53], v[2:17]
	s_nop 9
	v_not_b32_e32 v66, v18
	v_or_b32_e32 v67, 0x80000000, v18
	v_cmp_gt_i32_e32 vcc, 0, v18
	v_or_b32_e32 v91, 2, v146
	v_not_b32_e32 v68, v19
	v_or_b32_e32 v69, 0x80000000, v19
	v_cndmask_b32_e32 v18, v67, v66, vcc
	v_mfma_f32_32x32x16_bf16 v[2:17], v[112:115], v[46:49], v[2:17]
	global_load_dwordx4 v[112:115], v[136:137], off
	v_cmp_gt_i32_e32 vcc, 0, v19
	v_sub_u32_e32 v101, 0x7f, v91
	v_not_b32_e32 v91, v20
	v_or_b32_e32 v102, 0x80000000, v20
	v_cndmask_b32_e32 v19, v69, v68, vcc
	v_cmp_gt_i32_e32 vcc, 0, v20
	v_not_b32_e32 v103, v21
	v_or_b32_e32 v116, 0x80000000, v21
	v_cndmask_b32_e32 v20, v102, v91, vcc
	v_cmp_gt_i32_e32 vcc, 0, v21
	v_not_b32_e32 v117, v22
	v_or_b32_e32 v118, 0x80000000, v22
	v_cndmask_b32_e32 v21, v116, v103, vcc
	v_cmp_gt_i32_e32 vcc, 0, v22
	v_not_b32_e32 v119, v23
	v_or_b32_e32 v120, 0x80000000, v23
	v_cndmask_b32_e32 v22, v118, v117, vcc
	v_cmp_gt_i32_e32 vcc, 0, v23
	v_not_b32_e32 v121, v24
	v_or_b32_e32 v122, 0x80000000, v24
	v_cndmask_b32_e32 v23, v120, v119, vcc
	global_load_dwordx4 v[116:119], v[136:137], off offset:32
	v_cmp_gt_i32_e32 vcc, 0, v24
	v_not_b32_e32 v123, v25
	v_or_b32_e32 v124, 0x80000000, v25
	v_cndmask_b32_e32 v24, v122, v121, vcc
	v_cmp_gt_i32_e32 vcc, 0, v25
	v_not_b32_e32 v125, v26
	v_or_b32_e32 v126, 0x80000000, v26
	v_cndmask_b32_e32 v25, v124, v123, vcc
	global_load_dwordx4 v[120:123], v[136:137], off offset:64
	v_cmp_gt_i32_e32 vcc, 0, v26
	v_not_b32_e32 v127, v27
	v_or_b32_e32 v128, 0x80000000, v27
	v_cndmask_b32_e32 v26, v126, v125, vcc
	v_cmp_gt_i32_e32 vcc, 0, v27
	v_mfma_f32_32x32x16_bf16 v[2:17], v[104:107], v[42:45], v[2:17]
	v_not_b32_e32 v129, v28
	v_cndmask_b32_e32 v27, v128, v127, vcc
	global_load_dwordx4 v[124:127], v[136:137], off offset:96
	v_or_b32_e32 v130, 0x80000000, v28
	v_cmp_gt_i32_e32 vcc, 0, v28
	v_not_b32_e32 v131, v29
	v_or_b32_e32 v132, 0x80000000, v29
	v_cndmask_b32_e32 v28, v130, v129, vcc
	v_cmp_gt_i32_e32 vcc, 0, v29
	v_mfma_f32_32x32x16_bf16 v[2:17], v[108:111], v[38:41], v[2:17]
	v_not_b32_e32 v133, v30
	v_cndmask_b32_e32 v29, v132, v131, vcc
	global_load_dwordx4 v[128:131], v[136:137], off offset:128
	v_or_b32_e32 v134, 0x80000000, v30
	v_cmp_gt_i32_e32 vcc, 0, v30
	v_not_b32_e32 v135, v31
	v_or_b32_e32 v138, 0x80000000, v31
	v_cndmask_b32_e32 v30, v134, v133, vcc
	v_cmp_gt_i32_e32 vcc, 0, v31
	v_and_or_b32 v159, v18, s23, v100
	v_and_or_b32 v168, v19, s23, v98
	v_cndmask_b32_e32 v31, v138, v135, vcc
	v_not_b32_e32 v18, v32
	v_or_b32_e32 v19, 0x80000000, v32
	v_cmp_gt_i32_e32 vcc, 0, v32
	v_sub_u32_e32 v102, 0x65, v146
	v_sub_u32_e32 v103, 0x64, v146
	v_cndmask_b32_e32 v18, v19, v18, vcc
	v_and_or_b32 v181, v18, s23, v102
	v_not_b32_e32 v18, v33
	v_or_b32_e32 v19, 0x80000000, v33
	v_cmp_gt_i32_e32 vcc, 0, v33
	global_load_dwordx4 v[132:135], v[136:137], off offset:160
	v_sub_u32_e32 v104, 0x5f, v146
	v_cndmask_b32_e32 v18, v19, v18, vcc
	v_and_or_b32 v182, v18, s23, v103
	v_not_b32_e32 v18, v2
	v_or_b32_e32 v19, 0x80000000, v2
	v_cmp_gt_i32_e32 vcc, 0, v2
	v_sub_u32_e32 v105, 0x5e, v146
	v_sub_u32_e32 v107, 0x5d, v146
	v_cndmask_b32_e32 v2, v19, v18, vcc
	v_and_or_b32 v147, v2, s23, v104
	v_not_b32_e32 v2, v3
	v_or_b32_e32 v18, 0x80000000, v3
	v_cmp_gt_i32_e32 vcc, 0, v3
	v_or_b32_e32 v3, 0x80000000, v4
	v_sub_u32_e32 v106, 0x5c, v146
	v_cndmask_b32_e32 v2, v18, v2, vcc
	v_and_or_b32 v148, v2, s23, v105
	v_not_b32_e32 v2, v4
	v_cmp_gt_i32_e32 vcc, 0, v4
	v_or_b32_e32 v19, 0x80000000, v6
	v_sub_u32_e32 v108, 0x57, v146
	v_cndmask_b32_e32 v2, v3, v2, vcc
	v_and_or_b32 v149, v2, s23, v107
	v_not_b32_e32 v2, v5
	v_or_b32_e32 v3, 0x80000000, v5
	v_cmp_gt_i32_e32 vcc, 0, v5
	v_sub_u32_e32 v90, 0x6d, v146
	v_sub_u32_e32 v89, 0x6c, v146
	v_cndmask_b32_e32 v18, v3, v2, vcc
	global_load_dwordx4 v[2:5], v[136:137], off offset:192
	v_and_or_b32 v150, v18, s23, v106
	global_load_dwordx4 v[136:139], v[136:137], off offset:224
	v_not_b32_e32 v18, v6
	v_cmp_gt_i32_e32 vcc, 0, v6
	v_sub_u32_e32 v88, 0x67, v146
	v_and_or_b32 v169, v20, s23, v101
	v_cndmask_b32_e32 v6, v19, v18, vcc
	v_and_or_b32 v151, v6, s23, v108
	v_not_b32_e32 v6, v7
	v_or_b32_e32 v18, 0x80000000, v7
	v_cmp_gt_i32_e32 vcc, 0, v7
	v_and_or_b32 v170, v21, s23, v99
	v_and_or_b32 v171, v22, s23, v97
	v_and_or_b32 v172, v23, s23, v96
	v_and_or_b32 v173, v24, s23, v95
	v_and_or_b32 v174, v25, s23, v94
	v_and_or_b32 v175, v26, s23, v93
	v_and_or_b32 v176, v27, s23, v92
	v_and_or_b32 v177, v28, s23, v90
	v_and_or_b32 v178, v29, s23, v89
	v_and_or_b32 v179, v30, s23, v88
	v_and_or_b32 v180, v31, s23, v78
	v_cndmask_b32_e32 v6, v18, v6, vcc
	v_sub_u32_e32 v109, 0x56, v146
	s_waitcnt vmcnt(0)
	v_mfma_f32_32x32x16_bf16 v[18:33], v[112:115], v[34:37], 0
	v_and_or_b32 v152, v6, s23, v109
	v_not_b32_e32 v6, v8
	v_or_b32_e32 v7, 0x80000000, v8
	v_cmp_gt_i32_e32 vcc, 0, v8
	v_sub_u32_e32 v110, 0x55, v146
	v_sub_u32_e32 v111, 0x54, v146
	v_cndmask_b32_e32 v6, v7, v6, vcc
	v_and_or_b32 v153, v6, s23, v110
	v_not_b32_e32 v6, v9
	v_or_b32_e32 v7, 0x80000000, v9
	v_cmp_gt_i32_e32 vcc, 0, v9
	v_sub_u32_e32 v68, 0x4f, v146
	v_sub_u32_e32 v91, 0x4e, v146
	v_cndmask_b32_e32 v6, v7, v6, vcc
	v_and_or_b32 v154, v6, s23, v111
	v_not_b32_e32 v6, v10
	v_or_b32_e32 v7, 0x80000000, v10
	v_cmp_gt_i32_e32 vcc, 0, v10
	v_mfma_f32_32x32x16_bf16 v[18:33], v[116:119], v[62:65], v[18:33]
	v_sub_u32_e32 v69, 0x4d, v146
	v_cndmask_b32_e32 v6, v7, v6, vcc
	v_and_or_b32 v155, v6, s23, v68
	v_not_b32_e32 v6, v11
	v_or_b32_e32 v7, 0x80000000, v11
	v_cmp_gt_i32_e32 vcc, 0, v11
	v_sub_u32_e32 v67, 0x4c, v146
	v_mfma_f32_32x32x16_bf16 v[18:33], v[120:123], v[58:61], v[18:33]
	v_cndmask_b32_e32 v6, v7, v6, vcc
	v_and_or_b32 v156, v6, s23, v91
	v_not_b32_e32 v6, v12
	v_or_b32_e32 v7, 0x80000000, v12
	v_cmp_gt_i32_e32 vcc, 0, v12
	v_sub_u32_e32 v66, 0x47, v146
	v_sub_u32_e32 v112, 0x46, v146
	v_cndmask_b32_e32 v6, v7, v6, vcc
	v_and_or_b32 v157, v6, s23, v69
	v_not_b32_e32 v6, v13
	v_or_b32_e32 v7, 0x80000000, v13
	v_cmp_gt_i32_e32 vcc, 0, v13
	v_mfma_f32_32x32x16_bf16 v[18:33], v[124:127], v[54:57], v[18:33]
	v_or_b32_e32 v13, 0x80000000, v15
	v_cndmask_b32_e32 v6, v7, v6, vcc
	v_and_or_b32 v158, v6, s23, v67
	v_not_b32_e32 v6, v14
	v_or_b32_e32 v7, 0x80000000, v14
	v_cmp_gt_i32_e32 vcc, 0, v14
	v_sub_u32_e32 v113, 0x45, v146
	v_mfma_f32_32x32x16_bf16 v[18:33], v[128:131], v[50:53], v[18:33]
	v_cndmask_b32_e32 v12, v7, v6, vcc
	v_add_co_u32_e32 v10, vcc, s27, v80
	v_and_or_b32 v183, v12, s23, v66
	s_nop 0
	v_addc_co_u32_e32 v11, vcc, 0, v81, vcc
	global_load_dwordx4 v[6:9], v[10:11], off
	global_load_dwordx4 v[124:127], v[10:11], off offset:32
	global_load_dwordx4 v[128:131], v[10:11], off offset:64
	v_mfma_f32_32x32x16_bf16 v[18:33], v[132:135], v[46:49], v[18:33]
	global_load_dwordx4 v[132:135], v[10:11], off offset:96
	global_load_dwordx4 v[140:143], v[10:11], off offset:128
	global_load_dwordx4 v[160:163], v[10:11], off offset:192
	global_load_dwordx4 v[164:167], v[10:11], off offset:224
	v_not_b32_e32 v12, v15
	v_cmp_gt_i32_e32 vcc, 0, v15
	v_sub_u32_e32 v114, 0x44, v146
	v_mfma_f32_32x32x16_bf16 v[18:33], v[2:5], v[42:45], v[18:33]
	v_cndmask_b32_e32 v12, v13, v12, vcc
	v_and_or_b32 v184, v12, s23, v112
	v_not_b32_e32 v12, v16
	v_or_b32_e32 v13, 0x80000000, v16
	v_cmp_gt_i32_e32 vcc, 0, v16
	v_or_b32_e32 v2, 0x80000000, v17
	v_sub_u32_e32 v115, 63, v146
	v_mfma_f32_32x32x16_bf16 v[18:33], v[136:139], v[38:41], v[18:33]
	global_load_dwordx4 v[136:139], v[10:11], off offset:160
	v_cndmask_b32_e32 v12, v13, v12, vcc
	v_and_or_b32 v185, v12, s23, v113
	v_not_b32_e32 v12, v17
	v_cmp_gt_i32_e32 vcc, 0, v17
	v_sub_u32_e32 v116, 62, v146
	v_sub_u32_e32 v117, 61, v146
	v_cndmask_b32_e32 v2, v2, v12, vcc
	v_and_or_b32 v186, v2, s23, v114
	s_nop 2
	v_not_b32_e32 v2, v18
	v_or_b32_e32 v3, 0x80000000, v18
	v_cmp_gt_i32_e32 vcc, 0, v18
	v_sub_u32_e32 v118, 60, v146
	v_sub_u32_e32 v119, 55, v146
	v_cndmask_b32_e32 v2, v3, v2, vcc
	v_and_or_b32 v18, v2, s23, v115
	v_not_b32_e32 v2, v19
	v_or_b32_e32 v3, 0x80000000, v19
	v_cmp_gt_i32_e32 vcc, 0, v19
	v_sub_u32_e32 v120, 54, v146
	v_sub_u32_e32 v121, 53, v146
	v_cndmask_b32_e32 v2, v3, v2, vcc
	v_and_or_b32 v19, v2, s23, v116
	v_not_b32_e32 v2, v20
	v_or_b32_e32 v3, 0x80000000, v20
	v_cmp_gt_i32_e32 vcc, 0, v20
	v_sub_u32_e32 v122, 52, v146
	v_sub_u32_e32 v123, 47, v146
	v_cndmask_b32_e32 v2, v3, v2, vcc
	v_and_or_b32 v20, v2, s23, v117
	v_not_b32_e32 v2, v21
	v_or_b32_e32 v3, 0x80000000, v21
	v_cmp_gt_i32_e32 vcc, 0, v21
	s_nop 1
	v_cndmask_b32_e32 v2, v3, v2, vcc
	v_and_or_b32 v21, v2, s23, v118
	v_not_b32_e32 v2, v22
	v_or_b32_e32 v3, 0x80000000, v22
	v_cmp_gt_i32_e32 vcc, 0, v22
	s_nop 1
	v_cndmask_b32_e32 v2, v3, v2, vcc
	v_and_or_b32 v22, v2, s23, v119
	v_not_b32_e32 v2, v23
	v_or_b32_e32 v3, 0x80000000, v23
	v_cmp_gt_i32_e32 vcc, 0, v23
	s_nop 1
	v_cndmask_b32_e32 v2, v3, v2, vcc
	v_and_or_b32 v23, v2, s23, v120
	v_not_b32_e32 v2, v24
	v_or_b32_e32 v3, 0x80000000, v24
	v_cmp_gt_i32_e32 vcc, 0, v24
	s_nop 1
	v_cndmask_b32_e32 v2, v3, v2, vcc
	v_and_or_b32 v24, v2, s23, v121
	v_not_b32_e32 v2, v25
	v_or_b32_e32 v3, 0x80000000, v25
	v_cmp_gt_i32_e32 vcc, 0, v25
	s_nop 1
	v_cndmask_b32_e32 v25, v3, v2, vcc
	s_waitcnt vmcnt(0)
	v_mfma_f32_32x32x16_bf16 v[2:17], v[6:9], v[34:37], 0
	v_not_b32_e32 v34, v26
	v_or_b32_e32 v35, 0x80000000, v26
	v_cmp_gt_i32_e32 vcc, 0, v26
	v_and_or_b32 v25, v25, s23, v122
	v_max_u32_e32 v36, v169, v170
	v_cndmask_b32_e32 v26, v35, v34, vcc
	v_not_b32_e32 v34, v27
	v_mfma_f32_32x32x16_bf16 v[2:17], v[124:127], v[62:65], v[2:17]
	v_or_b32_e32 v35, 0x80000000, v27
	v_cmp_gt_i32_e32 vcc, 0, v27
	v_sub_u32_e32 v124, 46, v146
	v_sub_u32_e32 v125, 45, v146
	v_cndmask_b32_e32 v27, v35, v34, vcc
	v_not_b32_e32 v34, v28
	v_or_b32_e32 v35, 0x80000000, v28
	v_mfma_f32_32x32x16_bf16 v[2:17], v[128:131], v[58:61], v[2:17]
	v_cmp_gt_i32_e32 vcc, 0, v28
	v_sub_u32_e32 v126, 44, v146
	v_sub_u32_e32 v127, 39, v146
	v_cndmask_b32_e32 v28, v35, v34, vcc
	v_not_b32_e32 v34, v29
	v_or_b32_e32 v35, 0x80000000, v29
	v_cmp_gt_i32_e32 vcc, 0, v29
	v_mfma_f32_32x32x16_bf16 v[2:17], v[132:135], v[54:57], v[2:17]
	v_sub_u32_e32 v128, 38, v146
	v_cndmask_b32_e32 v29, v35, v34, vcc
	v_not_b32_e32 v34, v30
	v_or_b32_e32 v35, 0x80000000, v30
	v_cmp_gt_i32_e32 vcc, 0, v30
	v_sub_u32_e32 v129, 37, v146
	v_sub_u32_e32 v130, 36, v146
	v_mfma_f32_32x32x16_bf16 v[2:17], v[140:143], v[50:53], v[2:17]
	v_cndmask_b32_e32 v30, v35, v34, vcc
	v_not_b32_e32 v34, v31
	v_or_b32_e32 v35, 0x80000000, v31
	v_cmp_gt_i32_e32 vcc, 0, v31
	v_sub_u32_e32 v131, 31, v146
	v_sub_u32_e32 v132, 30, v146
	v_cndmask_b32_e32 v31, v35, v34, vcc
	v_mfma_f32_32x32x16_bf16 v[2:17], v[136:139], v[46:49], v[2:17]
	v_not_b32_e32 v34, v32
	v_or_b32_e32 v35, 0x80000000, v32
	v_cmp_gt_i32_e32 vcc, 0, v32
	v_sub_u32_e32 v133, 29, v146
	v_sub_u32_e32 v134, 28, v146
	v_cndmask_b32_e32 v32, v35, v34, vcc
	v_not_b32_e32 v34, v33
	v_mfma_f32_32x32x16_bf16 v[2:17], v[160:163], v[42:45], v[2:17]
	v_or_b32_e32 v35, 0x80000000, v33
	v_cmp_gt_i32_e32 vcc, 0, v33
	v_sub_u32_e32 v135, 23, v146
	v_sub_u32_e32 v136, 22, v146
	v_cndmask_b32_e32 v33, v35, v34, vcc
	v_sub_u32_e32 v137, 21, v146
	v_sub_u32_e32 v138, 20, v146
	v_mfma_f32_32x32x16_bf16 v[2:17], v[164:167], v[38:41], v[2:17]
	v_sub_u32_e32 v139, 15, v146
	v_sub_u32_e32 v140, 14, v146
	v_sub_u32_e32 v141, 13, v146
	v_sub_u32_e32 v142, 12, v146
	v_sub_u32_e32 v143, 7, v146
	v_sub_u32_e32 v146, 4, v146
	v_and_or_b32 v26, v26, s23, v123
	s_nop 4
	v_not_b32_e32 v34, v2
	v_or_b32_e32 v35, 0x80000000, v2
	v_cmp_gt_i32_e32 vcc, 0, v2
	v_and_or_b32 v27, v27, s23, v124
	global_load_dwordx4 v[200:203], v[236:237], off
	global_load_dwordx4 v[204:207], v[236:237], off offset:16
	global_load_dwordx4 v[208:211], v[236:237], off offset:32
	global_load_dwordx4 v[212:215], v[236:237], off offset:48
	global_load_dwordx4 v[216:219], v[238:239], off
	global_load_dwordx4 v[220:223], v[238:239], off offset:16
	global_load_dwordx4 v[224:227], v[238:239], off offset:32
	global_load_dwordx4 v[228:231], v[238:239], off offset:48
	v_lshl_add_u64 v[236:237], v[236:237], 0, v[244:245]
	v_lshl_add_u64 v[238:239], v[238:239], 0, v[244:245]
	v_and_or_b32 v28, v28, s23, v125
	v_cndmask_b32_e32 v2, v35, v34, vcc
	v_not_b32_e32 v34, v3
	v_or_b32_e32 v35, 0x80000000, v3
	v_cmp_gt_i32_e32 vcc, 0, v3
	v_and_or_b32 v29, v29, s23, v126
	v_and_or_b32 v30, v30, s23, v127
	v_cndmask_b32_e32 v3, v35, v34, vcc
	v_not_b32_e32 v34, v4
	v_or_b32_e32 v35, 0x80000000, v4
	v_cmp_gt_i32_e32 vcc, 0, v4
	v_and_or_b32 v31, v31, s23, v128
	v_and_or_b32 v32, v32, s23, v129
	v_cndmask_b32_e32 v4, v35, v34, vcc
	v_not_b32_e32 v34, v5
	v_or_b32_e32 v35, 0x80000000, v5
	v_cmp_gt_i32_e32 vcc, 0, v5
	v_and_or_b32 v33, v33, s23, v130
	v_and_or_b32 v2, v2, s23, v131
	v_cndmask_b32_e32 v5, v35, v34, vcc
	v_not_b32_e32 v34, v6
	v_or_b32_e32 v35, 0x80000000, v6
	v_cmp_gt_i32_e32 vcc, 0, v6
	v_and_or_b32 v3, v3, s23, v132
	v_and_or_b32 v4, v4, s23, v133
	v_cndmask_b32_e32 v6, v35, v34, vcc
	v_not_b32_e32 v34, v7
	v_or_b32_e32 v35, 0x80000000, v7
	v_cmp_gt_i32_e32 vcc, 0, v7
	v_and_or_b32 v5, v5, s23, v134
	v_and_or_b32 v6, v6, s23, v135
	v_cndmask_b32_e32 v7, v35, v34, vcc
	v_not_b32_e32 v34, v8
	v_or_b32_e32 v35, 0x80000000, v8
	v_cmp_gt_i32_e32 vcc, 0, v8
	v_and_or_b32 v7, v7, s23, v136
	v_min_u32_e32 v37, v169, v170
	v_cndmask_b32_e32 v8, v35, v34, vcc
	v_not_b32_e32 v34, v9
	v_or_b32_e32 v35, 0x80000000, v9
	v_cmp_gt_i32_e32 vcc, 0, v9
	v_and_or_b32 v8, v8, s23, v137
	v_max_u32_e32 v38, v171, v172
	v_cndmask_b32_e32 v9, v35, v34, vcc
	v_not_b32_e32 v34, v10
	v_or_b32_e32 v35, 0x80000000, v10
	v_cmp_gt_i32_e32 vcc, 0, v10
	v_and_or_b32 v9, v9, s23, v138
	v_min_u32_e32 v39, v171, v172
	v_cndmask_b32_e32 v10, v35, v34, vcc
	v_not_b32_e32 v34, v11
	v_or_b32_e32 v35, 0x80000000, v11
	v_cmp_gt_i32_e32 vcc, 0, v11
	v_and_or_b32 v10, v10, s23, v139
	v_max_u32_e32 v40, v173, v174
	v_cndmask_b32_e32 v11, v35, v34, vcc
	v_not_b32_e32 v34, v12
	v_or_b32_e32 v35, 0x80000000, v12
	v_cmp_gt_i32_e32 vcc, 0, v12
	v_and_or_b32 v11, v11, s23, v140
	v_min_u32_e32 v41, v173, v174
	v_cndmask_b32_e32 v12, v35, v34, vcc
	v_not_b32_e32 v34, v13
	v_or_b32_e32 v35, 0x80000000, v13
	v_cmp_gt_i32_e32 vcc, 0, v13
	v_and_or_b32 v12, v12, s23, v141
	v_max_u32_e32 v42, v175, v176
	v_cndmask_b32_e32 v13, v35, v34, vcc
	v_not_b32_e32 v34, v14
	v_or_b32_e32 v35, 0x80000000, v14
	v_cmp_gt_i32_e32 vcc, 0, v14
	v_and_or_b32 v13, v13, s23, v142
	v_min_u32_e32 v43, v175, v176
	v_cndmask_b32_e32 v14, v35, v34, vcc
	v_not_b32_e32 v34, v15
	v_or_b32_e32 v35, 0x80000000, v15
	v_cmp_gt_i32_e32 vcc, 0, v15
	v_and_or_b32 v14, v14, s23, v143
	v_max_u32_e32 v44, v177, v178
	v_cndmask_b32_e32 v15, v35, v34, vcc
	v_not_b32_e32 v34, v16
	v_or_b32_e32 v35, 0x80000000, v16
	v_cmp_gt_i32_e32 vcc, 0, v16
	v_and_or_b32 v15, v15, s23, v144
	v_min_u32_e32 v45, v177, v178
	v_cndmask_b32_e32 v16, v35, v34, vcc
	v_not_b32_e32 v34, v17
	v_or_b32_e32 v35, 0x80000000, v17
	v_cmp_gt_i32_e32 vcc, 0, v17
	v_and_or_b32 v16, v16, s23, v145
	v_max_u32_e32 v46, v179, v180
	v_cndmask_b32_e32 v17, v35, v34, vcc
	v_and_or_b32 v17, v17, s23, v146
	v_max_u32_e32 v34, v159, v168
	v_min_u32_e32 v35, v159, v168
	v_min_u32_e32 v47, v179, v180
	v_max_u32_e32 v48, v181, v182
	v_min_u32_e32 v49, v181, v182
	v_max_u32_e32 v58, v147, v148
	v_min_u32_e32 v59, v147, v148
	v_max_u32_e32 v60, v149, v150
	v_min_u32_e32 v61, v149, v150
	v_max_u32_e32 v62, v151, v152
	v_min_u32_e32 v63, v151, v152
	v_max_u32_e32 v64, v153, v154
	v_min_u32_e32 v65, v153, v154
	v_max_u32_e32 v147, v155, v156
	v_min_u32_e32 v148, v155, v156
	v_max_u32_e32 v149, v157, v158
	v_min_u32_e32 v150, v157, v158
	v_max_u32_e32 v151, v183, v184
	v_min_u32_e32 v152, v183, v184
	v_max_u32_e32 v153, v185, v186
	v_min_u32_e32 v154, v185, v186
	v_max_u32_e32 v163, v18, v19
	v_min_u32_e32 v18, v18, v19
	v_max_u32_e32 v19, v20, v21
	v_min_u32_e32 v20, v20, v21
	v_max_u32_e32 v21, v22, v23
	v_min_u32_e32 v22, v22, v23
	v_max_u32_e32 v23, v24, v25
	v_min_u32_e32 v24, v24, v25
	v_max_u32_e32 v25, v26, v27
	v_min_u32_e32 v26, v26, v27
	v_max_u32_e32 v27, v28, v29
	v_min_u32_e32 v28, v28, v29
	v_max_u32_e32 v29, v30, v31
	v_min_u32_e32 v30, v30, v31
	v_max_u32_e32 v31, v32, v33
	v_min_u32_e32 v32, v32, v33
	v_max_u32_e32 v171, v2, v3
	v_min_u32_e32 v2, v2, v3
	v_max_u32_e32 v3, v4, v5
	v_min_u32_e32 v4, v4, v5
	v_max_u32_e32 v5, v6, v7
	v_min_u32_e32 v6, v6, v7
	v_max_u32_e32 v7, v8, v9
	v_min_u32_e32 v8, v8, v9
	v_max_u32_e32 v9, v10, v11
	v_min_u32_e32 v10, v10, v11
	v_max_u32_e32 v11, v12, v13
	v_min_u32_e32 v12, v12, v13
	v_max_u32_e32 v13, v14, v15
	v_min_u32_e32 v14, v14, v15
	v_max_u32_e32 v15, v16, v17
	v_min_u32_e32 v16, v16, v17
	v_max_u32_e32 v50, v34, v37
	v_min_u32_e32 v34, v34, v37
	v_max_u32_e32 v37, v35, v36
	v_min_u32_e32 v35, v35, v36
	v_max_u32_e32 v36, v38, v41
	v_min_u32_e32 v38, v38, v41
	v_max_u32_e32 v41, v39, v40
	v_min_u32_e32 v39, v39, v40
	v_max_u32_e32 v40, v42, v45
	v_min_u32_e32 v42, v42, v45
	v_max_u32_e32 v45, v43, v44
	v_min_u32_e32 v43, v43, v44
	v_max_u32_e32 v44, v46, v49
	v_min_u32_e32 v46, v46, v49
	v_max_u32_e32 v49, v47, v48
	v_min_u32_e32 v47, v47, v48
	v_max_u32_e32 v155, v58, v61
	v_min_u32_e32 v58, v58, v61
	v_max_u32_e32 v61, v59, v60
	v_min_u32_e32 v59, v59, v60
	v_max_u32_e32 v60, v62, v65
	v_min_u32_e32 v62, v62, v65
	v_max_u32_e32 v65, v63, v64
	v_min_u32_e32 v63, v63, v64
	v_max_u32_e32 v64, v147, v150
	v_min_u32_e32 v147, v147, v150
	v_max_u32_e32 v150, v148, v149
	v_min_u32_e32 v148, v148, v149
	v_max_u32_e32 v149, v151, v154
	v_min_u32_e32 v151, v151, v154
	v_max_u32_e32 v154, v152, v153
	v_min_u32_e32 v152, v152, v153
	v_max_u32_e32 v33, v163, v20
	v_min_u32_e32 v20, v163, v20
	v_max_u32_e32 v163, v18, v19
	v_min_u32_e32 v18, v18, v19
	v_max_u32_e32 v19, v21, v24
	v_min_u32_e32 v21, v21, v24
	v_max_u32_e32 v24, v22, v23
	v_min_u32_e32 v22, v22, v23
	v_max_u32_e32 v23, v25, v28
	v_min_u32_e32 v25, v25, v28
	v_max_u32_e32 v28, v26, v27
	v_min_u32_e32 v26, v26, v27
	v_max_u32_e32 v27, v29, v32
	v_min_u32_e32 v29, v29, v32
	v_max_u32_e32 v32, v30, v31
	v_min_u32_e32 v30, v30, v31
	v_max_u32_e32 v17, v171, v4
	v_min_u32_e32 v4, v171, v4
	v_max_u32_e32 v171, v2, v3
	v_min_u32_e32 v2, v2, v3
	v_max_u32_e32 v3, v5, v8
	v_min_u32_e32 v5, v5, v8
	v_max_u32_e32 v8, v6, v7
	v_min_u32_e32 v6, v6, v7
	v_max_u32_e32 v7, v9, v12
	v_min_u32_e32 v9, v9, v12
	v_max_u32_e32 v12, v10, v11
	v_min_u32_e32 v10, v10, v11
	v_max_u32_e32 v11, v13, v16
	v_min_u32_e32 v13, v13, v16
	v_max_u32_e32 v16, v14, v15
	v_min_u32_e32 v14, v14, v15
	v_max_u32_e32 v48, v50, v37
	v_min_u32_e32 v37, v50, v37
	v_max_u32_e32 v50, v34, v35
	v_min_u32_e32 v34, v34, v35
	v_max_u32_e32 v35, v38, v39
	v_min_u32_e32 v38, v38, v39
	v_max_u32_e32 v39, v36, v41
	v_min_u32_e32 v36, v36, v41
	v_max_u32_e32 v41, v40, v45
	v_min_u32_e32 v40, v40, v45
	v_max_u32_e32 v45, v42, v43
	v_min_u32_e32 v42, v42, v43
	v_max_u32_e32 v43, v46, v47
	v_min_u32_e32 v46, v46, v47
	v_max_u32_e32 v47, v44, v49
	v_min_u32_e32 v44, v44, v49
	v_max_u32_e32 v153, v155, v61
	v_min_u32_e32 v61, v155, v61
	v_max_u32_e32 v155, v58, v59
	v_min_u32_e32 v58, v58, v59
	v_max_u32_e32 v59, v62, v63
	v_min_u32_e32 v62, v62, v63
	v_max_u32_e32 v63, v60, v65
	v_min_u32_e32 v60, v60, v65
	v_max_u32_e32 v65, v64, v150
	v_min_u32_e32 v64, v64, v150
	v_max_u32_e32 v150, v147, v148
	v_min_u32_e32 v147, v147, v148
	v_max_u32_e32 v148, v151, v152
	v_min_u32_e32 v151, v151, v152
	v_max_u32_e32 v152, v149, v154
	v_min_u32_e32 v149, v149, v154
	v_max_u32_e32 v31, v33, v163
	v_min_u32_e32 v33, v33, v163
	v_max_u32_e32 v163, v20, v18
	v_min_u32_e32 v18, v20, v18
	v_max_u32_e32 v20, v21, v22
	v_min_u32_e32 v21, v21, v22
	v_max_u32_e32 v22, v19, v24
	v_min_u32_e32 v19, v19, v24
	v_max_u32_e32 v24, v23, v28
	v_min_u32_e32 v23, v23, v28
	v_max_u32_e32 v28, v25, v26
	v_min_u32_e32 v25, v25, v26
	v_max_u32_e32 v26, v29, v30
	v_min_u32_e32 v29, v29, v30
	v_max_u32_e32 v30, v27, v32
	v_min_u32_e32 v27, v27, v32
	v_max_u32_e32 v15, v17, v171
	v_min_u32_e32 v17, v17, v171
	v_max_u32_e32 v171, v4, v2
	v_min_u32_e32 v2, v4, v2
	v_max_u32_e32 v4, v5, v6
	v_min_u32_e32 v5, v5, v6
	v_max_u32_e32 v6, v3, v8
	v_min_u32_e32 v3, v3, v8
	v_max_u32_e32 v8, v7, v12
	v_min_u32_e32 v7, v7, v12
	v_max_u32_e32 v12, v9, v10
	v_min_u32_e32 v9, v9, v10
	v_max_u32_e32 v10, v13, v14
	v_min_u32_e32 v13, v13, v14
	v_max_u32_e32 v14, v11, v16
	v_min_u32_e32 v11, v11, v16
	v_max_u32_e32 v49, v48, v38
	v_min_u32_e32 v38, v48, v38
	v_max_u32_e32 v48, v37, v35
	v_min_u32_e32 v35, v37, v35
	v_max_u32_e32 v37, v50, v36
	v_min_u32_e32 v36, v50, v36
	v_max_u32_e32 v50, v34, v39
	v_min_u32_e32 v34, v34, v39
	v_max_u32_e32 v39, v41, v46
	v_min_u32_e32 v41, v41, v46
	v_max_u32_e32 v46, v40, v43
	v_min_u32_e32 v40, v40, v43
	v_max_u32_e32 v43, v45, v44
	v_min_u32_e32 v44, v45, v44
	v_max_u32_e32 v45, v42, v47
	v_min_u32_e32 v42, v42, v47
	v_max_u32_e32 v154, v153, v62
	v_min_u32_e32 v62, v153, v62
	v_max_u32_e32 v153, v61, v59
	s_waitcnt vmcnt(0)
	v_pk_mul_f32 v[200:201], v[200:201], s[96:97] op_sel_hi:[1,0]
	v_pk_mul_f32 v[202:203], v[202:203], s[96:97] op_sel_hi:[1,0]
	v_pk_mul_f32 v[204:205], v[204:205], s[96:97] op_sel_hi:[1,0]
	v_pk_mul_f32 v[206:207], v[206:207], s[96:97] op_sel_hi:[1,0]
	v_pk_mul_f32 v[208:209], v[208:209], s[96:97] op_sel_hi:[1,0]
	v_pk_mul_f32 v[210:211], v[210:211], s[96:97] op_sel_hi:[1,0]
	v_pk_mul_f32 v[212:213], v[212:213], s[96:97] op_sel_hi:[1,0]
	v_pk_mul_f32 v[214:215], v[214:215], s[96:97] op_sel_hi:[1,0]
	v_pk_mul_f32 v[216:217], v[216:217], s[96:97] op_sel_hi:[1,0]
	v_pk_mul_f32 v[218:219], v[218:219], s[96:97] op_sel_hi:[1,0]
	v_pk_mul_f32 v[220:221], v[220:221], s[96:97] op_sel_hi:[1,0]
	v_pk_mul_f32 v[222:223], v[222:223], s[96:97] op_sel_hi:[1,0]
	v_pk_mul_f32 v[224:225], v[224:225], s[96:97] op_sel_hi:[1,0]
	v_pk_mul_f32 v[226:227], v[226:227], s[96:97] op_sel_hi:[1,0]
	v_pk_mul_f32 v[228:229], v[228:229], s[96:97] op_sel_hi:[1,0]
	v_pk_mul_f32 v[230:231], v[230:231], s[96:97] op_sel_hi:[1,0]
	v_cvt_scalef32_pk_fp4_f32 v232, v200, v201, 1.0
	v_cvt_scalef32_pk_fp4_f32 v233, v208, v209, 1.0
	v_cvt_scalef32_pk_fp4_f32 v234, v216, v217, 1.0
	v_cvt_scalef32_pk_fp4_f32 v235, v224, v225, 1.0
	v_cvt_scalef32_pk_fp4_f32 v232, v202, v203, 1.0 op_sel:[0,0,1,0]
	v_cvt_scalef32_pk_fp4_f32 v233, v210, v211, 1.0 op_sel:[0,0,1,0]
	v_cvt_scalef32_pk_fp4_f32 v234, v218, v219, 1.0 op_sel:[0,0,1,0]
	v_cvt_scalef32_pk_fp4_f32 v235, v226, v227, 1.0 op_sel:[0,0,1,0]
	v_cvt_scalef32_pk_fp4_f32 v232, v204, v205, 1.0 op_sel:[0,0,0,1]
	v_cvt_scalef32_pk_fp4_f32 v233, v212, v213, 1.0 op_sel:[0,0,0,1]
	v_cvt_scalef32_pk_fp4_f32 v234, v220, v221, 1.0 op_sel:[0,0,0,1]
	v_cvt_scalef32_pk_fp4_f32 v235, v228, v229, 1.0 op_sel:[0,0,0,1]
	v_cvt_scalef32_pk_fp4_f32 v232, v206, v207, 1.0 op_sel:[0,0,1,1]
	v_cvt_scalef32_pk_fp4_f32 v233, v214, v215, 1.0 op_sel:[0,0,1,1]
	v_cvt_scalef32_pk_fp4_f32 v234, v222, v223, 1.0 op_sel:[0,0,1,1]
	v_cvt_scalef32_pk_fp4_f32 v235, v230, v231, 1.0 op_sel:[0,0,1,1]
	s_nop 0
	global_store_dwordx4 v[240:241], v[232:235], off
	v_lshl_add_u64 v[240:241], v[240:241], 0, v[246:247]
	global_load_dwordx4 v[200:203], v[236:237], off
	global_load_dwordx4 v[204:207], v[236:237], off offset:16
	global_load_dwordx4 v[208:211], v[236:237], off offset:32
	global_load_dwordx4 v[212:215], v[236:237], off offset:48
	global_load_dwordx4 v[216:219], v[238:239], off
	global_load_dwordx4 v[220:223], v[238:239], off offset:16
	global_load_dwordx4 v[224:227], v[238:239], off offset:32
	global_load_dwordx4 v[228:231], v[238:239], off offset:48
	v_lshl_add_u64 v[236:237], v[236:237], 0, v[244:245]
	v_lshl_add_u64 v[238:239], v[238:239], 0, v[244:245]
	v_min_u32_e32 v59, v61, v59
	v_max_u32_e32 v61, v155, v60
	v_min_u32_e32 v60, v155, v60
	v_max_u32_e32 v155, v58, v63
	v_min_u32_e32 v58, v58, v63
	v_max_u32_e32 v63, v65, v151
	v_min_u32_e32 v65, v65, v151
	v_max_u32_e32 v151, v64, v148
	v_min_u32_e32 v64, v64, v148
	v_max_u32_e32 v148, v150, v149
	v_min_u32_e32 v149, v150, v149
	v_max_u32_e32 v150, v147, v152
	v_min_u32_e32 v147, v147, v152
	v_max_u32_e32 v32, v31, v21
	v_min_u32_e32 v21, v31, v21
	v_max_u32_e32 v31, v33, v20
	v_min_u32_e32 v20, v33, v20
	v_max_u32_e32 v33, v163, v19
	v_min_u32_e32 v19, v163, v19
	v_max_u32_e32 v163, v18, v22
	v_min_u32_e32 v18, v18, v22
	v_max_u32_e32 v22, v24, v29
	v_min_u32_e32 v24, v24, v29
	v_max_u32_e32 v29, v23, v26
	v_min_u32_e32 v23, v23, v26
	v_max_u32_e32 v26, v28, v27
	v_min_u32_e32 v27, v28, v27
	v_max_u32_e32 v28, v25, v30
	v_min_u32_e32 v25, v25, v30
	v_max_u32_e32 v16, v15, v5
	v_min_u32_e32 v5, v15, v5
	v_max_u32_e32 v15, v17, v4
	v_min_u32_e32 v4, v17, v4
	v_max_u32_e32 v17, v171, v3
	v_min_u32_e32 v3, v171, v3
	v_max_u32_e32 v171, v2, v6
	v_min_u32_e32 v2, v2, v6
	v_max_u32_e32 v6, v8, v13
	v_min_u32_e32 v8, v8, v13
	v_max_u32_e32 v13, v7, v10
	v_min_u32_e32 v7, v7, v10
	v_max_u32_e32 v10, v12, v11
	v_min_u32_e32 v11, v12, v11
	v_max_u32_e32 v12, v9, v14
	v_min_u32_e32 v9, v9, v14
	v_max_u32_e32 v47, v49, v37
	v_min_u32_e32 v37, v49, v37
	v_max_u32_e32 v49, v48, v50
	v_min_u32_e32 v48, v48, v50
	v_max_u32_e32 v50, v38, v36
	v_min_u32_e32 v36, v38, v36
	v_max_u32_e32 v38, v35, v34
	v_min_u32_e32 v34, v35, v34
	v_max_u32_e32 v35, v41, v44
	v_min_u32_e32 v41, v41, v44
	v_max_u32_e32 v44, v40, v42
	v_min_u32_e32 v40, v40, v42
	v_max_u32_e32 v42, v39, v43
	v_min_u32_e32 v39, v39, v43
	v_max_u32_e32 v43, v46, v45
	v_min_u32_e32 v45, v46, v45
	v_max_u32_e32 v152, v154, v61
	v_min_u32_e32 v61, v154, v61
	v_max_u32_e32 v154, v153, v155
	v_min_u32_e32 v153, v153, v155
	v_max_u32_e32 v155, v62, v60
	v_min_u32_e32 v60, v62, v60
	v_max_u32_e32 v62, v59, v58
	v_min_u32_e32 v58, v59, v58
	v_max_u32_e32 v59, v65, v149
	v_min_u32_e32 v65, v65, v149
	v_max_u32_e32 v149, v64, v147
	v_min_u32_e32 v64, v64, v147
	v_max_u32_e32 v147, v63, v148
	v_min_u32_e32 v63, v63, v148
	v_max_u32_e32 v148, v151, v150
	v_min_u32_e32 v150, v151, v150
	v_max_u32_e32 v30, v32, v33
	v_min_u32_e32 v32, v32, v33
	v_max_u32_e32 v33, v31, v163
	v_min_u32_e32 v31, v31, v163
	v_max_u32_e32 v163, v21, v19
	v_min_u32_e32 v19, v21, v19
	v_max_u32_e32 v21, v20, v18
	v_min_u32_e32 v18, v20, v18
	v_max_u32_e32 v20, v24, v27
	v_min_u32_e32 v24, v24, v27
	v_max_u32_e32 v27, v23, v25
	v_min_u32_e32 v23, v23, v25
	v_max_u32_e32 v25, v22, v26
	v_min_u32_e32 v22, v22, v26
	v_max_u32_e32 v26, v29, v28
	v_min_u32_e32 v28, v29, v28
	v_max_u32_e32 v14, v16, v17
	v_min_u32_e32 v16, v16, v17
	v_max_u32_e32 v17, v15, v171
	v_min_u32_e32 v15, v15, v171
	v_max_u32_e32 v171, v5, v3
	v_min_u32_e32 v3, v5, v3
	v_max_u32_e32 v5, v4, v2
	v_min_u32_e32 v2, v4, v2
	v_max_u32_e32 v4, v8, v11
	v_min_u32_e32 v8, v8, v11
	v_max_u32_e32 v11, v7, v9
	v_min_u32_e32 v7, v7, v9
	v_max_u32_e32 v9, v6, v10
	v_min_u32_e32 v6, v6, v10
	v_max_u32_e32 v10, v13, v12
	v_min_u32_e32 v12, v13, v12
	v_max_u32_e32 v46, v47, v49
	v_min_u32_e32 v47, v47, v49
	v_max_u32_e32 v49, v37, v48
	v_min_u32_e32 v37, v37, v48
	v_max_u32_e32 v48, v50, v38
	v_min_u32_e32 v38, v50, v38
	v_max_u32_e32 v50, v36, v34
	v_min_u32_e32 v34, v36, v34
	v_max_u32_e32 v36, v41, v40
	v_min_u32_e32 v40, v41, v40
	v_max_u32_e32 v41, v35, v44
	v_min_u32_e32 v35, v35, v44
	v_max_u32_e32 v44, v39, v45
	v_min_u32_e32 v39, v39, v45
	v_max_u32_e32 v45, v42, v43
	v_min_u32_e32 v42, v42, v43
	v_max_u32_e32 v151, v152, v154
	v_min_u32_e32 v152, v152, v154
	v_max_u32_e32 v154, v61, v153
	v_min_u32_e32 v61, v61, v153
	v_max_u32_e32 v153, v155, v62
	v_min_u32_e32 v62, v155, v62
	v_max_u32_e32 v155, v60, v58
	v_min_u32_e32 v58, v60, v58
	v_max_u32_e32 v60, v65, v64
	v_min_u32_e32 v64, v65, v64
	v_max_u32_e32 v65, v59, v149
	v_min_u32_e32 v59, v59, v149
	v_max_u32_e32 v149, v63, v150
	v_min_u32_e32 v63, v63, v150
	v_max_u32_e32 v150, v147, v148
	v_min_u32_e32 v147, v147, v148
	v_max_u32_e32 v29, v30, v33
	v_min_u32_e32 v30, v30, v33
	v_max_u32_e32 v33, v32, v31
	v_min_u32_e32 v31, v32, v31
	v_max_u32_e32 v32, v163, v21
	v_min_u32_e32 v21, v163, v21
	v_max_u32_e32 v163, v19, v18
	v_min_u32_e32 v18, v19, v18
	v_max_u32_e32 v19, v24, v23
	v_min_u32_e32 v23, v24, v23
	v_max_u32_e32 v24, v20, v27
	v_min_u32_e32 v20, v20, v27
	v_max_u32_e32 v27, v22, v28
	v_min_u32_e32 v22, v22, v28
	v_max_u32_e32 v28, v25, v26
	v_min_u32_e32 v25, v25, v26
	v_max_u32_e32 v13, v14, v17
	v_min_u32_e32 v14, v14, v17
	v_max_u32_e32 v17, v16, v15
	v_min_u32_e32 v15, v16, v15
	v_max_u32_e32 v16, v171, v5
	v_min_u32_e32 v5, v171, v5
	v_max_u32_e32 v171, v3, v2
	v_min_u32_e32 v2, v3, v2
	v_max_u32_e32 v3, v8, v7
	v_min_u32_e32 v7, v8, v7
	v_max_u32_e32 v8, v4, v11
	v_min_u32_e32 v4, v4, v11
	v_max_u32_e32 v11, v6, v12
	v_min_u32_e32 v6, v6, v12
	v_max_u32_e32 v12, v9, v10
	v_min_u32_e32 v9, v9, v10
	v_max_u32_e32 v43, v46, v40
	v_min_u32_e32 v40, v46, v40
	v_max_u32_e32 v46, v47, v36
	v_min_u32_e32 v36, v47, v36
	v_max_u32_e32 v47, v49, v35
	v_min_u32_e32 v35, v49, v35
	v_max_u32_e32 v49, v37, v41
	v_min_u32_e32 v37, v37, v41
	v_max_u32_e32 v41, v48, v39
	v_min_u32_e32 v39, v48, v39
	v_max_u32_e32 v48, v38, v44
	v_min_u32_e32 v38, v38, v44
	v_max_u32_e32 v44, v50, v42
	v_min_u32_e32 v42, v50, v42
	v_max_u32_e32 v50, v34, v45
	v_min_u32_e32 v34, v34, v45
	v_max_u32_e32 v148, v151, v64
	v_min_u32_e32 v64, v151, v64
	v_max_u32_e32 v151, v152, v60
	v_min_u32_e32 v60, v152, v60
	v_max_u32_e32 v152, v154, v59
	v_min_u32_e32 v59, v154, v59
	v_max_u32_e32 v154, v61, v65
	v_min_u32_e32 v61, v61, v65
	v_max_u32_e32 v65, v153, v63
	v_min_u32_e32 v63, v153, v63
	v_max_u32_e32 v153, v62, v149
	v_min_u32_e32 v62, v62, v149
	v_max_u32_e32 v149, v155, v147
	v_min_u32_e32 v147, v155, v147
	v_max_u32_e32 v155, v58, v150
	v_min_u32_e32 v58, v58, v150
	v_max_u32_e32 v26, v29, v23
	v_min_u32_e32 v23, v29, v23
	v_max_u32_e32 v29, v30, v19
	v_min_u32_e32 v19, v30, v19
	v_max_u32_e32 v30, v33, v20
	v_min_u32_e32 v20, v33, v20
	v_max_u32_e32 v33, v31, v24
	v_min_u32_e32 v24, v31, v24
	v_max_u32_e32 v31, v32, v22
	v_min_u32_e32 v22, v32, v22
	v_max_u32_e32 v32, v21, v27
	v_min_u32_e32 v21, v21, v27
	v_max_u32_e32 v27, v163, v25
	v_min_u32_e32 v25, v163, v25
	v_max_u32_e32 v163, v18, v28
	v_min_u32_e32 v18, v18, v28
	v_max_u32_e32 v10, v13, v7
	v_min_u32_e32 v7, v13, v7
	v_max_u32_e32 v13, v14, v3
	v_min_u32_e32 v3, v14, v3
	v_max_u32_e32 v14, v17, v4
	v_min_u32_e32 v4, v17, v4
	v_max_u32_e32 v17, v15, v8
	v_min_u32_e32 v8, v15, v8
	v_max_u32_e32 v15, v16, v6
	v_min_u32_e32 v6, v16, v6
	v_max_u32_e32 v16, v5, v11
	v_min_u32_e32 v5, v5, v11
	v_max_u32_e32 v11, v171, v9
	v_min_u32_e32 v9, v171, v9
	v_max_u32_e32 v171, v2, v12
	v_min_u32_e32 v2, v2, v12
	v_max_u32_e32 v45, v43, v41
	v_min_u32_e32 v41, v43, v41
	v_max_u32_e32 v43, v46, v48
	v_min_u32_e32 v46, v46, v48
	v_max_u32_e32 v48, v47, v44
	v_min_u32_e32 v44, v47, v44
	v_max_u32_e32 v47, v49, v50
	v_min_u32_e32 v49, v49, v50
	v_max_u32_e32 v50, v40, v39
	v_min_u32_e32 v39, v40, v39
	v_max_u32_e32 v40, v36, v38
	v_min_u32_e32 v36, v36, v38
	v_max_u32_e32 v38, v35, v42
	v_min_u32_e32 v35, v35, v42
	v_max_u32_e32 v42, v37, v34
	v_min_u32_e32 v34, v37, v34
	v_max_u32_e32 v150, v148, v65
	v_min_u32_e32 v65, v148, v65
	v_max_u32_e32 v148, v151, v153
	v_min_u32_e32 v151, v151, v153
	v_max_u32_e32 v153, v152, v149
	v_min_u32_e32 v149, v152, v149
	v_max_u32_e32 v152, v154, v155
	v_min_u32_e32 v154, v154, v155
	v_max_u32_e32 v155, v64, v63
	v_min_u32_e32 v63, v64, v63
	v_max_u32_e32 v64, v60, v62
	v_min_u32_e32 v60, v60, v62
	v_max_u32_e32 v62, v59, v147
	v_min_u32_e32 v59, v59, v147
	v_max_u32_e32 v147, v61, v58
	v_min_u32_e32 v58, v61, v58
	v_max_u32_e32 v28, v26, v31
	v_min_u32_e32 v26, v26, v31
	v_max_u32_e32 v31, v29, v32
	v_min_u32_e32 v29, v29, v32
	v_max_u32_e32 v32, v30, v27
	v_min_u32_e32 v27, v30, v27
	v_max_u32_e32 v30, v33, v163
	v_min_u32_e32 v33, v33, v163
	v_max_u32_e32 v163, v23, v22
	v_min_u32_e32 v22, v23, v22
	v_max_u32_e32 v23, v19, v21
	v_min_u32_e32 v19, v19, v21
	v_max_u32_e32 v21, v20, v25
	v_min_u32_e32 v20, v20, v25
	v_max_u32_e32 v25, v24, v18
	v_min_u32_e32 v18, v24, v18
	v_max_u32_e32 v12, v10, v15
	v_min_u32_e32 v10, v10, v15
	v_max_u32_e32 v15, v13, v16
	v_min_u32_e32 v13, v13, v16
	v_max_u32_e32 v16, v14, v11
	v_min_u32_e32 v11, v14, v11
	v_max_u32_e32 v14, v17, v171
	v_min_u32_e32 v17, v17, v171
	v_max_u32_e32 v171, v7, v6
	v_min_u32_e32 v6, v7, v6
	v_max_u32_e32 v7, v3, v5
	v_min_u32_e32 v3, v3, v5
	v_max_u32_e32 v5, v4, v9
	v_min_u32_e32 v4, v4, v9
	v_max_u32_e32 v9, v8, v2
	v_min_u32_e32 v2, v8, v2
	v_max_u32_e32 v37, v45, v48
	v_min_u32_e32 v45, v45, v48
	v_max_u32_e32 v48, v43, v47
	v_min_u32_e32 v43, v43, v47
	s_waitcnt vmcnt(0)
	v_pk_mul_f32 v[200:201], v[200:201], s[96:97] op_sel_hi:[1,0]
	v_pk_mul_f32 v[202:203], v[202:203], s[96:97] op_sel_hi:[1,0]
	v_pk_mul_f32 v[204:205], v[204:205], s[96:97] op_sel_hi:[1,0]
	v_pk_mul_f32 v[206:207], v[206:207], s[96:97] op_sel_hi:[1,0]
	v_pk_mul_f32 v[208:209], v[208:209], s[96:97] op_sel_hi:[1,0]
	v_pk_mul_f32 v[210:211], v[210:211], s[96:97] op_sel_hi:[1,0]
	v_pk_mul_f32 v[212:213], v[212:213], s[96:97] op_sel_hi:[1,0]
	v_pk_mul_f32 v[214:215], v[214:215], s[96:97] op_sel_hi:[1,0]
	v_pk_mul_f32 v[216:217], v[216:217], s[96:97] op_sel_hi:[1,0]
	v_pk_mul_f32 v[218:219], v[218:219], s[96:97] op_sel_hi:[1,0]
	v_pk_mul_f32 v[220:221], v[220:221], s[96:97] op_sel_hi:[1,0]
	v_pk_mul_f32 v[222:223], v[222:223], s[96:97] op_sel_hi:[1,0]
	v_pk_mul_f32 v[224:225], v[224:225], s[96:97] op_sel_hi:[1,0]
	v_pk_mul_f32 v[226:227], v[226:227], s[96:97] op_sel_hi:[1,0]
	v_pk_mul_f32 v[228:229], v[228:229], s[96:97] op_sel_hi:[1,0]
	v_pk_mul_f32 v[230:231], v[230:231], s[96:97] op_sel_hi:[1,0]
	v_cvt_scalef32_pk_fp4_f32 v232, v200, v201, 1.0
	v_cvt_scalef32_pk_fp4_f32 v233, v208, v209, 1.0
	v_cvt_scalef32_pk_fp4_f32 v234, v216, v217, 1.0
	v_cvt_scalef32_pk_fp4_f32 v235, v224, v225, 1.0
	v_cvt_scalef32_pk_fp4_f32 v232, v202, v203, 1.0 op_sel:[0,0,1,0]
	v_cvt_scalef32_pk_fp4_f32 v233, v210, v211, 1.0 op_sel:[0,0,1,0]
	v_cvt_scalef32_pk_fp4_f32 v234, v218, v219, 1.0 op_sel:[0,0,1,0]
	v_cvt_scalef32_pk_fp4_f32 v235, v226, v227, 1.0 op_sel:[0,0,1,0]
	v_cvt_scalef32_pk_fp4_f32 v232, v204, v205, 1.0 op_sel:[0,0,0,1]
	v_cvt_scalef32_pk_fp4_f32 v233, v212, v213, 1.0 op_sel:[0,0,0,1]
	v_cvt_scalef32_pk_fp4_f32 v234, v220, v221, 1.0 op_sel:[0,0,0,1]
	v_cvt_scalef32_pk_fp4_f32 v235, v228, v229, 1.0 op_sel:[0,0,0,1]
	v_cvt_scalef32_pk_fp4_f32 v232, v206, v207, 1.0 op_sel:[0,0,1,1]
	v_cvt_scalef32_pk_fp4_f32 v233, v214, v215, 1.0 op_sel:[0,0,1,1]
	v_cvt_scalef32_pk_fp4_f32 v234, v222, v223, 1.0 op_sel:[0,0,1,1]
	v_cvt_scalef32_pk_fp4_f32 v235, v230, v231, 1.0 op_sel:[0,0,1,1]
	s_nop 0
	global_store_dwordx4 v[240:241], v[232:235], off
	v_lshl_add_u64 v[240:241], v[240:241], 0, v[246:247]
	global_load_dwordx4 v[200:203], v[236:237], off
	global_load_dwordx4 v[204:207], v[236:237], off offset:16
	global_load_dwordx4 v[208:211], v[236:237], off offset:32
	global_load_dwordx4 v[212:215], v[236:237], off offset:48
	global_load_dwordx4 v[216:219], v[238:239], off
	global_load_dwordx4 v[220:223], v[238:239], off offset:16
	global_load_dwordx4 v[224:227], v[238:239], off offset:32
	global_load_dwordx4 v[228:231], v[238:239], off offset:48
	v_lshl_add_u64 v[236:237], v[236:237], 0, v[244:245]
	v_lshl_add_u64 v[238:239], v[238:239], 0, v[244:245]
	v_max_u32_e32 v47, v41, v44
	v_min_u32_e32 v41, v41, v44
	v_max_u32_e32 v44, v46, v49
	v_min_u32_e32 v46, v46, v49
	v_max_u32_e32 v49, v50, v38
	v_min_u32_e32 v38, v50, v38
	v_max_u32_e32 v50, v40, v42
	v_min_u32_e32 v40, v40, v42
	v_max_u32_e32 v42, v39, v35
	v_min_u32_e32 v35, v39, v35
	v_max_u32_e32 v39, v36, v34
	v_min_u32_e32 v34, v36, v34
	v_max_u32_e32 v61, v150, v153
	v_min_u32_e32 v150, v150, v153
	v_max_u32_e32 v153, v148, v152
	v_min_u32_e32 v148, v148, v152
	v_max_u32_e32 v152, v65, v149
	v_min_u32_e32 v65, v65, v149
	v_max_u32_e32 v149, v151, v154
	v_min_u32_e32 v151, v151, v154
	v_max_u32_e32 v154, v155, v62
	v_min_u32_e32 v62, v155, v62
	v_max_u32_e32 v155, v64, v147
	v_min_u32_e32 v64, v64, v147
	v_max_u32_e32 v147, v63, v59
	v_min_u32_e32 v59, v63, v59
	v_max_u32_e32 v63, v60, v58
	v_min_u32_e32 v58, v60, v58
	v_max_u32_e32 v24, v28, v32
	v_min_u32_e32 v28, v28, v32
	v_max_u32_e32 v32, v31, v30
	v_min_u32_e32 v30, v31, v30
	v_max_u32_e32 v31, v26, v27
	v_min_u32_e32 v26, v26, v27
	v_max_u32_e32 v27, v29, v33
	v_min_u32_e32 v29, v29, v33
	v_max_u32_e32 v33, v163, v21
	v_min_u32_e32 v21, v163, v21
	v_max_u32_e32 v163, v23, v25
	v_min_u32_e32 v23, v23, v25
	v_max_u32_e32 v25, v22, v20
	v_min_u32_e32 v20, v22, v20
	v_max_u32_e32 v22, v19, v18
	v_min_u32_e32 v18, v19, v18
	v_max_u32_e32 v8, v12, v16
	v_min_u32_e32 v12, v12, v16
	v_max_u32_e32 v16, v15, v14
	v_min_u32_e32 v14, v15, v14
	v_max_u32_e32 v15, v10, v11
	v_min_u32_e32 v10, v10, v11
	v_max_u32_e32 v11, v13, v17
	v_min_u32_e32 v13, v13, v17
	v_max_u32_e32 v17, v171, v5
	v_min_u32_e32 v5, v171, v5
	v_max_u32_e32 v171, v7, v9
	v_min_u32_e32 v7, v7, v9
	v_max_u32_e32 v9, v6, v4
	v_min_u32_e32 v4, v6, v4
	v_max_u32_e32 v6, v3, v2
	v_min_u32_e32 v2, v3, v2
	v_min_u32_e32 v36, v37, v48
	v_min_u32_e32 v51, v45, v43
	v_min_u32_e32 v52, v47, v44
	v_min_u32_e32 v53, v41, v46
	v_min_u32_e32 v54, v49, v50
	v_min_u32_e32 v55, v38, v40
	v_min_u32_e32 v56, v42, v39
	v_min_u32_e32 v57, v35, v34
	v_min_u32_e32 v60, v61, v153
	v_min_u32_e32 v156, v150, v148
	v_min_u32_e32 v157, v152, v149
	v_min_u32_e32 v158, v65, v151
	v_min_u32_e32 v159, v154, v155
	v_min_u32_e32 v160, v62, v64
	v_min_u32_e32 v161, v147, v63
	v_min_u32_e32 v162, v59, v58
	v_min_u32_e32 v19, v24, v32
	v_min_u32_e32 v164, v28, v30
	v_min_u32_e32 v165, v31, v27
	v_min_u32_e32 v166, v26, v29
	v_min_u32_e32 v167, v33, v163
	v_min_u32_e32 v168, v21, v23
	v_min_u32_e32 v169, v25, v22
	v_min_u32_e32 v170, v20, v18
	v_min_u32_e32 v3, v8, v16
	v_min_u32_e32 v172, v12, v14
	v_min_u32_e32 v173, v15, v11
	v_min_u32_e32 v174, v10, v13
	v_min_u32_e32 v175, v17, v171
	v_min_u32_e32 v176, v5, v7
	v_min_u32_e32 v177, v9, v6
	v_min_u32_e32 v178, v4, v2
	v_max3_u32 v37, v37, v48, v162
	v_max3_u32 v24, v24, v32, v178
	v_max3_u32 v32, v36, v59, v58
	v_max3_u32 v2, v19, v4, v2
	v_max3_u32 v4, v45, v43, v161
	v_max3_u32 v19, v28, v30, v177
	v_max3_u32 v28, v51, v147, v63
	v_max3_u32 v6, v164, v9, v6
	v_max3_u32 v9, v47, v44, v160
	v_max3_u32 v27, v31, v27, v176
	v_max3_u32 v30, v52, v62, v64
	v_max3_u32 v5, v165, v5, v7
	v_max3_u32 v7, v41, v46, v159
	v_max3_u32 v26, v26, v29, v175
	v_max3_u32 v29, v53, v154, v155
	v_max3_u32 v17, v166, v17, v171
	v_max3_u32 v31, v49, v50, v158
	v_max3_u32 v33, v33, v163, v174
	v_max3_u32 v36, v54, v65, v151
	v_max3_u32 v10, v167, v10, v13
	v_max3_u32 v13, v38, v40, v157
	v_max3_u32 v21, v21, v23, v173
	v_max3_u32 v23, v55, v152, v149
	v_max3_u32 v11, v168, v15, v11
	v_max3_u32 v15, v42, v39, v156
	v_max3_u32 v22, v25, v22, v172
	v_max3_u32 v25, v56, v150, v148
	v_max3_u32 v12, v169, v12, v14
	v_max3_u32 v14, v35, v34, v60
	v_max3_u32 v3, v20, v18, v3
	v_max3_u32 v18, v57, v61, v153
	v_max3_u32 v8, v170, v8, v16
	v_max_u32_e32 v16, v37, v31
	v_min_u32_e32 v20, v37, v31
	v_max_u32_e32 v31, v32, v36
	v_min_u32_e32 v32, v32, v36
	v_max_u32_e32 v34, v4, v13
	v_min_u32_e32 v4, v4, v13
	v_max_u32_e32 v13, v28, v23
	v_min_u32_e32 v23, v28, v23
	v_max_u32_e32 v28, v9, v15
	v_min_u32_e32 v9, v9, v15
	v_max_u32_e32 v15, v30, v25
	v_min_u32_e32 v25, v30, v25
	v_max_u32_e32 v30, v7, v14
	v_min_u32_e32 v7, v7, v14
	v_max_u32_e32 v14, v29, v18
	v_min_u32_e32 v18, v29, v18
	v_max_u32_e32 v42, v24, v33
	v_min_u32_e32 v24, v24, v33
	v_max_u32_e32 v33, v2, v10
	v_min_u32_e32 v2, v2, v10
	v_max_u32_e32 v10, v19, v21
	v_min_u32_e32 v19, v19, v21
	v_max_u32_e32 v21, v6, v11
	v_min_u32_e32 v6, v6, v11
	v_max_u32_e32 v11, v27, v22
	v_min_u32_e32 v22, v27, v22
	v_max_u32_e32 v27, v5, v12
	v_min_u32_e32 v5, v5, v12
	v_max_u32_e32 v12, v26, v3
	v_min_u32_e32 v3, v26, v3
	v_max_u32_e32 v26, v17, v8
	v_min_u32_e32 v8, v17, v8
	v_max_u32_e32 v29, v16, v28
	v_min_u32_e32 v16, v16, v28
	v_max_u32_e32 v28, v31, v15
	v_min_u32_e32 v15, v31, v15
	v_max_u32_e32 v31, v34, v30
	v_min_u32_e32 v30, v34, v30
	v_max_u32_e32 v34, v13, v14
	v_min_u32_e32 v13, v13, v14
	v_max_u32_e32 v14, v20, v9
	v_min_u32_e32 v9, v20, v9
	v_max_u32_e32 v20, v32, v25
	v_min_u32_e32 v25, v32, v25
	v_max_u32_e32 v32, v4, v7
	v_min_u32_e32 v4, v4, v7
	v_max_u32_e32 v7, v23, v18
	v_min_u32_e32 v18, v23, v18
	v_max_u32_e32 v17, v42, v11
	v_min_u32_e32 v11, v42, v11
	v_max_u32_e32 v42, v33, v27
	v_min_u32_e32 v27, v33, v27
	v_max_u32_e32 v33, v10, v12
	v_min_u32_e32 v10, v10, v12
	v_max_u32_e32 v12, v21, v26
	v_min_u32_e32 v21, v21, v26
	v_max_u32_e32 v26, v24, v22
	v_min_u32_e32 v22, v24, v22
	v_max_u32_e32 v24, v2, v5
	v_min_u32_e32 v2, v2, v5
	v_max_u32_e32 v5, v19, v3
	v_min_u32_e32 v3, v19, v3
	v_max_u32_e32 v19, v6, v8
	v_min_u32_e32 v6, v6, v8
	v_max_u32_e32 v23, v29, v31
	v_min_u32_e32 v29, v29, v31
	v_max_u32_e32 v31, v28, v34
	v_min_u32_e32 v28, v28, v34
	v_max_u32_e32 v34, v16, v30
	v_min_u32_e32 v16, v16, v30
	v_max_u32_e32 v30, v15, v13
	v_min_u32_e32 v13, v15, v13
	v_max_u32_e32 v15, v14, v32
	v_min_u32_e32 v14, v14, v32
	v_max_u32_e32 v32, v20, v7
	v_min_u32_e32 v7, v20, v7
	v_max_u32_e32 v20, v9, v4
	v_min_u32_e32 v4, v9, v4
	v_max_u32_e32 v9, v25, v18
	v_min_u32_e32 v18, v25, v18
	v_max_u32_e32 v8, v17, v33
	v_min_u32_e32 v17, v17, v33
	v_max_u32_e32 v33, v42, v12
	v_min_u32_e32 v12, v42, v12
	v_max_u32_e32 v42, v11, v10
	v_min_u32_e32 v10, v11, v10
	v_max_u32_e32 v11, v27, v21
	v_min_u32_e32 v21, v27, v21
	v_max_u32_e32 v27, v26, v5
	v_min_u32_e32 v5, v26, v5
	v_max_u32_e32 v26, v24, v19
	v_min_u32_e32 v19, v24, v19
	v_max_u32_e32 v24, v22, v3
	v_min_u32_e32 v3, v22, v3
	v_max_u32_e32 v22, v2, v6
	v_min_u32_e32 v2, v2, v6
	v_min_u32_e32 v25, v23, v31
	v_min_u32_e32 v35, v29, v28
	v_min_u32_e32 v36, v34, v30
	v_min_u32_e32 v37, v16, v13
	v_min_u32_e32 v38, v15, v32
	v_min_u32_e32 v39, v14, v7
	v_min_u32_e32 v40, v20, v9
	v_min_u32_e32 v41, v4, v18
	v_min_u32_e32 v6, v8, v33
	v_min_u32_e32 v43, v17, v12
	v_min_u32_e32 v44, v42, v11
	v_min_u32_e32 v45, v10, v21
	v_min_u32_e32 v46, v27, v26
	v_min_u32_e32 v47, v5, v19
	v_min_u32_e32 v48, v24, v22
	v_min_u32_e32 v49, v3, v2
	v_max3_u32 v23, v23, v31, v49
	v_max3_u32 v2, v25, v3, v2
	v_max3_u32 v3, v29, v28, v48
	v_max3_u32 v22, v35, v24, v22
	v_max3_u32 v24, v34, v30, v47
	v_max3_u32 v5, v36, v5, v19
	v_max3_u32 v13, v16, v13, v46
	v_max3_u32 v16, v37, v27, v26
	v_max3_u32 v15, v15, v32, v45
	s_waitcnt vmcnt(0)
	v_pk_mul_f32 v[200:201], v[200:201], s[96:97] op_sel_hi:[1,0]
	v_pk_mul_f32 v[202:203], v[202:203], s[96:97] op_sel_hi:[1,0]
	v_pk_mul_f32 v[204:205], v[204:205], s[96:97] op_sel_hi:[1,0]
	v_pk_mul_f32 v[206:207], v[206:207], s[96:97] op_sel_hi:[1,0]
	v_pk_mul_f32 v[208:209], v[208:209], s[96:97] op_sel_hi:[1,0]
	v_pk_mul_f32 v[210:211], v[210:211], s[96:97] op_sel_hi:[1,0]
	v_pk_mul_f32 v[212:213], v[212:213], s[96:97] op_sel_hi:[1,0]
	v_pk_mul_f32 v[214:215], v[214:215], s[96:97] op_sel_hi:[1,0]
	v_pk_mul_f32 v[216:217], v[216:217], s[96:97] op_sel_hi:[1,0]
	v_pk_mul_f32 v[218:219], v[218:219], s[96:97] op_sel_hi:[1,0]
	v_pk_mul_f32 v[220:221], v[220:221], s[96:97] op_sel_hi:[1,0]
	v_pk_mul_f32 v[222:223], v[222:223], s[96:97] op_sel_hi:[1,0]
	v_pk_mul_f32 v[224:225], v[224:225], s[96:97] op_sel_hi:[1,0]
	v_pk_mul_f32 v[226:227], v[226:227], s[96:97] op_sel_hi:[1,0]
	v_pk_mul_f32 v[228:229], v[228:229], s[96:97] op_sel_hi:[1,0]
	v_pk_mul_f32 v[230:231], v[230:231], s[96:97] op_sel_hi:[1,0]
	v_cvt_scalef32_pk_fp4_f32 v232, v200, v201, 1.0
	v_cvt_scalef32_pk_fp4_f32 v233, v208, v209, 1.0
	v_cvt_scalef32_pk_fp4_f32 v234, v216, v217, 1.0
	v_cvt_scalef32_pk_fp4_f32 v235, v224, v225, 1.0
	v_cvt_scalef32_pk_fp4_f32 v232, v202, v203, 1.0 op_sel:[0,0,1,0]
	v_cvt_scalef32_pk_fp4_f32 v233, v210, v211, 1.0 op_sel:[0,0,1,0]
	v_cvt_scalef32_pk_fp4_f32 v234, v218, v219, 1.0 op_sel:[0,0,1,0]
	v_cvt_scalef32_pk_fp4_f32 v235, v226, v227, 1.0 op_sel:[0,0,1,0]
	v_cvt_scalef32_pk_fp4_f32 v232, v204, v205, 1.0 op_sel:[0,0,0,1]
	v_cvt_scalef32_pk_fp4_f32 v233, v212, v213, 1.0 op_sel:[0,0,0,1]
	v_cvt_scalef32_pk_fp4_f32 v234, v220, v221, 1.0 op_sel:[0,0,0,1]
	v_cvt_scalef32_pk_fp4_f32 v235, v228, v229, 1.0 op_sel:[0,0,0,1]
	v_cvt_scalef32_pk_fp4_f32 v232, v206, v207, 1.0 op_sel:[0,0,1,1]
	v_cvt_scalef32_pk_fp4_f32 v233, v214, v215, 1.0 op_sel:[0,0,1,1]
	v_cvt_scalef32_pk_fp4_f32 v234, v222, v223, 1.0 op_sel:[0,0,1,1]
	v_cvt_scalef32_pk_fp4_f32 v235, v230, v231, 1.0 op_sel:[0,0,1,1]
	s_nop 0
	global_store_dwordx4 v[240:241], v[232:235], off
	v_lshl_add_u64 v[240:241], v[240:241], 0, v[246:247]
	v_max3_u32 v10, v38, v10, v21
	v_max3_u32 v7, v14, v7, v44
	v_max3_u32 v11, v39, v42, v11
	v_max3_u32 v9, v20, v9, v43
	v_max3_u32 v12, v40, v17, v12
	v_max3_u32 v4, v4, v18, v6
	v_max3_u32 v6, v41, v8, v33
	v_max_u32_e32 v8, v23, v15
	v_min_u32_e32 v14, v23, v15
	v_max_u32_e32 v15, v2, v10
	v_min_u32_e32 v2, v2, v10
	v_max_u32_e32 v10, v3, v7
	v_min_u32_e32 v3, v3, v7
	v_max_u32_e32 v7, v22, v11
	v_max_u32_e32 v17, v24, v9
	v_max_u32_e32 v18, v5, v12
	v_min_u32_e32 v5, v5, v12
	v_max_u32_e32 v12, v13, v4
	v_min_u32_e32 v4, v13, v4
	v_max_u32_e32 v13, v16, v6
	v_min_u32_e32 v11, v22, v11
	v_min_u32_e32 v9, v24, v9
	v_min_u32_e32 v6, v16, v6
	v_max_u32_e32 v16, v8, v17
	v_min_u32_e32 v8, v8, v17
	v_max_u32_e32 v17, v15, v18
	v_min_u32_e32 v15, v15, v18
	v_max_u32_e32 v18, v10, v12
	v_min_u32_e32 v10, v10, v12
	v_max_u32_e32 v12, v7, v13
	v_min_u32_e32 v7, v7, v13
	v_max_u32_e32 v13, v14, v9
	v_min_u32_e32 v9, v14, v9
	v_max_u32_e32 v14, v2, v5
	v_min_u32_e32 v2, v2, v5
	v_max_u32_e32 v5, v3, v4
	v_min_u32_e32 v3, v3, v4
	v_max_u32_e32 v4, v11, v6
	v_min_u32_e32 v6, v11, v6
	v_max_u32_e32 v11, v16, v18
	v_min_u32_e32 v16, v16, v18
	v_max_u32_e32 v18, v17, v12
	v_min_u32_e32 v12, v17, v12
	v_max_u32_e32 v17, v8, v10
	v_min_u32_e32 v8, v8, v10
	v_add_co_u32_e32 v10, vcc, s28, v80
	v_max_u32_e32 v25, v11, v18
	v_min_u32_e32 v18, v11, v18
	v_addc_co_u32_e32 v11, vcc, 0, v81, vcc
	v_max_u32_e32 v19, v15, v7
	v_min_u32_e32 v7, v15, v7
	v_max_u32_e32 v15, v13, v5
	v_min_u32_e32 v13, v13, v5
	v_max_u32_e32 v20, v14, v4
	v_min_u32_e32 v14, v14, v4
	v_max_u32_e32 v21, v9, v3
	v_min_u32_e32 v22, v9, v3
	v_max_u32_e32 v23, v2, v6
	v_min_u32_e32 v24, v2, v6
	global_load_dwordx4 v[2:5], v[10:11], off
	global_load_dwordx4 v[34:37], v[82:83], off offset:256
	global_load_dwordx4 v[38:41], v[82:83], off offset:288
	v_max_u32_e32 v26, v16, v12
	v_min_u32_e32 v12, v16, v12
	v_max_u32_e32 v16, v17, v19
	v_min_u32_e32 v17, v17, v19
	v_max_u32_e32 v19, v8, v7
	v_min_u32_e32 v27, v8, v7
	global_load_dwordx4 v[6:9], v[10:11], off offset:32
	global_load_dwordx4 v[28:31], v[10:11], off offset:64
	global_load_dwordx4 v[148:151], v[10:11], off offset:96
	v_cmp_lt_i32_e32 vcc, v84, v85
	global_load_dwordx4 v[42:45], v[82:83], off offset:320
	v_max_u32_e32 v33, v22, v24
	v_min_u32_e32 v22, v22, v24
	v_cndmask_b32_e32 v24, v77, v84, vcc
	v_max_u32_e32 v32, v15, v20
	v_min_u32_e32 v15, v15, v20
	v_max_u32_e32 v20, v13, v14
	v_min_u32_e32 v13, v13, v14
	v_min_u32_e32 v14, v21, v23
	v_lshlrev_b32_e32 v153, 2, v24
	ds_bpermute_b32 v46, v153, v33
	ds_bpermute_b32 v47, v153, v14
	ds_bpermute_b32 v50, v153, v13
	ds_bpermute_b32 v51, v153, v20
	ds_bpermute_b32 v52, v153, v15
	s_waitcnt lgkmcnt(0)
	v_max_u32_e32 v147, v18, v46
	v_max_u32_e32 v152, v26, v47
	global_load_dwordx4 v[46:49], v[82:83], off offset:352
	ds_bpermute_b32 v53, v153, v32
	global_load_dwordx4 v[154:157], v[10:11], off offset:128
	global_load_dwordx4 v[158:161], v[10:11], off offset:160
	v_max_u32_e32 v170, v16, v50
	v_max_u32_e32 v171, v17, v51
	v_max_u32_e32 v172, v19, v52
	s_waitcnt lgkmcnt(0)
	v_max_u32_e32 v173, v27, v53
	global_load_dwordx4 v[50:53], v[82:83], off offset:384
	global_load_dwordx4 v[54:57], v[82:83], off offset:416
	global_load_dwordx4 v[162:165], v[10:11], off offset:192
	global_load_dwordx4 v[166:169], v[10:11], off offset:224
	global_load_dwordx4 v[58:61], v[82:83], off offset:448
	global_load_dwordx4 v[62:65], v[82:83], off offset:480
	v_max_u32_e32 v21, v21, v23
	ds_bpermute_b32 v23, v153, v21
	ds_bpermute_b32 v16, v153, v16
	ds_bpermute_b32 v19, v153, v19
	ds_bpermute_b32 v24, v153, v22
	ds_bpermute_b32 v27, v153, v27
	s_waitcnt lgkmcnt(4)
	v_max_u32_e32 v23, v12, v23
	ds_bpermute_b32 v17, v153, v17
	s_waitcnt lgkmcnt(4)
	v_max_u32_e32 v13, v13, v16
	ds_bpermute_b32 v12, v153, v12
	ds_bpermute_b32 v16, v153, v26
	ds_bpermute_b32 v18, v153, v18
	s_waitcnt lgkmcnt(6)
	v_max_u32_e32 v15, v15, v19
	ds_bpermute_b32 v19, v153, v25
	s_waitcnt lgkmcnt(6)
	v_max_u32_e32 v24, v25, v24
	s_waitcnt lgkmcnt(5)
	v_max_u32_e32 v27, v32, v27
	s_waitcnt lgkmcnt(4)
	v_max_u32_e32 v17, v20, v17
	s_waitcnt lgkmcnt(3)
	v_max_u32_e32 v12, v21, v12
	s_waitcnt lgkmcnt(2)
	v_max_u32_e32 v14, v14, v16
	s_waitcnt lgkmcnt(1)
	v_max_u32_e32 v16, v33, v18
	s_waitcnt lgkmcnt(0)
	v_max_u32_e32 v10, v22, v19
	v_max_u32_e32 v11, v24, v27
	v_max_u32_e32 v18, v147, v15
	v_min_u32_e32 v33, v147, v15
	v_max_u32_e32 v15, v152, v17
	v_min_u32_e32 v82, v152, v17
	v_max_u32_e32 v83, v23, v13
	v_min_u32_e32 v147, v23, v13
	v_max_u32_e32 v13, v170, v12
	v_min_u32_e32 v152, v170, v12
	v_max_u32_e32 v12, v171, v14
	v_min_u32_e32 v170, v171, v14
	v_max_u32_e32 v14, v172, v16
	v_min_u32_e32 v32, v24, v27
	v_min_u32_e32 v171, v172, v16
	v_max_u32_e32 v172, v173, v10
	v_min_u32_e32 v10, v173, v10
	v_max_u32_e32 v173, v11, v13
	v_min_u32_e32 v11, v11, v13
	v_max_u32_e32 v174, v18, v12
	v_min_u32_e32 v175, v18, v12
	v_max_u32_e32 v176, v15, v14
	v_min_u32_e32 v177, v15, v14
	s_waitcnt vmcnt(14)
	v_mfma_f32_32x32x16_bf16 v[12:27], v[2:5], v[34:37], 0
	v_max_u32_e32 v2, v83, v172
	v_max_u32_e32 v178, v174, v2
	v_min_u32_e32 v174, v174, v2
	v_min_u32_e32 v83, v83, v172
	v_max_u32_e32 v172, v32, v152
	v_min_u32_e32 v32, v32, v152
	s_waitcnt vmcnt(12)
	v_mfma_f32_32x32x16_bf16 v[12:27], v[6:9], v[38:41], v[12:27]
	v_add_co_u32_e32 v6, vcc, s29, v80
	v_max_u32_e32 v152, v33, v170
	s_nop 0
	v_addc_co_u32_e32 v7, vcc, 0, v81, vcc
	global_load_dwordx4 v[2:5], v[6:7], off
	v_min_u32_e32 v33, v33, v170
	s_waitcnt vmcnt(10)
	v_mfma_f32_32x32x16_bf16 v[12:27], v[28:31], v[42:45], v[12:27]
	global_load_dwordx4 v[28:31], v[6:7], off offset:32
	v_max_u32_e32 v170, v82, v171
	v_min_u32_e32 v8, v82, v171
	v_max_u32_e32 v9, v147, v10
	v_min_u32_e32 v10, v147, v10
	v_max_u32_e32 v147, v173, v176
	v_min_u32_e32 v176, v173, v176
	s_waitcnt vmcnt(10)
	v_mfma_f32_32x32x16_bf16 v[12:27], v[148:151], v[46:49], v[12:27]
	v_max_u32_e32 v148, v172, v170
	v_min_u32_e32 v149, v172, v170
	global_load_dwordx4 v[170:173], v[6:7], off offset:64
	v_max_u32_e32 v179, v11, v177
	v_min_u32_e32 v11, v11, v177
	v_max_u32_e32 v177, v175, v83
	v_min_u32_e32 v83, v175, v83
	s_waitcnt vmcnt(8)
	v_mfma_f32_32x32x16_bf16 v[12:27], v[154:157], v[50:53], v[12:27]
	v_max_u32_e32 v156, v176, v174
	v_min_u32_e32 v157, v176, v174
	v_max_u32_e32 v150, v152, v9
	v_min_u32_e32 v9, v152, v9
	v_max_u32_e32 v82, v147, v178
	v_min_u32_e32 v152, v147, v178
	global_load_dwordx4 v[182:185], v[6:7], off offset:224
	s_waitcnt vmcnt(8)
	v_mfma_f32_32x32x16_bf16 v[12:27], v[158:161], v[54:57], v[12:27]
	v_max_u32_e32 v158, v179, v177
	v_min_u32_e32 v159, v179, v177
	global_load_dwordx4 v[174:177], v[6:7], off offset:96
	global_load_dwordx4 v[178:181], v[6:7], off offset:192
	v_max_u32_e32 v151, v32, v8
	v_min_u32_e32 v8, v32, v8
	v_max_u32_e32 v32, v33, v10
	s_waitcnt vmcnt(7)
	v_mfma_f32_32x32x16_bf16 v[12:27], v[162:165], v[58:61], v[12:27]
	global_load_dwordx4 v[162:165], v[6:7], off offset:128
	v_min_u32_e32 v10, v33, v10
	v_max_u32_e32 v160, v11, v83
	v_min_u32_e32 v161, v11, v83
	v_max_u32_e32 v83, v148, v150
	v_min_u32_e32 v147, v148, v150
	v_max_u32_e32 v148, v149, v9
	s_waitcnt vmcnt(7)
	v_mfma_f32_32x32x16_bf16 v[12:27], v[166:169], v[62:65], v[12:27]
	global_load_dwordx4 v[166:169], v[6:7], off offset:160
	v_min_u32_e32 v149, v149, v9
	v_max_u32_e32 v154, v8, v10
	v_min_u32_e32 v155, v8, v10
	v_max_u32_e32 v150, v151, v32
	v_min_u32_e32 v151, v151, v32
	s_nop 5
	v_not_b32_e32 v8, v12
	v_or_b32_e32 v9, 0x80000000, v12
	v_cmp_gt_i32_e32 vcc, 0, v12
	v_not_b32_e32 v6, v15
	v_or_b32_e32 v7, 0x80000000, v15
	v_cndmask_b32_e32 v8, v9, v8, vcc
	v_and_or_b32 v100, v8, s23, v100
	v_not_b32_e32 v8, v13
	v_or_b32_e32 v9, 0x80000000, v13
	v_cmp_gt_i32_e32 vcc, 0, v13
	v_or_b32_e32 v32, 0x80000000, v19
	s_nop 0
	v_cndmask_b32_e32 v8, v9, v8, vcc
	v_and_or_b32 v98, v8, s23, v98
	v_not_b32_e32 v8, v14
	v_or_b32_e32 v9, 0x80000000, v14
	v_cmp_gt_i32_e32 vcc, 0, v14
	s_nop 1
	v_cndmask_b32_e32 v8, v9, v8, vcc
	v_cmp_gt_i32_e32 vcc, 0, v15
	v_and_or_b32 v101, v8, s23, v101
	s_nop 0
	v_cndmask_b32_e32 v6, v7, v6, vcc
	v_and_or_b32 v99, v6, s23, v99
	v_not_b32_e32 v6, v16
	v_or_b32_e32 v7, 0x80000000, v16
	v_cmp_gt_i32_e32 vcc, 0, v16
	s_nop 1
	v_cndmask_b32_e32 v6, v7, v6, vcc
	v_and_or_b32 v97, v6, s23, v97
	v_not_b32_e32 v6, v17
	v_or_b32_e32 v7, 0x80000000, v17
	v_cmp_gt_i32_e32 vcc, 0, v17
	s_nop 1
	v_cndmask_b32_e32 v6, v7, v6, vcc
	v_and_or_b32 v96, v6, s23, v96
	v_not_b32_e32 v6, v18
	v_or_b32_e32 v7, 0x80000000, v18
	v_cmp_gt_i32_e32 vcc, 0, v18
	v_not_b32_e32 v18, v19
	s_nop 0
	v_cndmask_b32_e32 v6, v7, v6, vcc
	v_and_or_b32 v95, v6, s23, v95
	s_waitcnt vmcnt(7)
	v_mfma_f32_32x32x16_bf16 v[2:17], v[2:5], v[34:37], 0
	v_cmp_gt_i32_e32 vcc, 0, v19
	v_or_b32_e32 v19, 0x80000000, v20
	s_nop 0
	v_cndmask_b32_e32 v18, v32, v18, vcc
	v_and_or_b32 v94, v18, s23, v94
	v_not_b32_e32 v18, v20
	v_cmp_gt_i32_e32 vcc, 0, v20
	s_waitcnt vmcnt(6)
	v_mfma_f32_32x32x16_bf16 v[2:17], v[28:31], v[38:41], v[2:17]
	v_not_b32_e32 v30, v22
	v_cndmask_b32_e32 v18, v19, v18, vcc
	v_and_or_b32 v93, v18, s23, v93
	v_not_b32_e32 v18, v21
	v_or_b32_e32 v19, 0x80000000, v21
	v_cmp_gt_i32_e32 vcc, 0, v21
	v_or_b32_e32 v31, 0x80000000, v22
	s_waitcnt vmcnt(5)
	v_mfma_f32_32x32x16_bf16 v[2:17], v[170:173], v[42:45], v[2:17]
	v_cndmask_b32_e32 v18, v19, v18, vcc
	v_add_co_u32_e32 v28, vcc, s30, v80
	v_and_or_b32 v92, v18, s23, v92
	s_nop 0
	v_addc_co_u32_e32 v29, vcc, 0, v81, vcc
	global_load_dwordx4 v[18:21], v[28:29], off
	global_load_dwordx4 v[170:173], v[28:29], off offset:32
	s_waitcnt vmcnt(5)
	v_mfma_f32_32x32x16_bf16 v[2:17], v[174:177], v[46:49], v[2:17]
	global_load_dwordx4 v[174:177], v[28:29], off offset:128
	v_cmp_gt_i32_e32 vcc, 0, v22
	s_nop 1
	v_cndmask_b32_e32 v22, v31, v30, vcc
	v_and_or_b32 v90, v22, s23, v90
	v_not_b32_e32 v22, v23
	s_waitcnt vmcnt(4)
	v_mfma_f32_32x32x16_bf16 v[2:17], v[162:165], v[50:53], v[2:17]
	global_load_dwordx4 v[162:165], v[28:29], off offset:64
	v_or_b32_e32 v30, 0x80000000, v23
	v_cmp_gt_i32_e32 vcc, 0, v23
	v_or_b32_e32 v23, 0x80000000, v24
	s_nop 0
	v_cndmask_b32_e32 v22, v30, v22, vcc
	v_and_or_b32 v186, v22, s23, v89
	s_waitcnt vmcnt(4)
	v_mfma_f32_32x32x16_bf16 v[2:17], v[166:169], v[54:57], v[2:17]
	global_load_dwordx4 v[166:169], v[28:29], off offset:96
	v_not_b32_e32 v22, v24
	v_cmp_gt_i32_e32 vcc, 0, v24
	s_nop 1
	v_cndmask_b32_e32 v22, v23, v22, vcc
	v_and_or_b32 v187, v22, s23, v88
	v_mfma_f32_32x32x16_bf16 v[2:17], v[178:181], v[58:61], v[2:17]
	global_load_dwordx4 v[178:181], v[28:29], off offset:160
	v_not_b32_e32 v22, v25
	v_or_b32_e32 v23, 0x80000000, v25
	v_cmp_gt_i32_e32 vcc, 0, v25
	s_nop 1
	v_cndmask_b32_e32 v22, v23, v22, vcc
	v_mfma_f32_32x32x16_bf16 v[2:17], v[182:185], v[62:65], v[2:17]
	v_and_or_b32 v188, v22, s23, v78
	v_not_b32_e32 v22, v26
	v_or_b32_e32 v23, 0x80000000, v26
	v_cmp_gt_i32_e32 vcc, 0, v26
	global_load_dwordx4 v[182:185], v[28:29], off offset:192
	s_nop 0
	v_cndmask_b32_e32 v22, v23, v22, vcc
	v_and_or_b32 v189, v22, s23, v102
	v_not_b32_e32 v22, v27
	v_or_b32_e32 v23, 0x80000000, v27
	v_cmp_gt_i32_e32 vcc, 0, v27
	s_nop 1
	v_cndmask_b32_e32 v22, v23, v22, vcc
	v_and_or_b32 v190, v22, s23, v103
	v_not_b32_e32 v22, v2
	v_or_b32_e32 v23, 0x80000000, v2
	v_cmp_gt_i32_e32 vcc, 0, v2
	s_nop 1
	v_cndmask_b32_e32 v2, v23, v22, vcc
	v_and_or_b32 v78, v2, s23, v104
	v_not_b32_e32 v2, v3
	v_or_b32_e32 v22, 0x80000000, v3
	v_cmp_gt_i32_e32 vcc, 0, v3
	v_or_b32_e32 v3, 0x80000000, v4
	s_nop 0
	v_cndmask_b32_e32 v2, v22, v2, vcc
	v_and_or_b32 v88, v2, s23, v105
	global_load_dwordx4 v[102:105], v[28:29], off offset:224
	v_not_b32_e32 v2, v4
	v_cmp_gt_i32_e32 vcc, 0, v4
	s_waitcnt vmcnt(7)
	v_mfma_f32_32x32x16_bf16 v[18:33], v[18:21], v[34:37], 0
	v_cndmask_b32_e32 v2, v3, v2, vcc
	v_and_or_b32 v89, v2, s23, v107
	v_not_b32_e32 v2, v5
	v_or_b32_e32 v3, 0x80000000, v5
	v_cmp_gt_i32_e32 vcc, 0, v5
	s_nop 1
	v_cndmask_b32_e32 v2, v3, v2, vcc
	v_and_or_b32 v191, v2, s23, v106
	v_not_b32_e32 v2, v6
	v_or_b32_e32 v3, 0x80000000, v6
	v_cmp_gt_i32_e32 vcc, 0, v6
	s_waitcnt vmcnt(6)
	v_mfma_f32_32x32x16_bf16 v[18:33], v[170:173], v[38:41], v[18:33]
	v_cndmask_b32_e32 v2, v3, v2, vcc
	v_and_or_b32 v192, v2, s23, v108
	v_not_b32_e32 v2, v7
	v_or_b32_e32 v3, 0x80000000, v7
	v_cmp_gt_i32_e32 vcc, 0, v7
	s_waitcnt vmcnt(4)
	v_mfma_f32_32x32x16_bf16 v[18:33], v[162:165], v[42:45], v[18:33]
	v_cndmask_b32_e32 v2, v3, v2, vcc
	v_and_or_b32 v193, v2, s23, v109
	v_not_b32_e32 v2, v8
	v_or_b32_e32 v3, 0x80000000, v8
	v_cmp_gt_i32_e32 vcc, 0, v8
	s_nop 1
	v_cndmask_b32_e32 v2, v3, v2, vcc
	v_and_or_b32 v194, v2, s23, v110
	v_not_b32_e32 v2, v9
	v_or_b32_e32 v3, 0x80000000, v9
	v_cmp_gt_i32_e32 vcc, 0, v9
	v_or_b32_e32 v9, 0x80000000, v11
	s_waitcnt vmcnt(3)
	v_mfma_f32_32x32x16_bf16 v[18:33], v[166:169], v[46:49], v[18:33]
	v_cndmask_b32_e32 v2, v3, v2, vcc
	v_and_or_b32 v195, v2, s23, v111
	v_not_b32_e32 v2, v10
	v_or_b32_e32 v3, 0x80000000, v10
	v_cmp_gt_i32_e32 vcc, 0, v10
	s_nop 1
	v_cndmask_b32_e32 v8, v3, v2, vcc
	v_add_co_u32_e32 v6, vcc, s31, v80
	v_and_or_b32 v80, v8, s23, v68
	s_nop 0
	v_addc_co_u32_e32 v7, vcc, 0, v81, vcc
	global_load_dwordx4 v[2:5], v[6:7], off
	global_load_dwordx4 v[106:109], v[6:7], off offset:32
	global_load_dwordx4 v[162:165], v[6:7], off offset:64
	global_load_dwordx4 v[166:169], v[6:7], off offset:96
	v_not_b32_e32 v8, v11
	v_cmp_gt_i32_e32 vcc, 0, v11
	v_mfma_f32_32x32x16_bf16 v[18:33], v[174:177], v[50:53], v[18:33]
	global_load_dwordx4 v[170:173], v[6:7], off offset:192
	v_cndmask_b32_e32 v8, v9, v8, vcc
	v_and_or_b32 v81, v8, s23, v91
	v_not_b32_e32 v8, v12
	v_or_b32_e32 v9, 0x80000000, v12
	v_cmp_gt_i32_e32 vcc, 0, v12
	s_waitcnt vmcnt(7)
	v_mfma_f32_32x32x16_bf16 v[18:33], v[178:181], v[54:57], v[18:33]
	v_cndmask_b32_e32 v8, v9, v8, vcc
	v_and_or_b32 v91, v8, s23, v69
	v_not_b32_e32 v8, v13
	v_or_b32_e32 v9, 0x80000000, v13
	v_cmp_gt_i32_e32 vcc, 0, v13
	s_nop 1
	v_cndmask_b32_e32 v8, v9, v8, vcc
	v_and_or_b32 v196, v8, s23, v67
	v_not_b32_e32 v8, v14
	v_or_b32_e32 v9, 0x80000000, v14
	v_cmp_gt_i32_e32 vcc, 0, v14
	s_waitcnt vmcnt(6)
	v_mfma_f32_32x32x16_bf16 v[18:33], v[182:185], v[58:61], v[18:33]
	v_cndmask_b32_e32 v8, v9, v8, vcc
	v_and_or_b32 v174, v8, s23, v66
	global_load_dwordx4 v[66:69], v[6:7], off offset:128
	v_not_b32_e32 v8, v15
	v_or_b32_e32 v9, 0x80000000, v15
	v_cmp_gt_i32_e32 vcc, 0, v15
	s_waitcnt vmcnt(6)
	v_mfma_f32_32x32x16_bf16 v[18:33], v[102:105], v[62:65], v[18:33]
	global_load_dwordx4 v[102:105], v[6:7], off offset:224
	v_cndmask_b32_e32 v8, v9, v8, vcc
	v_and_or_b32 v175, v8, s23, v112
	v_not_b32_e32 v8, v16
	v_or_b32_e32 v9, 0x80000000, v16
	v_cmp_gt_i32_e32 vcc, 0, v16
	s_nop 1
	v_cndmask_b32_e32 v8, v9, v8, vcc
	v_and_or_b32 v176, v8, s23, v113
	global_load_dwordx4 v[110:113], v[6:7], off offset:160
	v_not_b32_e32 v8, v17
	v_or_b32_e32 v9, 0x80000000, v17
	v_cmp_gt_i32_e32 vcc, 0, v17
	v_not_b32_e32 v6, v19
	v_or_b32_e32 v7, 0x80000000, v19
	v_cndmask_b32_e32 v8, v9, v8, vcc
	v_and_or_b32 v114, v8, s23, v114
	v_not_b32_e32 v8, v18
	v_or_b32_e32 v9, 0x80000000, v18
	v_cmp_gt_i32_e32 vcc, 0, v18
	s_nop 1
	v_cndmask_b32_e32 v8, v9, v8, vcc
	v_cmp_gt_i32_e32 vcc, 0, v19
	v_and_or_b32 v18, v8, s23, v115
	v_not_b32_e32 v115, v23
	v_cndmask_b32_e32 v6, v7, v6, vcc
	v_and_or_b32 v19, v6, s23, v116
	v_not_b32_e32 v6, v20
	v_or_b32_e32 v7, 0x80000000, v20
	v_cmp_gt_i32_e32 vcc, 0, v20
	v_or_b32_e32 v116, 0x80000000, v23
	s_nop 0
	v_cndmask_b32_e32 v6, v7, v6, vcc
	v_and_or_b32 v20, v6, s23, v117
	v_not_b32_e32 v6, v21
	v_or_b32_e32 v7, 0x80000000, v21
	v_cmp_gt_i32_e32 vcc, 0, v21
	s_nop 1
	v_cndmask_b32_e32 v6, v7, v6, vcc
	v_and_or_b32 v21, v6, s23, v118
	v_not_b32_e32 v6, v22
	v_or_b32_e32 v7, 0x80000000, v22
	v_cmp_gt_i32_e32 vcc, 0, v22
	s_nop 1
	v_cndmask_b32_e32 v6, v7, v6, vcc
	v_and_or_b32 v22, v6, s23, v119
	s_waitcnt vmcnt(7)
	v_mfma_f32_32x32x16_bf16 v[2:17], v[2:5], v[34:37], 0
	v_cmp_gt_i32_e32 vcc, 0, v23
	v_not_b32_e32 v34, v24
	v_or_b32_e32 v35, 0x80000000, v24
	v_cndmask_b32_e32 v23, v116, v115, vcc
	v_cmp_gt_i32_e32 vcc, 0, v24
	v_and_or_b32 v23, v23, s23, v120
	v_max_u32_e32 v36, v101, v99
	s_waitcnt vmcnt(6)
	v_mfma_f32_32x32x16_bf16 v[2:17], v[106:109], v[38:41], v[2:17]
	v_cndmask_b32_e32 v24, v35, v34, vcc
	v_not_b32_e32 v34, v25
	v_or_b32_e32 v35, 0x80000000, v25
	v_cmp_gt_i32_e32 vcc, 0, v25
	v_and_or_b32 v24, v24, s23, v121
	v_min_u32_e32 v37, v101, v99
	v_cndmask_b32_e32 v25, v35, v34, vcc
	s_waitcnt vmcnt(5)
	v_mfma_f32_32x32x16_bf16 v[2:17], v[162:165], v[42:45], v[2:17]
	v_not_b32_e32 v34, v26
	v_or_b32_e32 v35, 0x80000000, v26
	v_cmp_gt_i32_e32 vcc, 0, v26
	v_and_or_b32 v25, v25, s23, v122
	v_max_u32_e32 v38, v97, v96
	v_cndmask_b32_e32 v26, v35, v34, vcc
	v_not_b32_e32 v34, v27
	s_waitcnt vmcnt(4)
	v_mfma_f32_32x32x16_bf16 v[2:17], v[166:169], v[46:49], v[2:17]
	v_or_b32_e32 v35, 0x80000000, v27
	v_cmp_gt_i32_e32 vcc, 0, v27
	v_and_or_b32 v26, v26, s23, v123
	v_min_u32_e32 v39, v97, v96
	v_cndmask_b32_e32 v27, v35, v34, vcc
	v_not_b32_e32 v34, v28
	v_or_b32_e32 v35, 0x80000000, v28
	s_waitcnt vmcnt(2)
	v_mfma_f32_32x32x16_bf16 v[2:17], v[66:69], v[50:53], v[2:17]
	v_cmp_gt_i32_e32 vcc, 0, v28
	v_and_or_b32 v27, v27, s23, v124
	v_max_u32_e32 v40, v95, v94
	v_cndmask_b32_e32 v28, v35, v34, vcc
	v_not_b32_e32 v34, v29
	v_or_b32_e32 v35, 0x80000000, v29
	v_cmp_gt_i32_e32 vcc, 0, v29
	s_waitcnt vmcnt(0)
	v_mfma_f32_32x32x16_bf16 v[2:17], v[110:113], v[54:57], v[2:17]
	v_cndmask_b32_e32 v29, v35, v34, vcc
	v_not_b32_e32 v34, v30
	v_or_b32_e32 v35, 0x80000000, v30
	v_cmp_gt_i32_e32 vcc, 0, v30
	v_and_or_b32 v28, v28, s23, v125
	v_and_or_b32 v29, v29, s23, v126
	v_cndmask_b32_e32 v30, v35, v34, vcc
	v_mfma_f32_32x32x16_bf16 v[2:17], v[170:173], v[58:61], v[2:17]
	v_not_b32_e32 v34, v31
	v_or_b32_e32 v35, 0x80000000, v31
	v_cmp_gt_i32_e32 vcc, 0, v31
	v_and_or_b32 v30, v30, s23, v127
	v_min_u32_e32 v41, v95, v94
	v_cndmask_b32_e32 v31, v35, v34, vcc
	v_not_b32_e32 v34, v32
	v_mfma_f32_32x32x16_bf16 v[2:17], v[102:105], v[62:65], v[2:17]
	v_or_b32_e32 v35, 0x80000000, v32
	v_cmp_gt_i32_e32 vcc, 0, v32
	v_and_or_b32 v31, v31, s23, v128
	v_max_u32_e32 v42, v93, v92
	v_cndmask_b32_e32 v32, v35, v34, vcc
	v_not_b32_e32 v34, v33
	v_or_b32_e32 v35, 0x80000000, v33
	v_cmp_gt_i32_e32 vcc, 0, v33
	v_and_or_b32 v32, v32, s23, v129
	v_min_u32_e32 v43, v93, v92
	v_cndmask_b32_e32 v33, v35, v34, vcc
	s_nop 0
	v_not_b32_e32 v34, v2
	v_or_b32_e32 v35, 0x80000000, v2
	v_cmp_gt_i32_e32 vcc, 0, v2
	global_load_dwordx4 v[200:203], v[236:237], off
	global_load_dwordx4 v[204:207], v[236:237], off offset:16
	global_load_dwordx4 v[208:211], v[236:237], off offset:32
	global_load_dwordx4 v[212:215], v[236:237], off offset:48
	global_load_dwordx4 v[216:219], v[238:239], off
	global_load_dwordx4 v[220:223], v[238:239], off offset:16
	global_load_dwordx4 v[224:227], v[238:239], off offset:32
	global_load_dwordx4 v[228:231], v[238:239], off offset:48
	v_lshl_add_u64 v[236:237], v[236:237], 0, v[244:245]
	v_lshl_add_u64 v[238:239], v[238:239], 0, v[244:245]
	v_and_or_b32 v33, v33, s23, v130
	v_max_u32_e32 v44, v90, v186
	v_cndmask_b32_e32 v2, v35, v34, vcc
	v_not_b32_e32 v34, v3
	v_or_b32_e32 v35, 0x80000000, v3
	v_cmp_gt_i32_e32 vcc, 0, v3
	v_and_or_b32 v2, v2, s23, v131
	v_min_u32_e32 v45, v90, v186
	v_cndmask_b32_e32 v3, v35, v34, vcc
	v_not_b32_e32 v34, v4
	v_or_b32_e32 v35, 0x80000000, v4
	v_cmp_gt_i32_e32 vcc, 0, v4
	v_and_or_b32 v3, v3, s23, v132
	v_max_u32_e32 v46, v187, v188
	v_cndmask_b32_e32 v4, v35, v34, vcc
	v_not_b32_e32 v34, v5
	v_or_b32_e32 v35, 0x80000000, v5
	v_cmp_gt_i32_e32 vcc, 0, v5
	v_and_or_b32 v4, v4, s23, v133
	v_min_u32_e32 v47, v187, v188
	v_cndmask_b32_e32 v5, v35, v34, vcc
	v_not_b32_e32 v34, v6
	v_or_b32_e32 v35, 0x80000000, v6
	v_cmp_gt_i32_e32 vcc, 0, v6
	v_and_or_b32 v5, v5, s23, v134
	v_max_u32_e32 v48, v189, v190
	v_cndmask_b32_e32 v6, v35, v34, vcc
	v_not_b32_e32 v34, v7
	v_or_b32_e32 v35, 0x80000000, v7
	v_cmp_gt_i32_e32 vcc, 0, v7
	v_and_or_b32 v6, v6, s23, v135
	v_min_u32_e32 v49, v189, v190
	v_cndmask_b32_e32 v7, v35, v34, vcc
	v_not_b32_e32 v34, v8
	v_or_b32_e32 v35, 0x80000000, v8
	v_cmp_gt_i32_e32 vcc, 0, v8
	v_and_or_b32 v7, v7, s23, v136
	v_max_u32_e32 v58, v78, v88
	v_cndmask_b32_e32 v8, v35, v34, vcc
	v_not_b32_e32 v34, v9
	v_or_b32_e32 v35, 0x80000000, v9
	v_cmp_gt_i32_e32 vcc, 0, v9
	v_and_or_b32 v8, v8, s23, v137
	v_min_u32_e32 v59, v78, v88
	v_cndmask_b32_e32 v9, v35, v34, vcc
	v_not_b32_e32 v34, v10
	v_or_b32_e32 v35, 0x80000000, v10
	v_cmp_gt_i32_e32 vcc, 0, v10
	v_and_or_b32 v9, v9, s23, v138
	v_max_u32_e32 v60, v89, v191
	v_cndmask_b32_e32 v10, v35, v34, vcc
	v_not_b32_e32 v34, v11
	v_or_b32_e32 v35, 0x80000000, v11
	v_cmp_gt_i32_e32 vcc, 0, v11
	v_and_or_b32 v10, v10, s23, v139
	v_min_u32_e32 v61, v89, v191
	v_cndmask_b32_e32 v11, v35, v34, vcc
	v_not_b32_e32 v34, v12
	v_or_b32_e32 v35, 0x80000000, v12
	v_cmp_gt_i32_e32 vcc, 0, v12
	v_and_or_b32 v11, v11, s23, v140
	v_max_u32_e32 v62, v192, v193
	v_cndmask_b32_e32 v12, v35, v34, vcc
	v_not_b32_e32 v34, v13
	v_or_b32_e32 v35, 0x80000000, v13
	v_cmp_gt_i32_e32 vcc, 0, v13
	v_and_or_b32 v12, v12, s23, v141
	v_min_u32_e32 v63, v192, v193
	v_cndmask_b32_e32 v13, v35, v34, vcc
	v_not_b32_e32 v34, v14
	v_or_b32_e32 v35, 0x80000000, v14
	v_cmp_gt_i32_e32 vcc, 0, v14
	v_and_or_b32 v13, v13, s23, v142
	v_max_u32_e32 v64, v194, v195
	v_cndmask_b32_e32 v14, v35, v34, vcc
	v_not_b32_e32 v34, v15
	v_or_b32_e32 v35, 0x80000000, v15
	v_cmp_gt_i32_e32 vcc, 0, v15
	v_and_or_b32 v14, v14, s23, v143
	v_min_u32_e32 v65, v194, v195
	v_cndmask_b32_e32 v15, v35, v34, vcc
	v_not_b32_e32 v34, v16
	v_or_b32_e32 v35, 0x80000000, v16
	v_cmp_gt_i32_e32 vcc, 0, v16
	v_and_or_b32 v15, v15, s23, v144
	v_max_u32_e32 v66, v80, v81
	v_cndmask_b32_e32 v16, v35, v34, vcc
	v_not_b32_e32 v34, v17
	v_or_b32_e32 v35, 0x80000000, v17
	v_cmp_gt_i32_e32 vcc, 0, v17
	v_and_or_b32 v16, v16, s23, v145
	v_min_u32_e32 v67, v80, v81
	v_cndmask_b32_e32 v17, v35, v34, vcc
	v_and_or_b32 v17, v17, s23, v146
	v_max_u32_e32 v34, v100, v98
	v_min_u32_e32 v35, v100, v98
	v_max_u32_e32 v68, v91, v196
	v_min_u32_e32 v69, v91, v196
	v_max_u32_e32 v78, v174, v175
	v_min_u32_e32 v80, v174, v175
	v_max_u32_e32 v81, v176, v114
	v_min_u32_e32 v88, v176, v114
	v_max_u32_e32 v97, v18, v19
	v_min_u32_e32 v18, v18, v19
	v_max_u32_e32 v19, v20, v21
	v_min_u32_e32 v20, v20, v21
	v_max_u32_e32 v21, v22, v23
	v_min_u32_e32 v22, v22, v23
	v_max_u32_e32 v23, v24, v25
	v_min_u32_e32 v24, v24, v25
	v_max_u32_e32 v25, v26, v27
	v_min_u32_e32 v26, v26, v27
	v_max_u32_e32 v27, v28, v29
	v_min_u32_e32 v28, v28, v29
	v_max_u32_e32 v29, v30, v31
	v_min_u32_e32 v30, v30, v31
	v_max_u32_e32 v31, v32, v33
	v_min_u32_e32 v32, v32, v33
	v_max_u32_e32 v105, v2, v3
	v_min_u32_e32 v2, v2, v3
	v_max_u32_e32 v3, v4, v5
	v_min_u32_e32 v4, v4, v5
	v_max_u32_e32 v5, v6, v7
	v_min_u32_e32 v6, v6, v7
	v_max_u32_e32 v7, v8, v9
	v_min_u32_e32 v8, v8, v9
	v_max_u32_e32 v9, v10, v11
	v_min_u32_e32 v10, v10, v11
	v_max_u32_e32 v11, v12, v13
	v_min_u32_e32 v12, v12, v13
	v_max_u32_e32 v13, v14, v15
	v_min_u32_e32 v14, v14, v15
	v_max_u32_e32 v15, v16, v17
	v_min_u32_e32 v16, v16, v17
	v_max_u32_e32 v50, v34, v37
	v_min_u32_e32 v34, v34, v37
	v_max_u32_e32 v37, v35, v36
	v_min_u32_e32 v35, v35, v36
	v_max_u32_e32 v36, v38, v41
	v_min_u32_e32 v38, v38, v41
	v_max_u32_e32 v41, v39, v40
	v_min_u32_e32 v39, v39, v40
	v_max_u32_e32 v40, v42, v45
	v_min_u32_e32 v42, v42, v45
	v_max_u32_e32 v45, v43, v44
	v_min_u32_e32 v43, v43, v44
	v_max_u32_e32 v44, v46, v49
	v_min_u32_e32 v46, v46, v49
	v_max_u32_e32 v49, v47, v48
	v_min_u32_e32 v47, v47, v48
	v_max_u32_e32 v89, v58, v61
	v_min_u32_e32 v58, v58, v61
	v_max_u32_e32 v61, v59, v60
	v_min_u32_e32 v59, v59, v60
	v_max_u32_e32 v60, v62, v65
	v_min_u32_e32 v62, v62, v65
	v_max_u32_e32 v65, v63, v64
	v_min_u32_e32 v63, v63, v64
	v_max_u32_e32 v64, v66, v69
	v_min_u32_e32 v66, v66, v69
	v_max_u32_e32 v69, v67, v68
	v_min_u32_e32 v67, v67, v68
	v_max_u32_e32 v68, v78, v88
	v_min_u32_e32 v78, v78, v88
	v_max_u32_e32 v88, v80, v81
	v_min_u32_e32 v80, v80, v81
	v_max_u32_e32 v33, v97, v20
	v_min_u32_e32 v20, v97, v20
	v_max_u32_e32 v97, v18, v19
	v_min_u32_e32 v18, v18, v19
	v_max_u32_e32 v19, v21, v24
	v_min_u32_e32 v21, v21, v24
	v_max_u32_e32 v24, v22, v23
	v_min_u32_e32 v22, v22, v23
	v_max_u32_e32 v23, v25, v28
	v_min_u32_e32 v25, v25, v28
	v_max_u32_e32 v28, v26, v27
	v_min_u32_e32 v26, v26, v27
	v_max_u32_e32 v27, v29, v32
	v_min_u32_e32 v29, v29, v32
	v_max_u32_e32 v32, v30, v31
	v_min_u32_e32 v30, v30, v31
	v_max_u32_e32 v17, v105, v4
	v_min_u32_e32 v4, v105, v4
	v_max_u32_e32 v105, v2, v3
	v_min_u32_e32 v2, v2, v3
	v_max_u32_e32 v3, v5, v8
	v_min_u32_e32 v5, v5, v8
	v_max_u32_e32 v8, v6, v7
	v_min_u32_e32 v6, v6, v7
	v_max_u32_e32 v7, v9, v12
	v_min_u32_e32 v9, v9, v12
	v_max_u32_e32 v12, v10, v11
	v_min_u32_e32 v10, v10, v11
	v_max_u32_e32 v11, v13, v16
	v_min_u32_e32 v13, v13, v16
	v_max_u32_e32 v16, v14, v15
	v_min_u32_e32 v14, v14, v15
	v_max_u32_e32 v48, v50, v37
	v_min_u32_e32 v37, v50, v37
	v_max_u32_e32 v50, v34, v35
	v_min_u32_e32 v34, v34, v35
	v_max_u32_e32 v35, v38, v39
	v_min_u32_e32 v38, v38, v39
	v_max_u32_e32 v39, v36, v41
	v_min_u32_e32 v36, v36, v41
	v_max_u32_e32 v41, v40, v45
	v_min_u32_e32 v40, v40, v45
	v_max_u32_e32 v45, v42, v43
	v_min_u32_e32 v42, v42, v43
	v_max_u32_e32 v43, v46, v47
	v_min_u32_e32 v46, v46, v47
	v_max_u32_e32 v47, v44, v49
	v_min_u32_e32 v44, v44, v49
	v_max_u32_e32 v81, v89, v61
	v_min_u32_e32 v61, v89, v61
	v_max_u32_e32 v89, v58, v59
	v_min_u32_e32 v58, v58, v59
	v_max_u32_e32 v59, v62, v63
	v_min_u32_e32 v62, v62, v63
	v_max_u32_e32 v63, v60, v65
	v_min_u32_e32 v60, v60, v65
	v_max_u32_e32 v65, v64, v69
	v_min_u32_e32 v64, v64, v69
	v_max_u32_e32 v69, v66, v67
	v_min_u32_e32 v66, v66, v67
	v_max_u32_e32 v67, v78, v80
	v_min_u32_e32 v78, v78, v80
	v_max_u32_e32 v80, v68, v88
	v_min_u32_e32 v68, v68, v88
	v_max_u32_e32 v31, v33, v97
	v_min_u32_e32 v33, v33, v97
	v_max_u32_e32 v97, v20, v18
	v_min_u32_e32 v18, v20, v18
	v_max_u32_e32 v20, v21, v22
	v_min_u32_e32 v21, v21, v22
	v_max_u32_e32 v22, v19, v24
	v_min_u32_e32 v19, v19, v24
	v_max_u32_e32 v24, v23, v28
	v_min_u32_e32 v23, v23, v28
	v_max_u32_e32 v28, v25, v26
	v_min_u32_e32 v25, v25, v26
	v_max_u32_e32 v26, v29, v30
	v_min_u32_e32 v29, v29, v30
	v_max_u32_e32 v30, v27, v32
	v_min_u32_e32 v27, v27, v32
	v_max_u32_e32 v15, v17, v105
	v_min_u32_e32 v17, v17, v105
	v_max_u32_e32 v105, v4, v2
	v_min_u32_e32 v2, v4, v2
	v_max_u32_e32 v4, v5, v6
	v_min_u32_e32 v5, v5, v6
	v_max_u32_e32 v6, v3, v8
	v_min_u32_e32 v3, v3, v8
	v_max_u32_e32 v8, v7, v12
	v_min_u32_e32 v7, v7, v12
	v_max_u32_e32 v12, v9, v10
	v_min_u32_e32 v9, v9, v10
	v_max_u32_e32 v10, v13, v14
	v_min_u32_e32 v13, v13, v14
	v_max_u32_e32 v14, v11, v16
	v_min_u32_e32 v11, v11, v16
	v_max_u32_e32 v49, v48, v38
	v_min_u32_e32 v38, v48, v38
	v_max_u32_e32 v48, v37, v35
	v_min_u32_e32 v35, v37, v35
	v_max_u32_e32 v37, v50, v36
	v_min_u32_e32 v36, v50, v36
	v_max_u32_e32 v50, v34, v39
	v_min_u32_e32 v34, v34, v39
	v_max_u32_e32 v39, v41, v46
	v_min_u32_e32 v41, v41, v46
	v_max_u32_e32 v46, v40, v43
	v_min_u32_e32 v40, v40, v43
	v_max_u32_e32 v43, v45, v44
	v_min_u32_e32 v44, v45, v44
	v_max_u32_e32 v45, v42, v47
	v_min_u32_e32 v42, v42, v47
	v_max_u32_e32 v88, v81, v62
	v_min_u32_e32 v62, v81, v62
	v_max_u32_e32 v81, v61, v59
	v_min_u32_e32 v59, v61, v59
	v_max_u32_e32 v61, v89, v60
	v_min_u32_e32 v60, v89, v60
	v_max_u32_e32 v89, v58, v63
	v_min_u32_e32 v58, v58, v63
	v_max_u32_e32 v63, v65, v78
	v_min_u32_e32 v65, v65, v78
	v_max_u32_e32 v78, v64, v67
	v_min_u32_e32 v64, v64, v67
	v_max_u32_e32 v67, v69, v68
	v_min_u32_e32 v68, v69, v68
	v_max_u32_e32 v69, v66, v80
	v_min_u32_e32 v66, v66, v80
	v_max_u32_e32 v32, v31, v21
	v_min_u32_e32 v21, v31, v21
	v_max_u32_e32 v31, v33, v20
	v_min_u32_e32 v20, v33, v20
	v_max_u32_e32 v33, v97, v19
	v_min_u32_e32 v19, v97, v19
	v_max_u32_e32 v97, v18, v22
	v_min_u32_e32 v18, v18, v22
	v_max_u32_e32 v22, v24, v29
	v_min_u32_e32 v24, v24, v29
	v_max_u32_e32 v29, v23, v26
	v_min_u32_e32 v23, v23, v26
	v_max_u32_e32 v26, v28, v27
	v_min_u32_e32 v27, v28, v27
	v_max_u32_e32 v28, v25, v30
	v_min_u32_e32 v25, v25, v30
	v_max_u32_e32 v16, v15, v5
	v_min_u32_e32 v5, v15, v5
	v_max_u32_e32 v15, v17, v4
	v_min_u32_e32 v4, v17, v4
	v_max_u32_e32 v17, v105, v3
	v_min_u32_e32 v3, v105, v3
	v_max_u32_e32 v105, v2, v6
	v_min_u32_e32 v2, v2, v6
	v_max_u32_e32 v6, v8, v13
	v_min_u32_e32 v8, v8, v13
	v_max_u32_e32 v13, v7, v10
	v_min_u32_e32 v7, v7, v10
	v_max_u32_e32 v10, v12, v11
	v_min_u32_e32 v11, v12, v11
	v_max_u32_e32 v12, v9, v14
	v_min_u32_e32 v9, v9, v14
	v_max_u32_e32 v47, v49, v37
	v_min_u32_e32 v37, v49, v37
	v_max_u32_e32 v49, v48, v50
	v_min_u32_e32 v48, v48, v50
	v_max_u32_e32 v50, v38, v36
	v_min_u32_e32 v36, v38, v36
	v_max_u32_e32 v38, v35, v34
	v_min_u32_e32 v34, v35, v34
	v_max_u32_e32 v35, v41, v44
	v_min_u32_e32 v41, v41, v44
	v_max_u32_e32 v44, v40, v42
	v_min_u32_e32 v40, v40, v42
	v_max_u32_e32 v42, v39, v43
	v_min_u32_e32 v39, v39, v43
	v_max_u32_e32 v43, v46, v45
	v_min_u32_e32 v45, v46, v45
	v_max_u32_e32 v80, v88, v61
	v_min_u32_e32 v61, v88, v61
	v_max_u32_e32 v88, v81, v89
	s_waitcnt vmcnt(0)
	v_pk_mul_f32 v[200:201], v[200:201], s[96:97] op_sel_hi:[1,0]
	v_pk_mul_f32 v[202:203], v[202:203], s[96:97] op_sel_hi:[1,0]
	v_pk_mul_f32 v[204:205], v[204:205], s[96:97] op_sel_hi:[1,0]
	v_pk_mul_f32 v[206:207], v[206:207], s[96:97] op_sel_hi:[1,0]
	v_pk_mul_f32 v[208:209], v[208:209], s[96:97] op_sel_hi:[1,0]
	v_pk_mul_f32 v[210:211], v[210:211], s[96:97] op_sel_hi:[1,0]
	v_pk_mul_f32 v[212:213], v[212:213], s[96:97] op_sel_hi:[1,0]
	v_pk_mul_f32 v[214:215], v[214:215], s[96:97] op_sel_hi:[1,0]
	v_pk_mul_f32 v[216:217], v[216:217], s[96:97] op_sel_hi:[1,0]
	v_pk_mul_f32 v[218:219], v[218:219], s[96:97] op_sel_hi:[1,0]
	v_pk_mul_f32 v[220:221], v[220:221], s[96:97] op_sel_hi:[1,0]
	v_pk_mul_f32 v[222:223], v[222:223], s[96:97] op_sel_hi:[1,0]
	v_pk_mul_f32 v[224:225], v[224:225], s[96:97] op_sel_hi:[1,0]
	v_pk_mul_f32 v[226:227], v[226:227], s[96:97] op_sel_hi:[1,0]
	v_pk_mul_f32 v[228:229], v[228:229], s[96:97] op_sel_hi:[1,0]
	v_pk_mul_f32 v[230:231], v[230:231], s[96:97] op_sel_hi:[1,0]
	v_cvt_scalef32_pk_fp4_f32 v232, v200, v201, 1.0
	v_cvt_scalef32_pk_fp4_f32 v233, v208, v209, 1.0
	v_cvt_scalef32_pk_fp4_f32 v234, v216, v217, 1.0
	v_cvt_scalef32_pk_fp4_f32 v235, v224, v225, 1.0
	v_cvt_scalef32_pk_fp4_f32 v232, v202, v203, 1.0 op_sel:[0,0,1,0]
	v_cvt_scalef32_pk_fp4_f32 v233, v210, v211, 1.0 op_sel:[0,0,1,0]
	v_cvt_scalef32_pk_fp4_f32 v234, v218, v219, 1.0 op_sel:[0,0,1,0]
	v_cvt_scalef32_pk_fp4_f32 v235, v226, v227, 1.0 op_sel:[0,0,1,0]
	v_cvt_scalef32_pk_fp4_f32 v232, v204, v205, 1.0 op_sel:[0,0,0,1]
	v_cvt_scalef32_pk_fp4_f32 v233, v212, v213, 1.0 op_sel:[0,0,0,1]
	v_cvt_scalef32_pk_fp4_f32 v234, v220, v221, 1.0 op_sel:[0,0,0,1]
	v_cvt_scalef32_pk_fp4_f32 v235, v228, v229, 1.0 op_sel:[0,0,0,1]
	v_cvt_scalef32_pk_fp4_f32 v232, v206, v207, 1.0 op_sel:[0,0,1,1]
	v_cvt_scalef32_pk_fp4_f32 v233, v214, v215, 1.0 op_sel:[0,0,1,1]
	v_cvt_scalef32_pk_fp4_f32 v234, v222, v223, 1.0 op_sel:[0,0,1,1]
	v_cvt_scalef32_pk_fp4_f32 v235, v230, v231, 1.0 op_sel:[0,0,1,1]
	s_nop 0
	global_store_dwordx4 v[240:241], v[232:235], off
	v_lshl_add_u64 v[240:241], v[240:241], 0, v[246:247]
	global_load_dwordx4 v[200:203], v[236:237], off
	global_load_dwordx4 v[204:207], v[236:237], off offset:16
	global_load_dwordx4 v[208:211], v[236:237], off offset:32
	global_load_dwordx4 v[212:215], v[236:237], off offset:48
	global_load_dwordx4 v[216:219], v[238:239], off
	global_load_dwordx4 v[220:223], v[238:239], off offset:16
	global_load_dwordx4 v[224:227], v[238:239], off offset:32
	global_load_dwordx4 v[228:231], v[238:239], off offset:48
	v_lshl_add_u64 v[236:237], v[236:237], 0, v[244:245]
	v_lshl_add_u64 v[238:239], v[238:239], 0, v[244:245]
	v_min_u32_e32 v81, v81, v89
	v_max_u32_e32 v89, v62, v60
	v_min_u32_e32 v60, v62, v60
	v_max_u32_e32 v62, v59, v58
	v_min_u32_e32 v58, v59, v58
	v_max_u32_e32 v59, v65, v68
	v_min_u32_e32 v65, v65, v68
	v_max_u32_e32 v68, v64, v66
	v_min_u32_e32 v64, v64, v66
	v_max_u32_e32 v66, v63, v67
	v_min_u32_e32 v63, v63, v67
	v_max_u32_e32 v67, v78, v69
	v_min_u32_e32 v69, v78, v69
	v_max_u32_e32 v30, v32, v33
	v_min_u32_e32 v32, v32, v33
	v_max_u32_e32 v33, v31, v97
	v_min_u32_e32 v31, v31, v97
	v_max_u32_e32 v97, v21, v19
	v_min_u32_e32 v19, v21, v19
	v_max_u32_e32 v21, v20, v18
	v_min_u32_e32 v18, v20, v18
	v_max_u32_e32 v20, v24, v27
	v_min_u32_e32 v24, v24, v27
	v_max_u32_e32 v27, v23, v25
	v_min_u32_e32 v23, v23, v25
	v_max_u32_e32 v25, v22, v26
	v_min_u32_e32 v22, v22, v26
	v_max_u32_e32 v26, v29, v28
	v_min_u32_e32 v28, v29, v28
	v_max_u32_e32 v14, v16, v17
	v_min_u32_e32 v16, v16, v17
	v_max_u32_e32 v17, v15, v105
	v_min_u32_e32 v15, v15, v105
	v_max_u32_e32 v105, v5, v3
	v_min_u32_e32 v3, v5, v3
	v_max_u32_e32 v5, v4, v2
	v_min_u32_e32 v2, v4, v2
	v_max_u32_e32 v4, v8, v11
	v_min_u32_e32 v8, v8, v11
	v_max_u32_e32 v11, v7, v9
	v_min_u32_e32 v7, v7, v9
	v_max_u32_e32 v9, v6, v10
	v_min_u32_e32 v6, v6, v10
	v_max_u32_e32 v10, v13, v12
	v_min_u32_e32 v12, v13, v12
	v_max_u32_e32 v46, v47, v49
	v_min_u32_e32 v47, v47, v49
	v_max_u32_e32 v49, v37, v48
	v_min_u32_e32 v37, v37, v48
	v_max_u32_e32 v48, v50, v38
	v_min_u32_e32 v38, v50, v38
	v_max_u32_e32 v50, v36, v34
	v_min_u32_e32 v34, v36, v34
	v_max_u32_e32 v36, v41, v40
	v_min_u32_e32 v40, v41, v40
	v_max_u32_e32 v41, v35, v44
	v_min_u32_e32 v35, v35, v44
	v_max_u32_e32 v44, v39, v45
	v_min_u32_e32 v39, v39, v45
	v_max_u32_e32 v45, v42, v43
	v_min_u32_e32 v42, v42, v43
	v_max_u32_e32 v78, v80, v88
	v_min_u32_e32 v80, v80, v88
	v_max_u32_e32 v88, v61, v81
	v_min_u32_e32 v61, v61, v81
	v_max_u32_e32 v81, v89, v62
	v_min_u32_e32 v62, v89, v62
	v_max_u32_e32 v89, v60, v58
	v_min_u32_e32 v58, v60, v58
	v_max_u32_e32 v60, v65, v64
	v_min_u32_e32 v64, v65, v64
	v_max_u32_e32 v65, v59, v68
	v_min_u32_e32 v59, v59, v68
	v_max_u32_e32 v68, v63, v69
	v_min_u32_e32 v63, v63, v69
	v_max_u32_e32 v69, v66, v67
	v_min_u32_e32 v66, v66, v67
	v_max_u32_e32 v29, v30, v33
	v_min_u32_e32 v30, v30, v33
	v_max_u32_e32 v33, v32, v31
	v_min_u32_e32 v31, v32, v31
	v_max_u32_e32 v32, v97, v21
	v_min_u32_e32 v21, v97, v21
	v_max_u32_e32 v97, v19, v18
	v_min_u32_e32 v18, v19, v18
	v_max_u32_e32 v19, v24, v23
	v_min_u32_e32 v23, v24, v23
	v_max_u32_e32 v24, v20, v27
	v_min_u32_e32 v20, v20, v27
	v_max_u32_e32 v27, v22, v28
	v_min_u32_e32 v22, v22, v28
	v_max_u32_e32 v28, v25, v26
	v_min_u32_e32 v25, v25, v26
	v_max_u32_e32 v13, v14, v17
	v_min_u32_e32 v14, v14, v17
	v_max_u32_e32 v17, v16, v15
	v_min_u32_e32 v15, v16, v15
	v_max_u32_e32 v16, v105, v5
	v_min_u32_e32 v5, v105, v5
	v_max_u32_e32 v105, v3, v2
	v_min_u32_e32 v2, v3, v2
	v_max_u32_e32 v3, v8, v7
	v_min_u32_e32 v7, v8, v7
	v_max_u32_e32 v8, v4, v11
	v_min_u32_e32 v4, v4, v11
	v_max_u32_e32 v11, v6, v12
	v_min_u32_e32 v6, v6, v12
	v_max_u32_e32 v12, v9, v10
	v_min_u32_e32 v9, v9, v10
	v_max_u32_e32 v43, v46, v40
	v_min_u32_e32 v40, v46, v40
	v_max_u32_e32 v46, v47, v36
	v_min_u32_e32 v36, v47, v36
	v_max_u32_e32 v47, v49, v35
	v_min_u32_e32 v35, v49, v35
	v_max_u32_e32 v49, v37, v41
	v_min_u32_e32 v37, v37, v41
	v_max_u32_e32 v41, v48, v39
	v_min_u32_e32 v39, v48, v39
	v_max_u32_e32 v48, v38, v44
	v_min_u32_e32 v38, v38, v44
	v_max_u32_e32 v44, v50, v42
	v_min_u32_e32 v42, v50, v42
	v_max_u32_e32 v50, v34, v45
	v_min_u32_e32 v34, v34, v45
	v_max_u32_e32 v67, v78, v64
	v_min_u32_e32 v64, v78, v64
	v_max_u32_e32 v78, v80, v60
	v_min_u32_e32 v60, v80, v60
	v_max_u32_e32 v80, v88, v59
	v_min_u32_e32 v59, v88, v59
	v_max_u32_e32 v88, v61, v65
	v_min_u32_e32 v61, v61, v65
	v_max_u32_e32 v65, v81, v63
	v_min_u32_e32 v63, v81, v63
	v_max_u32_e32 v81, v62, v68
	v_min_u32_e32 v62, v62, v68
	v_max_u32_e32 v68, v89, v66
	v_min_u32_e32 v66, v89, v66
	v_max_u32_e32 v89, v58, v69
	v_min_u32_e32 v58, v58, v69
	v_max_u32_e32 v26, v29, v23
	v_min_u32_e32 v23, v29, v23
	v_max_u32_e32 v29, v30, v19
	v_min_u32_e32 v19, v30, v19
	v_max_u32_e32 v30, v33, v20
	v_min_u32_e32 v20, v33, v20
	v_max_u32_e32 v33, v31, v24
	v_min_u32_e32 v24, v31, v24
	v_max_u32_e32 v31, v32, v22
	v_min_u32_e32 v22, v32, v22
	v_max_u32_e32 v32, v21, v27
	v_min_u32_e32 v21, v21, v27
	v_max_u32_e32 v27, v97, v25
	v_min_u32_e32 v25, v97, v25
	v_max_u32_e32 v97, v18, v28
	v_min_u32_e32 v18, v18, v28
	v_max_u32_e32 v10, v13, v7
	v_min_u32_e32 v7, v13, v7
	v_max_u32_e32 v13, v14, v3
	v_min_u32_e32 v3, v14, v3
	v_max_u32_e32 v14, v17, v4
	v_min_u32_e32 v4, v17, v4
	v_max_u32_e32 v17, v15, v8
	v_min_u32_e32 v8, v15, v8
	v_max_u32_e32 v15, v16, v6
	v_min_u32_e32 v6, v16, v6
	v_max_u32_e32 v16, v5, v11
	v_min_u32_e32 v5, v5, v11
	v_max_u32_e32 v11, v105, v9
	v_min_u32_e32 v9, v105, v9
	v_max_u32_e32 v105, v2, v12
	v_min_u32_e32 v2, v2, v12
	v_max_u32_e32 v45, v43, v41
	v_min_u32_e32 v41, v43, v41
	v_max_u32_e32 v43, v46, v48
	v_min_u32_e32 v46, v46, v48
	v_max_u32_e32 v48, v47, v44
	v_min_u32_e32 v44, v47, v44
	v_max_u32_e32 v47, v49, v50
	v_min_u32_e32 v49, v49, v50
	v_max_u32_e32 v50, v40, v39
	v_min_u32_e32 v39, v40, v39
	v_max_u32_e32 v40, v36, v38
	v_min_u32_e32 v36, v36, v38
	v_max_u32_e32 v38, v35, v42
	v_min_u32_e32 v35, v35, v42
	v_max_u32_e32 v42, v37, v34
	v_min_u32_e32 v34, v37, v34
	v_max_u32_e32 v69, v67, v65
	v_min_u32_e32 v65, v67, v65
	v_max_u32_e32 v67, v78, v81
	v_min_u32_e32 v78, v78, v81
	v_max_u32_e32 v81, v80, v68
	v_min_u32_e32 v68, v80, v68
	v_max_u32_e32 v80, v88, v89
	v_min_u32_e32 v88, v88, v89
	v_max_u32_e32 v89, v64, v63
	v_min_u32_e32 v63, v64, v63
	v_max_u32_e32 v64, v60, v62
	v_min_u32_e32 v60, v60, v62
	v_max_u32_e32 v62, v59, v66
	v_min_u32_e32 v59, v59, v66
	v_max_u32_e32 v66, v61, v58
	v_min_u32_e32 v58, v61, v58
	v_max_u32_e32 v28, v26, v31
	v_min_u32_e32 v26, v26, v31
	v_max_u32_e32 v31, v29, v32
	v_min_u32_e32 v29, v29, v32
	v_max_u32_e32 v32, v30, v27
	v_min_u32_e32 v27, v30, v27
	v_max_u32_e32 v30, v33, v97
	v_min_u32_e32 v33, v33, v97
	v_max_u32_e32 v97, v23, v22
	v_min_u32_e32 v22, v23, v22
	v_max_u32_e32 v23, v19, v21
	v_min_u32_e32 v19, v19, v21
	v_max_u32_e32 v21, v20, v25
	v_min_u32_e32 v20, v20, v25
	v_max_u32_e32 v25, v24, v18
	v_min_u32_e32 v18, v24, v18
	v_max_u32_e32 v12, v10, v15
	v_min_u32_e32 v10, v10, v15
	v_max_u32_e32 v15, v13, v16
	v_min_u32_e32 v13, v13, v16
	v_max_u32_e32 v16, v14, v11
	v_min_u32_e32 v11, v14, v11
	v_max_u32_e32 v14, v17, v105
	v_min_u32_e32 v17, v17, v105
	v_max_u32_e32 v105, v7, v6
	v_min_u32_e32 v6, v7, v6
	v_max_u32_e32 v7, v3, v5
	v_min_u32_e32 v3, v3, v5
	v_max_u32_e32 v5, v4, v9
	v_min_u32_e32 v4, v4, v9
	v_max_u32_e32 v9, v8, v2
	v_min_u32_e32 v2, v8, v2
	v_max_u32_e32 v37, v45, v48
	v_min_u32_e32 v45, v45, v48
	v_max_u32_e32 v48, v43, v47
	v_min_u32_e32 v43, v43, v47
	v_max_u32_e32 v47, v41, v44
	v_min_u32_e32 v41, v41, v44
	v_max_u32_e32 v44, v46, v49
	v_min_u32_e32 v46, v46, v49
	v_max_u32_e32 v49, v50, v38
	v_min_u32_e32 v38, v50, v38
	v_max_u32_e32 v50, v40, v42
	v_min_u32_e32 v40, v40, v42
	v_max_u32_e32 v42, v39, v35
	v_min_u32_e32 v35, v39, v35
	v_max_u32_e32 v39, v36, v34
	v_min_u32_e32 v34, v36, v34
	v_max_u32_e32 v61, v69, v81
	v_min_u32_e32 v69, v69, v81
	v_max_u32_e32 v81, v67, v80
	v_min_u32_e32 v67, v67, v80
	v_max_u32_e32 v80, v65, v68
	v_min_u32_e32 v65, v65, v68
	v_max_u32_e32 v68, v78, v88
	v_min_u32_e32 v78, v78, v88
	v_max_u32_e32 v88, v89, v62
	v_min_u32_e32 v62, v89, v62
	v_max_u32_e32 v89, v64, v66
	v_min_u32_e32 v64, v64, v66
	v_max_u32_e32 v66, v63, v59
	v_min_u32_e32 v59, v63, v59
	v_max_u32_e32 v63, v60, v58
	v_min_u32_e32 v58, v60, v58
	v_max_u32_e32 v24, v28, v32
	v_min_u32_e32 v28, v28, v32
	v_max_u32_e32 v32, v31, v30
	v_min_u32_e32 v30, v31, v30
	v_max_u32_e32 v31, v26, v27
	v_min_u32_e32 v26, v26, v27
	v_max_u32_e32 v27, v29, v33
	v_min_u32_e32 v29, v29, v33
	v_max_u32_e32 v33, v97, v21
	v_min_u32_e32 v21, v97, v21
	v_max_u32_e32 v97, v23, v25
	v_min_u32_e32 v23, v23, v25
	v_max_u32_e32 v25, v22, v20
	v_min_u32_e32 v20, v22, v20
	v_max_u32_e32 v22, v19, v18
	v_min_u32_e32 v18, v19, v18
	v_max_u32_e32 v8, v12, v16
	v_min_u32_e32 v12, v12, v16
	v_max_u32_e32 v16, v15, v14
	v_min_u32_e32 v14, v15, v14
	v_max_u32_e32 v15, v10, v11
	v_min_u32_e32 v10, v10, v11
	v_max_u32_e32 v11, v13, v17
	v_min_u32_e32 v13, v13, v17
	v_max_u32_e32 v17, v105, v5
	v_min_u32_e32 v5, v105, v5
	v_max_u32_e32 v105, v7, v9
	v_min_u32_e32 v7, v7, v9
	v_max_u32_e32 v9, v6, v4
	v_min_u32_e32 v4, v6, v4
	v_max_u32_e32 v6, v3, v2
	v_min_u32_e32 v2, v3, v2
	v_min_u32_e32 v36, v37, v48
	v_min_u32_e32 v51, v45, v43
	v_min_u32_e32 v52, v47, v44
	v_min_u32_e32 v53, v41, v46
	v_min_u32_e32 v54, v49, v50
	v_min_u32_e32 v55, v38, v40
	v_min_u32_e32 v56, v42, v39
	v_min_u32_e32 v57, v35, v34
	v_min_u32_e32 v60, v61, v81
	v_min_u32_e32 v90, v69, v67
	v_min_u32_e32 v91, v80, v68
	v_min_u32_e32 v92, v65, v78
	v_min_u32_e32 v93, v88, v89
	v_min_u32_e32 v94, v62, v64
	v_min_u32_e32 v95, v66, v63
	v_min_u32_e32 v96, v59, v58
	v_min_u32_e32 v19, v24, v32
	v_min_u32_e32 v98, v28, v30
	v_min_u32_e32 v99, v31, v27
	v_min_u32_e32 v100, v26, v29
	v_min_u32_e32 v101, v33, v97
	v_min_u32_e32 v102, v21, v23
	v_min_u32_e32 v103, v25, v22
	v_min_u32_e32 v104, v20, v18
	v_min_u32_e32 v3, v8, v16
	v_min_u32_e32 v106, v12, v14
	v_min_u32_e32 v107, v15, v11
	v_min_u32_e32 v108, v10, v13
	v_min_u32_e32 v109, v17, v105
	v_min_u32_e32 v110, v5, v7
	v_min_u32_e32 v111, v9, v6
	v_min_u32_e32 v112, v4, v2
	v_max3_u32 v37, v37, v48, v96
	v_max3_u32 v24, v24, v32, v112
	v_max3_u32 v32, v36, v59, v58
	v_max3_u32 v2, v19, v4, v2
	v_max3_u32 v4, v45, v43, v95
	v_max3_u32 v19, v28, v30, v111
	v_max3_u32 v28, v51, v66, v63
	v_max3_u32 v6, v98, v9, v6
	v_max3_u32 v9, v47, v44, v94
	v_max3_u32 v27, v31, v27, v110
	v_max3_u32 v30, v52, v62, v64
	v_max3_u32 v5, v99, v5, v7
	v_max3_u32 v7, v41, v46, v93
	v_max3_u32 v26, v26, v29, v109
	v_max3_u32 v29, v53, v88, v89
	v_max3_u32 v17, v100, v17, v105
	v_max3_u32 v31, v49, v50, v92
	v_max3_u32 v33, v33, v97, v108
	v_max3_u32 v36, v54, v65, v78
	v_max3_u32 v10, v101, v10, v13
	v_max3_u32 v13, v38, v40, v91
	v_max3_u32 v21, v21, v23, v107
	v_max3_u32 v23, v55, v80, v68
	v_max3_u32 v11, v102, v15, v11
	v_max3_u32 v15, v42, v39, v90
	v_max3_u32 v22, v25, v22, v106
	v_max3_u32 v25, v56, v69, v67
	s_waitcnt vmcnt(0)
	v_pk_mul_f32 v[200:201], v[200:201], s[96:97] op_sel_hi:[1,0]
	v_pk_mul_f32 v[202:203], v[202:203], s[96:97] op_sel_hi:[1,0]
	v_pk_mul_f32 v[204:205], v[204:205], s[96:97] op_sel_hi:[1,0]
	v_pk_mul_f32 v[206:207], v[206:207], s[96:97] op_sel_hi:[1,0]
	v_pk_mul_f32 v[208:209], v[208:209], s[96:97] op_sel_hi:[1,0]
	v_pk_mul_f32 v[210:211], v[210:211], s[96:97] op_sel_hi:[1,0]
	v_pk_mul_f32 v[212:213], v[212:213], s[96:97] op_sel_hi:[1,0]
	v_pk_mul_f32 v[214:215], v[214:215], s[96:97] op_sel_hi:[1,0]
	v_pk_mul_f32 v[216:217], v[216:217], s[96:97] op_sel_hi:[1,0]
	v_pk_mul_f32 v[218:219], v[218:219], s[96:97] op_sel_hi:[1,0]
	v_pk_mul_f32 v[220:221], v[220:221], s[96:97] op_sel_hi:[1,0]
	v_pk_mul_f32 v[222:223], v[222:223], s[96:97] op_sel_hi:[1,0]
	v_pk_mul_f32 v[224:225], v[224:225], s[96:97] op_sel_hi:[1,0]
	v_pk_mul_f32 v[226:227], v[226:227], s[96:97] op_sel_hi:[1,0]
	v_pk_mul_f32 v[228:229], v[228:229], s[96:97] op_sel_hi:[1,0]
	v_pk_mul_f32 v[230:231], v[230:231], s[96:97] op_sel_hi:[1,0]
	v_cvt_scalef32_pk_fp4_f32 v232, v200, v201, 1.0
	v_cvt_scalef32_pk_fp4_f32 v233, v208, v209, 1.0
	v_cvt_scalef32_pk_fp4_f32 v234, v216, v217, 1.0
	v_cvt_scalef32_pk_fp4_f32 v235, v224, v225, 1.0
	v_cvt_scalef32_pk_fp4_f32 v232, v202, v203, 1.0 op_sel:[0,0,1,0]
	v_cvt_scalef32_pk_fp4_f32 v233, v210, v211, 1.0 op_sel:[0,0,1,0]
	v_cvt_scalef32_pk_fp4_f32 v234, v218, v219, 1.0 op_sel:[0,0,1,0]
	v_cvt_scalef32_pk_fp4_f32 v235, v226, v227, 1.0 op_sel:[0,0,1,0]
	v_cvt_scalef32_pk_fp4_f32 v232, v204, v205, 1.0 op_sel:[0,0,0,1]
	v_cvt_scalef32_pk_fp4_f32 v233, v212, v213, 1.0 op_sel:[0,0,0,1]
	v_cvt_scalef32_pk_fp4_f32 v234, v220, v221, 1.0 op_sel:[0,0,0,1]
	v_cvt_scalef32_pk_fp4_f32 v235, v228, v229, 1.0 op_sel:[0,0,0,1]
	v_cvt_scalef32_pk_fp4_f32 v232, v206, v207, 1.0 op_sel:[0,0,1,1]
	v_cvt_scalef32_pk_fp4_f32 v233, v214, v215, 1.0 op_sel:[0,0,1,1]
	v_cvt_scalef32_pk_fp4_f32 v234, v222, v223, 1.0 op_sel:[0,0,1,1]
	v_cvt_scalef32_pk_fp4_f32 v235, v230, v231, 1.0 op_sel:[0,0,1,1]
	s_nop 0
	global_store_dwordx4 v[240:241], v[232:235], off
	v_lshl_add_u64 v[240:241], v[240:241], 0, v[246:247]
	global_load_dwordx4 v[200:203], v[236:237], off
	global_load_dwordx4 v[204:207], v[236:237], off offset:16
	global_load_dwordx4 v[208:211], v[236:237], off offset:32
	global_load_dwordx4 v[212:215], v[236:237], off offset:48
	global_load_dwordx4 v[216:219], v[238:239], off
	global_load_dwordx4 v[220:223], v[238:239], off offset:16
	global_load_dwordx4 v[224:227], v[238:239], off offset:32
	global_load_dwordx4 v[228:231], v[238:239], off offset:48
	v_lshl_add_u64 v[236:237], v[236:237], 0, v[244:245]
	v_lshl_add_u64 v[238:239], v[238:239], 0, v[244:245]
	v_max3_u32 v12, v103, v12, v14
	v_max3_u32 v14, v35, v34, v60
	v_max3_u32 v3, v20, v18, v3
	v_max3_u32 v18, v57, v61, v81
	v_max3_u32 v8, v104, v8, v16
	v_max_u32_e32 v16, v37, v31
	v_min_u32_e32 v20, v37, v31
	v_max_u32_e32 v31, v32, v36
	v_min_u32_e32 v32, v32, v36
	v_max_u32_e32 v34, v4, v13
	v_min_u32_e32 v4, v4, v13
	v_max_u32_e32 v13, v28, v23
	v_min_u32_e32 v23, v28, v23
	v_max_u32_e32 v28, v9, v15
	v_min_u32_e32 v9, v9, v15
	v_max_u32_e32 v15, v30, v25
	v_min_u32_e32 v25, v30, v25
	v_max_u32_e32 v30, v7, v14
	v_min_u32_e32 v7, v7, v14
	v_max_u32_e32 v14, v29, v18
	v_min_u32_e32 v18, v29, v18
	v_max_u32_e32 v42, v24, v33
	v_min_u32_e32 v24, v24, v33
	v_max_u32_e32 v33, v2, v10
	v_min_u32_e32 v2, v2, v10
	v_max_u32_e32 v10, v19, v21
	v_min_u32_e32 v19, v19, v21
	v_max_u32_e32 v21, v6, v11
	v_min_u32_e32 v6, v6, v11
	v_max_u32_e32 v11, v27, v22
	v_min_u32_e32 v22, v27, v22
	v_max_u32_e32 v27, v5, v12
	v_min_u32_e32 v5, v5, v12
	v_max_u32_e32 v12, v26, v3
	v_min_u32_e32 v3, v26, v3
	v_max_u32_e32 v26, v17, v8
	v_min_u32_e32 v8, v17, v8
	v_max_u32_e32 v29, v16, v28
	v_min_u32_e32 v16, v16, v28
	v_max_u32_e32 v28, v31, v15
	v_min_u32_e32 v15, v31, v15
	v_max_u32_e32 v31, v34, v30
	v_min_u32_e32 v30, v34, v30
	v_max_u32_e32 v34, v13, v14
	v_min_u32_e32 v13, v13, v14
	v_max_u32_e32 v14, v20, v9
	v_min_u32_e32 v9, v20, v9
	v_max_u32_e32 v20, v32, v25
	v_min_u32_e32 v25, v32, v25
	v_max_u32_e32 v32, v4, v7
	v_min_u32_e32 v4, v4, v7
	v_max_u32_e32 v7, v23, v18
	v_min_u32_e32 v18, v23, v18
	v_max_u32_e32 v17, v42, v11
	v_min_u32_e32 v11, v42, v11
	v_max_u32_e32 v42, v33, v27
	v_min_u32_e32 v27, v33, v27
	v_max_u32_e32 v33, v10, v12
	v_min_u32_e32 v10, v10, v12
	v_max_u32_e32 v12, v21, v26
	v_min_u32_e32 v21, v21, v26
	v_max_u32_e32 v26, v24, v22
	v_min_u32_e32 v22, v24, v22
	v_max_u32_e32 v24, v2, v5
	v_min_u32_e32 v2, v2, v5
	v_max_u32_e32 v5, v19, v3
	v_min_u32_e32 v3, v19, v3
	v_max_u32_e32 v19, v6, v8
	v_min_u32_e32 v6, v6, v8
	v_max_u32_e32 v23, v29, v31
	v_min_u32_e32 v29, v29, v31
	v_max_u32_e32 v31, v28, v34
	v_min_u32_e32 v28, v28, v34
	v_max_u32_e32 v34, v16, v30
	v_min_u32_e32 v16, v16, v30
	v_max_u32_e32 v30, v15, v13
	v_min_u32_e32 v13, v15, v13
	v_max_u32_e32 v15, v14, v32
	v_min_u32_e32 v14, v14, v32
	v_max_u32_e32 v32, v20, v7
	v_min_u32_e32 v7, v20, v7
	v_max_u32_e32 v20, v9, v4
	v_min_u32_e32 v4, v9, v4
	v_max_u32_e32 v9, v25, v18
	v_min_u32_e32 v18, v25, v18
	v_max_u32_e32 v8, v17, v33
	v_min_u32_e32 v17, v17, v33
	v_max_u32_e32 v33, v42, v12
	v_min_u32_e32 v12, v42, v12
	v_max_u32_e32 v42, v11, v10
	v_min_u32_e32 v10, v11, v10
	v_max_u32_e32 v11, v27, v21
	v_min_u32_e32 v21, v27, v21
	v_max_u32_e32 v27, v26, v5
	v_min_u32_e32 v5, v26, v5
	v_max_u32_e32 v26, v24, v19
	v_min_u32_e32 v19, v24, v19
	v_max_u32_e32 v24, v22, v3
	v_min_u32_e32 v3, v22, v3
	v_max_u32_e32 v22, v2, v6
	v_min_u32_e32 v2, v2, v6
	v_min_u32_e32 v25, v23, v31
	v_min_u32_e32 v35, v29, v28
	v_min_u32_e32 v36, v34, v30
	v_min_u32_e32 v37, v16, v13
	v_min_u32_e32 v38, v15, v32
	v_min_u32_e32 v39, v14, v7
	v_min_u32_e32 v40, v20, v9
	v_min_u32_e32 v41, v4, v18
	v_min_u32_e32 v6, v8, v33
	v_min_u32_e32 v43, v17, v12
	v_min_u32_e32 v44, v42, v11
	v_min_u32_e32 v45, v10, v21
	v_min_u32_e32 v46, v27, v26
	v_min_u32_e32 v47, v5, v19
	v_min_u32_e32 v48, v24, v22
	v_min_u32_e32 v49, v3, v2
	v_max3_u32 v23, v23, v31, v49
	v_max3_u32 v2, v25, v3, v2
	v_max3_u32 v3, v29, v28, v48
	v_max3_u32 v22, v35, v24, v22
	v_max3_u32 v24, v34, v30, v47
	v_max3_u32 v5, v36, v5, v19
	v_max3_u32 v13, v16, v13, v46
	v_max3_u32 v16, v37, v27, v26
	v_max3_u32 v15, v15, v32, v45
	v_max3_u32 v10, v38, v10, v21
	v_max3_u32 v7, v14, v7, v44
	v_max3_u32 v11, v39, v42, v11
	v_max3_u32 v9, v20, v9, v43
	v_max3_u32 v12, v40, v17, v12
	v_max3_u32 v4, v4, v18, v6
	v_max3_u32 v6, v41, v8, v33
	v_max_u32_e32 v8, v23, v15
	v_min_u32_e32 v14, v23, v15
	v_max_u32_e32 v15, v2, v10
	v_min_u32_e32 v2, v2, v10
	v_max_u32_e32 v10, v3, v7
	v_min_u32_e32 v3, v3, v7
	v_max_u32_e32 v7, v22, v11
	v_min_u32_e32 v11, v22, v11
	v_max_u32_e32 v17, v24, v9
	v_min_u32_e32 v9, v24, v9
	v_max_u32_e32 v18, v5, v12
	v_min_u32_e32 v5, v5, v12
	v_max_u32_e32 v12, v13, v4
	v_min_u32_e32 v4, v13, v4
	v_max_u32_e32 v13, v16, v6
	v_min_u32_e32 v6, v16, v6
	v_max_u32_e32 v16, v8, v17
	v_min_u32_e32 v8, v8, v17
	v_max_u32_e32 v17, v15, v18
	v_min_u32_e32 v15, v15, v18
	v_max_u32_e32 v18, v10, v12
	v_min_u32_e32 v10, v10, v12
	v_max_u32_e32 v12, v7, v13
	v_min_u32_e32 v7, v7, v13
	v_max_u32_e32 v13, v14, v9
	v_min_u32_e32 v9, v14, v9
	v_max_u32_e32 v14, v2, v5
	v_min_u32_e32 v2, v2, v5
	v_max_u32_e32 v5, v3, v4
	v_min_u32_e32 v3, v3, v4
	v_max_u32_e32 v4, v11, v6
	v_min_u32_e32 v6, v11, v6
	v_max_u32_e32 v11, v16, v18
	v_min_u32_e32 v16, v16, v18
	v_max_u32_e32 v18, v17, v12
	v_min_u32_e32 v12, v17, v12
	v_max_u32_e32 v17, v8, v10
	v_min_u32_e32 v8, v8, v10
	v_max_u32_e32 v10, v15, v7
	v_min_u32_e32 v7, v15, v7
	v_max_u32_e32 v15, v13, v5
	v_min_u32_e32 v5, v13, v5
	v_max_u32_e32 v13, v14, v4
	v_min_u32_e32 v4, v14, v4
	v_max_u32_e32 v14, v9, v3
	v_min_u32_e32 v3, v9, v3
	v_max_u32_e32 v9, v2, v6
	v_min_u32_e32 v2, v2, v6
	v_max_u32_e32 v6, v11, v18
	v_min_u32_e32 v11, v11, v18
	v_max_u32_e32 v18, v16, v12
	v_min_u32_e32 v12, v16, v12
	v_max_u32_e32 v16, v17, v10
	v_min_u32_e32 v10, v17, v10
	v_max_u32_e32 v17, v8, v7
	v_min_u32_e32 v7, v8, v7
	v_max_u32_e32 v8, v15, v13
	v_min_u32_e32 v13, v15, v13
	v_max_u32_e32 v15, v5, v4
	ds_bpermute_b32 v23, v153, v15
	v_min_u32_e32 v19, v3, v2
	v_min_u32_e32 v4, v5, v4
	v_max_u32_e32 v5, v14, v9
	v_max_u32_e32 v2, v3, v2
	ds_bpermute_b32 v20, v153, v19
	v_min_u32_e32 v9, v14, v9
	ds_bpermute_b32 v14, v153, v2
	ds_bpermute_b32 v21, v153, v5
	ds_bpermute_b32 v22, v153, v4
	s_waitcnt lgkmcnt(4)
	v_max_u32_e32 v23, v10, v23
	ds_bpermute_b32 v10, v153, v10
	s_waitcnt lgkmcnt(4)
	v_max_u32_e32 v3, v6, v20
	ds_bpermute_b32 v20, v153, v9
	s_waitcnt lgkmcnt(4)
	v_max_u32_e32 v14, v11, v14
	s_waitcnt lgkmcnt(3)
	v_max_u32_e32 v21, v12, v21
	s_waitcnt lgkmcnt(2)
	v_max_u32_e32 v22, v16, v22
	ds_bpermute_b32 v24, v153, v13
	ds_bpermute_b32 v25, v153, v8
	ds_bpermute_b32 v26, v153, v7
	ds_bpermute_b32 v27, v153, v17
	s_waitcnt lgkmcnt(5)
	v_max_u32_e32 v10, v15, v10
	ds_bpermute_b32 v15, v153, v16
	ds_bpermute_b32 v12, v153, v12
	ds_bpermute_b32 v16, v153, v18
	ds_bpermute_b32 v11, v153, v11
	ds_bpermute_b32 v6, v153, v6
	s_waitcnt lgkmcnt(9)
	v_max_u32_e32 v20, v18, v20
	s_waitcnt lgkmcnt(8)
	v_max_u32_e32 v17, v17, v24
	s_waitcnt lgkmcnt(7)
	v_max_u32_e32 v7, v7, v25
	s_waitcnt lgkmcnt(6)
	v_max_u32_e32 v8, v8, v26
	s_waitcnt lgkmcnt(5)
	v_max_u32_e32 v13, v13, v27
	s_waitcnt lgkmcnt(4)
	v_max_u32_e32 v4, v4, v15
	s_waitcnt lgkmcnt(3)
	v_max_u32_e32 v5, v5, v12
	s_waitcnt lgkmcnt(2)
	v_max_u32_e32 v9, v9, v16
	s_waitcnt lgkmcnt(1)
	v_max_u32_e32 v2, v2, v11
	s_waitcnt lgkmcnt(0)
	v_max_u32_e32 v6, v19, v6
	v_max_u32_e32 v11, v3, v8
	v_min_u32_e32 v3, v3, v8
	v_max_u32_e32 v8, v14, v13
	v_min_u32_e32 v12, v14, v13
	v_max_u32_e32 v13, v20, v10
	v_min_u32_e32 v10, v20, v10
	v_max_u32_e32 v14, v21, v4
	v_min_u32_e32 v4, v21, v4
	v_max_u32_e32 v15, v22, v5
	v_min_u32_e32 v5, v22, v5
	v_max_u32_e32 v16, v23, v9
	v_min_u32_e32 v9, v23, v9
	v_max_u32_e32 v18, v17, v2
	v_min_u32_e32 v2, v17, v2
	v_max_u32_e32 v17, v7, v6
	v_min_u32_e32 v6, v7, v6
	v_max_u32_e32 v7, v11, v15
	v_min_u32_e32 v11, v11, v15
	v_max_u32_e32 v15, v8, v16
	v_min_u32_e32 v8, v8, v16
	v_max_u32_e32 v16, v13, v18
	v_min_u32_e32 v13, v13, v18
	v_max_u32_e32 v18, v14, v17
	v_min_u32_e32 v14, v14, v17
	v_max_u32_e32 v17, v3, v5
	v_min_u32_e32 v3, v3, v5
	v_max_u32_e32 v5, v12, v9
	v_min_u32_e32 v9, v12, v9
	v_max_u32_e32 v12, v10, v2
	v_min_u32_e32 v2, v10, v2
	v_max_u32_e32 v10, v4, v6
	v_min_u32_e32 v4, v4, v6
	v_max_u32_e32 v6, v7, v16
	v_min_u32_e32 v7, v7, v16
	v_max_u32_e32 v16, v15, v18
	s_waitcnt vmcnt(0)
	v_pk_mul_f32 v[200:201], v[200:201], s[96:97] op_sel_hi:[1,0]
	v_pk_mul_f32 v[202:203], v[202:203], s[96:97] op_sel_hi:[1,0]
	v_pk_mul_f32 v[204:205], v[204:205], s[96:97] op_sel_hi:[1,0]
	v_pk_mul_f32 v[206:207], v[206:207], s[96:97] op_sel_hi:[1,0]
	v_pk_mul_f32 v[208:209], v[208:209], s[96:97] op_sel_hi:[1,0]
	v_pk_mul_f32 v[210:211], v[210:211], s[96:97] op_sel_hi:[1,0]
	v_pk_mul_f32 v[212:213], v[212:213], s[96:97] op_sel_hi:[1,0]
	v_pk_mul_f32 v[214:215], v[214:215], s[96:97] op_sel_hi:[1,0]
	v_pk_mul_f32 v[216:217], v[216:217], s[96:97] op_sel_hi:[1,0]
	v_pk_mul_f32 v[218:219], v[218:219], s[96:97] op_sel_hi:[1,0]
	v_pk_mul_f32 v[220:221], v[220:221], s[96:97] op_sel_hi:[1,0]
	v_pk_mul_f32 v[222:223], v[222:223], s[96:97] op_sel_hi:[1,0]
	v_pk_mul_f32 v[224:225], v[224:225], s[96:97] op_sel_hi:[1,0]
	v_pk_mul_f32 v[226:227], v[226:227], s[96:97] op_sel_hi:[1,0]
	v_pk_mul_f32 v[228:229], v[228:229], s[96:97] op_sel_hi:[1,0]
	v_pk_mul_f32 v[230:231], v[230:231], s[96:97] op_sel_hi:[1,0]
	v_cvt_scalef32_pk_fp4_f32 v232, v200, v201, 1.0
	v_cvt_scalef32_pk_fp4_f32 v233, v208, v209, 1.0
	v_cvt_scalef32_pk_fp4_f32 v234, v216, v217, 1.0
	v_cvt_scalef32_pk_fp4_f32 v235, v224, v225, 1.0
	v_cvt_scalef32_pk_fp4_f32 v232, v202, v203, 1.0 op_sel:[0,0,1,0]
	v_cvt_scalef32_pk_fp4_f32 v233, v210, v211, 1.0 op_sel:[0,0,1,0]
	v_cvt_scalef32_pk_fp4_f32 v234, v218, v219, 1.0 op_sel:[0,0,1,0]
	v_cvt_scalef32_pk_fp4_f32 v235, v226, v227, 1.0 op_sel:[0,0,1,0]
	v_cvt_scalef32_pk_fp4_f32 v232, v204, v205, 1.0 op_sel:[0,0,0,1]
	v_cvt_scalef32_pk_fp4_f32 v233, v212, v213, 1.0 op_sel:[0,0,0,1]
	v_cvt_scalef32_pk_fp4_f32 v234, v220, v221, 1.0 op_sel:[0,0,0,1]
	v_cvt_scalef32_pk_fp4_f32 v235, v228, v229, 1.0 op_sel:[0,0,0,1]
	v_cvt_scalef32_pk_fp4_f32 v232, v206, v207, 1.0 op_sel:[0,0,1,1]
	v_cvt_scalef32_pk_fp4_f32 v233, v214, v215, 1.0 op_sel:[0,0,1,1]
	v_cvt_scalef32_pk_fp4_f32 v234, v222, v223, 1.0 op_sel:[0,0,1,1]
	v_cvt_scalef32_pk_fp4_f32 v235, v230, v231, 1.0 op_sel:[0,0,1,1]
	s_nop 0
	global_store_dwordx4 v[240:241], v[232:235], off
	v_lshl_add_u64 v[240:241], v[240:241], 0, v[246:247]
	global_load_dwordx4 v[200:203], v[236:237], off
	global_load_dwordx4 v[204:207], v[236:237], off offset:16
	global_load_dwordx4 v[208:211], v[236:237], off offset:32
	global_load_dwordx4 v[212:215], v[236:237], off offset:48
	global_load_dwordx4 v[216:219], v[238:239], off
	global_load_dwordx4 v[220:223], v[238:239], off offset:16
	global_load_dwordx4 v[224:227], v[238:239], off offset:32
	global_load_dwordx4 v[228:231], v[238:239], off offset:48
	v_lshl_add_u64 v[236:237], v[236:237], 0, v[244:245]
	v_lshl_add_u64 v[238:239], v[238:239], 0, v[244:245]
	v_max_u32_e32 v19, v17, v12
	v_min_u32_e32 v12, v17, v12
	v_max_u32_e32 v17, v5, v10
	v_min_u32_e32 v21, v3, v2
	v_max_u32_e32 v22, v9, v4
	v_min_u32_e32 v4, v9, v4
	v_min_u32_e32 v15, v15, v18
	v_max_u32_e32 v18, v11, v13
	v_min_u32_e32 v11, v11, v13
	v_max_u32_e32 v13, v8, v14
	v_min_u32_e32 v14, v8, v14
	v_min_u32_e32 v5, v5, v10
	v_max_u32_e32 v8, v6, v16
	v_min_u32_e32 v10, v6, v16
	v_max_u32_e32 v39, v19, v17
	v_min_u32_e32 v40, v19, v17
	v_max_u32_e32 v45, v21, v4
	v_min_u32_e32 v46, v21, v4
	v_bitop3_b32 v4, v82, s22, v82 bitop3:0xc
	v_lshl_add_u32 v19, v87, 2, s26
	v_bitop3_b32 v6, v152, s22, v152 bitop3:0xc
	v_max_u32_e32 v41, v12, v5
	v_min_u32_e32 v42, v12, v5
	v_bitop3_b32 v5, v8, s22, v8 bitop3:0xc
	ds_write2st64_b32 v19, v4, v6 offset1:1
	v_bitop3_b32 v4, v10, s22, v10 bitop3:0xc
	v_max_u32_e32 v20, v3, v2
	v_max_u32_e32 v3, v7, v15
	v_min_u32_e32 v2, v7, v15
	ds_write2st64_b32 v19, v5, v4 offset0:16 offset1:17
	v_bitop3_b32 v4, v156, s22, v156 bitop3:0xc
	v_bitop3_b32 v6, v157, s22, v157 bitop3:0xc
	v_bitop3_b32 v5, v3, s22, v3 bitop3:0xc
	ds_write2st64_b32 v19, v4, v6 offset0:2 offset1:3
	v_bitop3_b32 v4, v2, s22, v2 bitop3:0xc
	v_max_u32_e32 v35, v18, v13
	v_min_u32_e32 v36, v18, v13
	ds_write2st64_b32 v19, v5, v4 offset0:18 offset1:19
	v_bitop3_b32 v4, v158, s22, v158 bitop3:0xc
	v_bitop3_b32 v6, v159, s22, v159 bitop3:0xc
	v_bitop3_b32 v5, v35, s22, v35 bitop3:0xc
	ds_write2st64_b32 v19, v4, v6 offset0:4 offset1:5
	v_bitop3_b32 v4, v36, s22, v36 bitop3:0xc
	v_max_u32_e32 v37, v11, v14
	v_min_u32_e32 v38, v11, v14
	ds_write2st64_b32 v19, v5, v4 offset0:20 offset1:21
	v_bitop3_b32 v4, v160, s22, v160 bitop3:0xc
	v_bitop3_b32 v6, v161, s22, v161 bitop3:0xc
	v_bitop3_b32 v5, v37, s22, v37 bitop3:0xc
	ds_write2st64_b32 v19, v4, v6 offset0:6 offset1:7
	v_bitop3_b32 v4, v38, s22, v38 bitop3:0xc
	ds_write2st64_b32 v19, v5, v4 offset0:22 offset1:23
	v_bitop3_b32 v4, v83, s22, v83 bitop3:0xc
	v_bitop3_b32 v6, v147, s22, v147 bitop3:0xc
	v_bitop3_b32 v5, v39, s22, v39 bitop3:0xc
	ds_write2st64_b32 v19, v4, v6 offset0:8 offset1:9
	v_bitop3_b32 v4, v40, s22, v40 bitop3:0xc
	ds_write2st64_b32 v19, v5, v4 offset0:24 offset1:25
	v_bitop3_b32 v4, v148, s22, v148 bitop3:0xc
	v_bitop3_b32 v6, v149, s22, v149 bitop3:0xc
	v_bitop3_b32 v5, v41, s22, v41 bitop3:0xc
	ds_write2st64_b32 v19, v4, v6 offset0:10 offset1:11
	v_bitop3_b32 v4, v42, s22, v42 bitop3:0xc
	v_max_u32_e32 v43, v20, v22
	v_min_u32_e32 v44, v20, v22
	ds_write2st64_b32 v19, v5, v4 offset0:26 offset1:27
	v_bitop3_b32 v4, v150, s22, v150 bitop3:0xc
	v_bitop3_b32 v6, v151, s22, v151 bitop3:0xc
	v_bitop3_b32 v5, v43, s22, v43 bitop3:0xc
	ds_write2st64_b32 v19, v4, v6 offset0:12 offset1:13
	v_bitop3_b32 v4, v44, s22, v44 bitop3:0xc
	ds_write2st64_b32 v19, v5, v4 offset0:28 offset1:29
	v_bitop3_b32 v4, v154, s22, v154 bitop3:0xc
	v_bitop3_b32 v6, v155, s22, v155 bitop3:0xc
	v_bitop3_b32 v5, v45, s22, v45 bitop3:0xc
	ds_write2st64_b32 v19, v4, v6 offset0:14 offset1:15
	v_bitop3_b32 v4, v46, s22, v46 bitop3:0xc
	v_cmp_gt_u32_e32 vcc, 32, v87
	ds_write2st64_b32 v19, v5, v4 offset0:30 offset1:31
	s_and_saveexec_b64 s[16:17], vcc
	s_cbranch_execz .LBB0_795
	v_cmp_lt_i32_e32 vcc, -1, v161
	v_and_b32_e32 v6, 0xffffff80, v157
	v_and_b32_e32 v9, 0xffffff80, v8
	v_cndmask_b32_e64 v4, v86, -1, vcc
	v_cmp_lt_i32_e32 vcc, -1, v160
	v_bitop3_b32 v26, v4, v161, s23 bitop3:0x78
	v_and_b32_e32 v15, 0xffffff80, v152
	v_cndmask_b32_e64 v4, v86, -1, vcc
	v_cmp_lt_i32_e32 vcc, -1, v159
	v_bitop3_b32 v28, v4, v160, s23 bitop3:0x78
	v_and_b32_e32 v11, 0xffffff80, v155
	v_cndmask_b32_e64 v4, v86, -1, vcc
	v_cmp_lt_i32_e32 vcc, -1, v158
	v_bitop3_b32 v30, v4, v159, s23 bitop3:0x78
	v_and_b32_e32 v14, 0xffffff80, v154
	v_cndmask_b32_e64 v4, v86, -1, vcc
	v_cmp_lt_i32_e32 vcc, -1, v3
	v_bitop3_b32 v49, v4, v158, s23 bitop3:0x78
	v_and_b32_e32 v4, 0xffffff80, v3
	v_cndmask_b32_e64 v3, v86, -1, vcc
	v_cmp_lt_i32_e32 vcc, -1, v157
	v_xor_b32_e32 v5, v3, v4
	v_and_b32_e32 v3, 0xffffff80, v2
	v_cndmask_b32_e64 v7, v86, -1, vcc
	v_cmp_lt_i32_e32 vcc, -1, v2
	v_xor_b32_e32 v4, v7, v6
	v_and_b32_e32 v6, 0xffffff80, v156
	v_cndmask_b32_e64 v2, v86, -1, vcc
	v_cmp_lt_i32_e32 vcc, -1, v156
	v_xor_b32_e32 v7, v2, v3
	v_mov_b32_e32 v2, v5
	v_cndmask_b32_e64 v12, v86, -1, vcc
	v_xor_b32_e32 v6, v12, v6
	v_mov_b32_e32 v3, v7
	v_pk_add_f32 v[12:13], v[6:7], v[2:3] op_sel_hi:[0,1]
	v_not_b32_e32 v23, v13
	v_or_b32_e32 v24, 0x80000000, v13
	v_cmp_gt_i32_e32 vcc, 0, v13
	v_and_b32_e32 v16, 0xffffff80, v151
	v_and_b32_e32 v17, 0xffffff80, v150
	v_cndmask_b32_e32 v13, v24, v23, vcc
	v_and_b32_e32 v13, 0xffffff00, v13
	v_or_b32_e32 v31, 0xdc, v13
	v_not_b32_e32 v13, v12
	v_or_b32_e32 v23, 0x80000000, v12
	v_cmp_gt_i32_e32 vcc, 0, v12
	v_and_b32_e32 v18, 0xffffff80, v149
	v_and_b32_e32 v20, 0xffffff80, v148
	v_cndmask_b32_e32 v12, v23, v13, vcc
	v_cmp_lt_i32_e32 vcc, -1, v8
	v_and_b32_e32 v12, 0xffffff00, v12
	v_or_b32_e32 v32, 0xdd, v12
	v_cndmask_b32_e64 v8, v86, -1, vcc
	v_cmp_lt_i32_e32 vcc, -1, v152
	v_xor_b32_e32 v9, v8, v9
	v_and_b32_e32 v21, 0xffffff80, v147
	v_cndmask_b32_e64 v12, v86, -1, vcc
	v_cmp_lt_i32_e32 vcc, -1, v155
	v_xor_b32_e32 v8, v12, v15
	v_and_b32_e32 v22, 0xffffff80, v83
	v_cndmask_b32_e64 v12, v86, -1, vcc
	v_cmp_lt_i32_e32 vcc, -1, v154
	v_xor_b32_e32 v13, v12, v11
	v_mov_b32_e32 v48, v4
	v_cndmask_b32_e64 v15, v86, -1, vcc
	v_xor_b32_e32 v12, v15, v14
	v_pk_add_f32 v[12:13], v[8:9], v[12:13] op_sel:[1,0]
	v_and_b32_e32 v25, 0xffffff80, v10
	v_not_b32_e32 v11, v13
	v_or_b32_e32 v14, 0x80000000, v13
	v_cmp_gt_i32_e32 vcc, 0, v13
	v_or_b32_e32 v13, 0x80000000, v12
	v_and_b32_e32 v27, 0xffffff80, v82
	v_cndmask_b32_e32 v11, v14, v11, vcc
	v_and_or_b32 v14, v11, s33, 15
	v_not_b32_e32 v11, v12
	v_cmp_gt_i32_e32 vcc, 0, v12
	v_mov_b32_e32 v34, v49
	v_and_b32_e32 v54, 0xffffff80, v38
	v_cndmask_b32_e32 v11, v13, v11, vcc
	v_cmp_lt_i32_e32 vcc, -1, v151
	v_and_or_b32 v15, v11, s33, 31
	v_and_b32_e32 v55, 0xffffff80, v37
	v_cndmask_b32_e64 v11, v86, -1, vcc
	v_cmp_lt_i32_e32 vcc, -1, v150
	v_xor_b32_e32 v13, v11, v16
	v_and_b32_e32 v53, 0xffffff80, v35
	v_cndmask_b32_e64 v12, v86, -1, vcc
	v_xor_b32_e32 v12, v12, v17
	v_pk_add_f32 v[12:13], v[8:9], v[12:13] op_sel:[1,0]
	v_and_b32_e32 v52, 0xffffff80, v36
	v_not_b32_e32 v11, v13
	v_or_b32_e32 v16, 0x80000000, v13
	v_cmp_gt_i32_e32 vcc, 0, v13
	v_or_b32_e32 v13, 0x80000000, v12
	v_min_u32_e32 v88, v32, v31
	v_cndmask_b32_e32 v11, v16, v11, vcc
	v_and_or_b32 v16, v11, s33, 47
	v_not_b32_e32 v11, v12
	v_cmp_gt_i32_e32 vcc, 0, v12
	s_lshl_b32 s14, s35, 6
	s_nop 0
	v_cndmask_b32_e32 v11, v13, v11, vcc
	v_cmp_lt_i32_e32 vcc, -1, v149
	v_and_or_b32 v17, v11, s33, 63
	s_nop 0
	v_cndmask_b32_e64 v11, v86, -1, vcc
	v_cmp_lt_i32_e32 vcc, -1, v148
	v_xor_b32_e32 v13, v11, v18
	s_nop 0
	v_cndmask_b32_e64 v12, v86, -1, vcc
	v_xor_b32_e32 v12, v12, v20
	v_pk_add_f32 v[12:13], v[8:9], v[12:13] op_sel:[1,0]
	s_nop 0
	v_not_b32_e32 v11, v13
	v_or_b32_e32 v18, 0x80000000, v13
	v_cmp_gt_i32_e32 vcc, 0, v13
	v_or_b32_e32 v13, 0x80000000, v12
	s_nop 0
	v_cndmask_b32_e32 v11, v18, v11, vcc
	v_and_b32_e32 v11, 0xffffff00, v11
	v_or_b32_e32 v18, 0x4f, v11
	v_not_b32_e32 v11, v12
	v_cmp_gt_i32_e32 vcc, 0, v12
	s_nop 1
	v_cndmask_b32_e32 v11, v13, v11, vcc
	v_and_b32_e32 v11, 0xffffff00, v11
	v_cmp_lt_i32_e32 vcc, -1, v147
	v_or_b32_e32 v20, 0x5f, v11
	s_nop 0
	v_cndmask_b32_e64 v11, v86, -1, vcc
	v_cmp_lt_i32_e32 vcc, -1, v83
	v_xor_b32_e32 v13, v11, v21
	s_nop 0
	v_cndmask_b32_e64 v12, v86, -1, vcc
	v_xor_b32_e32 v12, v12, v22
	v_pk_add_f32 v[12:13], v[8:9], v[12:13] op_sel:[1,0]
	s_nop 0
	v_not_b32_e32 v11, v13
	v_or_b32_e32 v21, 0x80000000, v13
	v_cmp_gt_i32_e32 vcc, 0, v13
	v_or_b32_e32 v13, 0x80000000, v12
	s_nop 0
	v_cndmask_b32_e32 v11, v21, v11, vcc
	v_and_b32_e32 v11, 0xffffff00, v11
	v_or_b32_e32 v21, 0x6f, v11
	v_not_b32_e32 v11, v12
	v_cmp_gt_i32_e32 vcc, 0, v12
	v_mov_b32_e32 v12, v7
	s_nop 0
	v_cndmask_b32_e32 v11, v13, v11, vcc
	v_mov_b32_e32 v13, v9
	v_and_b32_e32 v11, 0xffffff00, v11
	v_pk_add_f32 v[12:13], v[48:49], v[12:13]
	v_or_b32_e32 v22, 0x7f, v11
	v_not_b32_e32 v11, v12
	v_or_b32_e32 v23, 0x80000000, v12
	v_cmp_gt_i32_e32 vcc, 0, v12
	v_or_b32_e32 v12, 0x80000000, v13
	v_mov_b32_e32 v49, v5
	v_cndmask_b32_e32 v11, v23, v11, vcc
	v_and_b32_e32 v11, 0xffffff00, v11
	v_or_b32_e32 v23, 0xcc, v11
	v_not_b32_e32 v11, v13
	v_cmp_gt_i32_e32 vcc, 0, v13
	s_nop 1
	v_cndmask_b32_e32 v11, v12, v11, vcc
	v_and_b32_e32 v11, 0xffffff00, v11
	v_pk_add_f32 v[12:13], v[8:9], v[2:3] op_sel_hi:[0,1]
	v_or_b32_e32 v24, 0xbf, v11
	v_not_b32_e32 v11, v13
	v_or_b32_e32 v29, 0x80000000, v13
	v_cmp_gt_i32_e32 vcc, 0, v13
	v_or_b32_e32 v13, 0x80000000, v12
	s_nop 0
	v_cndmask_b32_e32 v11, v29, v11, vcc
	v_and_b32_e32 v11, 0xffffff00, v11
	v_or_b32_e32 v56, 0xec, v11
	v_not_b32_e32 v11, v12
	v_cmp_gt_i32_e32 vcc, 0, v12
	s_nop 1
	v_cndmask_b32_e32 v11, v13, v11, vcc
	v_cmp_lt_i32_e32 vcc, -1, v10
	v_and_b32_e32 v11, 0xffffff00, v11
	v_or_b32_e32 v57, 0xed, v11
	v_cndmask_b32_e64 v10, v86, -1, vcc
	v_cmp_lt_i32_e32 vcc, -1, v82
	v_xor_b32_e32 v11, v10, v25
	v_mov_b32_e32 v13, v11
	v_cndmask_b32_e64 v12, v86, -1, vcc
	v_xor_b32_e32 v10, v12, v27
	v_mov_b32_e32 v12, v9
	v_pk_add_f32 v[26:27], v[26:27], v[12:13] op_sel_hi:[0,1]
	v_not_b32_e32 v25, v26
	v_or_b32_e32 v29, 0x80000000, v26
	v_cmp_gt_i32_e32 vcc, 0, v26
	v_not_b32_e32 v26, v27
	v_pk_add_f32 v[50:51], v[30:31], v[12:13] op_sel_hi:[0,1]
	v_cndmask_b32_e32 v25, v29, v25, vcc
	v_or_b32_e32 v29, 0x80000000, v27
	v_cmp_gt_i32_e32 vcc, 0, v27
	v_or_b32_e32 v30, 0x80000000, v50
	v_mov_b32_e32 v48, v11
	v_cndmask_b32_e32 v26, v29, v26, vcc
	v_pk_add_f32 v[28:29], v[28:29], v[12:13] op_sel_hi:[0,1]
	v_not_b32_e32 v27, v28
	v_or_b32_e32 v33, 0x80000000, v28
	v_cmp_gt_i32_e32 vcc, 0, v28
	v_not_b32_e32 v28, v29
	v_pk_add_f32 v[2:3], v[10:11], v[2:3] op_sel_hi:[0,1]
	v_cndmask_b32_e32 v27, v33, v27, vcc
	v_or_b32_e32 v33, 0x80000000, v29
	v_cmp_gt_i32_e32 vcc, 0, v29
	v_not_b32_e32 v29, v50
	v_min_u32_e32 v68, v57, v56
	v_cndmask_b32_e32 v28, v33, v28, vcc
	v_cmp_gt_i32_e32 vcc, 0, v50
	v_or_b32_e32 v33, 0x80000000, v51
	v_max_u32_e32 v31, v32, v31
	v_cndmask_b32_e32 v29, v30, v29, vcc
	v_not_b32_e32 v30, v51
	v_cmp_gt_i32_e32 vcc, 0, v51
	v_pk_add_f32 v[50:51], v[34:35], v[48:49] op_sel_hi:[0,1]
	v_or_b32_e32 v34, 0x80000000, v51
	v_cndmask_b32_e32 v30, v33, v30, vcc
	v_not_b32_e32 v33, v51
	v_cmp_gt_i32_e32 vcc, 0, v51
	v_or_b32_e32 v47, 0x80000000, v50
	v_pk_add_f32 v[48:49], v[4:5], v[48:49] op_sel_hi:[0,1]
	v_cndmask_b32_e32 v33, v34, v33, vcc
	v_not_b32_e32 v34, v50
	v_cmp_gt_i32_e32 vcc, 0, v50
	v_not_b32_e32 v5, v49
	v_and_b32_e32 v25, 0xffffff00, v25
	v_cndmask_b32_e32 v34, v47, v34, vcc
	v_or_b32_e32 v47, 0x80000000, v49
	v_cmp_gt_i32_e32 vcc, 0, v49
	v_and_b32_e32 v26, 0xffffff00, v26
	v_and_b32_e32 v27, 0xffffff00, v27
	v_cndmask_b32_e32 v5, v47, v5, vcc
	v_and_b32_e32 v5, 0xffffff00, v5
	v_or_b32_e32 v50, 0xcd, v5
	v_not_b32_e32 v5, v48
	v_or_b32_e32 v47, 0x80000000, v48
	v_cmp_gt_i32_e32 vcc, 0, v48
	v_pk_add_f32 v[48:49], v[6:7], v[12:13] op_sel_hi:[0,1]
	v_or_b32_e32 v7, 0x80000000, v48
	v_cndmask_b32_e32 v5, v47, v5, vcc
	v_and_b32_e32 v5, 0xffffff00, v5
	v_or_b32_e32 v51, 0xce, v5
	v_not_b32_e32 v5, v48
	v_cmp_gt_i32_e32 vcc, 0, v48
	v_min_u32_e32 v91, v51, v50
	v_and_b32_e32 v28, 0xffffff00, v28
	v_cndmask_b32_e32 v5, v7, v5, vcc
	v_and_b32_e32 v5, 0xffffff00, v5
	v_or_b32_e32 v58, 0xdf, v5
	v_not_b32_e32 v5, v49
	v_or_b32_e32 v7, 0x80000000, v49
	v_cmp_gt_i32_e32 vcc, 0, v49
	v_pk_add_f32 v[48:49], v[8:9], v[12:13] op_sel_hi:[0,1]
	v_and_b32_e32 v29, 0xffffff00, v29
	v_cndmask_b32_e32 v5, v7, v5, vcc
	v_and_b32_e32 v5, 0xffffff00, v5
	v_or_b32_e32 v59, 0xde, v5
	v_not_b32_e32 v5, v48
	v_or_b32_e32 v7, 0x80000000, v48
	v_cmp_gt_i32_e32 vcc, 0, v48
	v_max_u32_e32 v83, v58, v59
	v_min_u32_e32 v58, v58, v59
	v_cndmask_b32_e32 v5, v7, v5, vcc
	v_and_b32_e32 v5, 0xffffff00, v5
	v_or_b32_e32 v48, 0xef, v5
	v_not_b32_e32 v5, v49
	v_or_b32_e32 v7, 0x80000000, v49
	v_cmp_gt_i32_e32 vcc, 0, v49
	v_max_u32_e32 v89, v83, v88
	v_max_u32_e32 v32, v58, v31
	v_cndmask_b32_e32 v5, v7, v5, vcc
	v_and_b32_e32 v5, 0xffffff00, v5
	v_cmp_lt_i32_e32 vcc, -1, v46
	v_or_b32_e32 v49, 0xee, v5
	v_and_b32_e32 v5, 0xffffff80, v46
	v_cndmask_b32_e64 v46, v86, -1, vcc
	v_cmp_lt_i32_e32 vcc, -1, v45
	v_and_b32_e32 v7, 0xffffff80, v45
	v_xor_b32_e32 v47, v46, v5
	v_cndmask_b32_e64 v45, v86, -1, vcc
	v_xor_b32_e32 v46, v45, v7
	v_pk_add_f32 v[46:47], v[10:11], v[46:47] op_sel_hi:[0,1]
	v_not_b32_e32 v5, v47
	v_or_b32_e32 v7, 0x80000000, v47
	v_cmp_gt_i32_e32 vcc, 0, v47
	v_min_u32_e32 v83, v83, v88
	v_min_u32_e32 v31, v58, v31
	v_cndmask_b32_e32 v5, v7, v5, vcc
	v_and_b32_e32 v5, 0xffffff00, v5
	v_or_b32_e32 v47, 0xf0, v5
	v_not_b32_e32 v5, v46
	v_or_b32_e32 v7, 0x80000000, v46
	v_cmp_gt_i32_e32 vcc, 0, v46
	v_max_u32_e32 v59, v89, v32
	v_max_u32_e32 v58, v83, v31
	v_cndmask_b32_e32 v5, v7, v5, vcc
	v_and_b32_e32 v5, 0xffffff00, v5
	v_cmp_lt_i32_e32 vcc, -1, v44
	v_or_b32_e32 v46, 0xf1, v5
	v_and_b32_e32 v5, 0xffffff80, v44
	v_cndmask_b32_e64 v44, v86, -1, vcc
	v_cmp_lt_i32_e32 vcc, -1, v43
	v_and_b32_e32 v7, 0xffffff80, v43
	v_xor_b32_e32 v45, v44, v5
	v_cndmask_b32_e64 v43, v86, -1, vcc
	v_xor_b32_e32 v44, v43, v7
	v_pk_add_f32 v[44:45], v[10:11], v[44:45] op_sel_hi:[0,1]
	v_not_b32_e32 v5, v45
	v_or_b32_e32 v7, 0x80000000, v45
	v_cmp_gt_i32_e32 vcc, 0, v45
	v_min_u32_e32 v64, v46, v47
	v_min_u32_e32 v32, v89, v32
	v_cndmask_b32_e32 v5, v7, v5, vcc
	v_and_b32_e32 v5, 0xffffff00, v5
	v_or_b32_e32 v45, 0xf2, v5
	v_not_b32_e32 v5, v44
	v_or_b32_e32 v7, 0x80000000, v44
	v_cmp_gt_i32_e32 vcc, 0, v44
	v_min_u32_e32 v31, v83, v31
	v_and_b32_e32 v30, 0xffffff00, v30
	v_cndmask_b32_e32 v5, v7, v5, vcc
	v_and_b32_e32 v5, 0xffffff00, v5
	v_cmp_lt_i32_e32 vcc, -1, v42
	v_or_b32_e32 v44, 0xf3, v5
	v_and_b32_e32 v5, 0xffffff80, v42
	v_cndmask_b32_e64 v42, v86, -1, vcc
	v_cmp_lt_i32_e32 vcc, -1, v41
	v_and_b32_e32 v7, 0xffffff80, v41
	v_xor_b32_e32 v43, v42, v5
	v_cndmask_b32_e64 v41, v86, -1, vcc
	v_xor_b32_e32 v42, v41, v7
	v_pk_add_f32 v[42:43], v[10:11], v[42:43] op_sel_hi:[0,1]
	v_not_b32_e32 v5, v43
	v_or_b32_e32 v7, 0x80000000, v43
	v_cmp_gt_i32_e32 vcc, 0, v43
	v_max_u32_e32 v63, v44, v45
	v_min_u32_e32 v44, v44, v45
	v_cndmask_b32_e32 v5, v7, v5, vcc
	v_and_b32_e32 v5, 0xffffff00, v5
	v_or_b32_e32 v43, 0xf4, v5
	v_not_b32_e32 v5, v42
	v_or_b32_e32 v7, 0x80000000, v42
	v_cmp_gt_i32_e32 vcc, 0, v42
	v_max_u32_e32 v45, v46, v47
	v_min_u32_e32 v65, v63, v64
	v_cndmask_b32_e32 v5, v7, v5, vcc
	v_and_b32_e32 v5, 0xffffff00, v5
	v_cmp_lt_i32_e32 vcc, -1, v40
	v_or_b32_e32 v42, 0xf5, v5
	v_and_b32_e32 v5, 0xffffff80, v40
	v_cndmask_b32_e64 v40, v86, -1, vcc
	v_cmp_lt_i32_e32 vcc, -1, v39
	v_and_b32_e32 v7, 0xffffff80, v39
	v_xor_b32_e32 v41, v40, v5
	v_cndmask_b32_e64 v39, v86, -1, vcc
	v_xor_b32_e32 v40, v39, v7
	v_pk_add_f32 v[40:41], v[10:11], v[40:41] op_sel_hi:[0,1]
	v_not_b32_e32 v5, v41
	v_or_b32_e32 v7, 0x80000000, v41
	v_cmp_gt_i32_e32 vcc, 0, v41
	v_min_u32_e32 v46, v44, v45
	v_max_u32_e32 v44, v44, v45
	v_cndmask_b32_e32 v5, v7, v5, vcc
	v_and_b32_e32 v5, 0xffffff00, v5
	v_or_b32_e32 v60, 0xf6, v5
	v_not_b32_e32 v5, v40
	v_or_b32_e32 v7, 0x80000000, v40
	v_cmp_gt_i32_e32 vcc, 0, v40
	v_min_u32_e32 v47, v65, v46
	v_max_u32_e32 v46, v65, v46
	v_cndmask_b32_e32 v5, v7, v5, vcc
	v_and_b32_e32 v5, 0xffffff00, v5
	v_cmp_lt_i32_e32 vcc, -1, v38
	v_or_b32_e32 v61, 0xf7, v5
	v_and_b32_e32 v33, 0xffffff00, v33
	v_cndmask_b32_e64 v5, v86, -1, vcc
	v_cmp_lt_i32_e32 vcc, -1, v37
	v_xor_b32_e32 v39, v5, v54
	v_max_u32_e32 v54, v61, v60
	v_cndmask_b32_e64 v7, v86, -1, vcc
	v_xor_b32_e32 v38, v7, v55
	v_pk_add_f32 v[40:41], v[8:9], v[38:39] op_sel_hi:[0,1]
	v_not_b32_e32 v5, v41
	v_or_b32_e32 v7, 0x80000000, v41
	v_cmp_gt_i32_e32 vcc, 0, v41
	v_pk_add_f32 v[38:39], v[10:11], v[38:39] op_sel_hi:[0,1]
	v_min_u32_e32 v55, v42, v43
	v_cndmask_b32_e32 v5, v7, v5, vcc
	v_and_b32_e32 v5, 0xffffff00, v5
	v_or_b32_e32 v41, 0xe8, v5
	v_not_b32_e32 v5, v40
	v_or_b32_e32 v7, 0x80000000, v40
	v_cmp_gt_i32_e32 vcc, 0, v40
	v_min_u32_e32 v60, v61, v60
	v_max_u32_e32 v42, v42, v43
	v_cndmask_b32_e32 v5, v7, v5, vcc
	v_and_b32_e32 v5, 0xffffff00, v5
	v_or_b32_e32 v40, 0xe9, v5
	v_not_b32_e32 v5, v39
	v_or_b32_e32 v7, 0x80000000, v39
	v_cmp_gt_i32_e32 vcc, 0, v39
	v_max_u32_e32 v62, v54, v55
	v_max_u32_e32 v43, v60, v42
	v_cndmask_b32_e32 v5, v7, v5, vcc
	v_and_b32_e32 v5, 0xffffff00, v5
	v_or_b32_e32 v39, 0xf8, v5
	v_not_b32_e32 v5, v38
	v_or_b32_e32 v7, 0x80000000, v38
	v_cmp_gt_i32_e32 vcc, 0, v38
	v_min_u32_e32 v54, v54, v55
	v_min_u32_e32 v42, v60, v42
	v_cndmask_b32_e32 v5, v7, v5, vcc
	v_and_b32_e32 v5, 0xffffff00, v5
	v_cmp_lt_i32_e32 vcc, -1, v36
	v_or_b32_e32 v38, 0xf9, v5
	v_max_u32_e32 v60, v63, v64
	v_cndmask_b32_e64 v5, v86, -1, vcc
	v_cmp_lt_i32_e32 vcc, -1, v35
	v_xor_b32_e32 v37, v5, v52
	v_mov_b32_e32 v5, v9
	v_cndmask_b32_e64 v7, v86, -1, vcc
	v_xor_b32_e32 v36, v7, v53
	v_mov_b32_e32 v7, v4
	v_mov_b32_e32 v4, v36
	v_pk_add_f32 v[4:5], v[6:7], v[4:5]
	v_max_u32_e32 v61, v62, v43
	v_not_b32_e32 v6, v5
	v_or_b32_e32 v7, 0x80000000, v5
	v_cmp_gt_i32_e32 vcc, 0, v5
	v_max_u32_e32 v55, v54, v42
	v_min_u32_e32 v45, v60, v44
	v_cndmask_b32_e32 v5, v7, v6, vcc
	v_and_b32_e32 v5, 0xffffff00, v5
	v_or_b32_e32 v6, 0xcf, v5
	v_not_b32_e32 v5, v4
	v_or_b32_e32 v7, 0x80000000, v4
	v_cmp_gt_i32_e32 vcc, 0, v4
	v_min_u32_e32 v43, v62, v43
	v_min_u32_e32 v42, v54, v42
	v_cndmask_b32_e32 v4, v7, v5, vcc
	v_and_b32_e32 v4, 0xffffff00, v4
	v_or_b32_e32 v7, 0xdb, v4
	v_pk_add_f32 v[4:5], v[8:9], v[36:37] op_sel_hi:[0,1]
	v_not_b32_e32 v8, v5
	v_or_b32_e32 v9, 0x80000000, v5
	v_cmp_gt_i32_e32 vcc, 0, v5
	v_max_u32_e32 v44, v60, v44
	v_min_u32_e32 v66, v61, v47
	v_cndmask_b32_e32 v5, v9, v8, vcc
	v_and_b32_e32 v5, 0xffffff00, v5
	v_or_b32_e32 v8, 0xea, v5
	v_not_b32_e32 v5, v4
	v_or_b32_e32 v9, 0x80000000, v4
	v_cmp_gt_i32_e32 vcc, 0, v4
	v_min_u32_e32 v63, v55, v45
	v_min_u32_e32 v62, v43, v46
	v_cndmask_b32_e32 v4, v9, v5, vcc
	v_and_b32_e32 v4, 0xffffff00, v4
	v_or_b32_e32 v9, 0xeb, v4
	v_pk_add_f32 v[4:5], v[10:11], v[36:37] op_sel_hi:[0,1]
	v_not_b32_e32 v35, v5
	v_or_b32_e32 v36, 0x80000000, v5
	v_cmp_gt_i32_e32 vcc, 0, v5
	v_min_u32_e32 v37, v38, v39
	v_min_u32_e32 v54, v42, v44
	v_cndmask_b32_e32 v5, v36, v35, vcc
	v_not_b32_e32 v35, v4
	v_or_b32_e32 v36, 0x80000000, v4
	v_cmp_gt_i32_e32 vcc, 0, v4
	v_and_b32_e32 v5, 0xffffff00, v5
	v_or_b32_e32 v5, 0xfa, v5
	v_cndmask_b32_e32 v4, v36, v35, vcc
	v_not_b32_e32 v35, v3
	v_or_b32_e32 v36, 0x80000000, v3
	v_cmp_gt_i32_e32 vcc, 0, v3
	s_mov_b64 s[50:51], exec
	s_mov_b64 exec, -1
	s_waitcnt vmcnt(0)
	v_pk_mul_f32 v[200:201], v[200:201], s[96:97] op_sel_hi:[1,0]
	v_pk_mul_f32 v[202:203], v[202:203], s[96:97] op_sel_hi:[1,0]
	v_pk_mul_f32 v[204:205], v[204:205], s[96:97] op_sel_hi:[1,0]
	v_pk_mul_f32 v[206:207], v[206:207], s[96:97] op_sel_hi:[1,0]
	v_pk_mul_f32 v[208:209], v[208:209], s[96:97] op_sel_hi:[1,0]
	v_pk_mul_f32 v[210:211], v[210:211], s[96:97] op_sel_hi:[1,0]
	v_pk_mul_f32 v[212:213], v[212:213], s[96:97] op_sel_hi:[1,0]
	v_pk_mul_f32 v[214:215], v[214:215], s[96:97] op_sel_hi:[1,0]
	v_pk_mul_f32 v[216:217], v[216:217], s[96:97] op_sel_hi:[1,0]
	v_pk_mul_f32 v[218:219], v[218:219], s[96:97] op_sel_hi:[1,0]
	v_pk_mul_f32 v[220:221], v[220:221], s[96:97] op_sel_hi:[1,0]
	v_pk_mul_f32 v[222:223], v[222:223], s[96:97] op_sel_hi:[1,0]
	v_pk_mul_f32 v[224:225], v[224:225], s[96:97] op_sel_hi:[1,0]
	v_pk_mul_f32 v[226:227], v[226:227], s[96:97] op_sel_hi:[1,0]
	v_pk_mul_f32 v[228:229], v[228:229], s[96:97] op_sel_hi:[1,0]
	v_pk_mul_f32 v[230:231], v[230:231], s[96:97] op_sel_hi:[1,0]
	v_cvt_scalef32_pk_fp4_f32 v232, v200, v201, 1.0
	v_cvt_scalef32_pk_fp4_f32 v233, v208, v209, 1.0
	v_cvt_scalef32_pk_fp4_f32 v234, v216, v217, 1.0
	v_cvt_scalef32_pk_fp4_f32 v235, v224, v225, 1.0
	v_cvt_scalef32_pk_fp4_f32 v232, v202, v203, 1.0 op_sel:[0,0,1,0]
	v_cvt_scalef32_pk_fp4_f32 v233, v210, v211, 1.0 op_sel:[0,0,1,0]
	v_cvt_scalef32_pk_fp4_f32 v234, v218, v219, 1.0 op_sel:[0,0,1,0]
	v_cvt_scalef32_pk_fp4_f32 v235, v226, v227, 1.0 op_sel:[0,0,1,0]
	v_cvt_scalef32_pk_fp4_f32 v232, v204, v205, 1.0 op_sel:[0,0,0,1]
	v_cvt_scalef32_pk_fp4_f32 v233, v212, v213, 1.0 op_sel:[0,0,0,1]
	v_cvt_scalef32_pk_fp4_f32 v234, v220, v221, 1.0 op_sel:[0,0,0,1]
	v_cvt_scalef32_pk_fp4_f32 v235, v228, v229, 1.0 op_sel:[0,0,0,1]
	v_cvt_scalef32_pk_fp4_f32 v232, v206, v207, 1.0 op_sel:[0,0,1,1]
	v_cvt_scalef32_pk_fp4_f32 v233, v214, v215, 1.0 op_sel:[0,0,1,1]
	v_cvt_scalef32_pk_fp4_f32 v234, v222, v223, 1.0 op_sel:[0,0,1,1]
	v_cvt_scalef32_pk_fp4_f32 v235, v230, v231, 1.0 op_sel:[0,0,1,1]
	s_nop 0
	global_store_dwordx4 v[240:241], v[232:235], off
	v_lshl_add_u64 v[240:241], v[240:241], 0, v[246:247]
	global_load_dwordx4 v[200:203], v[236:237], off
	global_load_dwordx4 v[204:207], v[236:237], off offset:16
	global_load_dwordx4 v[208:211], v[236:237], off offset:32
	global_load_dwordx4 v[212:215], v[236:237], off offset:48
	global_load_dwordx4 v[216:219], v[238:239], off
	global_load_dwordx4 v[220:223], v[238:239], off offset:16
	global_load_dwordx4 v[224:227], v[238:239], off offset:32
	global_load_dwordx4 v[228:231], v[238:239], off offset:48
	v_lshl_add_u64 v[236:237], v[236:237], 0, v[244:245]
	v_lshl_add_u64 v[238:239], v[238:239], 0, v[244:245]
	s_mov_b64 exec, s[50:51]
	s_nop 4
	v_and_b32_e32 v4, 0xffffff00, v4
	v_or_b32_e32 v4, 0xfb, v4
	v_cndmask_b32_e32 v3, v36, v35, vcc
	v_and_b32_e32 v3, 0xffffff00, v3
	v_or_b32_e32 v35, 0xfc, v3
	v_not_b32_e32 v3, v2
	v_or_b32_e32 v36, 0x80000000, v2
	v_cmp_gt_i32_e32 vcc, 0, v2
	v_min_u32_e32 v64, v66, v63
	v_min_u32_e32 v60, v62, v54
	v_cndmask_b32_e32 v2, v36, v3, vcc
	v_and_b32_e32 v2, 0xffffff00, v2
	v_or_b32_e32 v36, 0xfd, v2
	v_pk_add_f32 v[2:3], v[10:11], v[12:13] op_sel_hi:[0,1]
	v_not_b32_e32 v10, v3
	v_or_b32_e32 v11, 0x80000000, v3
	v_cmp_gt_i32_e32 vcc, 0, v3
	v_min_u32_e32 v65, v64, v60
	v_max_u32_e32 v78, v9, v8
	v_cndmask_b32_e32 v3, v11, v10, vcc
	v_not_b32_e32 v10, v2
	v_or_b32_e32 v11, 0x80000000, v2
	v_cmp_gt_i32_e32 vcc, 0, v2
	v_and_b32_e32 v3, 0xffffff00, v3
	v_or_b32_e32 v3, 0xfe, v3
	v_cndmask_b32_e32 v2, v11, v10, vcc
	v_or_b32_e32 v2, 0xff, v2
	v_max_u32_e32 v10, v2, v3
	v_min_u32_e32 v11, v36, v35
	v_min_u32_e32 v2, v2, v3
	v_max_u32_e32 v3, v36, v35
	v_max_u32_e32 v36, v4, v5
	v_min_u32_e32 v4, v4, v5
	v_max_u32_e32 v5, v38, v39
	v_max_u32_e32 v12, v10, v11
	v_max_u32_e32 v13, v2, v3
	v_min_u32_e32 v52, v36, v37
	v_min_u32_e32 v38, v4, v5
	v_min_u32_e32 v10, v10, v11
	v_min_u32_e32 v2, v2, v3
	v_max_u32_e32 v11, v36, v37
	v_max_u32_e32 v4, v4, v5
	v_max_u32_e32 v35, v12, v13
	v_min_u32_e32 v39, v52, v38
	v_max_u32_e32 v3, v10, v2
	v_min_u32_e32 v5, v11, v4
	v_min_u32_e32 v12, v12, v13
	v_max_u32_e32 v13, v52, v38
	v_min_u32_e32 v2, v10, v2
	v_max_u32_e32 v4, v11, v4
	v_max_u32_e32 v53, v35, v39
	v_max_u32_e32 v36, v3, v5
	v_max_u32_e32 v38, v12, v13
	v_max_u32_e32 v10, v2, v4
	v_max_u32_e32 v37, v53, v36
	v_max_u32_e32 v11, v38, v10
	v_max_u32_e32 v52, v37, v11
	v_min_u32_e32 v11, v37, v11
	v_max_u32_e32 v37, v64, v60
	v_max_u32_e32 v64, v48, v49
	v_min_u32_e32 v48, v48, v49
	v_max_u32_e32 v49, v57, v56
	v_min_u32_e32 v80, v40, v41
	v_min_u32_e32 v8, v9, v8
	v_max_u32_e32 v9, v40, v41
	v_max_u32_e32 v90, v7, v6
	v_min_u32_e32 v6, v7, v6
	v_max_u32_e32 v7, v51, v50
	v_max_u32_e32 v69, v64, v68
	v_max_u32_e32 v56, v48, v49
	v_min_u32_e32 v81, v78, v80
	v_min_u32_e32 v40, v8, v9
	v_min_u32_e32 v64, v64, v68
	v_min_u32_e32 v48, v48, v49
	v_max_u32_e32 v68, v78, v80
	v_max_u32_e32 v8, v8, v9
	v_min_u32_e32 v92, v90, v91
	v_min_u32_e32 v50, v6, v7
	v_max_u32_e32 v88, v90, v91
	v_max_u32_e32 v6, v6, v7
	v_max_u32_e32 v57, v69, v56
	v_min_u32_e32 v41, v81, v40
	v_max_u32_e32 v49, v64, v48
	v_min_u32_e32 v9, v68, v8
	v_min_u32_e32 v56, v69, v56
	v_max_u32_e32 v40, v81, v40
	v_min_u32_e32 v48, v64, v48
	v_max_u32_e32 v8, v68, v8
	v_min_u32_e32 v51, v92, v50
	v_min_u32_e32 v7, v88, v6
	v_max_u32_e32 v50, v92, v50
	v_max_u32_e32 v6, v88, v6
	v_min_u32_e32 v35, v35, v39
	v_min_u32_e32 v3, v3, v5
	v_min_u32_e32 v12, v12, v13
	v_min_u32_e32 v2, v2, v4
	v_max_u32_e32 v39, v61, v47
	v_max_u32_e32 v45, v55, v45
	v_max_u32_e32 v43, v43, v46
	v_max_u32_e32 v42, v42, v44
	v_max_u32_e32 v82, v57, v41
	v_max_u32_e32 v78, v49, v9
	v_max_u32_e32 v69, v56, v40
	v_max_u32_e32 v64, v48, v8
	v_min_u32_e32 v93, v59, v51
	v_min_u32_e32 v90, v58, v7
	v_min_u32_e32 v89, v32, v50
	v_min_u32_e32 v83, v31, v6
	v_min_u32_e32 v41, v57, v41
	v_min_u32_e32 v9, v49, v9
	v_min_u32_e32 v40, v56, v40
	v_min_u32_e32 v8, v48, v8
	v_max_u32_e32 v51, v59, v51
	v_max_u32_e32 v7, v58, v7
	v_max_u32_e32 v32, v32, v50
	v_max_u32_e32 v6, v31, v6
	v_max_u32_e32 v5, v35, v3
	v_max_u32_e32 v4, v12, v2
	v_min_u32_e32 v47, v39, v45
	v_min_u32_e32 v44, v43, v42
	v_min_u32_e32 v36, v53, v36
	v_min_u32_e32 v10, v38, v10
	v_max_u32_e32 v53, v66, v63
	v_max_u32_e32 v54, v62, v54
	v_min_u32_e32 v3, v35, v3
	v_min_u32_e32 v2, v12, v2
	v_max_u32_e32 v35, v39, v45
	v_max_u32_e32 v39, v43, v42
	v_max_u32_e32 v80, v82, v78
	v_max_u32_e32 v68, v69, v64
	v_min_u32_e32 v91, v93, v90
	v_min_u32_e32 v88, v89, v83
	v_max_u32_e32 v49, v41, v9
	v_max_u32_e32 v48, v40, v8
	v_min_u32_e32 v57, v51, v7
	v_min_u32_e32 v31, v32, v6
	v_min_u32_e32 v78, v82, v78
	v_min_u32_e32 v64, v69, v64
	v_max_u32_e32 v82, v93, v90
	v_max_u32_e32 v83, v89, v83
	v_min_u32_e32 v9, v41, v9
	v_min_u32_e32 v8, v40, v8
	v_max_u32_e32 v7, v51, v7
	v_max_u32_e32 v6, v32, v6
	v_max_u32_e32 v13, v5, v4
	v_max_u32_e32 v38, v36, v10
	v_max_u32_e32 v12, v3, v2
	v_min_u32_e32 v4, v5, v4
	v_max_u32_e32 v5, v47, v44
	v_min_u32_e32 v10, v36, v10
	v_max_u32_e32 v36, v53, v54
	v_min_u32_e32 v2, v3, v2
	v_max_u32_e32 v3, v35, v39
	v_max_u32_e32 v81, v80, v68
	v_min_u32_e32 v92, v91, v88
	v_max_u32_e32 v56, v49, v48
	v_min_u32_e32 v50, v57, v31
	v_max_u32_e32 v69, v78, v64
	v_min_u32_e32 v89, v82, v83
	v_max_u32_e32 v40, v9, v8
	v_min_u32_e32 v32, v7, v6
	v_min_u32_e32 v68, v80, v68
	v_max_u32_e32 v80, v91, v88
	v_min_u32_e32 v48, v49, v48
	v_max_u32_e32 v31, v57, v31
	v_min_u32_e32 v64, v78, v64
	v_max_u32_e32 v78, v82, v83
	v_min_u32_e32 v8, v9, v8
	v_max_u32_e32 v6, v7, v6
	v_max_u32_e32 v67, v52, v65
	v_min_u32_e32 v46, v47, v44
	v_min_u32_e32 v62, v53, v54
	v_min_u32_e32 v42, v35, v39
	v_max_u32_e32 v60, v11, v37
	v_max_u32_e32 v44, v4, v5
	v_max_u32_e32 v53, v10, v36
	v_max_u32_e32 v35, v2, v3
	v_min_u32_e32 v58, v56, v50
	v_min_u32_e32 v41, v40, v32
	v_min_u32_e32 v88, v68, v80
	v_min_u32_e32 v49, v48, v31
	v_min_u32_e32 v82, v64, v78
	v_min_u32_e32 v7, v8, v6
	v_min_u32_e32 v52, v52, v65
	v_min_u32_e32 v11, v11, v37
	v_min_u32_e32 v4, v4, v5
	v_min_u32_e32 v10, v10, v36
	v_min_u32_e32 v2, v2, v3
	v_max_u32_e32 v37, v81, v92
	v_max_u32_e32 v50, v56, v50
	v_max_u32_e32 v65, v69, v89
	v_max_u32_e32 v32, v40, v32
	v_max_u32_e32 v68, v68, v80
	v_max_u32_e32 v31, v48, v31
	v_max_u32_e32 v64, v64, v78
	v_max_u32_e32 v6, v8, v6
	v_max_u32_e32 v55, v13, v46
	v_max_u32_e32 v63, v38, v62
	v_max_u32_e32 v43, v12, v42
	v_min_u32_e32 v94, v81, v92
	v_min_u32_e32 v90, v69, v89
	v_min_u32_e32 v13, v13, v46
	v_min_u32_e32 v38, v38, v62
	v_min_u32_e32 v12, v12, v42
	v_max_u32_e32 v5, v11, v4
	v_max_u32_e32 v3, v10, v2
	v_min_u32_e32 v56, v37, v50
	v_min_u32_e32 v40, v65, v32
	v_min_u32_e32 v48, v68, v31
	v_min_u32_e32 v8, v64, v6
	v_max_u32_e32 v47, v60, v44
	v_max_u32_e32 v39, v53, v35
	v_min_u32_e32 v59, v94, v58
	v_min_u32_e32 v51, v90, v41
	v_min_u32_e32 v57, v88, v49
	v_min_u32_e32 v9, v82, v7
	v_max_u32_e32 v46, v52, v13
	v_max_u32_e32 v42, v38, v12
	v_max_u32_e32 v36, v5, v3
	v_min_u32_e32 v78, v48, v8
	v_min_u32_e32 v4, v11, v4
	v_max_u32_e32 v11, v37, v50
	v_max_u32_e32 v32, v65, v32
	v_max_u32_e32 v31, v68, v31
	v_max_u32_e32 v6, v64, v6
	v_min_u32_e32 v3, v5, v3
	v_max_u32_e32 v5, v56, v40
	v_max_u32_e32 v8, v48, v8
	v_max_u32_e32 v61, v67, v55
	v_max_u32_e32 v45, v63, v43
	v_max_u32_e32 v54, v47, v39
	v_min_u32_e32 v83, v57, v9
	v_max_u32_e32 v62, v46, v42
	v_min_u32_e32 v69, v56, v40
	v_min_u32_e32 v55, v67, v55
	v_min_u32_e32 v43, v63, v43
	v_min_u32_e32 v44, v60, v44
	v_min_u32_e32 v35, v53, v35
	v_max_u32_e32 v58, v94, v58
	v_max_u32_e32 v41, v90, v41
	v_max_u32_e32 v49, v88, v49
	v_max_u32_e32 v7, v82, v7
	v_min_u32_e32 v13, v52, v13
	v_min_u32_e32 v12, v38, v12
	v_min_u32_e32 v2, v10, v2
	v_min_u32_e32 v37, v11, v32
	v_min_u32_e32 v50, v31, v6
	v_min_u32_e32 v39, v47, v39
	v_max_u32_e32 v47, v59, v51
	v_max_u32_e32 v9, v57, v9
	v_min_u32_e32 v42, v46, v42
	v_min_u32_e32 v40, v5, v8
	v_and_b32_e32 v34, 0xffffff00, v34
	v_max_u32_e32 v66, v61, v45
	v_min_u32_e32 v93, v59, v51
	v_max_u32_e32 v63, v55, v43
	v_max_u32_e32 v53, v44, v35
	v_min_u32_e32 v60, v58, v41
	v_min_u32_e32 v67, v49, v7
	v_max_u32_e32 v38, v13, v12
	v_max_u32_e32 v10, v4, v2
	v_min_u32_e32 v52, v37, v50
	v_min_u32_e32 v45, v61, v45
	v_min_u32_e32 v51, v47, v9
	v_max3_u32 v40, v42, v3, v40
	v_min_u32_e32 v43, v55, v43
	v_min_u32_e32 v35, v44, v35
	v_max_u32_e32 v41, v58, v41
	v_max_u32_e32 v7, v49, v7
	v_min_u32_e32 v2, v4, v2
	v_max_u32_e32 v4, v11, v32
	v_max_u32_e32 v6, v31, v6
	v_min_u32_e32 v3, v42, v3
	v_or_b32_e32 v25, 0x8f, v25
	v_or_b32_e32 v26, 0x8e, v26
	v_or_b32_e32 v27, 0x9f, v27
	v_or_b32_e32 v28, 0x9e, v28
	v_or_b32_e32 v29, 0xaf, v29
	v_or_b32_e32 v30, 0xae, v30
	v_or_b32_e32 v33, 0xbd, v33
	v_or_b32_e32 v34, 0xbe, v34
	v_max3_u32 v52, v38, v10, v52
	v_max3_u32 v51, v45, v39, v51
	v_min_u32_e32 v44, v41, v7
	v_min_u32_e32 v12, v13, v12
	v_min_u32_e32 v11, v4, v6
	v_min_u32_e32 v10, v38, v10
	v_min_u32_e32 v39, v45, v39
	v_max3_u32 v3, v3, v5, v8
	v_min_u32_e32 v8, v43, v35
	v_min_u32_e32 v91, v93, v83
	v_max3_u32 v44, v43, v35, v44
	v_max3_u32 v11, v12, v2, v11
	v_max3_u32 v10, v10, v37, v50
	v_max3_u32 v9, v39, v47, v9
	v_max3_u32 v7, v8, v41, v7
	v_min_u32_e32 v2, v12, v2
	v_max_u32_e32 v12, v23, v24
	v_min_u32_e32 v35, v34, v33
	v_min_u32_e32 v23, v23, v24
	v_max_u32_e32 v24, v34, v33
	v_max_u32_e32 v41, v29, v30
	v_min_u32_e32 v42, v27, v28
	v_min_u32_e32 v29, v29, v30
	v_max_u32_e32 v27, v27, v28
	v_max_u32_e32 v47, v25, v26
	v_min_u32_e32 v50, v22, v21
	v_min_u32_e32 v25, v25, v26
	v_max_u32_e32 v21, v22, v21
	v_max_u32_e32 v55, v20, v18
	v_min_u32_e32 v56, v17, v16
	v_min_u32_e32 v18, v20, v18
	v_max_u32_e32 v16, v17, v16
	v_max3_u32 v91, v66, v54, v91
	v_min_u32_e32 v48, v66, v54
	v_max_u32_e32 v39, v12, v35
	v_max_u32_e32 v33, v23, v24
	v_min_u32_e32 v43, v41, v42
	v_min_u32_e32 v28, v29, v27
	v_min_u32_e32 v12, v12, v35
	v_min_u32_e32 v23, v23, v24
	v_max_u32_e32 v35, v41, v42
	v_max_u32_e32 v27, v29, v27
	v_max_u32_e32 v54, v47, v50
	v_max_u32_e32 v22, v25, v21
	v_min_u32_e32 v57, v55, v56
	v_min_u32_e32 v17, v18, v16
	v_min_u32_e32 v47, v47, v50
	v_min_u32_e32 v21, v25, v21
	v_max_u32_e32 v50, v55, v56
	v_max_u32_e32 v16, v18, v16
	v_max_u32_e32 v34, v39, v33
	v_min_u32_e32 v30, v43, v28
	v_max_u32_e32 v24, v12, v23
	v_min_u32_e32 v29, v35, v27
	v_min_u32_e32 v33, v39, v33
	v_max_u32_e32 v28, v43, v28
	v_min_u32_e32 v12, v12, v23
	v_max_u32_e32 v23, v35, v27
	v_max_u32_e32 v26, v54, v22
	v_min_u32_e32 v20, v57, v17
	v_max_u32_e32 v25, v47, v21
	v_min_u32_e32 v18, v50, v16
	v_min_u32_e32 v22, v54, v22
	v_max_u32_e32 v17, v57, v17
	v_min_u32_e32 v21, v47, v21
	v_max_u32_e32 v16, v50, v16
	v_max_u32_e32 v45, v34, v30
	v_max_u32_e32 v41, v24, v29
	v_max_u32_e32 v39, v33, v28
	v_max_u32_e32 v27, v12, v23
	v_min_u32_e32 v58, v26, v20
	v_min_u32_e32 v55, v25, v18
	v_min_u32_e32 v54, v22, v17
	v_min_u32_e32 v47, v21, v16
	v_min_u32_e32 v30, v34, v30
	v_min_u32_e32 v24, v24, v29
	v_min_u32_e32 v28, v33, v28
	v_min_u32_e32 v12, v12, v23
	v_max_u32_e32 v20, v26, v20
	v_max_u32_e32 v18, v25, v18
	v_max_u32_e32 v17, v22, v17
	v_max_u32_e32 v16, v21, v16
	v_max_u32_e32 v42, v45, v41
	v_max_u32_e32 v35, v39, v27
	v_min_u32_e32 v56, v58, v55
	v_min_u32_e32 v50, v54, v47
	v_max_u32_e32 v29, v30, v24
	v_max_u32_e32 v23, v28, v12
	v_min_u32_e32 v25, v20, v18
	v_min_u32_e32 v21, v17, v16
	v_min_u32_e32 v41, v45, v41
	v_min_u32_e32 v27, v39, v27
	v_max_u32_e32 v45, v58, v55
	v_max_u32_e32 v47, v54, v47
	v_min_u32_e32 v24, v30, v24
	v_min_u32_e32 v12, v28, v12
	v_max_u32_e32 v18, v20, v18
	v_max_u32_e32 v16, v17, v16
	v_max_u32_e32 v43, v42, v35
	v_min_u32_e32 v57, v56, v50
	v_max_u32_e32 v33, v29, v23
	v_min_u32_e32 v22, v25, v21
	v_max_u32_e32 v39, v41, v27
	v_min_u32_e32 v54, v45, v47
	v_max_u32_e32 v28, v24, v12
	v_min_u32_e32 v17, v18, v16
	v_min_u32_e32 v35, v42, v35
	v_max_u32_e32 v42, v56, v50
	v_min_u32_e32 v23, v29, v23
	v_max_u32_e32 v21, v25, v21
	v_min_u32_e32 v27, v41, v27
	v_max_u32_e32 v41, v45, v47
	v_min_u32_e32 v12, v24, v12
	v_max_u32_e32 v16, v18, v16
	v_max_u32_e32 v59, v43, v57
	v_max_u32_e32 v26, v33, v22
	v_max_u32_e32 v55, v39, v54
	v_max_u32_e32 v20, v28, v17
	v_max_u32_e32 v50, v35, v42
	v_max_u32_e32 v25, v23, v21
	v_max_u32_e32 v45, v27, v41
	v_max_u32_e32 v18, v12, v16
	v_min_u32_e32 v43, v43, v57
	v_min_u32_e32 v22, v33, v22
	v_min_u32_e32 v39, v39, v54
	v_min_u32_e32 v17, v28, v17
	v_min_u32_e32 v35, v35, v42
	v_min_u32_e32 v21, v23, v21
	v_min_u32_e32 v27, v27, v41
	v_min_u32_e32 v12, v12, v16
	v_max_u32_e32 v33, v43, v22
	v_max_u32_e32 v28, v39, v17
	v_max_u32_e32 v23, v35, v21
	v_max_u32_e32 v16, v27, v12
	v_min_u32_e32 v22, v43, v22
	v_min_u32_e32 v17, v39, v17
	v_min_u32_e32 v21, v35, v21
	v_min_u32_e32 v12, v27, v12
	v_min_u32_e32 v80, v69, v78
	v_min_u32_e32 v82, v60, v67
	v_max_u32_e32 v34, v59, v26
	v_max_u32_e32 v30, v55, v20
	v_max_u32_e32 v29, v50, v25
	v_max_u32_e32 v24, v45, v18
	v_min_u32_e32 v26, v59, v26
	v_min_u32_e32 v20, v55, v20
	v_min_u32_e32 v25, v50, v25
	v_min_u32_e32 v18, v45, v18
	v_max_u32_e32 v39, v22, v17
	v_max_u32_e32 v27, v21, v12
	v_min_u32_e32 v17, v22, v17
	v_min_u32_e32 v12, v21, v12
	v_min_u32_e32 v21, v15, v14
	v_max3_u32 v80, v62, v36, v80
	v_max3_u32 v82, v63, v53, v82
	v_min_u32_e32 v36, v62, v36
	v_min_u32_e32 v53, v63, v53
	v_max_u32_e32 v58, v34, v30
	v_max_u32_e32 v47, v29, v24
	v_max_u32_e32 v54, v33, v28
	v_max_u32_e32 v41, v23, v16
	v_max_u32_e32 v55, v26, v20
	v_max_u32_e32 v45, v25, v18
	v_min_u32_e32 v30, v34, v30
	v_min_u32_e32 v24, v29, v24
	v_min_u32_e32 v28, v33, v28
	v_min_u32_e32 v16, v23, v16
	v_min_u32_e32 v20, v26, v20
	v_min_u32_e32 v18, v25, v18
	v_max3_u32 v21, v17, v12, v21
	v_min_u32_e32 v12, v17, v12
	v_max3_u32 v48, v48, v93, v83
	v_max3_u32 v36, v36, v69, v78
	v_max3_u32 v53, v53, v60, v67
	v_max3_u32 v2, v2, v4, v6
	v_max_u32_e32 v56, v58, v47
	v_max_u32_e32 v42, v54, v41
	v_max_u32_e32 v50, v55, v45
	v_max_u32_e32 v35, v39, v27
	v_max_u32_e32 v29, v30, v24
	v_max_u32_e32 v23, v28, v16
	v_max_u32_e32 v25, v20, v18
	v_min_u32_e32 v47, v58, v47
	v_min_u32_e32 v41, v54, v41
	v_min_u32_e32 v45, v55, v45
	v_min_u32_e32 v27, v39, v27
	v_min_u32_e32 v24, v30, v24
	v_min_u32_e32 v16, v28, v16
	v_min_u32_e32 v18, v20, v18
	v_max3_u32 v12, v12, v15, v14
	v_max_u32_e32 v49, v48, v36
	v_max_u32_e32 v37, v53, v10
	v_max_u32_e32 v5, v9, v3
	v_max_u32_e32 v4, v7, v2
	v_min_u32_e32 v57, v56, v42
	v_min_u32_e32 v43, v50, v35
	v_min_u32_e32 v33, v29, v23
	v_min_u32_e32 v22, v25, v21
	v_min_u32_e32 v54, v47, v41
	v_min_u32_e32 v39, v45, v27
	v_min_u32_e32 v28, v24, v16
	v_min_u32_e32 v14, v18, v12
	v_min_u32_e32 v36, v48, v36
	v_min_u32_e32 v10, v53, v10
	s_mov_b64 s[50:51], exec
	s_mov_b64 exec, -1
	s_waitcnt vmcnt(0)
	v_pk_mul_f32 v[200:201], v[200:201], s[96:97] op_sel_hi:[1,0]
	v_pk_mul_f32 v[202:203], v[202:203], s[96:97] op_sel_hi:[1,0]
	v_pk_mul_f32 v[204:205], v[204:205], s[96:97] op_sel_hi:[1,0]
	v_pk_mul_f32 v[206:207], v[206:207], s[96:97] op_sel_hi:[1,0]
	v_pk_mul_f32 v[208:209], v[208:209], s[96:97] op_sel_hi:[1,0]
	v_pk_mul_f32 v[210:211], v[210:211], s[96:97] op_sel_hi:[1,0]
	v_pk_mul_f32 v[212:213], v[212:213], s[96:97] op_sel_hi:[1,0]
	v_pk_mul_f32 v[214:215], v[214:215], s[96:97] op_sel_hi:[1,0]
	v_pk_mul_f32 v[216:217], v[216:217], s[96:97] op_sel_hi:[1,0]
	v_pk_mul_f32 v[218:219], v[218:219], s[96:97] op_sel_hi:[1,0]
	v_pk_mul_f32 v[220:221], v[220:221], s[96:97] op_sel_hi:[1,0]
	v_pk_mul_f32 v[222:223], v[222:223], s[96:97] op_sel_hi:[1,0]
	v_pk_mul_f32 v[224:225], v[224:225], s[96:97] op_sel_hi:[1,0]
	v_pk_mul_f32 v[226:227], v[226:227], s[96:97] op_sel_hi:[1,0]
	v_pk_mul_f32 v[228:229], v[228:229], s[96:97] op_sel_hi:[1,0]
	v_pk_mul_f32 v[230:231], v[230:231], s[96:97] op_sel_hi:[1,0]
	v_cvt_scalef32_pk_fp4_f32 v232, v200, v201, 1.0
	v_cvt_scalef32_pk_fp4_f32 v233, v208, v209, 1.0
	v_cvt_scalef32_pk_fp4_f32 v234, v216, v217, 1.0
	v_cvt_scalef32_pk_fp4_f32 v235, v224, v225, 1.0
	v_cvt_scalef32_pk_fp4_f32 v232, v202, v203, 1.0 op_sel:[0,0,1,0]
	v_cvt_scalef32_pk_fp4_f32 v233, v210, v211, 1.0 op_sel:[0,0,1,0]
	v_cvt_scalef32_pk_fp4_f32 v234, v218, v219, 1.0 op_sel:[0,0,1,0]
	v_cvt_scalef32_pk_fp4_f32 v235, v226, v227, 1.0 op_sel:[0,0,1,0]
	v_cvt_scalef32_pk_fp4_f32 v232, v204, v205, 1.0 op_sel:[0,0,0,1]
	v_cvt_scalef32_pk_fp4_f32 v233, v212, v213, 1.0 op_sel:[0,0,0,1]
	v_cvt_scalef32_pk_fp4_f32 v234, v220, v221, 1.0 op_sel:[0,0,0,1]
	v_cvt_scalef32_pk_fp4_f32 v235, v228, v229, 1.0 op_sel:[0,0,0,1]
	v_cvt_scalef32_pk_fp4_f32 v232, v206, v207, 1.0 op_sel:[0,0,1,1]
	v_cvt_scalef32_pk_fp4_f32 v233, v214, v215, 1.0 op_sel:[0,0,1,1]
	v_cvt_scalef32_pk_fp4_f32 v234, v222, v223, 1.0 op_sel:[0,0,1,1]
	v_cvt_scalef32_pk_fp4_f32 v235, v230, v231, 1.0 op_sel:[0,0,1,1]
	s_nop 0
	global_store_dwordx4 v[240:241], v[232:235], off
	v_lshl_add_u64 v[240:241], v[240:241], 0, v[246:247]
	s_mov_b64 exec, s[50:51]
	s_nop 4
	v_min_u32_e32 v3, v9, v3
	v_min_u32_e32 v2, v7, v2
	v_max_u32_e32 v42, v56, v42
	v_max_u32_e32 v35, v50, v35
	v_max_u32_e32 v23, v29, v23
	v_max_u32_e32 v21, v25, v21
	v_max_u32_e32 v41, v47, v41
	v_max_u32_e32 v27, v45, v27
	v_max_u32_e32 v16, v24, v16
	v_max_u32_e32 v12, v18, v12
	v_max_u32_e32 v81, v91, v80
	v_max_u32_e32 v64, v82, v52
	v_max_u32_e32 v46, v51, v40
	v_max_u32_e32 v13, v44, v11
	v_min_u32_e32 v59, v57, v43
	v_min_u32_e32 v26, v33, v22
	v_min_u32_e32 v55, v54, v39
	v_min_u32_e32 v15, v28, v14
	v_min_u32_e32 v30, v91, v80
	v_min_u32_e32 v52, v82, v52
	v_min_u32_e32 v40, v51, v40
	v_min_u32_e32 v11, v44, v11
	v_max_u32_e32 v48, v36, v10
	v_max_u32_e32 v7, v3, v2
	v_min_u32_e32 v50, v42, v35
	v_min_u32_e32 v25, v23, v21
	v_min_u32_e32 v45, v41, v27
	v_min_u32_e32 v18, v16, v12
	v_max_u32_e32 v43, v57, v43
	v_max_u32_e32 v22, v33, v22
	v_max_u32_e32 v39, v54, v39
	v_max_u32_e32 v14, v28, v14
	v_min_u32_e32 v10, v36, v10
	v_min_u32_e32 v2, v3, v2
	v_max_u32_e32 v35, v42, v35
	v_max_u32_e32 v21, v23, v21
	v_max_u32_e32 v27, v41, v27
	v_max_u32_e32 v12, v16, v12
	v_max_u32_e32 v65, v81, v64
	v_max_u32_e32 v31, v46, v13
	v_max_u32_e32 v38, v49, v37
	v_max_u32_e32 v6, v5, v4
	v_min_u32_e32 v34, v59, v26
	v_min_u32_e32 v17, v55, v15
	v_max_u32_e32 v58, v30, v52
	v_max_u32_e32 v44, v40, v11
	v_min_u32_e32 v29, v50, v25
	v_min_u32_e32 v24, v45, v18
	v_min_u32_e32 v56, v81, v64
	v_min_u32_e32 v13, v46, v13
	v_min_u32_e32 v37, v49, v37
	v_min_u32_e32 v4, v5, v4
	v_min_u32_e32 v33, v43, v22
	v_min_u32_e32 v28, v39, v14
	v_min_u32_e32 v30, v30, v52
	v_min_u32_e32 v11, v40, v11
	v_max_u32_e32 v3, v10, v2
	v_min_u32_e32 v23, v35, v21
	v_min_u32_e32 v16, v27, v12
	v_max_u32_e32 v26, v59, v26
	v_max_u32_e32 v15, v55, v15
	v_max_u32_e32 v25, v50, v25
	v_max_u32_e32 v18, v45, v18
	v_max_u32_e32 v22, v43, v22
	v_max_u32_e32 v14, v39, v14
	v_min_u32_e32 v2, v10, v2
	v_max_u32_e32 v10, v35, v21
	v_max_u32_e32 v12, v27, v12
	v_max_u32_e32 v32, v65, v31
	v_max_u32_e32 v8, v38, v6
	v_min_u32_e32 v20, v34, v17
	v_max_u32_e32 v51, v58, v44
	v_max_u32_e32 v9, v48, v7
	v_min_u32_e32 v47, v29, v24
	v_max_u32_e32 v46, v56, v13
	v_max_u32_e32 v5, v37, v4
	v_min_u32_e32 v49, v33, v28
	v_max_u32_e32 v40, v30, v11
	v_min_u32_e32 v36, v23, v16
	v_min_u32_e32 v31, v65, v31
	v_min_u32_e32 v6, v38, v6
	v_min_u32_e32 v38, v26, v15
	v_min_u32_e32 v44, v58, v44
	v_min_u32_e32 v7, v48, v7
	v_min_u32_e32 v45, v25, v18
	v_min_u32_e32 v13, v56, v13
	v_min_u32_e32 v4, v37, v4
	v_min_u32_e32 v37, v22, v14
	v_min_u32_e32 v11, v30, v11
	v_min_u32_e32 v21, v10, v12
	v_max3_u32 v20, v32, v8, v20
	v_max3_u32 v47, v51, v9, v47
	v_max3_u32 v49, v46, v5, v49
	v_max3_u32 v36, v40, v3, v36
	v_max3_u32 v38, v31, v6, v38
	v_max3_u32 v45, v44, v7, v45
	v_max3_u32 v37, v13, v4, v37
	v_max3_u32 v21, v11, v2, v21
	v_min_u32_e32 v8, v32, v8
	v_min_u32_e32 v9, v51, v9
	v_min_u32_e32 v5, v46, v5
	v_min_u32_e32 v3, v40, v3
	v_min_u32_e32 v6, v31, v6
	v_min_u32_e32 v7, v44, v7
	v_min_u32_e32 v4, v13, v4
	v_min_u32_e32 v2, v11, v2
	v_max3_u32 v8, v8, v34, v17
	v_max3_u32 v9, v9, v29, v24
	v_max3_u32 v5, v5, v33, v28
	v_max3_u32 v3, v3, v23, v16
	v_max3_u32 v6, v6, v26, v15
	v_max3_u32 v7, v7, v25, v18
	v_max3_u32 v4, v4, v22, v14
	v_max3_u32 v2, v2, v10, v12
	v_max_u32_e32 v53, v20, v47
	v_max_u32_e32 v41, v49, v36
	v_max_u32_e32 v48, v38, v45
	v_max_u32_e32 v27, v37, v21
	v_max_u32_e32 v17, v8, v9
	v_max_u32_e32 v16, v5, v3
	v_max_u32_e32 v15, v6, v7
	v_max_u32_e32 v10, v4, v2
	v_max_u32_e32 v42, v53, v41
	v_max_u32_e32 v30, v48, v27
	v_max_u32_e32 v23, v17, v16
	v_max_u32_e32 v11, v15, v10
	v_max_u32_e32 v35, v42, v30
	v_max_u32_e32 v12, v23, v11
	v_max_u32_e32 v13, v35, v12
	v_min_u32_e32 v12, v35, v12
	v_cmp_lt_i32_e32 vcc, -1, v12
	v_not_b32_e32 v32, v12
	v_min_u32_e32 v11, v23, v11
	v_cndmask_b32_e64 v14, v86, -1, vcc
	v_bitop3_b32 v12, v14, v12, s33 bitop3:0x78
	v_min_u32_e32 v14, v42, v30
	v_max_u32_e32 v18, v14, v11
	v_cmp_lt_i32_e32 vcc, -1, v18
	v_min_u32_e32 v11, v14, v11
	v_not_b32_e32 v33, v18
	v_cndmask_b32_e64 v22, v86, -1, vcc
	v_cmp_lt_i32_e32 vcc, -1, v11
	v_bitop3_b32 v18, v22, v18, s33 bitop3:0x78
	v_not_b32_e32 v34, v11
	v_cndmask_b32_e64 v14, v86, -1, vcc
	v_bitop3_b32 v11, v14, v11, s33 bitop3:0x78
	v_min_u32_e32 v14, v53, v41
	v_min_u32_e32 v22, v48, v27
	v_min_u32_e32 v16, v17, v16
	v_min_u32_e32 v10, v15, v10
	v_max_u32_e32 v23, v14, v22
	v_max_u32_e32 v15, v16, v10
	v_max_u32_e32 v17, v23, v15
	v_cmp_lt_i32_e32 vcc, -1, v17
	v_min_u32_e32 v15, v23, v15
	v_min_u32_e32 v14, v14, v22
	v_min_u32_e32 v10, v16, v10
	v_cndmask_b32_e64 v24, v86, -1, vcc
	v_cmp_lt_i32_e32 vcc, -1, v15
	v_max_u32_e32 v16, v14, v10
	v_min_u32_e32 v10, v14, v10
	v_cndmask_b32_e64 v23, v86, -1, vcc
	v_cmp_lt_i32_e32 vcc, -1, v16
	v_not_b32_e32 v30, v15
	v_bitop3_b32 v15, v23, v15, s33 bitop3:0x78
	v_cndmask_b32_e64 v22, v86, -1, vcc
	v_cmp_lt_i32_e32 vcc, -1, v10
	v_not_b32_e32 v35, v10
	v_min_u32_e32 v23, v38, v45
	v_cndmask_b32_e64 v14, v86, -1, vcc
	v_bitop3_b32 v14, v14, v10, s33 bitop3:0x78
	v_min_u32_e32 v10, v20, v47
	v_min_u32_e32 v20, v49, v36
	v_min_u32_e32 v21, v37, v21
	v_min_u32_e32 v8, v8, v9
	v_min_u32_e32 v3, v5, v3
	v_min_u32_e32 v6, v6, v7
	v_min_u32_e32 v2, v4, v2
	v_not_b32_e32 v29, v17
	v_bitop3_b32 v17, v24, v17, s33 bitop3:0x78
	v_not_b32_e32 v31, v16
	v_bitop3_b32 v16, v22, v16, s33 bitop3:0x78
	v_max_u32_e32 v22, v10, v20
	v_max_u32_e32 v24, v23, v21
	v_max_u32_e32 v5, v8, v3
	v_max_u32_e32 v4, v6, v2
	v_max_u32_e32 v25, v22, v24
	v_max_u32_e32 v7, v5, v4
	v_max_u32_e32 v9, v25, v7
	v_cmp_lt_i32_e32 vcc, -1, v9
	v_min_u32_e32 v7, v25, v7
	v_min_u32_e32 v22, v22, v24
	v_min_u32_e32 v4, v5, v4
	v_cndmask_b32_e64 v27, v86, -1, vcc
	v_cmp_lt_i32_e32 vcc, -1, v7
	v_max_u32_e32 v5, v22, v4
	v_not_b32_e32 v26, v9
	v_bitop3_b32 v9, v27, v9, s33 bitop3:0x78
	v_cndmask_b32_e64 v27, v86, -1, vcc
	v_cmp_lt_i32_e32 vcc, -1, v5
	v_min_u32_e32 v4, v22, v4
	v_not_b32_e32 v25, v7
	v_bitop3_b32 v7, v27, v7, s33 bitop3:0x78
	v_cndmask_b32_e64 v27, v86, -1, vcc
	v_cmp_lt_i32_e32 vcc, -1, v4
	v_not_b32_e32 v24, v5
	v_bitop3_b32 v27, v27, v5, s33 bitop3:0x78
	v_cndmask_b32_e64 v5, v86, -1, vcc
	v_not_b32_e32 v36, v4
	v_bitop3_b32 v22, v5, v4, s33 bitop3:0x78
	v_min_u32_e32 v4, v10, v20
	v_min_u32_e32 v5, v23, v21
	v_min_u32_e32 v3, v8, v3
	v_min_u32_e32 v2, v6, v2
	v_max_u32_e32 v10, v4, v5
	v_max_u32_e32 v6, v3, v2
	v_max_u32_e32 v8, v10, v6
	v_cmp_lt_i32_e32 vcc, -1, v8
	v_not_b32_e32 v20, v8
	v_min_u32_e32 v4, v4, v5
	v_cndmask_b32_e64 v21, v86, -1, vcc
	v_bitop3_b32 v8, v21, v8, s33 bitop3:0x78
	v_min_u32_e32 v21, v10, v6
	v_min_u32_e32 v2, v3, v2
	v_cmp_lt_i32_e32 vcc, -1, v21
	v_max_u32_e32 v37, v4, v2
	v_min_u32_e32 v39, v4, v2
	v_cndmask_b32_e64 v6, v86, -1, vcc
	v_cmp_lt_i32_e32 vcc, -1, v37
	v_and_b32_e32 v4, 0xffffff00, v13
	v_and_b32_e32 v5, 0xffffff00, v39
	v_cndmask_b32_e64 v3, v86, -1, vcc
	v_cmp_lt_i32_e32 vcc, -1, v13
	v_bitop3_b32 v38, v3, v37, s33 bitop3:0x78
	v_bitop3_b32 v23, v6, v21, s33 bitop3:0x78
	v_cndmask_b32_e64 v2, v86, -1, vcc
	v_cmp_lt_i32_e32 vcc, -1, v39
	v_xor_b32_e32 v40, v2, v4
	v_sub_f32_e32 v2, v40, v40
	v_cndmask_b32_e64 v3, v86, -1, vcc
	v_xor_b32_e32 v41, v3, v5
	v_mul_f32_e32 v2, 0x3fb8aa3b, v2
	v_sub_f32_e32 v3, v12, v40
	v_sub_f32_e32 v4, v18, v40
	v_exp_f32_e32 v2, v2
	v_mul_f32_e32 v3, 0x3fb8aa3b, v3
	v_mul_f32_e32 v4, 0x3fb8aa3b, v4
	v_exp_f32_e32 v3, v3
	v_exp_f32_e32 v10, v4
	v_sub_f32_e32 v4, v11, v40
	v_mul_f32_e32 v4, 0x3fb8aa3b, v4
	v_exp_f32_e32 v11, v4
	v_add_f32_e32 v4, 0, v2
	v_add_f32_e32 v4, v3, v4
	v_add_f32_e32 v4, v10, v4
	v_add_f32_e32 v6, v11, v4
	v_sub_f32_e32 v4, v17, v40
	v_mul_f32_e32 v4, 0x3fb8aa3b, v4
	v_sub_f32_e32 v5, v15, v40
	v_exp_f32_e32 v4, v4
	v_mul_f32_e32 v5, 0x3fb8aa3b, v5
	v_sub_f32_e32 v12, v16, v40
	v_not_b32_e32 v28, v13
	v_exp_f32_e32 v5, v5
	v_mul_f32_e32 v12, 0x3fb8aa3b, v12
	v_sub_f32_e32 v13, v14, v40
	v_exp_f32_e32 v12, v12
	v_mul_f32_e32 v13, 0x3fb8aa3b, v13
	v_exp_f32_e32 v13, v13
	v_add_f32_e32 v6, v4, v6
	v_add_f32_e32 v6, v5, v6
	v_add_f32_e32 v6, v12, v6
	v_add_f32_e32 v16, v13, v6
	v_sub_f32_e32 v6, v9, v40
	v_mul_f32_e32 v6, 0x3fb8aa3b, v6
	v_sub_f32_e32 v7, v7, v40
	v_sub_f32_e32 v9, v27, v40
	v_exp_f32_e32 v6, v6
	v_mul_f32_e32 v7, 0x3fb8aa3b, v7
	v_mul_f32_e32 v9, 0x3fb8aa3b, v9
	v_exp_f32_e32 v7, v7
	v_exp_f32_e32 v14, v9
	v_sub_f32_e32 v9, v22, v40
	v_mul_f32_e32 v9, 0x3fb8aa3b, v9
	v_exp_f32_e32 v15, v9
	v_add_f32_e32 v9, v6, v16
	v_add_f32_e32 v9, v7, v9
	v_add_f32_e32 v9, v14, v9
	v_sub_f32_e32 v8, v8, v40
	v_add_f32_e32 v18, v15, v9
	v_mul_f32_e32 v8, 0x3fb8aa3b, v8
	v_sub_f32_e32 v9, v23, v40
	v_exp_f32_e32 v8, v8
	v_mul_f32_e32 v9, 0x3fb8aa3b, v9
	v_sub_f32_e32 v16, v38, v40
	v_exp_f32_e32 v9, v9
	v_mul_f32_e32 v16, 0x3fb8aa3b, v16
	v_sub_f32_e32 v17, v41, v40
	v_exp_f32_e32 v16, v16
	v_mul_f32_e32 v17, 0x3fb8aa3b, v17
	v_exp_f32_e32 v17, v17
	v_add_f32_e32 v18, v8, v18
	v_add_f32_e32 v18, v9, v18
	v_add_f32_e32 v18, v16, v18
	v_add_f32_e32 v18, v17, v18
	v_div_scale_f32 v22, s[38:39], v18, v18, 1.0
	v_rcp_f32_e32 v23, v22
	v_not_b32_e32 v27, v37
	v_not_b32_e32 v37, v39
	v_not_b32_e32 v21, v21
	v_fma_f32 v38, -v22, v23, 1.0
	v_fmac_f32_e32 v23, v38, v23
	v_div_scale_f32 v38, vcc, 1.0, v18, 1.0
	v_mul_f32_e32 v39, v38, v23
	v_fma_f32 v40, -v22, v39, v38
	v_fmac_f32_e32 v39, v40, v23
	v_fma_f32 v22, -v22, v39, v38
	v_div_fmas_f32 v22, v22, v23, v39
	v_div_fixup_f32 v18, v22, v18, 1.0
	v_lshlrev_b32_e32 v22, 4, v37
	v_lshlrev_b32_e32 v23, 8, v37
	v_lshlrev_b32_e32 v38, 4, v27
	v_lshlrev_b32_e32 v27, 8, v27
	v_lshlrev_b32_e32 v39, 4, v21
	v_lshlrev_b32_e32 v21, 8, v21
	v_lshlrev_b32_e32 v40, 4, v20
	v_lshlrev_b32_e32 v20, 8, v20
	v_and_b32_e32 v22, 0xf00, v22
	v_and_b32_e32 v23, 0xf00, v23
	v_lshlrev_b32_e32 v37, 2, v87
	v_and_b32_e32 v38, 0xf00, v38
	v_and_b32_e32 v27, 0xf00, v27
	v_and_b32_e32 v39, 0xf00, v39
	v_and_b32_e32 v21, 0xf00, v21
	v_and_b32_e32 v40, 0xf00, v40
	v_and_b32_e32 v20, 0xf00, v20
	v_add_u32_e32 v22, v19, v22
	v_add3_u32 v23, s26, v23, v37
	v_add_u32_e32 v38, v19, v38
	v_add3_u32 v27, s26, v27, v37
	v_add_u32_e32 v39, v19, v39
	v_add3_u32 v21, s26, v21, v37
	v_add_u32_e32 v40, v19, v40
	v_add3_u32 v20, s26, v20, v37
	ds_read_b32 v22, v22
	ds_read_b32 v23, v23 offset:4096
	ds_read_b32 v38, v38
	ds_read_b32 v27, v27 offset:4096
	ds_read_b32 v39, v39
	ds_read_b32 v21, v21 offset:4096
	ds_read_b32 v40, v40
	ds_read_b32 v20, v20 offset:4096
	s_waitcnt lgkmcnt(6)
	v_lshl_add_u32 v23, v22, 7, v23
	s_waitcnt lgkmcnt(4)
	v_lshl_add_u32 v22, v38, 7, v27
	s_waitcnt lgkmcnt(2)
	v_lshl_add_u32 v21, v39, 7, v21
	v_lshlrev_b32_e32 v27, 4, v36
	v_lshlrev_b32_e32 v36, 8, v36
	v_lshlrev_b32_e32 v38, 4, v24
	v_lshlrev_b32_e32 v24, 8, v24
	v_lshlrev_b32_e32 v39, 4, v25
	v_lshlrev_b32_e32 v25, 8, v25
	v_lshlrev_b32_e32 v41, 4, v26
	v_and_b32_e32 v27, 0xf00, v27
	v_and_b32_e32 v36, 0xf00, v36
	v_and_b32_e32 v38, 0xf00, v38
	v_and_b32_e32 v24, 0xf00, v24
	v_and_b32_e32 v39, 0xf00, v39
	v_and_b32_e32 v25, 0xf00, v25
	v_and_b32_e32 v41, 0xf00, v41
	v_lshlrev_b32_e32 v26, 8, v26
	v_add_u32_e32 v27, v19, v27
	v_add3_u32 v36, s26, v36, v37
	v_add_u32_e32 v38, v19, v38
	v_add3_u32 v24, s26, v24, v37
	v_add_u32_e32 v39, v19, v39
	v_add3_u32 v25, s26, v25, v37
	v_add_u32_e32 v41, v19, v41
	v_and_b32_e32 v26, 0xf00, v26
	v_add3_u32 v26, s26, v26, v37
	ds_read_b32 v27, v27
	ds_read_b32 v36, v36 offset:4096
	ds_read_b32 v38, v38
	ds_read_b32 v24, v24 offset:4096
	ds_read_b32 v39, v39
	ds_read_b32 v25, v25 offset:4096
	ds_read_b32 v41, v41
	ds_read_b32 v42, v26 offset:4096
	s_waitcnt lgkmcnt(8)
	v_lshl_add_u32 v20, v40, 7, v20
	s_waitcnt lgkmcnt(6)
	v_lshl_add_u32 v27, v27, 7, v36
	s_waitcnt lgkmcnt(4)
	v_lshl_add_u32 v26, v38, 7, v24
	s_waitcnt lgkmcnt(2)
	v_lshl_add_u32 v25, v39, 7, v25
	v_lshlrev_b32_e32 v36, 4, v35
	v_lshlrev_b32_e32 v35, 8, v35
	v_lshlrev_b32_e32 v38, 4, v31
	v_lshlrev_b32_e32 v39, 4, v30
	v_lshlrev_b32_e32 v40, 4, v29
	v_and_b32_e32 v36, 0xf00, v36
	v_and_b32_e32 v35, 0xf00, v35
	v_and_b32_e32 v38, 0xf00, v38
	v_lshlrev_b32_e32 v31, 8, v31
	v_and_b32_e32 v39, 0xf00, v39
	v_lshlrev_b32_e32 v30, 8, v30
	v_and_b32_e32 v40, 0xf00, v40
	v_lshlrev_b32_e32 v29, 8, v29
	v_add_u32_e32 v36, v19, v36
	v_add3_u32 v35, s26, v35, v37
	v_add_u32_e32 v38, v19, v38
	v_and_b32_e32 v31, 0xf00, v31
	v_add_u32_e32 v39, v19, v39
	v_and_b32_e32 v30, 0xf00, v30
	v_add_u32_e32 v40, v19, v40
	v_and_b32_e32 v29, 0xf00, v29
	s_waitcnt lgkmcnt(0)
	v_lshl_add_u32 v24, v41, 7, v42
	v_add3_u32 v31, s26, v31, v37
	v_add3_u32 v30, s26, v30, v37
	v_add3_u32 v29, s26, v29, v37
	ds_read_b32 v36, v36
	ds_read_b32 v35, v35 offset:4096
	ds_read_b32 v38, v38
	ds_read_b32 v41, v31 offset:4096
	ds_read_b32 v39, v39
	ds_read_b32 v42, v30 offset:4096
	ds_read_b32 v40, v40
	ds_read_b32 v43, v29 offset:4096
	s_waitcnt lgkmcnt(6)
	v_lshl_add_u32 v31, v36, 7, v35
	s_waitcnt lgkmcnt(4)
	v_lshl_add_u32 v30, v38, 7, v41
	s_waitcnt lgkmcnt(2)
	v_lshl_add_u32 v29, v39, 7, v42
	v_lshlrev_b32_e32 v35, 4, v34
	v_lshlrev_b32_e32 v34, 8, v34
	v_lshlrev_b32_e32 v36, 4, v33
	v_lshlrev_b32_e32 v33, 8, v33
	v_lshlrev_b32_e32 v38, 4, v32
	v_lshlrev_b32_e32 v32, 8, v32
	v_lshlrev_b32_e32 v39, 4, v28
	v_and_b32_e32 v35, 0xf00, v35
	v_and_b32_e32 v34, 0xf00, v34
	v_and_b32_e32 v36, 0xf00, v36
	v_and_b32_e32 v33, 0xf00, v33
	v_and_b32_e32 v38, 0xf00, v38
	v_and_b32_e32 v32, 0xf00, v32
	v_and_b32_e32 v39, 0xf00, v39
	v_lshlrev_b32_e32 v28, 8, v28
	v_add_u32_e32 v35, v19, v35
	v_add3_u32 v34, s26, v34, v37
	v_add_u32_e32 v36, v19, v36
	v_add3_u32 v33, s26, v33, v37
	v_add_u32_e32 v38, v19, v38
	v_add3_u32 v32, s26, v32, v37
	v_add_u32_e32 v19, v19, v39
	v_and_b32_e32 v28, 0xf00, v28
	v_add3_u32 v28, s26, v28, v37
	ds_read_b32 v35, v35
	ds_read_b32 v34, v34 offset:4096
	ds_read_b32 v36, v36
	ds_read_b32 v33, v33 offset:4096
	ds_read_b32 v37, v38
	ds_read_b32 v32, v32 offset:4096
	ds_read_b32 v19, v19
	ds_read_b32 v38, v28 offset:4096
	s_waitcnt lgkmcnt(6)
	v_lshl_add_u32 v35, v35, 7, v34
	s_waitcnt lgkmcnt(4)
	v_lshl_add_u32 v34, v36, 7, v33
	v_or_b32_e32 v36, s36, v87
	s_waitcnt lgkmcnt(2)
	v_lshl_add_u32 v33, v37, 7, v32
	v_ashrrev_i32_e32 v37, 31, v36
	v_lshlrev_b64 v[36:37], 9, v[36:37]
	s_waitcnt lgkmcnt(0)
	v_lshl_add_u32 v32, v19, 7, v38
	v_lshl_add_u64 v[38:39], s[8:9], 0, v[36:37]
	v_lshl_add_u64 v[38:39], v[38:39], 0, s[14:15]
	v_lshl_add_u64 v[36:37], s[10:11], 0, v[36:37]
	v_lshl_add_u64 v[36:37], v[36:37], 0, s[14:15]
	global_store_dwordx4 v[38:39], v[32:35], off
	v_pk_mul_f32 v[12:13], v[12:13], v[18:19] op_sel_hi:[1,0]
	v_lshl_add_u32 v28, v40, 7, v43
	v_pk_mul_f32 v[34:35], v[10:11], v[18:19] op_sel_hi:[1,0]
	v_pk_mul_f32 v[32:33], v[2:3], v[18:19] op_sel_hi:[1,0]
	v_pk_mul_f32 v[10:11], v[4:5], v[18:19] op_sel_hi:[1,0]
	v_pk_mul_f32 v[4:5], v[14:15], v[18:19] op_sel_hi:[1,0]
	v_pk_mul_f32 v[2:3], v[6:7], v[18:19] op_sel_hi:[1,0]
	global_store_dwordx4 v[36:37], v[32:35], off
	global_store_dwordx4 v[38:39], v[28:31], off offset:16
	global_store_dwordx4 v[36:37], v[10:13], off offset:16
	global_store_dwordx4 v[38:39], v[24:27], off offset:32
	global_store_dwordx4 v[36:37], v[2:5], off offset:32
	global_store_dwordx4 v[38:39], v[20:23], off offset:48
	s_nop 0
	v_pk_mul_f32 v[4:5], v[16:17], v[18:19] op_sel_hi:[1,0]
	v_pk_mul_f32 v[2:3], v[8:9], v[18:19] op_sel_hi:[1,0]
	global_store_dwordx4 v[36:37], v[2:5], off offset:48
	s_branch .LBB0_795

.LBB0_802:
	s_barrier
	s_bitcmp1_b32 s98, 0
	s_cselect_b32 s52, s94, s92
	s_cselect_b32 s53, s95, s93
	s_cselect_b32 s54, s48, s46
	s_cselect_b32 s55, s49, s47
	s_mov_b32 s96, 0x42580000
	s_cselect_b32 s96, 0x40b66666, s96
	s_add_i32 s98, s98, 1
	v_mbcnt_lo_u32_b32 v248, -1, 0
	v_mbcnt_hi_u32_b32 v248, -1, v248
	v_lshlrev_b32_e32 v236, 6, v248
	v_mov_b32_e32 v237, 0
	v_lshl_add_u64 v[236:237], s[52:53], 0, v[236:237]
	v_lshl_add_u64 v[238:239], v[236:237], 0, v[250:251]
	v_lshlrev_b32_e32 v240, 4, v248
	v_mov_b32_e32 v241, 0
	v_lshl_add_u64 v[240:241], s[54:55], 0, v[240:241]
	s_lshr_b32 s12, s19, 3
	s_and_b32 s12, s12, 0x7fffff8
	v_mov_b32_e32 v87, v1
	s_or_b32 s12, s12, s91
	s_lshl_b32 s31, s12, 5
	v_and_b32_e32 v4, 31, v87
	v_or_b32_e32 v2, s31, v4
	v_ashrrev_i32_e32 v3, 31, v2
	v_ashrrev_i32_e32 v118, 5, v87
	v_lshlrev_b64 v[2:3], 12, v[2:3]
	v_lshl_add_u64 v[6:7], s[2:3], 0, v[2:3]
	v_lshlrev_b32_e32 v2, 3, v118
	v_ashrrev_i32_e32 v3, 31, v2
	s_bfe_u32 s30, s19, 0x30003
	v_lshlrev_b64 v[8:9], 1, v[2:3]
	v_lshlrev_b32_e32 v4, 8, v4
	v_lshl_add_u64 v[2:3], s[6:7], 0, v[8:9]
	v_lshl_or_b32 v78, s30, 16, v4
	v_lshl_add_u64 v[80:81], v[2:3], 0, v[78:79]
	global_load_dwordx4 v[2:5], v[80:81], off
	s_lshl_b32 s12, s30, 9
	v_lshl_add_u64 v[6:7], v[6:7], 0, s[12:13]
	v_lshl_add_u64 v[82:83], v[6:7], 0, v[8:9]
	global_load_dwordx4 v[34:37], v[82:83], off
	global_load_dwordx4 v[88:91], v[80:81], off offset:32
	global_load_dwordx4 v[92:95], v[80:81], off offset:64
	global_load_dwordx4 v[96:99], v[80:81], off offset:96
	global_load_dwordx4 v[100:103], v[80:81], off offset:128
	global_load_dwordx4 v[104:107], v[80:81], off offset:160
	global_load_dwordx4 v[108:111], v[80:81], off offset:192
	global_load_dwordx4 v[66:69], v[80:81], off offset:224
	global_load_dwordx4 v[62:65], v[82:83], off offset:32
	global_load_dwordx4 v[58:61], v[82:83], off offset:64
	global_load_dwordx4 v[54:57], v[82:83], off offset:96
	global_load_dwordx4 v[50:53], v[82:83], off offset:128
	global_load_dwordx4 v[46:49], v[82:83], off offset:160
	global_load_dwordx4 v[42:45], v[82:83], off offset:192
	global_load_dwordx4 v[38:41], v[82:83], off offset:224
	v_add_co_u32_e32 v116, vcc, s20, v80
	v_lshlrev_b32_e32 v146, 2, v118
	s_nop 0
	v_addc_co_u32_e32 v117, vcc, 0, v81, vcc
	global_load_dwordx4 v[6:9], v[116:117], off
	global_load_dwordx4 v[112:115], v[116:117], off offset:32
	v_add_co_u32_e32 v136, vcc, s22, v80
	v_sub_u32_e32 v78, 0x66, v146
	s_nop 0
	v_addc_co_u32_e32 v137, vcc, 0, v81, vcc
	v_sub_u32_e32 v144, 6, v146
	v_sub_u32_e32 v145, 5, v146
	s_waitcnt vmcnt(0)
	v_mfma_f32_32x32x16_bf16 v[18:33], v[2:5], v[34:37], 0
	v_mfma_f32_32x32x16_bf16 v[18:33], v[88:91], v[62:65], v[18:33]
	global_load_dwordx4 v[88:91], v[116:117], off offset:64
	v_mfma_f32_32x32x16_bf16 v[2:17], v[6:9], v[34:37], 0
	v_mfma_f32_32x32x16_bf16 v[2:17], v[112:115], v[62:65], v[2:17]
	global_load_dwordx4 v[112:115], v[116:117], off offset:160
	v_mfma_f32_32x32x16_bf16 v[18:33], v[92:95], v[58:61], v[18:33]
	global_load_dwordx4 v[92:95], v[116:117], off offset:96
	s_waitcnt vmcnt(0)
	v_mfma_f32_32x32x16_bf16 v[2:17], v[88:91], v[58:61], v[2:17]
	global_load_dwordx4 v[88:91], v[116:117], off offset:128
	v_mfma_f32_32x32x16_bf16 v[18:33], v[96:99], v[54:57], v[18:33]
	v_sub_u32_e32 v98, 0x7e, v146
	v_or_b32_e32 v99, 3, v146
	v_sub_u32_e32 v97, 0x77, v146
	v_sub_u32_e32 v96, 0x76, v146
	v_sub_u32_e32 v99, 0x7f, v99
	v_mfma_f32_32x32x16_bf16 v[18:33], v[100:103], v[50:53], v[18:33]
	v_sub_u32_e32 v100, 0x7f, v146
	v_mfma_f32_32x32x16_bf16 v[18:33], v[104:107], v[46:49], v[18:33]
	v_mfma_f32_32x32x16_bf16 v[18:33], v[108:111], v[42:45], v[18:33]
	global_load_dwordx4 v[104:107], v[116:117], off offset:192
	global_load_dwordx4 v[108:111], v[116:117], off offset:224
	v_mfma_f32_32x32x16_bf16 v[2:17], v[92:95], v[54:57], v[2:17]
	v_sub_u32_e32 v95, 0x75, v146
	v_sub_u32_e32 v94, 0x74, v146
	v_sub_u32_e32 v93, 0x6f, v146
	v_sub_u32_e32 v92, 0x6e, v146
	v_mfma_f32_32x32x16_bf16 v[18:33], v[66:69], v[38:41], v[18:33]
	s_waitcnt vmcnt(0)
	v_mfma_f32_32x32x16_bf16 v[2:17], v[88:91], v[50:53], v[2:17]
	s_nop 9
	v_not_b32_e32 v66, v18
	v_or_b32_e32 v67, 0x80000000, v18
	v_cmp_gt_i32_e32 vcc, 0, v18
	v_or_b32_e32 v91, 2, v146
	v_not_b32_e32 v68, v19
	v_or_b32_e32 v69, 0x80000000, v19
	v_cndmask_b32_e32 v18, v67, v66, vcc
	v_mfma_f32_32x32x16_bf16 v[2:17], v[112:115], v[46:49], v[2:17]
	global_load_dwordx4 v[112:115], v[136:137], off
	v_cmp_gt_i32_e32 vcc, 0, v19
	v_sub_u32_e32 v101, 0x7f, v91
	v_not_b32_e32 v91, v20
	v_or_b32_e32 v102, 0x80000000, v20
	v_cndmask_b32_e32 v19, v69, v68, vcc
	v_cmp_gt_i32_e32 vcc, 0, v20
	v_not_b32_e32 v103, v21
	v_or_b32_e32 v116, 0x80000000, v21
	v_cndmask_b32_e32 v20, v102, v91, vcc
	v_cmp_gt_i32_e32 vcc, 0, v21
	v_not_b32_e32 v117, v22
	v_or_b32_e32 v118, 0x80000000, v22
	v_cndmask_b32_e32 v21, v116, v103, vcc
	v_cmp_gt_i32_e32 vcc, 0, v22
	v_not_b32_e32 v119, v23
	v_or_b32_e32 v120, 0x80000000, v23
	v_cndmask_b32_e32 v22, v118, v117, vcc
	v_cmp_gt_i32_e32 vcc, 0, v23
	v_not_b32_e32 v121, v24
	v_or_b32_e32 v122, 0x80000000, v24
	v_cndmask_b32_e32 v23, v120, v119, vcc
	global_load_dwordx4 v[116:119], v[136:137], off offset:32
	v_cmp_gt_i32_e32 vcc, 0, v24
	v_not_b32_e32 v123, v25
	v_or_b32_e32 v124, 0x80000000, v25
	v_cndmask_b32_e32 v24, v122, v121, vcc
	v_cmp_gt_i32_e32 vcc, 0, v25
	v_not_b32_e32 v125, v26
	v_or_b32_e32 v126, 0x80000000, v26
	v_cndmask_b32_e32 v25, v124, v123, vcc
	global_load_dwordx4 v[120:123], v[136:137], off offset:64
	v_cmp_gt_i32_e32 vcc, 0, v26
	v_not_b32_e32 v127, v27
	v_or_b32_e32 v128, 0x80000000, v27
	v_cndmask_b32_e32 v26, v126, v125, vcc
	v_cmp_gt_i32_e32 vcc, 0, v27
	v_mfma_f32_32x32x16_bf16 v[2:17], v[104:107], v[42:45], v[2:17]
	v_not_b32_e32 v129, v28
	v_cndmask_b32_e32 v27, v128, v127, vcc
	global_load_dwordx4 v[124:127], v[136:137], off offset:96
	v_or_b32_e32 v130, 0x80000000, v28
	v_cmp_gt_i32_e32 vcc, 0, v28
	v_not_b32_e32 v131, v29
	v_or_b32_e32 v132, 0x80000000, v29
	v_cndmask_b32_e32 v28, v130, v129, vcc
	v_cmp_gt_i32_e32 vcc, 0, v29
	v_mfma_f32_32x32x16_bf16 v[2:17], v[108:111], v[38:41], v[2:17]
	v_not_b32_e32 v133, v30
	v_cndmask_b32_e32 v29, v132, v131, vcc
	global_load_dwordx4 v[128:131], v[136:137], off offset:128
	v_or_b32_e32 v134, 0x80000000, v30
	v_cmp_gt_i32_e32 vcc, 0, v30
	v_not_b32_e32 v135, v31
	v_or_b32_e32 v138, 0x80000000, v31
	v_cndmask_b32_e32 v30, v134, v133, vcc
	v_cmp_gt_i32_e32 vcc, 0, v31
	v_and_or_b32 v159, v18, s17, v100
	v_and_or_b32 v168, v19, s17, v98
	v_cndmask_b32_e32 v31, v138, v135, vcc
	v_not_b32_e32 v18, v32
	v_or_b32_e32 v19, 0x80000000, v32
	v_cmp_gt_i32_e32 vcc, 0, v32
	v_sub_u32_e32 v102, 0x65, v146
	v_sub_u32_e32 v103, 0x64, v146
	v_cndmask_b32_e32 v18, v19, v18, vcc
	v_and_or_b32 v181, v18, s17, v102
	v_not_b32_e32 v18, v33
	v_or_b32_e32 v19, 0x80000000, v33
	v_cmp_gt_i32_e32 vcc, 0, v33
	global_load_dwordx4 v[132:135], v[136:137], off offset:160
	v_sub_u32_e32 v104, 0x5f, v146
	v_cndmask_b32_e32 v18, v19, v18, vcc
	v_and_or_b32 v182, v18, s17, v103
	v_not_b32_e32 v18, v2
	v_or_b32_e32 v19, 0x80000000, v2
	v_cmp_gt_i32_e32 vcc, 0, v2
	v_sub_u32_e32 v105, 0x5e, v146
	v_sub_u32_e32 v107, 0x5d, v146
	v_cndmask_b32_e32 v2, v19, v18, vcc
	v_and_or_b32 v147, v2, s17, v104
	v_not_b32_e32 v2, v3
	v_or_b32_e32 v18, 0x80000000, v3
	v_cmp_gt_i32_e32 vcc, 0, v3
	v_or_b32_e32 v3, 0x80000000, v4
	v_sub_u32_e32 v106, 0x5c, v146
	v_cndmask_b32_e32 v2, v18, v2, vcc
	v_and_or_b32 v148, v2, s17, v105
	v_not_b32_e32 v2, v4
	v_cmp_gt_i32_e32 vcc, 0, v4
	v_or_b32_e32 v19, 0x80000000, v6
	v_sub_u32_e32 v108, 0x57, v146
	v_cndmask_b32_e32 v2, v3, v2, vcc
	v_and_or_b32 v149, v2, s17, v107
	v_not_b32_e32 v2, v5
	v_or_b32_e32 v3, 0x80000000, v5
	v_cmp_gt_i32_e32 vcc, 0, v5
	v_sub_u32_e32 v90, 0x6d, v146
	v_sub_u32_e32 v89, 0x6c, v146
	v_cndmask_b32_e32 v18, v3, v2, vcc
	global_load_dwordx4 v[2:5], v[136:137], off offset:192
	v_and_or_b32 v150, v18, s17, v106
	global_load_dwordx4 v[136:139], v[136:137], off offset:224
	v_not_b32_e32 v18, v6
	v_cmp_gt_i32_e32 vcc, 0, v6
	v_sub_u32_e32 v88, 0x67, v146
	v_and_or_b32 v169, v20, s17, v101
	v_cndmask_b32_e32 v6, v19, v18, vcc
	v_and_or_b32 v151, v6, s17, v108
	v_not_b32_e32 v6, v7
	v_or_b32_e32 v18, 0x80000000, v7
	v_cmp_gt_i32_e32 vcc, 0, v7
	v_and_or_b32 v170, v21, s17, v99
	v_and_or_b32 v171, v22, s17, v97
	v_and_or_b32 v172, v23, s17, v96
	v_and_or_b32 v173, v24, s17, v95
	v_and_or_b32 v174, v25, s17, v94
	v_and_or_b32 v175, v26, s17, v93
	v_and_or_b32 v176, v27, s17, v92
	v_and_or_b32 v177, v28, s17, v90
	v_and_or_b32 v178, v29, s17, v89
	v_and_or_b32 v179, v30, s17, v88
	v_and_or_b32 v180, v31, s17, v78
	v_cndmask_b32_e32 v6, v18, v6, vcc
	v_sub_u32_e32 v109, 0x56, v146
	s_waitcnt vmcnt(0)
	v_mfma_f32_32x32x16_bf16 v[18:33], v[112:115], v[34:37], 0
	v_and_or_b32 v152, v6, s17, v109
	v_not_b32_e32 v6, v8
	v_or_b32_e32 v7, 0x80000000, v8
	v_cmp_gt_i32_e32 vcc, 0, v8
	v_sub_u32_e32 v110, 0x55, v146
	v_sub_u32_e32 v111, 0x54, v146
	v_cndmask_b32_e32 v6, v7, v6, vcc
	v_and_or_b32 v153, v6, s17, v110
	v_not_b32_e32 v6, v9
	v_or_b32_e32 v7, 0x80000000, v9
	v_cmp_gt_i32_e32 vcc, 0, v9
	v_sub_u32_e32 v68, 0x4f, v146
	v_sub_u32_e32 v91, 0x4e, v146
	v_cndmask_b32_e32 v6, v7, v6, vcc
	v_and_or_b32 v154, v6, s17, v111
	v_not_b32_e32 v6, v10
	v_or_b32_e32 v7, 0x80000000, v10
	v_cmp_gt_i32_e32 vcc, 0, v10
	v_mfma_f32_32x32x16_bf16 v[18:33], v[116:119], v[62:65], v[18:33]
	v_sub_u32_e32 v69, 0x4d, v146
	v_cndmask_b32_e32 v6, v7, v6, vcc
	v_and_or_b32 v155, v6, s17, v68
	v_not_b32_e32 v6, v11
	v_or_b32_e32 v7, 0x80000000, v11
	v_cmp_gt_i32_e32 vcc, 0, v11
	v_sub_u32_e32 v67, 0x4c, v146
	v_mfma_f32_32x32x16_bf16 v[18:33], v[120:123], v[58:61], v[18:33]
	v_cndmask_b32_e32 v6, v7, v6, vcc
	v_and_or_b32 v156, v6, s17, v91
	v_not_b32_e32 v6, v12
	v_or_b32_e32 v7, 0x80000000, v12
	v_cmp_gt_i32_e32 vcc, 0, v12
	v_sub_u32_e32 v66, 0x47, v146
	v_sub_u32_e32 v112, 0x46, v146
	v_cndmask_b32_e32 v6, v7, v6, vcc
	v_and_or_b32 v157, v6, s17, v69
	v_not_b32_e32 v6, v13
	v_or_b32_e32 v7, 0x80000000, v13
	v_cmp_gt_i32_e32 vcc, 0, v13
	v_mfma_f32_32x32x16_bf16 v[18:33], v[124:127], v[54:57], v[18:33]
	v_or_b32_e32 v13, 0x80000000, v15
	v_cndmask_b32_e32 v6, v7, v6, vcc
	v_and_or_b32 v158, v6, s17, v67
	v_not_b32_e32 v6, v14
	v_or_b32_e32 v7, 0x80000000, v14
	v_cmp_gt_i32_e32 vcc, 0, v14
	v_sub_u32_e32 v113, 0x45, v146
	v_mfma_f32_32x32x16_bf16 v[18:33], v[128:131], v[50:53], v[18:33]
	v_cndmask_b32_e32 v12, v7, v6, vcc
	v_add_co_u32_e32 v10, vcc, s23, v80
	v_and_or_b32 v183, v12, s17, v66
	s_nop 0
	v_addc_co_u32_e32 v11, vcc, 0, v81, vcc
	global_load_dwordx4 v[6:9], v[10:11], off
	global_load_dwordx4 v[124:127], v[10:11], off offset:32
	global_load_dwordx4 v[128:131], v[10:11], off offset:64
	v_mfma_f32_32x32x16_bf16 v[18:33], v[132:135], v[46:49], v[18:33]
	global_load_dwordx4 v[132:135], v[10:11], off offset:96
	global_load_dwordx4 v[140:143], v[10:11], off offset:128
	global_load_dwordx4 v[160:163], v[10:11], off offset:192
	global_load_dwordx4 v[164:167], v[10:11], off offset:224
	v_not_b32_e32 v12, v15
	v_cmp_gt_i32_e32 vcc, 0, v15
	v_sub_u32_e32 v114, 0x44, v146
	v_mfma_f32_32x32x16_bf16 v[18:33], v[2:5], v[42:45], v[18:33]
	v_cndmask_b32_e32 v12, v13, v12, vcc
	v_and_or_b32 v184, v12, s17, v112
	v_not_b32_e32 v12, v16
	v_or_b32_e32 v13, 0x80000000, v16
	v_cmp_gt_i32_e32 vcc, 0, v16
	v_or_b32_e32 v2, 0x80000000, v17
	v_sub_u32_e32 v115, 63, v146
	v_mfma_f32_32x32x16_bf16 v[18:33], v[136:139], v[38:41], v[18:33]
	global_load_dwordx4 v[136:139], v[10:11], off offset:160
	v_cndmask_b32_e32 v12, v13, v12, vcc
	v_and_or_b32 v185, v12, s17, v113
	v_not_b32_e32 v12, v17
	v_cmp_gt_i32_e32 vcc, 0, v17
	v_sub_u32_e32 v116, 62, v146
	v_sub_u32_e32 v117, 61, v146
	v_cndmask_b32_e32 v2, v2, v12, vcc
	v_and_or_b32 v186, v2, s17, v114
	s_nop 2
	v_not_b32_e32 v2, v18
	v_or_b32_e32 v3, 0x80000000, v18
	v_cmp_gt_i32_e32 vcc, 0, v18
	v_sub_u32_e32 v118, 60, v146
	v_sub_u32_e32 v119, 55, v146
	v_cndmask_b32_e32 v2, v3, v2, vcc
	v_and_or_b32 v18, v2, s17, v115
	v_not_b32_e32 v2, v19
	v_or_b32_e32 v3, 0x80000000, v19
	v_cmp_gt_i32_e32 vcc, 0, v19
	v_sub_u32_e32 v120, 54, v146
	v_sub_u32_e32 v121, 53, v146
	v_cndmask_b32_e32 v2, v3, v2, vcc
	v_and_or_b32 v19, v2, s17, v116
	v_not_b32_e32 v2, v20
	v_or_b32_e32 v3, 0x80000000, v20
	v_cmp_gt_i32_e32 vcc, 0, v20
	v_sub_u32_e32 v122, 52, v146
	v_sub_u32_e32 v123, 47, v146
	v_cndmask_b32_e32 v2, v3, v2, vcc
	v_and_or_b32 v20, v2, s17, v117
	v_not_b32_e32 v2, v21
	v_or_b32_e32 v3, 0x80000000, v21
	v_cmp_gt_i32_e32 vcc, 0, v21
	s_nop 1
	v_cndmask_b32_e32 v2, v3, v2, vcc
	v_and_or_b32 v21, v2, s17, v118
	v_not_b32_e32 v2, v22
	v_or_b32_e32 v3, 0x80000000, v22
	v_cmp_gt_i32_e32 vcc, 0, v22
	s_nop 1
	v_cndmask_b32_e32 v2, v3, v2, vcc
	v_and_or_b32 v22, v2, s17, v119
	v_not_b32_e32 v2, v23
	v_or_b32_e32 v3, 0x80000000, v23
	v_cmp_gt_i32_e32 vcc, 0, v23
	s_nop 1
	v_cndmask_b32_e32 v2, v3, v2, vcc
	v_and_or_b32 v23, v2, s17, v120
	v_not_b32_e32 v2, v24
	v_or_b32_e32 v3, 0x80000000, v24
	v_cmp_gt_i32_e32 vcc, 0, v24
	s_nop 1
	v_cndmask_b32_e32 v2, v3, v2, vcc
	v_and_or_b32 v24, v2, s17, v121
	v_not_b32_e32 v2, v25
	v_or_b32_e32 v3, 0x80000000, v25
	v_cmp_gt_i32_e32 vcc, 0, v25
	s_nop 1
	v_cndmask_b32_e32 v25, v3, v2, vcc
	s_waitcnt vmcnt(0)
	v_mfma_f32_32x32x16_bf16 v[2:17], v[6:9], v[34:37], 0
	v_not_b32_e32 v34, v26
	v_or_b32_e32 v35, 0x80000000, v26
	v_cmp_gt_i32_e32 vcc, 0, v26
	v_and_or_b32 v25, v25, s17, v122
	v_max_u32_e32 v36, v169, v170
	v_cndmask_b32_e32 v26, v35, v34, vcc
	v_not_b32_e32 v34, v27
	v_mfma_f32_32x32x16_bf16 v[2:17], v[124:127], v[62:65], v[2:17]
	v_or_b32_e32 v35, 0x80000000, v27
	v_cmp_gt_i32_e32 vcc, 0, v27
	v_sub_u32_e32 v124, 46, v146
	v_sub_u32_e32 v125, 45, v146
	v_cndmask_b32_e32 v27, v35, v34, vcc
	v_not_b32_e32 v34, v28
	v_or_b32_e32 v35, 0x80000000, v28
	v_mfma_f32_32x32x16_bf16 v[2:17], v[128:131], v[58:61], v[2:17]
	v_cmp_gt_i32_e32 vcc, 0, v28
	v_sub_u32_e32 v126, 44, v146
	v_sub_u32_e32 v127, 39, v146
	v_cndmask_b32_e32 v28, v35, v34, vcc
	v_not_b32_e32 v34, v29
	v_or_b32_e32 v35, 0x80000000, v29
	v_cmp_gt_i32_e32 vcc, 0, v29
	v_mfma_f32_32x32x16_bf16 v[2:17], v[132:135], v[54:57], v[2:17]
	v_sub_u32_e32 v128, 38, v146
	v_cndmask_b32_e32 v29, v35, v34, vcc
	v_not_b32_e32 v34, v30
	v_or_b32_e32 v35, 0x80000000, v30
	v_cmp_gt_i32_e32 vcc, 0, v30
	v_sub_u32_e32 v129, 37, v146
	v_sub_u32_e32 v130, 36, v146
	v_mfma_f32_32x32x16_bf16 v[2:17], v[140:143], v[50:53], v[2:17]
	v_cndmask_b32_e32 v30, v35, v34, vcc
	v_not_b32_e32 v34, v31
	v_or_b32_e32 v35, 0x80000000, v31
	v_cmp_gt_i32_e32 vcc, 0, v31
	v_sub_u32_e32 v131, 31, v146
	v_sub_u32_e32 v132, 30, v146
	v_cndmask_b32_e32 v31, v35, v34, vcc
	v_mfma_f32_32x32x16_bf16 v[2:17], v[136:139], v[46:49], v[2:17]
	v_not_b32_e32 v34, v32
	v_or_b32_e32 v35, 0x80000000, v32
	v_cmp_gt_i32_e32 vcc, 0, v32
	v_sub_u32_e32 v133, 29, v146
	v_sub_u32_e32 v134, 28, v146
	v_cndmask_b32_e32 v32, v35, v34, vcc
	v_not_b32_e32 v34, v33
	v_mfma_f32_32x32x16_bf16 v[2:17], v[160:163], v[42:45], v[2:17]
	v_or_b32_e32 v35, 0x80000000, v33
	v_cmp_gt_i32_e32 vcc, 0, v33
	v_sub_u32_e32 v135, 23, v146
	v_sub_u32_e32 v136, 22, v146
	v_cndmask_b32_e32 v33, v35, v34, vcc
	v_sub_u32_e32 v137, 21, v146
	v_sub_u32_e32 v138, 20, v146
	v_mfma_f32_32x32x16_bf16 v[2:17], v[164:167], v[38:41], v[2:17]
	v_sub_u32_e32 v139, 15, v146
	v_sub_u32_e32 v140, 14, v146
	v_sub_u32_e32 v141, 13, v146
	v_sub_u32_e32 v142, 12, v146
	v_sub_u32_e32 v143, 7, v146
	v_sub_u32_e32 v146, 4, v146
	v_and_or_b32 v26, v26, s17, v123
	s_nop 4
	v_not_b32_e32 v34, v2
	v_or_b32_e32 v35, 0x80000000, v2
	v_cmp_gt_i32_e32 vcc, 0, v2
	v_and_or_b32 v27, v27, s17, v124
	global_load_dwordx4 v[200:203], v[236:237], off
	global_load_dwordx4 v[204:207], v[236:237], off offset:16
	global_load_dwordx4 v[208:211], v[236:237], off offset:32
	global_load_dwordx4 v[212:215], v[236:237], off offset:48
	global_load_dwordx4 v[216:219], v[238:239], off
	global_load_dwordx4 v[220:223], v[238:239], off offset:16
	global_load_dwordx4 v[224:227], v[238:239], off offset:32
	global_load_dwordx4 v[228:231], v[238:239], off offset:48
	v_lshl_add_u64 v[236:237], v[236:237], 0, v[244:245]
	v_lshl_add_u64 v[238:239], v[238:239], 0, v[244:245]
	v_and_or_b32 v28, v28, s17, v125
	v_cndmask_b32_e32 v2, v35, v34, vcc
	v_not_b32_e32 v34, v3
	v_or_b32_e32 v35, 0x80000000, v3
	v_cmp_gt_i32_e32 vcc, 0, v3
	v_and_or_b32 v29, v29, s17, v126
	v_and_or_b32 v30, v30, s17, v127
	v_cndmask_b32_e32 v3, v35, v34, vcc
	v_not_b32_e32 v34, v4
	v_or_b32_e32 v35, 0x80000000, v4
	v_cmp_gt_i32_e32 vcc, 0, v4
	v_and_or_b32 v31, v31, s17, v128
	v_and_or_b32 v32, v32, s17, v129
	v_cndmask_b32_e32 v4, v35, v34, vcc
	v_not_b32_e32 v34, v5
	v_or_b32_e32 v35, 0x80000000, v5
	v_cmp_gt_i32_e32 vcc, 0, v5
	v_and_or_b32 v33, v33, s17, v130
	v_and_or_b32 v2, v2, s17, v131
	v_cndmask_b32_e32 v5, v35, v34, vcc
	v_not_b32_e32 v34, v6
	v_or_b32_e32 v35, 0x80000000, v6
	v_cmp_gt_i32_e32 vcc, 0, v6
	v_and_or_b32 v3, v3, s17, v132
	v_and_or_b32 v4, v4, s17, v133
	v_cndmask_b32_e32 v6, v35, v34, vcc
	v_not_b32_e32 v34, v7
	v_or_b32_e32 v35, 0x80000000, v7
	v_cmp_gt_i32_e32 vcc, 0, v7
	v_and_or_b32 v5, v5, s17, v134
	v_and_or_b32 v6, v6, s17, v135
	v_cndmask_b32_e32 v7, v35, v34, vcc
	v_not_b32_e32 v34, v8
	v_or_b32_e32 v35, 0x80000000, v8
	v_cmp_gt_i32_e32 vcc, 0, v8
	v_and_or_b32 v7, v7, s17, v136
	v_min_u32_e32 v37, v169, v170
	v_cndmask_b32_e32 v8, v35, v34, vcc
	v_not_b32_e32 v34, v9
	v_or_b32_e32 v35, 0x80000000, v9
	v_cmp_gt_i32_e32 vcc, 0, v9
	v_and_or_b32 v8, v8, s17, v137
	v_max_u32_e32 v38, v171, v172
	v_cndmask_b32_e32 v9, v35, v34, vcc
	v_not_b32_e32 v34, v10
	v_or_b32_e32 v35, 0x80000000, v10
	v_cmp_gt_i32_e32 vcc, 0, v10
	v_and_or_b32 v9, v9, s17, v138
	v_min_u32_e32 v39, v171, v172
	v_cndmask_b32_e32 v10, v35, v34, vcc
	v_not_b32_e32 v34, v11
	v_or_b32_e32 v35, 0x80000000, v11
	v_cmp_gt_i32_e32 vcc, 0, v11
	v_and_or_b32 v10, v10, s17, v139
	v_max_u32_e32 v40, v173, v174
	v_cndmask_b32_e32 v11, v35, v34, vcc
	v_not_b32_e32 v34, v12
	v_or_b32_e32 v35, 0x80000000, v12
	v_cmp_gt_i32_e32 vcc, 0, v12
	v_and_or_b32 v11, v11, s17, v140
	v_min_u32_e32 v41, v173, v174
	v_cndmask_b32_e32 v12, v35, v34, vcc
	v_not_b32_e32 v34, v13
	v_or_b32_e32 v35, 0x80000000, v13
	v_cmp_gt_i32_e32 vcc, 0, v13
	v_and_or_b32 v12, v12, s17, v141
	v_max_u32_e32 v42, v175, v176
	v_cndmask_b32_e32 v13, v35, v34, vcc
	v_not_b32_e32 v34, v14
	v_or_b32_e32 v35, 0x80000000, v14
	v_cmp_gt_i32_e32 vcc, 0, v14
	v_and_or_b32 v13, v13, s17, v142
	v_min_u32_e32 v43, v175, v176
	v_cndmask_b32_e32 v14, v35, v34, vcc
	v_not_b32_e32 v34, v15
	v_or_b32_e32 v35, 0x80000000, v15
	v_cmp_gt_i32_e32 vcc, 0, v15
	v_and_or_b32 v14, v14, s17, v143
	v_max_u32_e32 v44, v177, v178
	v_cndmask_b32_e32 v15, v35, v34, vcc
	v_not_b32_e32 v34, v16
	v_or_b32_e32 v35, 0x80000000, v16
	v_cmp_gt_i32_e32 vcc, 0, v16
	v_and_or_b32 v15, v15, s17, v144
	v_min_u32_e32 v45, v177, v178
	v_cndmask_b32_e32 v16, v35, v34, vcc
	v_not_b32_e32 v34, v17
	v_or_b32_e32 v35, 0x80000000, v17
	v_cmp_gt_i32_e32 vcc, 0, v17
	v_and_or_b32 v16, v16, s17, v145
	v_max_u32_e32 v46, v179, v180
	v_cndmask_b32_e32 v17, v35, v34, vcc
	v_and_or_b32 v17, v17, s17, v146
	v_max_u32_e32 v34, v159, v168
	v_min_u32_e32 v35, v159, v168
	v_min_u32_e32 v47, v179, v180
	v_max_u32_e32 v48, v181, v182
	v_min_u32_e32 v49, v181, v182
	v_max_u32_e32 v58, v147, v148
	v_min_u32_e32 v59, v147, v148
	v_max_u32_e32 v60, v149, v150
	v_min_u32_e32 v61, v149, v150
	v_max_u32_e32 v62, v151, v152
	v_min_u32_e32 v63, v151, v152
	v_max_u32_e32 v64, v153, v154
	v_min_u32_e32 v65, v153, v154
	v_max_u32_e32 v147, v155, v156
	v_min_u32_e32 v148, v155, v156
	v_max_u32_e32 v149, v157, v158
	v_min_u32_e32 v150, v157, v158
	v_max_u32_e32 v151, v183, v184
	v_min_u32_e32 v152, v183, v184
	v_max_u32_e32 v153, v185, v186
	v_min_u32_e32 v154, v185, v186
	v_max_u32_e32 v163, v18, v19
	v_min_u32_e32 v18, v18, v19
	v_max_u32_e32 v19, v20, v21
	v_min_u32_e32 v20, v20, v21
	v_max_u32_e32 v21, v22, v23
	v_min_u32_e32 v22, v22, v23
	v_max_u32_e32 v23, v24, v25
	v_min_u32_e32 v24, v24, v25
	v_max_u32_e32 v25, v26, v27
	v_min_u32_e32 v26, v26, v27
	v_max_u32_e32 v27, v28, v29
	v_min_u32_e32 v28, v28, v29
	v_max_u32_e32 v29, v30, v31
	v_min_u32_e32 v30, v30, v31
	v_max_u32_e32 v31, v32, v33
	v_min_u32_e32 v32, v32, v33
	v_max_u32_e32 v171, v2, v3
	v_min_u32_e32 v2, v2, v3
	v_max_u32_e32 v3, v4, v5
	v_min_u32_e32 v4, v4, v5
	v_max_u32_e32 v5, v6, v7
	v_min_u32_e32 v6, v6, v7
	v_max_u32_e32 v7, v8, v9
	v_min_u32_e32 v8, v8, v9
	v_max_u32_e32 v9, v10, v11
	v_min_u32_e32 v10, v10, v11
	v_max_u32_e32 v11, v12, v13
	v_min_u32_e32 v12, v12, v13
	v_max_u32_e32 v13, v14, v15
	v_min_u32_e32 v14, v14, v15
	v_max_u32_e32 v15, v16, v17
	v_min_u32_e32 v16, v16, v17
	v_max_u32_e32 v50, v34, v37
	v_min_u32_e32 v34, v34, v37
	v_max_u32_e32 v37, v35, v36
	v_min_u32_e32 v35, v35, v36
	v_max_u32_e32 v36, v38, v41
	v_min_u32_e32 v38, v38, v41
	v_max_u32_e32 v41, v39, v40
	v_min_u32_e32 v39, v39, v40
	v_max_u32_e32 v40, v42, v45
	v_min_u32_e32 v42, v42, v45
	v_max_u32_e32 v45, v43, v44
	v_min_u32_e32 v43, v43, v44
	v_max_u32_e32 v44, v46, v49
	v_min_u32_e32 v46, v46, v49
	v_max_u32_e32 v49, v47, v48
	v_min_u32_e32 v47, v47, v48
	v_max_u32_e32 v155, v58, v61
	v_min_u32_e32 v58, v58, v61
	v_max_u32_e32 v61, v59, v60
	v_min_u32_e32 v59, v59, v60
	v_max_u32_e32 v60, v62, v65
	v_min_u32_e32 v62, v62, v65
	v_max_u32_e32 v65, v63, v64
	v_min_u32_e32 v63, v63, v64
	v_max_u32_e32 v64, v147, v150
	v_min_u32_e32 v147, v147, v150
	v_max_u32_e32 v150, v148, v149
	v_min_u32_e32 v148, v148, v149
	v_max_u32_e32 v149, v151, v154
	v_min_u32_e32 v151, v151, v154
	v_max_u32_e32 v154, v152, v153
	v_min_u32_e32 v152, v152, v153
	v_max_u32_e32 v33, v163, v20
	v_min_u32_e32 v20, v163, v20
	v_max_u32_e32 v163, v18, v19
	v_min_u32_e32 v18, v18, v19
	v_max_u32_e32 v19, v21, v24
	v_min_u32_e32 v21, v21, v24
	v_max_u32_e32 v24, v22, v23
	v_min_u32_e32 v22, v22, v23
	v_max_u32_e32 v23, v25, v28
	v_min_u32_e32 v25, v25, v28
	v_max_u32_e32 v28, v26, v27
	v_min_u32_e32 v26, v26, v27
	v_max_u32_e32 v27, v29, v32
	v_min_u32_e32 v29, v29, v32
	v_max_u32_e32 v32, v30, v31
	v_min_u32_e32 v30, v30, v31
	v_max_u32_e32 v17, v171, v4
	v_min_u32_e32 v4, v171, v4
	v_max_u32_e32 v171, v2, v3
	v_min_u32_e32 v2, v2, v3
	v_max_u32_e32 v3, v5, v8
	v_min_u32_e32 v5, v5, v8
	v_max_u32_e32 v8, v6, v7
	v_min_u32_e32 v6, v6, v7
	v_max_u32_e32 v7, v9, v12
	v_min_u32_e32 v9, v9, v12
	v_max_u32_e32 v12, v10, v11
	v_min_u32_e32 v10, v10, v11
	v_max_u32_e32 v11, v13, v16
	v_min_u32_e32 v13, v13, v16
	v_max_u32_e32 v16, v14, v15
	v_min_u32_e32 v14, v14, v15
	v_max_u32_e32 v48, v50, v37
	v_min_u32_e32 v37, v50, v37
	v_max_u32_e32 v50, v34, v35
	v_min_u32_e32 v34, v34, v35
	v_max_u32_e32 v35, v38, v39
	v_min_u32_e32 v38, v38, v39
	v_max_u32_e32 v39, v36, v41
	v_min_u32_e32 v36, v36, v41
	v_max_u32_e32 v41, v40, v45
	v_min_u32_e32 v40, v40, v45
	v_max_u32_e32 v45, v42, v43
	v_min_u32_e32 v42, v42, v43
	v_max_u32_e32 v43, v46, v47
	v_min_u32_e32 v46, v46, v47
	v_max_u32_e32 v47, v44, v49
	v_min_u32_e32 v44, v44, v49
	v_max_u32_e32 v153, v155, v61
	v_min_u32_e32 v61, v155, v61
	v_max_u32_e32 v155, v58, v59
	v_min_u32_e32 v58, v58, v59
	v_max_u32_e32 v59, v62, v63
	v_min_u32_e32 v62, v62, v63
	v_max_u32_e32 v63, v60, v65
	v_min_u32_e32 v60, v60, v65
	v_max_u32_e32 v65, v64, v150
	v_min_u32_e32 v64, v64, v150
	v_max_u32_e32 v150, v147, v148
	v_min_u32_e32 v147, v147, v148
	v_max_u32_e32 v148, v151, v152
	v_min_u32_e32 v151, v151, v152
	v_max_u32_e32 v152, v149, v154
	v_min_u32_e32 v149, v149, v154
	v_max_u32_e32 v31, v33, v163
	v_min_u32_e32 v33, v33, v163
	v_max_u32_e32 v163, v20, v18
	v_min_u32_e32 v18, v20, v18
	v_max_u32_e32 v20, v21, v22
	v_min_u32_e32 v21, v21, v22
	v_max_u32_e32 v22, v19, v24
	v_min_u32_e32 v19, v19, v24
	v_max_u32_e32 v24, v23, v28
	v_min_u32_e32 v23, v23, v28
	v_max_u32_e32 v28, v25, v26
	v_min_u32_e32 v25, v25, v26
	v_max_u32_e32 v26, v29, v30
	v_min_u32_e32 v29, v29, v30
	v_max_u32_e32 v30, v27, v32
	v_min_u32_e32 v27, v27, v32
	v_max_u32_e32 v15, v17, v171
	v_min_u32_e32 v17, v17, v171
	v_max_u32_e32 v171, v4, v2
	v_min_u32_e32 v2, v4, v2
	v_max_u32_e32 v4, v5, v6
	v_min_u32_e32 v5, v5, v6
	v_max_u32_e32 v6, v3, v8
	v_min_u32_e32 v3, v3, v8
	v_max_u32_e32 v8, v7, v12
	v_min_u32_e32 v7, v7, v12
	v_max_u32_e32 v12, v9, v10
	v_min_u32_e32 v9, v9, v10
	v_max_u32_e32 v10, v13, v14
	v_min_u32_e32 v13, v13, v14
	v_max_u32_e32 v14, v11, v16
	v_min_u32_e32 v11, v11, v16
	v_max_u32_e32 v49, v48, v38
	v_min_u32_e32 v38, v48, v38
	v_max_u32_e32 v48, v37, v35
	v_min_u32_e32 v35, v37, v35
	v_max_u32_e32 v37, v50, v36
	v_min_u32_e32 v36, v50, v36
	v_max_u32_e32 v50, v34, v39
	v_min_u32_e32 v34, v34, v39
	v_max_u32_e32 v39, v41, v46
	v_min_u32_e32 v41, v41, v46
	v_max_u32_e32 v46, v40, v43
	v_min_u32_e32 v40, v40, v43
	v_max_u32_e32 v43, v45, v44
	v_min_u32_e32 v44, v45, v44
	v_max_u32_e32 v45, v42, v47
	v_min_u32_e32 v42, v42, v47
	v_max_u32_e32 v154, v153, v62
	v_min_u32_e32 v62, v153, v62
	v_max_u32_e32 v153, v61, v59
	s_waitcnt vmcnt(0)
	v_pk_mul_f32 v[200:201], v[200:201], s[96:97] op_sel_hi:[1,0]
	v_pk_mul_f32 v[202:203], v[202:203], s[96:97] op_sel_hi:[1,0]
	v_pk_mul_f32 v[204:205], v[204:205], s[96:97] op_sel_hi:[1,0]
	v_pk_mul_f32 v[206:207], v[206:207], s[96:97] op_sel_hi:[1,0]
	v_pk_mul_f32 v[208:209], v[208:209], s[96:97] op_sel_hi:[1,0]
	v_pk_mul_f32 v[210:211], v[210:211], s[96:97] op_sel_hi:[1,0]
	v_pk_mul_f32 v[212:213], v[212:213], s[96:97] op_sel_hi:[1,0]
	v_pk_mul_f32 v[214:215], v[214:215], s[96:97] op_sel_hi:[1,0]
	v_pk_mul_f32 v[216:217], v[216:217], s[96:97] op_sel_hi:[1,0]
	v_pk_mul_f32 v[218:219], v[218:219], s[96:97] op_sel_hi:[1,0]
	v_pk_mul_f32 v[220:221], v[220:221], s[96:97] op_sel_hi:[1,0]
	v_pk_mul_f32 v[222:223], v[222:223], s[96:97] op_sel_hi:[1,0]
	v_pk_mul_f32 v[224:225], v[224:225], s[96:97] op_sel_hi:[1,0]
	v_pk_mul_f32 v[226:227], v[226:227], s[96:97] op_sel_hi:[1,0]
	v_pk_mul_f32 v[228:229], v[228:229], s[96:97] op_sel_hi:[1,0]
	v_pk_mul_f32 v[230:231], v[230:231], s[96:97] op_sel_hi:[1,0]
	v_cvt_scalef32_pk_fp4_f32 v232, v200, v201, 1.0
	v_cvt_scalef32_pk_fp4_f32 v233, v208, v209, 1.0
	v_cvt_scalef32_pk_fp4_f32 v234, v216, v217, 1.0
	v_cvt_scalef32_pk_fp4_f32 v235, v224, v225, 1.0
	v_cvt_scalef32_pk_fp4_f32 v232, v202, v203, 1.0 op_sel:[0,0,1,0]
	v_cvt_scalef32_pk_fp4_f32 v233, v210, v211, 1.0 op_sel:[0,0,1,0]
	v_cvt_scalef32_pk_fp4_f32 v234, v218, v219, 1.0 op_sel:[0,0,1,0]
	v_cvt_scalef32_pk_fp4_f32 v235, v226, v227, 1.0 op_sel:[0,0,1,0]
	v_cvt_scalef32_pk_fp4_f32 v232, v204, v205, 1.0 op_sel:[0,0,0,1]
	v_cvt_scalef32_pk_fp4_f32 v233, v212, v213, 1.0 op_sel:[0,0,0,1]
	v_cvt_scalef32_pk_fp4_f32 v234, v220, v221, 1.0 op_sel:[0,0,0,1]
	v_cvt_scalef32_pk_fp4_f32 v235, v228, v229, 1.0 op_sel:[0,0,0,1]
	v_cvt_scalef32_pk_fp4_f32 v232, v206, v207, 1.0 op_sel:[0,0,1,1]
	v_cvt_scalef32_pk_fp4_f32 v233, v214, v215, 1.0 op_sel:[0,0,1,1]
	v_cvt_scalef32_pk_fp4_f32 v234, v222, v223, 1.0 op_sel:[0,0,1,1]
	v_cvt_scalef32_pk_fp4_f32 v235, v230, v231, 1.0 op_sel:[0,0,1,1]
	s_nop 0
	global_store_dwordx4 v[240:241], v[232:235], off
	v_lshl_add_u64 v[240:241], v[240:241], 0, v[246:247]
	global_load_dwordx4 v[200:203], v[236:237], off
	global_load_dwordx4 v[204:207], v[236:237], off offset:16
	global_load_dwordx4 v[208:211], v[236:237], off offset:32
	global_load_dwordx4 v[212:215], v[236:237], off offset:48
	global_load_dwordx4 v[216:219], v[238:239], off
	global_load_dwordx4 v[220:223], v[238:239], off offset:16
	global_load_dwordx4 v[224:227], v[238:239], off offset:32
	global_load_dwordx4 v[228:231], v[238:239], off offset:48
	v_lshl_add_u64 v[236:237], v[236:237], 0, v[244:245]
	v_lshl_add_u64 v[238:239], v[238:239], 0, v[244:245]
	v_min_u32_e32 v59, v61, v59
	v_max_u32_e32 v61, v155, v60
	v_min_u32_e32 v60, v155, v60
	v_max_u32_e32 v155, v58, v63
	v_min_u32_e32 v58, v58, v63
	v_max_u32_e32 v63, v65, v151
	v_min_u32_e32 v65, v65, v151
	v_max_u32_e32 v151, v64, v148
	v_min_u32_e32 v64, v64, v148
	v_max_u32_e32 v148, v150, v149
	v_min_u32_e32 v149, v150, v149
	v_max_u32_e32 v150, v147, v152
	v_min_u32_e32 v147, v147, v152
	v_max_u32_e32 v32, v31, v21
	v_min_u32_e32 v21, v31, v21
	v_max_u32_e32 v31, v33, v20
	v_min_u32_e32 v20, v33, v20
	v_max_u32_e32 v33, v163, v19
	v_min_u32_e32 v19, v163, v19
	v_max_u32_e32 v163, v18, v22
	v_min_u32_e32 v18, v18, v22
	v_max_u32_e32 v22, v24, v29
	v_min_u32_e32 v24, v24, v29
	v_max_u32_e32 v29, v23, v26
	v_min_u32_e32 v23, v23, v26
	v_max_u32_e32 v26, v28, v27
	v_min_u32_e32 v27, v28, v27
	v_max_u32_e32 v28, v25, v30
	v_min_u32_e32 v25, v25, v30
	v_max_u32_e32 v16, v15, v5
	v_min_u32_e32 v5, v15, v5
	v_max_u32_e32 v15, v17, v4
	v_min_u32_e32 v4, v17, v4
	v_max_u32_e32 v17, v171, v3
	v_min_u32_e32 v3, v171, v3
	v_max_u32_e32 v171, v2, v6
	v_min_u32_e32 v2, v2, v6
	v_max_u32_e32 v6, v8, v13
	v_min_u32_e32 v8, v8, v13
	v_max_u32_e32 v13, v7, v10
	v_min_u32_e32 v7, v7, v10
	v_max_u32_e32 v10, v12, v11
	v_min_u32_e32 v11, v12, v11
	v_max_u32_e32 v12, v9, v14
	v_min_u32_e32 v9, v9, v14
	v_max_u32_e32 v47, v49, v37
	v_min_u32_e32 v37, v49, v37
	v_max_u32_e32 v49, v48, v50
	v_min_u32_e32 v48, v48, v50
	v_max_u32_e32 v50, v38, v36
	v_min_u32_e32 v36, v38, v36
	v_max_u32_e32 v38, v35, v34
	v_min_u32_e32 v34, v35, v34
	v_max_u32_e32 v35, v41, v44
	v_min_u32_e32 v41, v41, v44
	v_max_u32_e32 v44, v40, v42
	v_min_u32_e32 v40, v40, v42
	v_max_u32_e32 v42, v39, v43
	v_min_u32_e32 v39, v39, v43
	v_max_u32_e32 v43, v46, v45
	v_min_u32_e32 v45, v46, v45
	v_max_u32_e32 v152, v154, v61
	v_min_u32_e32 v61, v154, v61
	v_max_u32_e32 v154, v153, v155
	v_min_u32_e32 v153, v153, v155
	v_max_u32_e32 v155, v62, v60
	v_min_u32_e32 v60, v62, v60
	v_max_u32_e32 v62, v59, v58
	v_min_u32_e32 v58, v59, v58
	v_max_u32_e32 v59, v65, v149
	v_min_u32_e32 v65, v65, v149
	v_max_u32_e32 v149, v64, v147
	v_min_u32_e32 v64, v64, v147
	v_max_u32_e32 v147, v63, v148
	v_min_u32_e32 v63, v63, v148
	v_max_u32_e32 v148, v151, v150
	v_min_u32_e32 v150, v151, v150
	v_max_u32_e32 v30, v32, v33
	v_min_u32_e32 v32, v32, v33
	v_max_u32_e32 v33, v31, v163
	v_min_u32_e32 v31, v31, v163
	v_max_u32_e32 v163, v21, v19
	v_min_u32_e32 v19, v21, v19
	v_max_u32_e32 v21, v20, v18
	v_min_u32_e32 v18, v20, v18
	v_max_u32_e32 v20, v24, v27
	v_min_u32_e32 v24, v24, v27
	v_max_u32_e32 v27, v23, v25
	v_min_u32_e32 v23, v23, v25
	v_max_u32_e32 v25, v22, v26
	v_min_u32_e32 v22, v22, v26
	v_max_u32_e32 v26, v29, v28
	v_min_u32_e32 v28, v29, v28
	v_max_u32_e32 v14, v16, v17
	v_min_u32_e32 v16, v16, v17
	v_max_u32_e32 v17, v15, v171
	v_min_u32_e32 v15, v15, v171
	v_max_u32_e32 v171, v5, v3
	v_min_u32_e32 v3, v5, v3
	v_max_u32_e32 v5, v4, v2
	v_min_u32_e32 v2, v4, v2
	v_max_u32_e32 v4, v8, v11
	v_min_u32_e32 v8, v8, v11
	v_max_u32_e32 v11, v7, v9
	v_min_u32_e32 v7, v7, v9
	v_max_u32_e32 v9, v6, v10
	v_min_u32_e32 v6, v6, v10
	v_max_u32_e32 v10, v13, v12
	v_min_u32_e32 v12, v13, v12
	v_max_u32_e32 v46, v47, v49
	v_min_u32_e32 v47, v47, v49
	v_max_u32_e32 v49, v37, v48
	v_min_u32_e32 v37, v37, v48
	v_max_u32_e32 v48, v50, v38
	v_min_u32_e32 v38, v50, v38
	v_max_u32_e32 v50, v36, v34
	v_min_u32_e32 v34, v36, v34
	v_max_u32_e32 v36, v41, v40
	v_min_u32_e32 v40, v41, v40
	v_max_u32_e32 v41, v35, v44
	v_min_u32_e32 v35, v35, v44
	v_max_u32_e32 v44, v39, v45
	v_min_u32_e32 v39, v39, v45
	v_max_u32_e32 v45, v42, v43
	v_min_u32_e32 v42, v42, v43
	v_max_u32_e32 v151, v152, v154
	v_min_u32_e32 v152, v152, v154
	v_max_u32_e32 v154, v61, v153
	v_min_u32_e32 v61, v61, v153
	v_max_u32_e32 v153, v155, v62
	v_min_u32_e32 v62, v155, v62
	v_max_u32_e32 v155, v60, v58
	v_min_u32_e32 v58, v60, v58
	v_max_u32_e32 v60, v65, v64
	v_min_u32_e32 v64, v65, v64
	v_max_u32_e32 v65, v59, v149
	v_min_u32_e32 v59, v59, v149
	v_max_u32_e32 v149, v63, v150
	v_min_u32_e32 v63, v63, v150
	v_max_u32_e32 v150, v147, v148
	v_min_u32_e32 v147, v147, v148
	v_max_u32_e32 v29, v30, v33
	v_min_u32_e32 v30, v30, v33
	v_max_u32_e32 v33, v32, v31
	v_min_u32_e32 v31, v32, v31
	v_max_u32_e32 v32, v163, v21
	v_min_u32_e32 v21, v163, v21
	v_max_u32_e32 v163, v19, v18
	v_min_u32_e32 v18, v19, v18
	v_max_u32_e32 v19, v24, v23
	v_min_u32_e32 v23, v24, v23
	v_max_u32_e32 v24, v20, v27
	v_min_u32_e32 v20, v20, v27
	v_max_u32_e32 v27, v22, v28
	v_min_u32_e32 v22, v22, v28
	v_max_u32_e32 v28, v25, v26
	v_min_u32_e32 v25, v25, v26
	v_max_u32_e32 v13, v14, v17
	v_min_u32_e32 v14, v14, v17
	v_max_u32_e32 v17, v16, v15
	v_min_u32_e32 v15, v16, v15
	v_max_u32_e32 v16, v171, v5
	v_min_u32_e32 v5, v171, v5
	v_max_u32_e32 v171, v3, v2
	v_min_u32_e32 v2, v3, v2
	v_max_u32_e32 v3, v8, v7
	v_min_u32_e32 v7, v8, v7
	v_max_u32_e32 v8, v4, v11
	v_min_u32_e32 v4, v4, v11
	v_max_u32_e32 v11, v6, v12
	v_min_u32_e32 v6, v6, v12
	v_max_u32_e32 v12, v9, v10
	v_min_u32_e32 v9, v9, v10
	v_max_u32_e32 v43, v46, v40
	v_min_u32_e32 v40, v46, v40
	v_max_u32_e32 v46, v47, v36
	v_min_u32_e32 v36, v47, v36
	v_max_u32_e32 v47, v49, v35
	v_min_u32_e32 v35, v49, v35
	v_max_u32_e32 v49, v37, v41
	v_min_u32_e32 v37, v37, v41
	v_max_u32_e32 v41, v48, v39
	v_min_u32_e32 v39, v48, v39
	v_max_u32_e32 v48, v38, v44
	v_min_u32_e32 v38, v38, v44
	v_max_u32_e32 v44, v50, v42
	v_min_u32_e32 v42, v50, v42
	v_max_u32_e32 v50, v34, v45
	v_min_u32_e32 v34, v34, v45
	v_max_u32_e32 v148, v151, v64
	v_min_u32_e32 v64, v151, v64
	v_max_u32_e32 v151, v152, v60
	v_min_u32_e32 v60, v152, v60
	v_max_u32_e32 v152, v154, v59
	v_min_u32_e32 v59, v154, v59
	v_max_u32_e32 v154, v61, v65
	v_min_u32_e32 v61, v61, v65
	v_max_u32_e32 v65, v153, v63
	v_min_u32_e32 v63, v153, v63
	v_max_u32_e32 v153, v62, v149
	v_min_u32_e32 v62, v62, v149
	v_max_u32_e32 v149, v155, v147
	v_min_u32_e32 v147, v155, v147
	v_max_u32_e32 v155, v58, v150
	v_min_u32_e32 v58, v58, v150
	v_max_u32_e32 v26, v29, v23
	v_min_u32_e32 v23, v29, v23
	v_max_u32_e32 v29, v30, v19
	v_min_u32_e32 v19, v30, v19
	v_max_u32_e32 v30, v33, v20
	v_min_u32_e32 v20, v33, v20
	v_max_u32_e32 v33, v31, v24
	v_min_u32_e32 v24, v31, v24
	v_max_u32_e32 v31, v32, v22
	v_min_u32_e32 v22, v32, v22
	v_max_u32_e32 v32, v21, v27
	v_min_u32_e32 v21, v21, v27
	v_max_u32_e32 v27, v163, v25
	v_min_u32_e32 v25, v163, v25
	v_max_u32_e32 v163, v18, v28
	v_min_u32_e32 v18, v18, v28
	v_max_u32_e32 v10, v13, v7
	v_min_u32_e32 v7, v13, v7
	v_max_u32_e32 v13, v14, v3
	v_min_u32_e32 v3, v14, v3
	v_max_u32_e32 v14, v17, v4
	v_min_u32_e32 v4, v17, v4
	v_max_u32_e32 v17, v15, v8
	v_min_u32_e32 v8, v15, v8
	v_max_u32_e32 v15, v16, v6
	v_min_u32_e32 v6, v16, v6
	v_max_u32_e32 v16, v5, v11
	v_min_u32_e32 v5, v5, v11
	v_max_u32_e32 v11, v171, v9
	v_min_u32_e32 v9, v171, v9
	v_max_u32_e32 v171, v2, v12
	v_min_u32_e32 v2, v2, v12
	v_max_u32_e32 v45, v43, v41
	v_min_u32_e32 v41, v43, v41
	v_max_u32_e32 v43, v46, v48
	v_min_u32_e32 v46, v46, v48
	v_max_u32_e32 v48, v47, v44
	v_min_u32_e32 v44, v47, v44
	v_max_u32_e32 v47, v49, v50
	v_min_u32_e32 v49, v49, v50
	v_max_u32_e32 v50, v40, v39
	v_min_u32_e32 v39, v40, v39
	v_max_u32_e32 v40, v36, v38
	v_min_u32_e32 v36, v36, v38
	v_max_u32_e32 v38, v35, v42
	v_min_u32_e32 v35, v35, v42
	v_max_u32_e32 v42, v37, v34
	v_min_u32_e32 v34, v37, v34
	v_max_u32_e32 v150, v148, v65
	v_min_u32_e32 v65, v148, v65
	v_max_u32_e32 v148, v151, v153
	v_min_u32_e32 v151, v151, v153
	v_max_u32_e32 v153, v152, v149
	v_min_u32_e32 v149, v152, v149
	v_max_u32_e32 v152, v154, v155
	v_min_u32_e32 v154, v154, v155
	v_max_u32_e32 v155, v64, v63
	v_min_u32_e32 v63, v64, v63
	v_max_u32_e32 v64, v60, v62
	v_min_u32_e32 v60, v60, v62
	v_max_u32_e32 v62, v59, v147
	v_min_u32_e32 v59, v59, v147
	v_max_u32_e32 v147, v61, v58
	v_min_u32_e32 v58, v61, v58
	v_max_u32_e32 v28, v26, v31
	v_min_u32_e32 v26, v26, v31
	v_max_u32_e32 v31, v29, v32
	v_min_u32_e32 v29, v29, v32
	v_max_u32_e32 v32, v30, v27
	v_min_u32_e32 v27, v30, v27
	v_max_u32_e32 v30, v33, v163
	v_min_u32_e32 v33, v33, v163
	v_max_u32_e32 v163, v23, v22
	v_min_u32_e32 v22, v23, v22
	v_max_u32_e32 v23, v19, v21
	v_min_u32_e32 v19, v19, v21
	v_max_u32_e32 v21, v20, v25
	v_min_u32_e32 v20, v20, v25
	v_max_u32_e32 v25, v24, v18
	v_min_u32_e32 v18, v24, v18
	v_max_u32_e32 v12, v10, v15
	v_min_u32_e32 v10, v10, v15
	v_max_u32_e32 v15, v13, v16
	v_min_u32_e32 v13, v13, v16
	v_max_u32_e32 v16, v14, v11
	v_min_u32_e32 v11, v14, v11
	v_max_u32_e32 v14, v17, v171
	v_min_u32_e32 v17, v17, v171
	v_max_u32_e32 v171, v7, v6
	v_min_u32_e32 v6, v7, v6
	v_max_u32_e32 v7, v3, v5
	v_min_u32_e32 v3, v3, v5
	v_max_u32_e32 v5, v4, v9
	v_min_u32_e32 v4, v4, v9
	v_max_u32_e32 v9, v8, v2
	v_min_u32_e32 v2, v8, v2
	v_max_u32_e32 v37, v45, v48
	v_min_u32_e32 v45, v45, v48
	v_max_u32_e32 v48, v43, v47
	v_min_u32_e32 v43, v43, v47
	s_waitcnt vmcnt(0)
	v_pk_mul_f32 v[200:201], v[200:201], s[96:97] op_sel_hi:[1,0]
	v_pk_mul_f32 v[202:203], v[202:203], s[96:97] op_sel_hi:[1,0]
	v_pk_mul_f32 v[204:205], v[204:205], s[96:97] op_sel_hi:[1,0]
	v_pk_mul_f32 v[206:207], v[206:207], s[96:97] op_sel_hi:[1,0]
	v_pk_mul_f32 v[208:209], v[208:209], s[96:97] op_sel_hi:[1,0]
	v_pk_mul_f32 v[210:211], v[210:211], s[96:97] op_sel_hi:[1,0]
	v_pk_mul_f32 v[212:213], v[212:213], s[96:97] op_sel_hi:[1,0]
	v_pk_mul_f32 v[214:215], v[214:215], s[96:97] op_sel_hi:[1,0]
	v_pk_mul_f32 v[216:217], v[216:217], s[96:97] op_sel_hi:[1,0]
	v_pk_mul_f32 v[218:219], v[218:219], s[96:97] op_sel_hi:[1,0]
	v_pk_mul_f32 v[220:221], v[220:221], s[96:97] op_sel_hi:[1,0]
	v_pk_mul_f32 v[222:223], v[222:223], s[96:97] op_sel_hi:[1,0]
	v_pk_mul_f32 v[224:225], v[224:225], s[96:97] op_sel_hi:[1,0]
	v_pk_mul_f32 v[226:227], v[226:227], s[96:97] op_sel_hi:[1,0]
	v_pk_mul_f32 v[228:229], v[228:229], s[96:97] op_sel_hi:[1,0]
	v_pk_mul_f32 v[230:231], v[230:231], s[96:97] op_sel_hi:[1,0]
	v_cvt_scalef32_pk_fp4_f32 v232, v200, v201, 1.0
	v_cvt_scalef32_pk_fp4_f32 v233, v208, v209, 1.0
	v_cvt_scalef32_pk_fp4_f32 v234, v216, v217, 1.0
	v_cvt_scalef32_pk_fp4_f32 v235, v224, v225, 1.0
	v_cvt_scalef32_pk_fp4_f32 v232, v202, v203, 1.0 op_sel:[0,0,1,0]
	v_cvt_scalef32_pk_fp4_f32 v233, v210, v211, 1.0 op_sel:[0,0,1,0]
	v_cvt_scalef32_pk_fp4_f32 v234, v218, v219, 1.0 op_sel:[0,0,1,0]
	v_cvt_scalef32_pk_fp4_f32 v235, v226, v227, 1.0 op_sel:[0,0,1,0]
	v_cvt_scalef32_pk_fp4_f32 v232, v204, v205, 1.0 op_sel:[0,0,0,1]
	v_cvt_scalef32_pk_fp4_f32 v233, v212, v213, 1.0 op_sel:[0,0,0,1]
	v_cvt_scalef32_pk_fp4_f32 v234, v220, v221, 1.0 op_sel:[0,0,0,1]
	v_cvt_scalef32_pk_fp4_f32 v235, v228, v229, 1.0 op_sel:[0,0,0,1]
	v_cvt_scalef32_pk_fp4_f32 v232, v206, v207, 1.0 op_sel:[0,0,1,1]
	v_cvt_scalef32_pk_fp4_f32 v233, v214, v215, 1.0 op_sel:[0,0,1,1]
	v_cvt_scalef32_pk_fp4_f32 v234, v222, v223, 1.0 op_sel:[0,0,1,1]
	v_cvt_scalef32_pk_fp4_f32 v235, v230, v231, 1.0 op_sel:[0,0,1,1]
	s_nop 0
	global_store_dwordx4 v[240:241], v[232:235], off
	v_lshl_add_u64 v[240:241], v[240:241], 0, v[246:247]
	global_load_dwordx4 v[200:203], v[236:237], off
	global_load_dwordx4 v[204:207], v[236:237], off offset:16
	global_load_dwordx4 v[208:211], v[236:237], off offset:32
	global_load_dwordx4 v[212:215], v[236:237], off offset:48
	global_load_dwordx4 v[216:219], v[238:239], off
	global_load_dwordx4 v[220:223], v[238:239], off offset:16
	global_load_dwordx4 v[224:227], v[238:239], off offset:32
	global_load_dwordx4 v[228:231], v[238:239], off offset:48
	v_lshl_add_u64 v[236:237], v[236:237], 0, v[244:245]
	v_lshl_add_u64 v[238:239], v[238:239], 0, v[244:245]
	v_max_u32_e32 v47, v41, v44
	v_min_u32_e32 v41, v41, v44
	v_max_u32_e32 v44, v46, v49
	v_min_u32_e32 v46, v46, v49
	v_max_u32_e32 v49, v50, v38
	v_min_u32_e32 v38, v50, v38
	v_max_u32_e32 v50, v40, v42
	v_min_u32_e32 v40, v40, v42
	v_max_u32_e32 v42, v39, v35
	v_min_u32_e32 v35, v39, v35
	v_max_u32_e32 v39, v36, v34
	v_min_u32_e32 v34, v36, v34
	v_max_u32_e32 v61, v150, v153
	v_min_u32_e32 v150, v150, v153
	v_max_u32_e32 v153, v148, v152
	v_min_u32_e32 v148, v148, v152
	v_max_u32_e32 v152, v65, v149
	v_min_u32_e32 v65, v65, v149
	v_max_u32_e32 v149, v151, v154
	v_min_u32_e32 v151, v151, v154
	v_max_u32_e32 v154, v155, v62
	v_min_u32_e32 v62, v155, v62
	v_max_u32_e32 v155, v64, v147
	v_min_u32_e32 v64, v64, v147
	v_max_u32_e32 v147, v63, v59
	v_min_u32_e32 v59, v63, v59
	v_max_u32_e32 v63, v60, v58
	v_min_u32_e32 v58, v60, v58
	v_max_u32_e32 v24, v28, v32
	v_min_u32_e32 v28, v28, v32
	v_max_u32_e32 v32, v31, v30
	v_min_u32_e32 v30, v31, v30
	v_max_u32_e32 v31, v26, v27
	v_min_u32_e32 v26, v26, v27
	v_max_u32_e32 v27, v29, v33
	v_min_u32_e32 v29, v29, v33
	v_max_u32_e32 v33, v163, v21
	v_min_u32_e32 v21, v163, v21
	v_max_u32_e32 v163, v23, v25
	v_min_u32_e32 v23, v23, v25
	v_max_u32_e32 v25, v22, v20
	v_min_u32_e32 v20, v22, v20
	v_max_u32_e32 v22, v19, v18
	v_min_u32_e32 v18, v19, v18
	v_max_u32_e32 v8, v12, v16
	v_min_u32_e32 v12, v12, v16
	v_max_u32_e32 v16, v15, v14
	v_min_u32_e32 v14, v15, v14
	v_max_u32_e32 v15, v10, v11
	v_min_u32_e32 v10, v10, v11
	v_max_u32_e32 v11, v13, v17
	v_min_u32_e32 v13, v13, v17
	v_max_u32_e32 v17, v171, v5
	v_min_u32_e32 v5, v171, v5
	v_max_u32_e32 v171, v7, v9
	v_min_u32_e32 v7, v7, v9
	v_max_u32_e32 v9, v6, v4
	v_min_u32_e32 v4, v6, v4
	v_max_u32_e32 v6, v3, v2
	v_min_u32_e32 v2, v3, v2
	v_min_u32_e32 v36, v37, v48
	v_min_u32_e32 v51, v45, v43
	v_min_u32_e32 v52, v47, v44
	v_min_u32_e32 v53, v41, v46
	v_min_u32_e32 v54, v49, v50
	v_min_u32_e32 v55, v38, v40
	v_min_u32_e32 v56, v42, v39
	v_min_u32_e32 v57, v35, v34
	v_min_u32_e32 v60, v61, v153
	v_min_u32_e32 v156, v150, v148
	v_min_u32_e32 v157, v152, v149
	v_min_u32_e32 v158, v65, v151
	v_min_u32_e32 v159, v154, v155
	v_min_u32_e32 v160, v62, v64
	v_min_u32_e32 v161, v147, v63
	v_min_u32_e32 v162, v59, v58
	v_min_u32_e32 v19, v24, v32
	v_min_u32_e32 v164, v28, v30
	v_min_u32_e32 v165, v31, v27
	v_min_u32_e32 v166, v26, v29
	v_min_u32_e32 v167, v33, v163
	v_min_u32_e32 v168, v21, v23
	v_min_u32_e32 v169, v25, v22
	v_min_u32_e32 v170, v20, v18
	v_min_u32_e32 v3, v8, v16
	v_min_u32_e32 v172, v12, v14
	v_min_u32_e32 v173, v15, v11
	v_min_u32_e32 v174, v10, v13
	v_min_u32_e32 v175, v17, v171
	v_min_u32_e32 v176, v5, v7
	v_min_u32_e32 v177, v9, v6
	v_min_u32_e32 v178, v4, v2
	v_max3_u32 v37, v37, v48, v162
	v_max3_u32 v24, v24, v32, v178
	v_max3_u32 v32, v36, v59, v58
	v_max3_u32 v2, v19, v4, v2
	v_max3_u32 v4, v45, v43, v161
	v_max3_u32 v19, v28, v30, v177
	v_max3_u32 v28, v51, v147, v63
	v_max3_u32 v6, v164, v9, v6
	v_max3_u32 v9, v47, v44, v160
	v_max3_u32 v27, v31, v27, v176
	v_max3_u32 v30, v52, v62, v64
	v_max3_u32 v5, v165, v5, v7
	v_max3_u32 v7, v41, v46, v159
	v_max3_u32 v26, v26, v29, v175
	v_max3_u32 v29, v53, v154, v155
	v_max3_u32 v17, v166, v17, v171
	v_max3_u32 v31, v49, v50, v158
	v_max3_u32 v33, v33, v163, v174
	v_max3_u32 v36, v54, v65, v151
	v_max3_u32 v10, v167, v10, v13
	v_max3_u32 v13, v38, v40, v157
	v_max3_u32 v21, v21, v23, v173
	v_max3_u32 v23, v55, v152, v149
	v_max3_u32 v11, v168, v15, v11
	v_max3_u32 v15, v42, v39, v156
	v_max3_u32 v22, v25, v22, v172
	v_max3_u32 v25, v56, v150, v148
	v_max3_u32 v12, v169, v12, v14
	v_max3_u32 v14, v35, v34, v60
	v_max3_u32 v3, v20, v18, v3
	v_max3_u32 v18, v57, v61, v153
	v_max3_u32 v8, v170, v8, v16
	v_max_u32_e32 v16, v37, v31
	v_min_u32_e32 v20, v37, v31
	v_max_u32_e32 v31, v32, v36
	v_min_u32_e32 v32, v32, v36
	v_max_u32_e32 v34, v4, v13
	v_min_u32_e32 v4, v4, v13
	v_max_u32_e32 v13, v28, v23
	v_min_u32_e32 v23, v28, v23
	v_max_u32_e32 v28, v9, v15
	v_min_u32_e32 v9, v9, v15
	v_max_u32_e32 v15, v30, v25
	v_min_u32_e32 v25, v30, v25
	v_max_u32_e32 v30, v7, v14
	v_min_u32_e32 v7, v7, v14
	v_max_u32_e32 v14, v29, v18
	v_min_u32_e32 v18, v29, v18
	v_max_u32_e32 v42, v24, v33
	v_min_u32_e32 v24, v24, v33
	v_max_u32_e32 v33, v2, v10
	v_min_u32_e32 v2, v2, v10
	v_max_u32_e32 v10, v19, v21
	v_min_u32_e32 v19, v19, v21
	v_max_u32_e32 v21, v6, v11
	v_min_u32_e32 v6, v6, v11
	v_max_u32_e32 v11, v27, v22
	v_min_u32_e32 v22, v27, v22
	v_max_u32_e32 v27, v5, v12
	v_min_u32_e32 v5, v5, v12
	v_max_u32_e32 v12, v26, v3
	v_min_u32_e32 v3, v26, v3
	v_max_u32_e32 v26, v17, v8
	v_min_u32_e32 v8, v17, v8
	v_max_u32_e32 v29, v16, v28
	v_min_u32_e32 v16, v16, v28
	v_max_u32_e32 v28, v31, v15
	v_min_u32_e32 v15, v31, v15
	v_max_u32_e32 v31, v34, v30
	v_min_u32_e32 v30, v34, v30
	v_max_u32_e32 v34, v13, v14
	v_min_u32_e32 v13, v13, v14
	v_max_u32_e32 v14, v20, v9
	v_min_u32_e32 v9, v20, v9
	v_max_u32_e32 v20, v32, v25
	v_min_u32_e32 v25, v32, v25
	v_max_u32_e32 v32, v4, v7
	v_min_u32_e32 v4, v4, v7
	v_max_u32_e32 v7, v23, v18
	v_min_u32_e32 v18, v23, v18
	v_max_u32_e32 v17, v42, v11
	v_min_u32_e32 v11, v42, v11
	v_max_u32_e32 v42, v33, v27
	v_min_u32_e32 v27, v33, v27
	v_max_u32_e32 v33, v10, v12
	v_min_u32_e32 v10, v10, v12
	v_max_u32_e32 v12, v21, v26
	v_min_u32_e32 v21, v21, v26
	v_max_u32_e32 v26, v24, v22
	v_min_u32_e32 v22, v24, v22
	v_max_u32_e32 v24, v2, v5
	v_min_u32_e32 v2, v2, v5
	v_max_u32_e32 v5, v19, v3
	v_min_u32_e32 v3, v19, v3
	v_max_u32_e32 v19, v6, v8
	v_min_u32_e32 v6, v6, v8
	v_max_u32_e32 v23, v29, v31
	v_min_u32_e32 v29, v29, v31
	v_max_u32_e32 v31, v28, v34
	v_min_u32_e32 v28, v28, v34
	v_max_u32_e32 v34, v16, v30
	v_min_u32_e32 v16, v16, v30
	v_max_u32_e32 v30, v15, v13
	v_min_u32_e32 v13, v15, v13
	v_max_u32_e32 v15, v14, v32
	v_min_u32_e32 v14, v14, v32
	v_max_u32_e32 v32, v20, v7
	v_min_u32_e32 v7, v20, v7
	v_max_u32_e32 v20, v9, v4
	v_min_u32_e32 v4, v9, v4
	v_max_u32_e32 v9, v25, v18
	v_min_u32_e32 v18, v25, v18
	v_max_u32_e32 v8, v17, v33
	v_min_u32_e32 v17, v17, v33
	v_max_u32_e32 v33, v42, v12
	v_min_u32_e32 v12, v42, v12
	v_max_u32_e32 v42, v11, v10
	v_min_u32_e32 v10, v11, v10
	v_max_u32_e32 v11, v27, v21
	v_min_u32_e32 v21, v27, v21
	v_max_u32_e32 v27, v26, v5
	v_min_u32_e32 v5, v26, v5
	v_max_u32_e32 v26, v24, v19
	v_min_u32_e32 v19, v24, v19
	v_max_u32_e32 v24, v22, v3
	v_min_u32_e32 v3, v22, v3
	v_max_u32_e32 v22, v2, v6
	v_min_u32_e32 v2, v2, v6
	v_min_u32_e32 v25, v23, v31
	v_min_u32_e32 v35, v29, v28
	v_min_u32_e32 v36, v34, v30
	v_min_u32_e32 v37, v16, v13
	v_min_u32_e32 v38, v15, v32
	v_min_u32_e32 v39, v14, v7
	v_min_u32_e32 v40, v20, v9
	v_min_u32_e32 v41, v4, v18
	v_min_u32_e32 v6, v8, v33
	v_min_u32_e32 v43, v17, v12
	v_min_u32_e32 v44, v42, v11
	v_min_u32_e32 v45, v10, v21
	v_min_u32_e32 v46, v27, v26
	v_min_u32_e32 v47, v5, v19
	v_min_u32_e32 v48, v24, v22
	v_min_u32_e32 v49, v3, v2
	v_max3_u32 v23, v23, v31, v49
	v_max3_u32 v2, v25, v3, v2
	v_max3_u32 v3, v29, v28, v48
	v_max3_u32 v22, v35, v24, v22
	v_max3_u32 v24, v34, v30, v47
	v_max3_u32 v5, v36, v5, v19
	v_max3_u32 v13, v16, v13, v46
	v_max3_u32 v16, v37, v27, v26
	v_max3_u32 v15, v15, v32, v45
	s_waitcnt vmcnt(0)
	v_pk_mul_f32 v[200:201], v[200:201], s[96:97] op_sel_hi:[1,0]
	v_pk_mul_f32 v[202:203], v[202:203], s[96:97] op_sel_hi:[1,0]
	v_pk_mul_f32 v[204:205], v[204:205], s[96:97] op_sel_hi:[1,0]
	v_pk_mul_f32 v[206:207], v[206:207], s[96:97] op_sel_hi:[1,0]
	v_pk_mul_f32 v[208:209], v[208:209], s[96:97] op_sel_hi:[1,0]
	v_pk_mul_f32 v[210:211], v[210:211], s[96:97] op_sel_hi:[1,0]
	v_pk_mul_f32 v[212:213], v[212:213], s[96:97] op_sel_hi:[1,0]
	v_pk_mul_f32 v[214:215], v[214:215], s[96:97] op_sel_hi:[1,0]
	v_pk_mul_f32 v[216:217], v[216:217], s[96:97] op_sel_hi:[1,0]
	v_pk_mul_f32 v[218:219], v[218:219], s[96:97] op_sel_hi:[1,0]
	v_pk_mul_f32 v[220:221], v[220:221], s[96:97] op_sel_hi:[1,0]
	v_pk_mul_f32 v[222:223], v[222:223], s[96:97] op_sel_hi:[1,0]
	v_pk_mul_f32 v[224:225], v[224:225], s[96:97] op_sel_hi:[1,0]
	v_pk_mul_f32 v[226:227], v[226:227], s[96:97] op_sel_hi:[1,0]
	v_pk_mul_f32 v[228:229], v[228:229], s[96:97] op_sel_hi:[1,0]
	v_pk_mul_f32 v[230:231], v[230:231], s[96:97] op_sel_hi:[1,0]
	v_cvt_scalef32_pk_fp4_f32 v232, v200, v201, 1.0
	v_cvt_scalef32_pk_fp4_f32 v233, v208, v209, 1.0
	v_cvt_scalef32_pk_fp4_f32 v234, v216, v217, 1.0
	v_cvt_scalef32_pk_fp4_f32 v235, v224, v225, 1.0
	v_cvt_scalef32_pk_fp4_f32 v232, v202, v203, 1.0 op_sel:[0,0,1,0]
	v_cvt_scalef32_pk_fp4_f32 v233, v210, v211, 1.0 op_sel:[0,0,1,0]
	v_cvt_scalef32_pk_fp4_f32 v234, v218, v219, 1.0 op_sel:[0,0,1,0]
	v_cvt_scalef32_pk_fp4_f32 v235, v226, v227, 1.0 op_sel:[0,0,1,0]
	v_cvt_scalef32_pk_fp4_f32 v232, v204, v205, 1.0 op_sel:[0,0,0,1]
	v_cvt_scalef32_pk_fp4_f32 v233, v212, v213, 1.0 op_sel:[0,0,0,1]
	v_cvt_scalef32_pk_fp4_f32 v234, v220, v221, 1.0 op_sel:[0,0,0,1]
	v_cvt_scalef32_pk_fp4_f32 v235, v228, v229, 1.0 op_sel:[0,0,0,1]
	v_cvt_scalef32_pk_fp4_f32 v232, v206, v207, 1.0 op_sel:[0,0,1,1]
	v_cvt_scalef32_pk_fp4_f32 v233, v214, v215, 1.0 op_sel:[0,0,1,1]
	v_cvt_scalef32_pk_fp4_f32 v234, v222, v223, 1.0 op_sel:[0,0,1,1]
	v_cvt_scalef32_pk_fp4_f32 v235, v230, v231, 1.0 op_sel:[0,0,1,1]
	s_nop 0
	global_store_dwordx4 v[240:241], v[232:235], off
	v_lshl_add_u64 v[240:241], v[240:241], 0, v[246:247]
	v_max3_u32 v10, v38, v10, v21
	v_max3_u32 v7, v14, v7, v44
	v_max3_u32 v11, v39, v42, v11
	v_max3_u32 v9, v20, v9, v43
	v_max3_u32 v12, v40, v17, v12
	v_max3_u32 v4, v4, v18, v6
	v_max3_u32 v6, v41, v8, v33
	v_max_u32_e32 v8, v23, v15
	v_min_u32_e32 v14, v23, v15
	v_max_u32_e32 v15, v2, v10
	v_min_u32_e32 v2, v2, v10
	v_max_u32_e32 v10, v3, v7
	v_min_u32_e32 v3, v3, v7
	v_max_u32_e32 v7, v22, v11
	v_max_u32_e32 v17, v24, v9
	v_max_u32_e32 v18, v5, v12
	v_min_u32_e32 v5, v5, v12
	v_max_u32_e32 v12, v13, v4
	v_min_u32_e32 v4, v13, v4
	v_max_u32_e32 v13, v16, v6
	v_min_u32_e32 v11, v22, v11
	v_min_u32_e32 v9, v24, v9
	v_min_u32_e32 v6, v16, v6
	v_max_u32_e32 v16, v8, v17
	v_min_u32_e32 v8, v8, v17
	v_max_u32_e32 v17, v15, v18
	v_min_u32_e32 v15, v15, v18
	v_max_u32_e32 v18, v10, v12
	v_min_u32_e32 v10, v10, v12
	v_max_u32_e32 v12, v7, v13
	v_min_u32_e32 v7, v7, v13
	v_max_u32_e32 v13, v14, v9
	v_min_u32_e32 v9, v14, v9
	v_max_u32_e32 v14, v2, v5
	v_min_u32_e32 v2, v2, v5
	v_max_u32_e32 v5, v3, v4
	v_min_u32_e32 v3, v3, v4
	v_max_u32_e32 v4, v11, v6
	v_min_u32_e32 v6, v11, v6
	v_max_u32_e32 v11, v16, v18
	v_min_u32_e32 v16, v16, v18
	v_max_u32_e32 v18, v17, v12
	v_min_u32_e32 v12, v17, v12
	v_max_u32_e32 v17, v8, v10
	v_min_u32_e32 v8, v8, v10
	v_add_co_u32_e32 v10, vcc, s24, v80
	v_max_u32_e32 v25, v11, v18
	v_min_u32_e32 v18, v11, v18
	v_addc_co_u32_e32 v11, vcc, 0, v81, vcc
	v_max_u32_e32 v19, v15, v7
	v_min_u32_e32 v7, v15, v7
	v_max_u32_e32 v15, v13, v5
	v_min_u32_e32 v13, v13, v5
	v_max_u32_e32 v20, v14, v4
	v_min_u32_e32 v14, v14, v4
	v_max_u32_e32 v21, v9, v3
	v_min_u32_e32 v22, v9, v3
	v_max_u32_e32 v23, v2, v6
	v_min_u32_e32 v24, v2, v6
	global_load_dwordx4 v[2:5], v[10:11], off
	global_load_dwordx4 v[34:37], v[82:83], off offset:256
	global_load_dwordx4 v[38:41], v[82:83], off offset:288
	v_max_u32_e32 v26, v16, v12
	v_min_u32_e32 v12, v16, v12
	v_max_u32_e32 v16, v17, v19
	v_min_u32_e32 v17, v17, v19
	v_max_u32_e32 v19, v8, v7
	v_min_u32_e32 v27, v8, v7
	global_load_dwordx4 v[6:9], v[10:11], off offset:32
	global_load_dwordx4 v[28:31], v[10:11], off offset:64
	global_load_dwordx4 v[148:151], v[10:11], off offset:96
	v_cmp_lt_i32_e32 vcc, v84, v85
	global_load_dwordx4 v[42:45], v[82:83], off offset:320
	v_max_u32_e32 v33, v22, v24
	v_min_u32_e32 v22, v22, v24
	v_cndmask_b32_e32 v24, v77, v84, vcc
	v_max_u32_e32 v32, v15, v20
	v_min_u32_e32 v15, v15, v20
	v_max_u32_e32 v20, v13, v14
	v_min_u32_e32 v13, v13, v14
	v_min_u32_e32 v14, v21, v23
	v_lshlrev_b32_e32 v153, 2, v24
	ds_bpermute_b32 v46, v153, v33
	ds_bpermute_b32 v47, v153, v14
	ds_bpermute_b32 v50, v153, v13
	ds_bpermute_b32 v51, v153, v20
	ds_bpermute_b32 v52, v153, v15
	s_waitcnt lgkmcnt(0)
	v_max_u32_e32 v147, v18, v46
	v_max_u32_e32 v152, v26, v47
	global_load_dwordx4 v[46:49], v[82:83], off offset:352
	ds_bpermute_b32 v53, v153, v32
	global_load_dwordx4 v[154:157], v[10:11], off offset:128
	global_load_dwordx4 v[158:161], v[10:11], off offset:160
	v_max_u32_e32 v170, v16, v50
	v_max_u32_e32 v171, v17, v51
	v_max_u32_e32 v172, v19, v52
	s_waitcnt lgkmcnt(0)
	v_max_u32_e32 v173, v27, v53
	global_load_dwordx4 v[50:53], v[82:83], off offset:384
	global_load_dwordx4 v[54:57], v[82:83], off offset:416
	global_load_dwordx4 v[162:165], v[10:11], off offset:192
	global_load_dwordx4 v[166:169], v[10:11], off offset:224
	global_load_dwordx4 v[58:61], v[82:83], off offset:448
	global_load_dwordx4 v[62:65], v[82:83], off offset:480
	v_max_u32_e32 v21, v21, v23
	ds_bpermute_b32 v23, v153, v21
	ds_bpermute_b32 v16, v153, v16
	ds_bpermute_b32 v19, v153, v19
	ds_bpermute_b32 v24, v153, v22
	ds_bpermute_b32 v27, v153, v27
	s_waitcnt lgkmcnt(4)
	v_max_u32_e32 v23, v12, v23
	ds_bpermute_b32 v17, v153, v17
	s_waitcnt lgkmcnt(4)
	v_max_u32_e32 v13, v13, v16
	ds_bpermute_b32 v12, v153, v12
	ds_bpermute_b32 v16, v153, v26
	ds_bpermute_b32 v18, v153, v18
	s_waitcnt lgkmcnt(6)
	v_max_u32_e32 v15, v15, v19
	ds_bpermute_b32 v19, v153, v25
	s_waitcnt lgkmcnt(6)
	v_max_u32_e32 v24, v25, v24
	s_waitcnt lgkmcnt(5)
	v_max_u32_e32 v27, v32, v27
	s_waitcnt lgkmcnt(4)
	v_max_u32_e32 v17, v20, v17
	s_waitcnt lgkmcnt(3)
	v_max_u32_e32 v12, v21, v12
	s_waitcnt lgkmcnt(2)
	v_max_u32_e32 v14, v14, v16
	s_waitcnt lgkmcnt(1)
	v_max_u32_e32 v16, v33, v18
	s_waitcnt lgkmcnt(0)
	v_max_u32_e32 v10, v22, v19
	v_max_u32_e32 v11, v24, v27
	v_max_u32_e32 v18, v147, v15
	v_min_u32_e32 v33, v147, v15
	v_max_u32_e32 v15, v152, v17
	v_min_u32_e32 v82, v152, v17
	v_max_u32_e32 v83, v23, v13
	v_min_u32_e32 v147, v23, v13
	v_max_u32_e32 v13, v170, v12
	v_min_u32_e32 v152, v170, v12
	v_max_u32_e32 v12, v171, v14
	v_min_u32_e32 v170, v171, v14
	v_max_u32_e32 v14, v172, v16
	v_min_u32_e32 v32, v24, v27
	v_min_u32_e32 v171, v172, v16
	v_max_u32_e32 v172, v173, v10
	v_min_u32_e32 v10, v173, v10
	v_max_u32_e32 v173, v11, v13
	v_min_u32_e32 v11, v11, v13
	v_max_u32_e32 v174, v18, v12
	v_min_u32_e32 v175, v18, v12
	v_max_u32_e32 v176, v15, v14
	v_min_u32_e32 v177, v15, v14
	s_waitcnt vmcnt(14)
	v_mfma_f32_32x32x16_bf16 v[12:27], v[2:5], v[34:37], 0
	v_max_u32_e32 v2, v83, v172
	v_max_u32_e32 v178, v174, v2
	v_min_u32_e32 v174, v174, v2
	v_min_u32_e32 v83, v83, v172
	v_max_u32_e32 v172, v32, v152
	v_min_u32_e32 v32, v32, v152
	s_waitcnt vmcnt(12)
	v_mfma_f32_32x32x16_bf16 v[12:27], v[6:9], v[38:41], v[12:27]
	v_add_co_u32_e32 v6, vcc, s25, v80
	v_max_u32_e32 v152, v33, v170
	s_nop 0
	v_addc_co_u32_e32 v7, vcc, 0, v81, vcc
	global_load_dwordx4 v[2:5], v[6:7], off
	v_min_u32_e32 v33, v33, v170
	s_waitcnt vmcnt(10)
	v_mfma_f32_32x32x16_bf16 v[12:27], v[28:31], v[42:45], v[12:27]
	global_load_dwordx4 v[28:31], v[6:7], off offset:32
	v_max_u32_e32 v170, v82, v171
	v_min_u32_e32 v8, v82, v171
	v_max_u32_e32 v9, v147, v10
	v_min_u32_e32 v10, v147, v10
	v_max_u32_e32 v147, v173, v176
	v_min_u32_e32 v176, v173, v176
	s_waitcnt vmcnt(10)
	v_mfma_f32_32x32x16_bf16 v[12:27], v[148:151], v[46:49], v[12:27]
	v_max_u32_e32 v148, v172, v170
	v_min_u32_e32 v149, v172, v170
	global_load_dwordx4 v[170:173], v[6:7], off offset:64
	v_max_u32_e32 v179, v11, v177
	v_min_u32_e32 v11, v11, v177
	v_max_u32_e32 v177, v175, v83
	v_min_u32_e32 v83, v175, v83
	s_waitcnt vmcnt(8)
	v_mfma_f32_32x32x16_bf16 v[12:27], v[154:157], v[50:53], v[12:27]
	v_max_u32_e32 v156, v176, v174
	v_min_u32_e32 v157, v176, v174
	v_max_u32_e32 v150, v152, v9
	v_min_u32_e32 v9, v152, v9
	v_max_u32_e32 v82, v147, v178
	v_min_u32_e32 v152, v147, v178
	global_load_dwordx4 v[182:185], v[6:7], off offset:224
	s_waitcnt vmcnt(8)
	v_mfma_f32_32x32x16_bf16 v[12:27], v[158:161], v[54:57], v[12:27]
	v_max_u32_e32 v158, v179, v177
	v_min_u32_e32 v159, v179, v177
	global_load_dwordx4 v[174:177], v[6:7], off offset:96
	global_load_dwordx4 v[178:181], v[6:7], off offset:192
	v_max_u32_e32 v151, v32, v8
	v_min_u32_e32 v8, v32, v8
	v_max_u32_e32 v32, v33, v10
	s_waitcnt vmcnt(7)
	v_mfma_f32_32x32x16_bf16 v[12:27], v[162:165], v[58:61], v[12:27]
	global_load_dwordx4 v[162:165], v[6:7], off offset:128
	v_min_u32_e32 v10, v33, v10
	v_max_u32_e32 v160, v11, v83
	v_min_u32_e32 v161, v11, v83
	v_max_u32_e32 v83, v148, v150
	v_min_u32_e32 v147, v148, v150
	v_max_u32_e32 v148, v149, v9
	s_waitcnt vmcnt(7)
	v_mfma_f32_32x32x16_bf16 v[12:27], v[166:169], v[62:65], v[12:27]
	global_load_dwordx4 v[166:169], v[6:7], off offset:160
	v_min_u32_e32 v149, v149, v9
	v_max_u32_e32 v154, v8, v10
	v_min_u32_e32 v155, v8, v10
	v_max_u32_e32 v150, v151, v32
	v_min_u32_e32 v151, v151, v32
	s_nop 5
	v_not_b32_e32 v8, v12
	v_or_b32_e32 v9, 0x80000000, v12
	v_cmp_gt_i32_e32 vcc, 0, v12
	v_not_b32_e32 v6, v15
	v_or_b32_e32 v7, 0x80000000, v15
	v_cndmask_b32_e32 v8, v9, v8, vcc
	v_and_or_b32 v100, v8, s17, v100
	v_not_b32_e32 v8, v13
	v_or_b32_e32 v9, 0x80000000, v13
	v_cmp_gt_i32_e32 vcc, 0, v13
	v_or_b32_e32 v32, 0x80000000, v19
	s_nop 0
	v_cndmask_b32_e32 v8, v9, v8, vcc
	v_and_or_b32 v98, v8, s17, v98
	v_not_b32_e32 v8, v14
	v_or_b32_e32 v9, 0x80000000, v14
	v_cmp_gt_i32_e32 vcc, 0, v14
	s_nop 1
	v_cndmask_b32_e32 v8, v9, v8, vcc
	v_cmp_gt_i32_e32 vcc, 0, v15
	v_and_or_b32 v101, v8, s17, v101
	s_nop 0
	v_cndmask_b32_e32 v6, v7, v6, vcc
	v_and_or_b32 v99, v6, s17, v99
	v_not_b32_e32 v6, v16
	v_or_b32_e32 v7, 0x80000000, v16
	v_cmp_gt_i32_e32 vcc, 0, v16
	s_nop 1
	v_cndmask_b32_e32 v6, v7, v6, vcc
	v_and_or_b32 v97, v6, s17, v97
	v_not_b32_e32 v6, v17
	v_or_b32_e32 v7, 0x80000000, v17
	v_cmp_gt_i32_e32 vcc, 0, v17
	s_nop 1
	v_cndmask_b32_e32 v6, v7, v6, vcc
	v_and_or_b32 v96, v6, s17, v96
	v_not_b32_e32 v6, v18
	v_or_b32_e32 v7, 0x80000000, v18
	v_cmp_gt_i32_e32 vcc, 0, v18
	v_not_b32_e32 v18, v19
	s_nop 0
	v_cndmask_b32_e32 v6, v7, v6, vcc
	v_and_or_b32 v95, v6, s17, v95
	s_waitcnt vmcnt(7)
	v_mfma_f32_32x32x16_bf16 v[2:17], v[2:5], v[34:37], 0
	v_cmp_gt_i32_e32 vcc, 0, v19
	v_or_b32_e32 v19, 0x80000000, v20
	s_nop 0
	v_cndmask_b32_e32 v18, v32, v18, vcc
	v_and_or_b32 v94, v18, s17, v94
	v_not_b32_e32 v18, v20
	v_cmp_gt_i32_e32 vcc, 0, v20
	s_waitcnt vmcnt(6)
	v_mfma_f32_32x32x16_bf16 v[2:17], v[28:31], v[38:41], v[2:17]
	v_not_b32_e32 v30, v22
	v_cndmask_b32_e32 v18, v19, v18, vcc
	v_and_or_b32 v93, v18, s17, v93
	v_not_b32_e32 v18, v21
	v_or_b32_e32 v19, 0x80000000, v21
	v_cmp_gt_i32_e32 vcc, 0, v21
	v_or_b32_e32 v31, 0x80000000, v22
	s_waitcnt vmcnt(5)
	v_mfma_f32_32x32x16_bf16 v[2:17], v[170:173], v[42:45], v[2:17]
	v_cndmask_b32_e32 v18, v19, v18, vcc
	v_add_co_u32_e32 v28, vcc, s27, v80
	v_and_or_b32 v92, v18, s17, v92
	s_nop 0
	v_addc_co_u32_e32 v29, vcc, 0, v81, vcc
	global_load_dwordx4 v[18:21], v[28:29], off
	global_load_dwordx4 v[170:173], v[28:29], off offset:32
	s_waitcnt vmcnt(5)
	v_mfma_f32_32x32x16_bf16 v[2:17], v[174:177], v[46:49], v[2:17]
	global_load_dwordx4 v[174:177], v[28:29], off offset:128
	v_cmp_gt_i32_e32 vcc, 0, v22
	s_nop 1
	v_cndmask_b32_e32 v22, v31, v30, vcc
	v_and_or_b32 v90, v22, s17, v90
	v_not_b32_e32 v22, v23
	s_waitcnt vmcnt(4)
	v_mfma_f32_32x32x16_bf16 v[2:17], v[162:165], v[50:53], v[2:17]
	global_load_dwordx4 v[162:165], v[28:29], off offset:64
	v_or_b32_e32 v30, 0x80000000, v23
	v_cmp_gt_i32_e32 vcc, 0, v23
	v_or_b32_e32 v23, 0x80000000, v24
	s_nop 0
	v_cndmask_b32_e32 v22, v30, v22, vcc
	v_and_or_b32 v186, v22, s17, v89
	s_waitcnt vmcnt(4)
	v_mfma_f32_32x32x16_bf16 v[2:17], v[166:169], v[54:57], v[2:17]
	global_load_dwordx4 v[166:169], v[28:29], off offset:96
	v_not_b32_e32 v22, v24
	v_cmp_gt_i32_e32 vcc, 0, v24
	s_nop 1
	v_cndmask_b32_e32 v22, v23, v22, vcc
	v_and_or_b32 v187, v22, s17, v88
	v_mfma_f32_32x32x16_bf16 v[2:17], v[178:181], v[58:61], v[2:17]
	global_load_dwordx4 v[178:181], v[28:29], off offset:160
	v_not_b32_e32 v22, v25
	v_or_b32_e32 v23, 0x80000000, v25
	v_cmp_gt_i32_e32 vcc, 0, v25
	s_nop 1
	v_cndmask_b32_e32 v22, v23, v22, vcc
	v_mfma_f32_32x32x16_bf16 v[2:17], v[182:185], v[62:65], v[2:17]
	v_and_or_b32 v188, v22, s17, v78
	v_not_b32_e32 v22, v26
	v_or_b32_e32 v23, 0x80000000, v26
	v_cmp_gt_i32_e32 vcc, 0, v26
	global_load_dwordx4 v[182:185], v[28:29], off offset:192
	s_nop 0
	v_cndmask_b32_e32 v22, v23, v22, vcc
	v_and_or_b32 v189, v22, s17, v102
	v_not_b32_e32 v22, v27
	v_or_b32_e32 v23, 0x80000000, v27
	v_cmp_gt_i32_e32 vcc, 0, v27
	s_nop 1
	v_cndmask_b32_e32 v22, v23, v22, vcc
	v_and_or_b32 v190, v22, s17, v103
	v_not_b32_e32 v22, v2
	v_or_b32_e32 v23, 0x80000000, v2
	v_cmp_gt_i32_e32 vcc, 0, v2
	s_nop 1
	v_cndmask_b32_e32 v2, v23, v22, vcc
	v_and_or_b32 v78, v2, s17, v104
	v_not_b32_e32 v2, v3
	v_or_b32_e32 v22, 0x80000000, v3
	v_cmp_gt_i32_e32 vcc, 0, v3
	v_or_b32_e32 v3, 0x80000000, v4
	s_nop 0
	v_cndmask_b32_e32 v2, v22, v2, vcc
	v_and_or_b32 v88, v2, s17, v105
	global_load_dwordx4 v[102:105], v[28:29], off offset:224
	v_not_b32_e32 v2, v4
	v_cmp_gt_i32_e32 vcc, 0, v4
	s_waitcnt vmcnt(7)
	v_mfma_f32_32x32x16_bf16 v[18:33], v[18:21], v[34:37], 0
	v_cndmask_b32_e32 v2, v3, v2, vcc
	v_and_or_b32 v89, v2, s17, v107
	v_not_b32_e32 v2, v5
	v_or_b32_e32 v3, 0x80000000, v5
	v_cmp_gt_i32_e32 vcc, 0, v5
	s_nop 1
	v_cndmask_b32_e32 v2, v3, v2, vcc
	v_and_or_b32 v191, v2, s17, v106
	v_not_b32_e32 v2, v6
	v_or_b32_e32 v3, 0x80000000, v6
	v_cmp_gt_i32_e32 vcc, 0, v6
	s_waitcnt vmcnt(6)
	v_mfma_f32_32x32x16_bf16 v[18:33], v[170:173], v[38:41], v[18:33]
	v_cndmask_b32_e32 v2, v3, v2, vcc
	v_and_or_b32 v192, v2, s17, v108
	v_not_b32_e32 v2, v7
	v_or_b32_e32 v3, 0x80000000, v7
	v_cmp_gt_i32_e32 vcc, 0, v7
	s_waitcnt vmcnt(4)
	v_mfma_f32_32x32x16_bf16 v[18:33], v[162:165], v[42:45], v[18:33]
	v_cndmask_b32_e32 v2, v3, v2, vcc
	v_and_or_b32 v193, v2, s17, v109
	v_not_b32_e32 v2, v8
	v_or_b32_e32 v3, 0x80000000, v8
	v_cmp_gt_i32_e32 vcc, 0, v8
	s_nop 1
	v_cndmask_b32_e32 v2, v3, v2, vcc
	v_and_or_b32 v194, v2, s17, v110
	v_not_b32_e32 v2, v9
	v_or_b32_e32 v3, 0x80000000, v9
	v_cmp_gt_i32_e32 vcc, 0, v9
	v_or_b32_e32 v9, 0x80000000, v11
	s_waitcnt vmcnt(3)
	v_mfma_f32_32x32x16_bf16 v[18:33], v[166:169], v[46:49], v[18:33]
	v_cndmask_b32_e32 v2, v3, v2, vcc
	v_and_or_b32 v195, v2, s17, v111
	v_not_b32_e32 v2, v10
	v_or_b32_e32 v3, 0x80000000, v10
	v_cmp_gt_i32_e32 vcc, 0, v10
	s_nop 1
	v_cndmask_b32_e32 v8, v3, v2, vcc
	v_add_co_u32_e32 v6, vcc, s28, v80
	v_and_or_b32 v80, v8, s17, v68
	s_nop 0
	v_addc_co_u32_e32 v7, vcc, 0, v81, vcc
	global_load_dwordx4 v[2:5], v[6:7], off
	global_load_dwordx4 v[106:109], v[6:7], off offset:32
	global_load_dwordx4 v[162:165], v[6:7], off offset:64
	global_load_dwordx4 v[166:169], v[6:7], off offset:96
	v_not_b32_e32 v8, v11
	v_cmp_gt_i32_e32 vcc, 0, v11
	v_mfma_f32_32x32x16_bf16 v[18:33], v[174:177], v[50:53], v[18:33]
	global_load_dwordx4 v[170:173], v[6:7], off offset:192
	v_cndmask_b32_e32 v8, v9, v8, vcc
	v_and_or_b32 v81, v8, s17, v91
	v_not_b32_e32 v8, v12
	v_or_b32_e32 v9, 0x80000000, v12
	v_cmp_gt_i32_e32 vcc, 0, v12
	s_waitcnt vmcnt(7)
	v_mfma_f32_32x32x16_bf16 v[18:33], v[178:181], v[54:57], v[18:33]
	v_cndmask_b32_e32 v8, v9, v8, vcc
	v_and_or_b32 v91, v8, s17, v69
	v_not_b32_e32 v8, v13
	v_or_b32_e32 v9, 0x80000000, v13
	v_cmp_gt_i32_e32 vcc, 0, v13
	s_nop 1
	v_cndmask_b32_e32 v8, v9, v8, vcc
	v_and_or_b32 v196, v8, s17, v67
	v_not_b32_e32 v8, v14
	v_or_b32_e32 v9, 0x80000000, v14
	v_cmp_gt_i32_e32 vcc, 0, v14
	s_waitcnt vmcnt(6)
	v_mfma_f32_32x32x16_bf16 v[18:33], v[182:185], v[58:61], v[18:33]
	v_cndmask_b32_e32 v8, v9, v8, vcc
	v_and_or_b32 v174, v8, s17, v66
	global_load_dwordx4 v[66:69], v[6:7], off offset:128
	v_not_b32_e32 v8, v15
	v_or_b32_e32 v9, 0x80000000, v15
	v_cmp_gt_i32_e32 vcc, 0, v15
	s_waitcnt vmcnt(6)
	v_mfma_f32_32x32x16_bf16 v[18:33], v[102:105], v[62:65], v[18:33]
	global_load_dwordx4 v[102:105], v[6:7], off offset:224
	v_cndmask_b32_e32 v8, v9, v8, vcc
	v_and_or_b32 v175, v8, s17, v112
	v_not_b32_e32 v8, v16
	v_or_b32_e32 v9, 0x80000000, v16
	v_cmp_gt_i32_e32 vcc, 0, v16
	s_nop 1
	v_cndmask_b32_e32 v8, v9, v8, vcc
	v_and_or_b32 v176, v8, s17, v113
	global_load_dwordx4 v[110:113], v[6:7], off offset:160
	v_not_b32_e32 v8, v17
	v_or_b32_e32 v9, 0x80000000, v17
	v_cmp_gt_i32_e32 vcc, 0, v17
	v_not_b32_e32 v6, v19
	v_or_b32_e32 v7, 0x80000000, v19
	v_cndmask_b32_e32 v8, v9, v8, vcc
	v_and_or_b32 v114, v8, s17, v114
	v_not_b32_e32 v8, v18
	v_or_b32_e32 v9, 0x80000000, v18
	v_cmp_gt_i32_e32 vcc, 0, v18
	s_nop 1
	v_cndmask_b32_e32 v8, v9, v8, vcc
	v_cmp_gt_i32_e32 vcc, 0, v19
	v_and_or_b32 v18, v8, s17, v115
	v_not_b32_e32 v115, v23
	v_cndmask_b32_e32 v6, v7, v6, vcc
	v_and_or_b32 v19, v6, s17, v116
	v_not_b32_e32 v6, v20
	v_or_b32_e32 v7, 0x80000000, v20
	v_cmp_gt_i32_e32 vcc, 0, v20
	v_or_b32_e32 v116, 0x80000000, v23
	s_nop 0
	v_cndmask_b32_e32 v6, v7, v6, vcc
	v_and_or_b32 v20, v6, s17, v117
	v_not_b32_e32 v6, v21
	v_or_b32_e32 v7, 0x80000000, v21
	v_cmp_gt_i32_e32 vcc, 0, v21
	s_nop 1
	v_cndmask_b32_e32 v6, v7, v6, vcc
	v_and_or_b32 v21, v6, s17, v118
	v_not_b32_e32 v6, v22
	v_or_b32_e32 v7, 0x80000000, v22
	v_cmp_gt_i32_e32 vcc, 0, v22
	s_nop 1
	v_cndmask_b32_e32 v6, v7, v6, vcc
	v_and_or_b32 v22, v6, s17, v119
	s_waitcnt vmcnt(7)
	v_mfma_f32_32x32x16_bf16 v[2:17], v[2:5], v[34:37], 0
	v_cmp_gt_i32_e32 vcc, 0, v23
	v_not_b32_e32 v34, v24
	v_or_b32_e32 v35, 0x80000000, v24
	v_cndmask_b32_e32 v23, v116, v115, vcc
	v_cmp_gt_i32_e32 vcc, 0, v24
	v_and_or_b32 v23, v23, s17, v120
	v_max_u32_e32 v36, v101, v99
	s_waitcnt vmcnt(6)
	v_mfma_f32_32x32x16_bf16 v[2:17], v[106:109], v[38:41], v[2:17]
	v_cndmask_b32_e32 v24, v35, v34, vcc
	v_not_b32_e32 v34, v25
	v_or_b32_e32 v35, 0x80000000, v25
	v_cmp_gt_i32_e32 vcc, 0, v25
	v_and_or_b32 v24, v24, s17, v121
	v_min_u32_e32 v37, v101, v99
	v_cndmask_b32_e32 v25, v35, v34, vcc
	s_waitcnt vmcnt(5)
	v_mfma_f32_32x32x16_bf16 v[2:17], v[162:165], v[42:45], v[2:17]
	v_not_b32_e32 v34, v26
	v_or_b32_e32 v35, 0x80000000, v26
	v_cmp_gt_i32_e32 vcc, 0, v26
	v_and_or_b32 v25, v25, s17, v122
	v_max_u32_e32 v38, v97, v96
	v_cndmask_b32_e32 v26, v35, v34, vcc
	v_not_b32_e32 v34, v27
	s_waitcnt vmcnt(4)
	v_mfma_f32_32x32x16_bf16 v[2:17], v[166:169], v[46:49], v[2:17]
	v_or_b32_e32 v35, 0x80000000, v27
	v_cmp_gt_i32_e32 vcc, 0, v27
	v_and_or_b32 v26, v26, s17, v123
	v_min_u32_e32 v39, v97, v96
	v_cndmask_b32_e32 v27, v35, v34, vcc
	v_not_b32_e32 v34, v28
	v_or_b32_e32 v35, 0x80000000, v28
	s_waitcnt vmcnt(2)
	v_mfma_f32_32x32x16_bf16 v[2:17], v[66:69], v[50:53], v[2:17]
	v_cmp_gt_i32_e32 vcc, 0, v28
	v_and_or_b32 v27, v27, s17, v124
	v_max_u32_e32 v40, v95, v94
	v_cndmask_b32_e32 v28, v35, v34, vcc
	v_not_b32_e32 v34, v29
	v_or_b32_e32 v35, 0x80000000, v29
	v_cmp_gt_i32_e32 vcc, 0, v29
	s_waitcnt vmcnt(0)
	v_mfma_f32_32x32x16_bf16 v[2:17], v[110:113], v[54:57], v[2:17]
	v_cndmask_b32_e32 v29, v35, v34, vcc
	v_not_b32_e32 v34, v30
	v_or_b32_e32 v35, 0x80000000, v30
	v_cmp_gt_i32_e32 vcc, 0, v30
	v_and_or_b32 v28, v28, s17, v125
	v_and_or_b32 v29, v29, s17, v126
	v_cndmask_b32_e32 v30, v35, v34, vcc
	v_mfma_f32_32x32x16_bf16 v[2:17], v[170:173], v[58:61], v[2:17]
	v_not_b32_e32 v34, v31
	v_or_b32_e32 v35, 0x80000000, v31
	v_cmp_gt_i32_e32 vcc, 0, v31
	v_and_or_b32 v30, v30, s17, v127
	v_min_u32_e32 v41, v95, v94
	v_cndmask_b32_e32 v31, v35, v34, vcc
	v_not_b32_e32 v34, v32
	v_mfma_f32_32x32x16_bf16 v[2:17], v[102:105], v[62:65], v[2:17]
	v_or_b32_e32 v35, 0x80000000, v32
	v_cmp_gt_i32_e32 vcc, 0, v32
	v_and_or_b32 v31, v31, s17, v128
	v_max_u32_e32 v42, v93, v92
	v_cndmask_b32_e32 v32, v35, v34, vcc
	v_not_b32_e32 v34, v33
	v_or_b32_e32 v35, 0x80000000, v33
	v_cmp_gt_i32_e32 vcc, 0, v33
	v_and_or_b32 v32, v32, s17, v129
	v_min_u32_e32 v43, v93, v92
	v_cndmask_b32_e32 v33, v35, v34, vcc
	s_nop 0
	v_not_b32_e32 v34, v2
	v_or_b32_e32 v35, 0x80000000, v2
	v_cmp_gt_i32_e32 vcc, 0, v2
	global_load_dwordx4 v[200:203], v[236:237], off
	global_load_dwordx4 v[204:207], v[236:237], off offset:16
	global_load_dwordx4 v[208:211], v[236:237], off offset:32
	global_load_dwordx4 v[212:215], v[236:237], off offset:48
	global_load_dwordx4 v[216:219], v[238:239], off
	global_load_dwordx4 v[220:223], v[238:239], off offset:16
	global_load_dwordx4 v[224:227], v[238:239], off offset:32
	global_load_dwordx4 v[228:231], v[238:239], off offset:48
	v_lshl_add_u64 v[236:237], v[236:237], 0, v[244:245]
	v_lshl_add_u64 v[238:239], v[238:239], 0, v[244:245]
	v_and_or_b32 v33, v33, s17, v130
	v_max_u32_e32 v44, v90, v186
	v_cndmask_b32_e32 v2, v35, v34, vcc
	v_not_b32_e32 v34, v3
	v_or_b32_e32 v35, 0x80000000, v3
	v_cmp_gt_i32_e32 vcc, 0, v3
	v_and_or_b32 v2, v2, s17, v131
	v_min_u32_e32 v45, v90, v186
	v_cndmask_b32_e32 v3, v35, v34, vcc
	v_not_b32_e32 v34, v4
	v_or_b32_e32 v35, 0x80000000, v4
	v_cmp_gt_i32_e32 vcc, 0, v4
	v_and_or_b32 v3, v3, s17, v132
	v_max_u32_e32 v46, v187, v188
	v_cndmask_b32_e32 v4, v35, v34, vcc
	v_not_b32_e32 v34, v5
	v_or_b32_e32 v35, 0x80000000, v5
	v_cmp_gt_i32_e32 vcc, 0, v5
	v_and_or_b32 v4, v4, s17, v133
	v_min_u32_e32 v47, v187, v188
	v_cndmask_b32_e32 v5, v35, v34, vcc
	v_not_b32_e32 v34, v6
	v_or_b32_e32 v35, 0x80000000, v6
	v_cmp_gt_i32_e32 vcc, 0, v6
	v_and_or_b32 v5, v5, s17, v134
	v_max_u32_e32 v48, v189, v190
	v_cndmask_b32_e32 v6, v35, v34, vcc
	v_not_b32_e32 v34, v7
	v_or_b32_e32 v35, 0x80000000, v7
	v_cmp_gt_i32_e32 vcc, 0, v7
	v_and_or_b32 v6, v6, s17, v135
	v_min_u32_e32 v49, v189, v190
	v_cndmask_b32_e32 v7, v35, v34, vcc
	v_not_b32_e32 v34, v8
	v_or_b32_e32 v35, 0x80000000, v8
	v_cmp_gt_i32_e32 vcc, 0, v8
	v_and_or_b32 v7, v7, s17, v136
	v_max_u32_e32 v58, v78, v88
	v_cndmask_b32_e32 v8, v35, v34, vcc
	v_not_b32_e32 v34, v9
	v_or_b32_e32 v35, 0x80000000, v9
	v_cmp_gt_i32_e32 vcc, 0, v9
	v_and_or_b32 v8, v8, s17, v137
	v_min_u32_e32 v59, v78, v88
	v_cndmask_b32_e32 v9, v35, v34, vcc
	v_not_b32_e32 v34, v10
	v_or_b32_e32 v35, 0x80000000, v10
	v_cmp_gt_i32_e32 vcc, 0, v10
	v_and_or_b32 v9, v9, s17, v138
	v_max_u32_e32 v60, v89, v191
	v_cndmask_b32_e32 v10, v35, v34, vcc
	v_not_b32_e32 v34, v11
	v_or_b32_e32 v35, 0x80000000, v11
	v_cmp_gt_i32_e32 vcc, 0, v11
	v_and_or_b32 v10, v10, s17, v139
	v_min_u32_e32 v61, v89, v191
	v_cndmask_b32_e32 v11, v35, v34, vcc
	v_not_b32_e32 v34, v12
	v_or_b32_e32 v35, 0x80000000, v12
	v_cmp_gt_i32_e32 vcc, 0, v12
	v_and_or_b32 v11, v11, s17, v140
	v_max_u32_e32 v62, v192, v193
	v_cndmask_b32_e32 v12, v35, v34, vcc
	v_not_b32_e32 v34, v13
	v_or_b32_e32 v35, 0x80000000, v13
	v_cmp_gt_i32_e32 vcc, 0, v13
	v_and_or_b32 v12, v12, s17, v141
	v_min_u32_e32 v63, v192, v193
	v_cndmask_b32_e32 v13, v35, v34, vcc
	v_not_b32_e32 v34, v14
	v_or_b32_e32 v35, 0x80000000, v14
	v_cmp_gt_i32_e32 vcc, 0, v14
	v_and_or_b32 v13, v13, s17, v142
	v_max_u32_e32 v64, v194, v195
	v_cndmask_b32_e32 v14, v35, v34, vcc
	v_not_b32_e32 v34, v15
	v_or_b32_e32 v35, 0x80000000, v15
	v_cmp_gt_i32_e32 vcc, 0, v15
	v_and_or_b32 v14, v14, s17, v143
	v_min_u32_e32 v65, v194, v195
	v_cndmask_b32_e32 v15, v35, v34, vcc
	v_not_b32_e32 v34, v16
	v_or_b32_e32 v35, 0x80000000, v16
	v_cmp_gt_i32_e32 vcc, 0, v16
	v_and_or_b32 v15, v15, s17, v144
	v_max_u32_e32 v66, v80, v81
	v_cndmask_b32_e32 v16, v35, v34, vcc
	v_not_b32_e32 v34, v17
	v_or_b32_e32 v35, 0x80000000, v17
	v_cmp_gt_i32_e32 vcc, 0, v17
	v_and_or_b32 v16, v16, s17, v145
	v_min_u32_e32 v67, v80, v81
	v_cndmask_b32_e32 v17, v35, v34, vcc
	v_and_or_b32 v17, v17, s17, v146
	v_max_u32_e32 v34, v100, v98
	v_min_u32_e32 v35, v100, v98
	v_max_u32_e32 v68, v91, v196
	v_min_u32_e32 v69, v91, v196
	v_max_u32_e32 v78, v174, v175
	v_min_u32_e32 v80, v174, v175
	v_max_u32_e32 v81, v176, v114
	v_min_u32_e32 v88, v176, v114
	v_max_u32_e32 v97, v18, v19
	v_min_u32_e32 v18, v18, v19
	v_max_u32_e32 v19, v20, v21
	v_min_u32_e32 v20, v20, v21
	v_max_u32_e32 v21, v22, v23
	v_min_u32_e32 v22, v22, v23
	v_max_u32_e32 v23, v24, v25
	v_min_u32_e32 v24, v24, v25
	v_max_u32_e32 v25, v26, v27
	v_min_u32_e32 v26, v26, v27
	v_max_u32_e32 v27, v28, v29
	v_min_u32_e32 v28, v28, v29
	v_max_u32_e32 v29, v30, v31
	v_min_u32_e32 v30, v30, v31
	v_max_u32_e32 v31, v32, v33
	v_min_u32_e32 v32, v32, v33
	v_max_u32_e32 v105, v2, v3
	v_min_u32_e32 v2, v2, v3
	v_max_u32_e32 v3, v4, v5
	v_min_u32_e32 v4, v4, v5
	v_max_u32_e32 v5, v6, v7
	v_min_u32_e32 v6, v6, v7
	v_max_u32_e32 v7, v8, v9
	v_min_u32_e32 v8, v8, v9
	v_max_u32_e32 v9, v10, v11
	v_min_u32_e32 v10, v10, v11
	v_max_u32_e32 v11, v12, v13
	v_min_u32_e32 v12, v12, v13
	v_max_u32_e32 v13, v14, v15
	v_min_u32_e32 v14, v14, v15
	v_max_u32_e32 v15, v16, v17
	v_min_u32_e32 v16, v16, v17
	v_max_u32_e32 v50, v34, v37
	v_min_u32_e32 v34, v34, v37
	v_max_u32_e32 v37, v35, v36
	v_min_u32_e32 v35, v35, v36
	v_max_u32_e32 v36, v38, v41
	v_min_u32_e32 v38, v38, v41
	v_max_u32_e32 v41, v39, v40
	v_min_u32_e32 v39, v39, v40
	v_max_u32_e32 v40, v42, v45
	v_min_u32_e32 v42, v42, v45
	v_max_u32_e32 v45, v43, v44
	v_min_u32_e32 v43, v43, v44
	v_max_u32_e32 v44, v46, v49
	v_min_u32_e32 v46, v46, v49
	v_max_u32_e32 v49, v47, v48
	v_min_u32_e32 v47, v47, v48
	v_max_u32_e32 v89, v58, v61
	v_min_u32_e32 v58, v58, v61
	v_max_u32_e32 v61, v59, v60
	v_min_u32_e32 v59, v59, v60
	v_max_u32_e32 v60, v62, v65
	v_min_u32_e32 v62, v62, v65
	v_max_u32_e32 v65, v63, v64
	v_min_u32_e32 v63, v63, v64
	v_max_u32_e32 v64, v66, v69
	v_min_u32_e32 v66, v66, v69
	v_max_u32_e32 v69, v67, v68
	v_min_u32_e32 v67, v67, v68
	v_max_u32_e32 v68, v78, v88
	v_min_u32_e32 v78, v78, v88
	v_max_u32_e32 v88, v80, v81
	v_min_u32_e32 v80, v80, v81
	v_max_u32_e32 v33, v97, v20
	v_min_u32_e32 v20, v97, v20
	v_max_u32_e32 v97, v18, v19
	v_min_u32_e32 v18, v18, v19
	v_max_u32_e32 v19, v21, v24
	v_min_u32_e32 v21, v21, v24
	v_max_u32_e32 v24, v22, v23
	v_min_u32_e32 v22, v22, v23
	v_max_u32_e32 v23, v25, v28
	v_min_u32_e32 v25, v25, v28
	v_max_u32_e32 v28, v26, v27
	v_min_u32_e32 v26, v26, v27
	v_max_u32_e32 v27, v29, v32
	v_min_u32_e32 v29, v29, v32
	v_max_u32_e32 v32, v30, v31
	v_min_u32_e32 v30, v30, v31
	v_max_u32_e32 v17, v105, v4
	v_min_u32_e32 v4, v105, v4
	v_max_u32_e32 v105, v2, v3
	v_min_u32_e32 v2, v2, v3
	v_max_u32_e32 v3, v5, v8
	v_min_u32_e32 v5, v5, v8
	v_max_u32_e32 v8, v6, v7
	v_min_u32_e32 v6, v6, v7
	v_max_u32_e32 v7, v9, v12
	v_min_u32_e32 v9, v9, v12
	v_max_u32_e32 v12, v10, v11
	v_min_u32_e32 v10, v10, v11
	v_max_u32_e32 v11, v13, v16
	v_min_u32_e32 v13, v13, v16
	v_max_u32_e32 v16, v14, v15
	v_min_u32_e32 v14, v14, v15
	v_max_u32_e32 v48, v50, v37
	v_min_u32_e32 v37, v50, v37
	v_max_u32_e32 v50, v34, v35
	v_min_u32_e32 v34, v34, v35
	v_max_u32_e32 v35, v38, v39
	v_min_u32_e32 v38, v38, v39
	v_max_u32_e32 v39, v36, v41
	v_min_u32_e32 v36, v36, v41
	v_max_u32_e32 v41, v40, v45
	v_min_u32_e32 v40, v40, v45
	v_max_u32_e32 v45, v42, v43
	v_min_u32_e32 v42, v42, v43
	v_max_u32_e32 v43, v46, v47
	v_min_u32_e32 v46, v46, v47
	v_max_u32_e32 v47, v44, v49
	v_min_u32_e32 v44, v44, v49
	v_max_u32_e32 v81, v89, v61
	v_min_u32_e32 v61, v89, v61
	v_max_u32_e32 v89, v58, v59
	v_min_u32_e32 v58, v58, v59
	v_max_u32_e32 v59, v62, v63
	v_min_u32_e32 v62, v62, v63
	v_max_u32_e32 v63, v60, v65
	v_min_u32_e32 v60, v60, v65
	v_max_u32_e32 v65, v64, v69
	v_min_u32_e32 v64, v64, v69
	v_max_u32_e32 v69, v66, v67
	v_min_u32_e32 v66, v66, v67
	v_max_u32_e32 v67, v78, v80
	v_min_u32_e32 v78, v78, v80
	v_max_u32_e32 v80, v68, v88
	v_min_u32_e32 v68, v68, v88
	v_max_u32_e32 v31, v33, v97
	v_min_u32_e32 v33, v33, v97
	v_max_u32_e32 v97, v20, v18
	v_min_u32_e32 v18, v20, v18
	v_max_u32_e32 v20, v21, v22
	v_min_u32_e32 v21, v21, v22
	v_max_u32_e32 v22, v19, v24
	v_min_u32_e32 v19, v19, v24
	v_max_u32_e32 v24, v23, v28
	v_min_u32_e32 v23, v23, v28
	v_max_u32_e32 v28, v25, v26
	v_min_u32_e32 v25, v25, v26
	v_max_u32_e32 v26, v29, v30
	v_min_u32_e32 v29, v29, v30
	v_max_u32_e32 v30, v27, v32
	v_min_u32_e32 v27, v27, v32
	v_max_u32_e32 v15, v17, v105
	v_min_u32_e32 v17, v17, v105
	v_max_u32_e32 v105, v4, v2
	v_min_u32_e32 v2, v4, v2
	v_max_u32_e32 v4, v5, v6
	v_min_u32_e32 v5, v5, v6
	v_max_u32_e32 v6, v3, v8
	v_min_u32_e32 v3, v3, v8
	v_max_u32_e32 v8, v7, v12
	v_min_u32_e32 v7, v7, v12
	v_max_u32_e32 v12, v9, v10
	v_min_u32_e32 v9, v9, v10
	v_max_u32_e32 v10, v13, v14
	v_min_u32_e32 v13, v13, v14
	v_max_u32_e32 v14, v11, v16
	v_min_u32_e32 v11, v11, v16
	v_max_u32_e32 v49, v48, v38
	v_min_u32_e32 v38, v48, v38
	v_max_u32_e32 v48, v37, v35
	v_min_u32_e32 v35, v37, v35
	v_max_u32_e32 v37, v50, v36
	v_min_u32_e32 v36, v50, v36
	v_max_u32_e32 v50, v34, v39
	v_min_u32_e32 v34, v34, v39
	v_max_u32_e32 v39, v41, v46
	v_min_u32_e32 v41, v41, v46
	v_max_u32_e32 v46, v40, v43
	v_min_u32_e32 v40, v40, v43
	v_max_u32_e32 v43, v45, v44
	v_min_u32_e32 v44, v45, v44
	v_max_u32_e32 v45, v42, v47
	v_min_u32_e32 v42, v42, v47
	v_max_u32_e32 v88, v81, v62
	v_min_u32_e32 v62, v81, v62
	v_max_u32_e32 v81, v61, v59
	v_min_u32_e32 v59, v61, v59
	v_max_u32_e32 v61, v89, v60
	v_min_u32_e32 v60, v89, v60
	v_max_u32_e32 v89, v58, v63
	v_min_u32_e32 v58, v58, v63
	v_max_u32_e32 v63, v65, v78
	v_min_u32_e32 v65, v65, v78
	v_max_u32_e32 v78, v64, v67
	v_min_u32_e32 v64, v64, v67
	v_max_u32_e32 v67, v69, v68
	v_min_u32_e32 v68, v69, v68
	v_max_u32_e32 v69, v66, v80
	v_min_u32_e32 v66, v66, v80
	v_max_u32_e32 v32, v31, v21
	v_min_u32_e32 v21, v31, v21
	v_max_u32_e32 v31, v33, v20
	v_min_u32_e32 v20, v33, v20
	v_max_u32_e32 v33, v97, v19
	v_min_u32_e32 v19, v97, v19
	v_max_u32_e32 v97, v18, v22
	v_min_u32_e32 v18, v18, v22
	v_max_u32_e32 v22, v24, v29
	v_min_u32_e32 v24, v24, v29
	v_max_u32_e32 v29, v23, v26
	v_min_u32_e32 v23, v23, v26
	v_max_u32_e32 v26, v28, v27
	v_min_u32_e32 v27, v28, v27
	v_max_u32_e32 v28, v25, v30
	v_min_u32_e32 v25, v25, v30
	v_max_u32_e32 v16, v15, v5
	v_min_u32_e32 v5, v15, v5
	v_max_u32_e32 v15, v17, v4
	v_min_u32_e32 v4, v17, v4
	v_max_u32_e32 v17, v105, v3
	v_min_u32_e32 v3, v105, v3
	v_max_u32_e32 v105, v2, v6
	v_min_u32_e32 v2, v2, v6
	v_max_u32_e32 v6, v8, v13
	v_min_u32_e32 v8, v8, v13
	v_max_u32_e32 v13, v7, v10
	v_min_u32_e32 v7, v7, v10
	v_max_u32_e32 v10, v12, v11
	v_min_u32_e32 v11, v12, v11
	v_max_u32_e32 v12, v9, v14
	v_min_u32_e32 v9, v9, v14
	v_max_u32_e32 v47, v49, v37
	v_min_u32_e32 v37, v49, v37
	v_max_u32_e32 v49, v48, v50
	v_min_u32_e32 v48, v48, v50
	v_max_u32_e32 v50, v38, v36
	v_min_u32_e32 v36, v38, v36
	v_max_u32_e32 v38, v35, v34
	v_min_u32_e32 v34, v35, v34
	v_max_u32_e32 v35, v41, v44
	v_min_u32_e32 v41, v41, v44
	v_max_u32_e32 v44, v40, v42
	v_min_u32_e32 v40, v40, v42
	v_max_u32_e32 v42, v39, v43
	v_min_u32_e32 v39, v39, v43
	v_max_u32_e32 v43, v46, v45
	v_min_u32_e32 v45, v46, v45
	v_max_u32_e32 v80, v88, v61
	v_min_u32_e32 v61, v88, v61
	v_max_u32_e32 v88, v81, v89
	s_waitcnt vmcnt(0)
	v_pk_mul_f32 v[200:201], v[200:201], s[96:97] op_sel_hi:[1,0]
	v_pk_mul_f32 v[202:203], v[202:203], s[96:97] op_sel_hi:[1,0]
	v_pk_mul_f32 v[204:205], v[204:205], s[96:97] op_sel_hi:[1,0]
	v_pk_mul_f32 v[206:207], v[206:207], s[96:97] op_sel_hi:[1,0]
	v_pk_mul_f32 v[208:209], v[208:209], s[96:97] op_sel_hi:[1,0]
	v_pk_mul_f32 v[210:211], v[210:211], s[96:97] op_sel_hi:[1,0]
	v_pk_mul_f32 v[212:213], v[212:213], s[96:97] op_sel_hi:[1,0]
	v_pk_mul_f32 v[214:215], v[214:215], s[96:97] op_sel_hi:[1,0]
	v_pk_mul_f32 v[216:217], v[216:217], s[96:97] op_sel_hi:[1,0]
	v_pk_mul_f32 v[218:219], v[218:219], s[96:97] op_sel_hi:[1,0]
	v_pk_mul_f32 v[220:221], v[220:221], s[96:97] op_sel_hi:[1,0]
	v_pk_mul_f32 v[222:223], v[222:223], s[96:97] op_sel_hi:[1,0]
	v_pk_mul_f32 v[224:225], v[224:225], s[96:97] op_sel_hi:[1,0]
	v_pk_mul_f32 v[226:227], v[226:227], s[96:97] op_sel_hi:[1,0]
	v_pk_mul_f32 v[228:229], v[228:229], s[96:97] op_sel_hi:[1,0]
	v_pk_mul_f32 v[230:231], v[230:231], s[96:97] op_sel_hi:[1,0]
	v_cvt_scalef32_pk_fp4_f32 v232, v200, v201, 1.0
	v_cvt_scalef32_pk_fp4_f32 v233, v208, v209, 1.0
	v_cvt_scalef32_pk_fp4_f32 v234, v216, v217, 1.0
	v_cvt_scalef32_pk_fp4_f32 v235, v224, v225, 1.0
	v_cvt_scalef32_pk_fp4_f32 v232, v202, v203, 1.0 op_sel:[0,0,1,0]
	v_cvt_scalef32_pk_fp4_f32 v233, v210, v211, 1.0 op_sel:[0,0,1,0]
	v_cvt_scalef32_pk_fp4_f32 v234, v218, v219, 1.0 op_sel:[0,0,1,0]
	v_cvt_scalef32_pk_fp4_f32 v235, v226, v227, 1.0 op_sel:[0,0,1,0]
	v_cvt_scalef32_pk_fp4_f32 v232, v204, v205, 1.0 op_sel:[0,0,0,1]
	v_cvt_scalef32_pk_fp4_f32 v233, v212, v213, 1.0 op_sel:[0,0,0,1]
	v_cvt_scalef32_pk_fp4_f32 v234, v220, v221, 1.0 op_sel:[0,0,0,1]
	v_cvt_scalef32_pk_fp4_f32 v235, v228, v229, 1.0 op_sel:[0,0,0,1]
	v_cvt_scalef32_pk_fp4_f32 v232, v206, v207, 1.0 op_sel:[0,0,1,1]
	v_cvt_scalef32_pk_fp4_f32 v233, v214, v215, 1.0 op_sel:[0,0,1,1]
	v_cvt_scalef32_pk_fp4_f32 v234, v222, v223, 1.0 op_sel:[0,0,1,1]
	v_cvt_scalef32_pk_fp4_f32 v235, v230, v231, 1.0 op_sel:[0,0,1,1]
	s_nop 0
	global_store_dwordx4 v[240:241], v[232:235], off
	v_lshl_add_u64 v[240:241], v[240:241], 0, v[246:247]
	global_load_dwordx4 v[200:203], v[236:237], off
	global_load_dwordx4 v[204:207], v[236:237], off offset:16
	global_load_dwordx4 v[208:211], v[236:237], off offset:32
	global_load_dwordx4 v[212:215], v[236:237], off offset:48
	global_load_dwordx4 v[216:219], v[238:239], off
	global_load_dwordx4 v[220:223], v[238:239], off offset:16
	global_load_dwordx4 v[224:227], v[238:239], off offset:32
	global_load_dwordx4 v[228:231], v[238:239], off offset:48
	v_lshl_add_u64 v[236:237], v[236:237], 0, v[244:245]
	v_lshl_add_u64 v[238:239], v[238:239], 0, v[244:245]
	v_min_u32_e32 v81, v81, v89
	v_max_u32_e32 v89, v62, v60
	v_min_u32_e32 v60, v62, v60
	v_max_u32_e32 v62, v59, v58
	v_min_u32_e32 v58, v59, v58
	v_max_u32_e32 v59, v65, v68
	v_min_u32_e32 v65, v65, v68
	v_max_u32_e32 v68, v64, v66
	v_min_u32_e32 v64, v64, v66
	v_max_u32_e32 v66, v63, v67
	v_min_u32_e32 v63, v63, v67
	v_max_u32_e32 v67, v78, v69
	v_min_u32_e32 v69, v78, v69
	v_max_u32_e32 v30, v32, v33
	v_min_u32_e32 v32, v32, v33
	v_max_u32_e32 v33, v31, v97
	v_min_u32_e32 v31, v31, v97
	v_max_u32_e32 v97, v21, v19
	v_min_u32_e32 v19, v21, v19
	v_max_u32_e32 v21, v20, v18
	v_min_u32_e32 v18, v20, v18
	v_max_u32_e32 v20, v24, v27
	v_min_u32_e32 v24, v24, v27
	v_max_u32_e32 v27, v23, v25
	v_min_u32_e32 v23, v23, v25
	v_max_u32_e32 v25, v22, v26
	v_min_u32_e32 v22, v22, v26
	v_max_u32_e32 v26, v29, v28
	v_min_u32_e32 v28, v29, v28
	v_max_u32_e32 v14, v16, v17
	v_min_u32_e32 v16, v16, v17
	v_max_u32_e32 v17, v15, v105
	v_min_u32_e32 v15, v15, v105
	v_max_u32_e32 v105, v5, v3
	v_min_u32_e32 v3, v5, v3
	v_max_u32_e32 v5, v4, v2
	v_min_u32_e32 v2, v4, v2
	v_max_u32_e32 v4, v8, v11
	v_min_u32_e32 v8, v8, v11
	v_max_u32_e32 v11, v7, v9
	v_min_u32_e32 v7, v7, v9
	v_max_u32_e32 v9, v6, v10
	v_min_u32_e32 v6, v6, v10
	v_max_u32_e32 v10, v13, v12
	v_min_u32_e32 v12, v13, v12
	v_max_u32_e32 v46, v47, v49
	v_min_u32_e32 v47, v47, v49
	v_max_u32_e32 v49, v37, v48
	v_min_u32_e32 v37, v37, v48
	v_max_u32_e32 v48, v50, v38
	v_min_u32_e32 v38, v50, v38
	v_max_u32_e32 v50, v36, v34
	v_min_u32_e32 v34, v36, v34
	v_max_u32_e32 v36, v41, v40
	v_min_u32_e32 v40, v41, v40
	v_max_u32_e32 v41, v35, v44
	v_min_u32_e32 v35, v35, v44
	v_max_u32_e32 v44, v39, v45
	v_min_u32_e32 v39, v39, v45
	v_max_u32_e32 v45, v42, v43
	v_min_u32_e32 v42, v42, v43
	v_max_u32_e32 v78, v80, v88
	v_min_u32_e32 v80, v80, v88
	v_max_u32_e32 v88, v61, v81
	v_min_u32_e32 v61, v61, v81
	v_max_u32_e32 v81, v89, v62
	v_min_u32_e32 v62, v89, v62
	v_max_u32_e32 v89, v60, v58
	v_min_u32_e32 v58, v60, v58
	v_max_u32_e32 v60, v65, v64
	v_min_u32_e32 v64, v65, v64
	v_max_u32_e32 v65, v59, v68
	v_min_u32_e32 v59, v59, v68
	v_max_u32_e32 v68, v63, v69
	v_min_u32_e32 v63, v63, v69
	v_max_u32_e32 v69, v66, v67
	v_min_u32_e32 v66, v66, v67
	v_max_u32_e32 v29, v30, v33
	v_min_u32_e32 v30, v30, v33
	v_max_u32_e32 v33, v32, v31
	v_min_u32_e32 v31, v32, v31
	v_max_u32_e32 v32, v97, v21
	v_min_u32_e32 v21, v97, v21
	v_max_u32_e32 v97, v19, v18
	v_min_u32_e32 v18, v19, v18
	v_max_u32_e32 v19, v24, v23
	v_min_u32_e32 v23, v24, v23
	v_max_u32_e32 v24, v20, v27
	v_min_u32_e32 v20, v20, v27
	v_max_u32_e32 v27, v22, v28
	v_min_u32_e32 v22, v22, v28
	v_max_u32_e32 v28, v25, v26
	v_min_u32_e32 v25, v25, v26
	v_max_u32_e32 v13, v14, v17
	v_min_u32_e32 v14, v14, v17
	v_max_u32_e32 v17, v16, v15
	v_min_u32_e32 v15, v16, v15
	v_max_u32_e32 v16, v105, v5
	v_min_u32_e32 v5, v105, v5
	v_max_u32_e32 v105, v3, v2
	v_min_u32_e32 v2, v3, v2
	v_max_u32_e32 v3, v8, v7
	v_min_u32_e32 v7, v8, v7
	v_max_u32_e32 v8, v4, v11
	v_min_u32_e32 v4, v4, v11
	v_max_u32_e32 v11, v6, v12
	v_min_u32_e32 v6, v6, v12
	v_max_u32_e32 v12, v9, v10
	v_min_u32_e32 v9, v9, v10
	v_max_u32_e32 v43, v46, v40
	v_min_u32_e32 v40, v46, v40
	v_max_u32_e32 v46, v47, v36
	v_min_u32_e32 v36, v47, v36
	v_max_u32_e32 v47, v49, v35
	v_min_u32_e32 v35, v49, v35
	v_max_u32_e32 v49, v37, v41
	v_min_u32_e32 v37, v37, v41
	v_max_u32_e32 v41, v48, v39
	v_min_u32_e32 v39, v48, v39
	v_max_u32_e32 v48, v38, v44
	v_min_u32_e32 v38, v38, v44
	v_max_u32_e32 v44, v50, v42
	v_min_u32_e32 v42, v50, v42
	v_max_u32_e32 v50, v34, v45
	v_min_u32_e32 v34, v34, v45
	v_max_u32_e32 v67, v78, v64
	v_min_u32_e32 v64, v78, v64
	v_max_u32_e32 v78, v80, v60
	v_min_u32_e32 v60, v80, v60
	v_max_u32_e32 v80, v88, v59
	v_min_u32_e32 v59, v88, v59
	v_max_u32_e32 v88, v61, v65
	v_min_u32_e32 v61, v61, v65
	v_max_u32_e32 v65, v81, v63
	v_min_u32_e32 v63, v81, v63
	v_max_u32_e32 v81, v62, v68
	v_min_u32_e32 v62, v62, v68
	v_max_u32_e32 v68, v89, v66
	v_min_u32_e32 v66, v89, v66
	v_max_u32_e32 v89, v58, v69
	v_min_u32_e32 v58, v58, v69
	v_max_u32_e32 v26, v29, v23
	v_min_u32_e32 v23, v29, v23
	v_max_u32_e32 v29, v30, v19
	v_min_u32_e32 v19, v30, v19
	v_max_u32_e32 v30, v33, v20
	v_min_u32_e32 v20, v33, v20
	v_max_u32_e32 v33, v31, v24
	v_min_u32_e32 v24, v31, v24
	v_max_u32_e32 v31, v32, v22
	v_min_u32_e32 v22, v32, v22
	v_max_u32_e32 v32, v21, v27
	v_min_u32_e32 v21, v21, v27
	v_max_u32_e32 v27, v97, v25
	v_min_u32_e32 v25, v97, v25
	v_max_u32_e32 v97, v18, v28
	v_min_u32_e32 v18, v18, v28
	v_max_u32_e32 v10, v13, v7
	v_min_u32_e32 v7, v13, v7
	v_max_u32_e32 v13, v14, v3
	v_min_u32_e32 v3, v14, v3
	v_max_u32_e32 v14, v17, v4
	v_min_u32_e32 v4, v17, v4
	v_max_u32_e32 v17, v15, v8
	v_min_u32_e32 v8, v15, v8
	v_max_u32_e32 v15, v16, v6
	v_min_u32_e32 v6, v16, v6
	v_max_u32_e32 v16, v5, v11
	v_min_u32_e32 v5, v5, v11
	v_max_u32_e32 v11, v105, v9
	v_min_u32_e32 v9, v105, v9
	v_max_u32_e32 v105, v2, v12
	v_min_u32_e32 v2, v2, v12
	v_max_u32_e32 v45, v43, v41
	v_min_u32_e32 v41, v43, v41
	v_max_u32_e32 v43, v46, v48
	v_min_u32_e32 v46, v46, v48
	v_max_u32_e32 v48, v47, v44
	v_min_u32_e32 v44, v47, v44
	v_max_u32_e32 v47, v49, v50
	v_min_u32_e32 v49, v49, v50
	v_max_u32_e32 v50, v40, v39
	v_min_u32_e32 v39, v40, v39
	v_max_u32_e32 v40, v36, v38
	v_min_u32_e32 v36, v36, v38
	v_max_u32_e32 v38, v35, v42
	v_min_u32_e32 v35, v35, v42
	v_max_u32_e32 v42, v37, v34
	v_min_u32_e32 v34, v37, v34
	v_max_u32_e32 v69, v67, v65
	v_min_u32_e32 v65, v67, v65
	v_max_u32_e32 v67, v78, v81
	v_min_u32_e32 v78, v78, v81
	v_max_u32_e32 v81, v80, v68
	v_min_u32_e32 v68, v80, v68
	v_max_u32_e32 v80, v88, v89
	v_min_u32_e32 v88, v88, v89
	v_max_u32_e32 v89, v64, v63
	v_min_u32_e32 v63, v64, v63
	v_max_u32_e32 v64, v60, v62
	v_min_u32_e32 v60, v60, v62
	v_max_u32_e32 v62, v59, v66
	v_min_u32_e32 v59, v59, v66
	v_max_u32_e32 v66, v61, v58
	v_min_u32_e32 v58, v61, v58
	v_max_u32_e32 v28, v26, v31
	v_min_u32_e32 v26, v26, v31
	v_max_u32_e32 v31, v29, v32
	v_min_u32_e32 v29, v29, v32
	v_max_u32_e32 v32, v30, v27
	v_min_u32_e32 v27, v30, v27
	v_max_u32_e32 v30, v33, v97
	v_min_u32_e32 v33, v33, v97
	v_max_u32_e32 v97, v23, v22
	v_min_u32_e32 v22, v23, v22
	v_max_u32_e32 v23, v19, v21
	v_min_u32_e32 v19, v19, v21
	v_max_u32_e32 v21, v20, v25
	v_min_u32_e32 v20, v20, v25
	v_max_u32_e32 v25, v24, v18
	v_min_u32_e32 v18, v24, v18
	v_max_u32_e32 v12, v10, v15
	v_min_u32_e32 v10, v10, v15
	v_max_u32_e32 v15, v13, v16
	v_min_u32_e32 v13, v13, v16
	v_max_u32_e32 v16, v14, v11
	v_min_u32_e32 v11, v14, v11
	v_max_u32_e32 v14, v17, v105
	v_min_u32_e32 v17, v17, v105
	v_max_u32_e32 v105, v7, v6
	v_min_u32_e32 v6, v7, v6
	v_max_u32_e32 v7, v3, v5
	v_min_u32_e32 v3, v3, v5
	v_max_u32_e32 v5, v4, v9
	v_min_u32_e32 v4, v4, v9
	v_max_u32_e32 v9, v8, v2
	v_min_u32_e32 v2, v8, v2
	v_max_u32_e32 v37, v45, v48
	v_min_u32_e32 v45, v45, v48
	v_max_u32_e32 v48, v43, v47
	v_min_u32_e32 v43, v43, v47
	v_max_u32_e32 v47, v41, v44
	v_min_u32_e32 v41, v41, v44
	v_max_u32_e32 v44, v46, v49
	v_min_u32_e32 v46, v46, v49
	v_max_u32_e32 v49, v50, v38
	v_min_u32_e32 v38, v50, v38
	v_max_u32_e32 v50, v40, v42
	v_min_u32_e32 v40, v40, v42
	v_max_u32_e32 v42, v39, v35
	v_min_u32_e32 v35, v39, v35
	v_max_u32_e32 v39, v36, v34
	v_min_u32_e32 v34, v36, v34
	v_max_u32_e32 v61, v69, v81
	v_min_u32_e32 v69, v69, v81
	v_max_u32_e32 v81, v67, v80
	v_min_u32_e32 v67, v67, v80
	v_max_u32_e32 v80, v65, v68
	v_min_u32_e32 v65, v65, v68
	v_max_u32_e32 v68, v78, v88
	v_min_u32_e32 v78, v78, v88
	v_max_u32_e32 v88, v89, v62
	v_min_u32_e32 v62, v89, v62
	v_max_u32_e32 v89, v64, v66
	v_min_u32_e32 v64, v64, v66
	v_max_u32_e32 v66, v63, v59
	v_min_u32_e32 v59, v63, v59
	v_max_u32_e32 v63, v60, v58
	v_min_u32_e32 v58, v60, v58
	v_max_u32_e32 v24, v28, v32
	v_min_u32_e32 v28, v28, v32
	v_max_u32_e32 v32, v31, v30
	v_min_u32_e32 v30, v31, v30
	v_max_u32_e32 v31, v26, v27
	v_min_u32_e32 v26, v26, v27
	v_max_u32_e32 v27, v29, v33
	v_min_u32_e32 v29, v29, v33
	v_max_u32_e32 v33, v97, v21
	v_min_u32_e32 v21, v97, v21
	v_max_u32_e32 v97, v23, v25
	v_min_u32_e32 v23, v23, v25
	v_max_u32_e32 v25, v22, v20
	v_min_u32_e32 v20, v22, v20
	v_max_u32_e32 v22, v19, v18
	v_min_u32_e32 v18, v19, v18
	v_max_u32_e32 v8, v12, v16
	v_min_u32_e32 v12, v12, v16
	v_max_u32_e32 v16, v15, v14
	v_min_u32_e32 v14, v15, v14
	v_max_u32_e32 v15, v10, v11
	v_min_u32_e32 v10, v10, v11
	v_max_u32_e32 v11, v13, v17
	v_min_u32_e32 v13, v13, v17
	v_max_u32_e32 v17, v105, v5
	v_min_u32_e32 v5, v105, v5
	v_max_u32_e32 v105, v7, v9
	v_min_u32_e32 v7, v7, v9
	v_max_u32_e32 v9, v6, v4
	v_min_u32_e32 v4, v6, v4
	v_max_u32_e32 v6, v3, v2
	v_min_u32_e32 v2, v3, v2
	v_min_u32_e32 v36, v37, v48
	v_min_u32_e32 v51, v45, v43
	v_min_u32_e32 v52, v47, v44
	v_min_u32_e32 v53, v41, v46
	v_min_u32_e32 v54, v49, v50
	v_min_u32_e32 v55, v38, v40
	v_min_u32_e32 v56, v42, v39
	v_min_u32_e32 v57, v35, v34
	v_min_u32_e32 v60, v61, v81
	v_min_u32_e32 v90, v69, v67
	v_min_u32_e32 v91, v80, v68
	v_min_u32_e32 v92, v65, v78
	v_min_u32_e32 v93, v88, v89
	v_min_u32_e32 v94, v62, v64
	v_min_u32_e32 v95, v66, v63
	v_min_u32_e32 v96, v59, v58
	v_min_u32_e32 v19, v24, v32
	v_min_u32_e32 v98, v28, v30
	v_min_u32_e32 v99, v31, v27
	v_min_u32_e32 v100, v26, v29
	v_min_u32_e32 v101, v33, v97
	v_min_u32_e32 v102, v21, v23
	v_min_u32_e32 v103, v25, v22
	v_min_u32_e32 v104, v20, v18
	v_min_u32_e32 v3, v8, v16
	v_min_u32_e32 v106, v12, v14
	v_min_u32_e32 v107, v15, v11
	v_min_u32_e32 v108, v10, v13
	v_min_u32_e32 v109, v17, v105
	v_min_u32_e32 v110, v5, v7
	v_min_u32_e32 v111, v9, v6
	v_min_u32_e32 v112, v4, v2
	v_max3_u32 v37, v37, v48, v96
	v_max3_u32 v24, v24, v32, v112
	v_max3_u32 v32, v36, v59, v58
	v_max3_u32 v2, v19, v4, v2
	v_max3_u32 v4, v45, v43, v95
	v_max3_u32 v19, v28, v30, v111
	v_max3_u32 v28, v51, v66, v63
	v_max3_u32 v6, v98, v9, v6
	v_max3_u32 v9, v47, v44, v94
	v_max3_u32 v27, v31, v27, v110
	v_max3_u32 v30, v52, v62, v64
	v_max3_u32 v5, v99, v5, v7
	v_max3_u32 v7, v41, v46, v93
	v_max3_u32 v26, v26, v29, v109
	v_max3_u32 v29, v53, v88, v89
	v_max3_u32 v17, v100, v17, v105
	v_max3_u32 v31, v49, v50, v92
	v_max3_u32 v33, v33, v97, v108
	v_max3_u32 v36, v54, v65, v78
	v_max3_u32 v10, v101, v10, v13
	v_max3_u32 v13, v38, v40, v91
	v_max3_u32 v21, v21, v23, v107
	v_max3_u32 v23, v55, v80, v68
	v_max3_u32 v11, v102, v15, v11
	v_max3_u32 v15, v42, v39, v90
	v_max3_u32 v22, v25, v22, v106
	v_max3_u32 v25, v56, v69, v67
	s_waitcnt vmcnt(0)
	v_pk_mul_f32 v[200:201], v[200:201], s[96:97] op_sel_hi:[1,0]
	v_pk_mul_f32 v[202:203], v[202:203], s[96:97] op_sel_hi:[1,0]
	v_pk_mul_f32 v[204:205], v[204:205], s[96:97] op_sel_hi:[1,0]
	v_pk_mul_f32 v[206:207], v[206:207], s[96:97] op_sel_hi:[1,0]
	v_pk_mul_f32 v[208:209], v[208:209], s[96:97] op_sel_hi:[1,0]
	v_pk_mul_f32 v[210:211], v[210:211], s[96:97] op_sel_hi:[1,0]
	v_pk_mul_f32 v[212:213], v[212:213], s[96:97] op_sel_hi:[1,0]
	v_pk_mul_f32 v[214:215], v[214:215], s[96:97] op_sel_hi:[1,0]
	v_pk_mul_f32 v[216:217], v[216:217], s[96:97] op_sel_hi:[1,0]
	v_pk_mul_f32 v[218:219], v[218:219], s[96:97] op_sel_hi:[1,0]
	v_pk_mul_f32 v[220:221], v[220:221], s[96:97] op_sel_hi:[1,0]
	v_pk_mul_f32 v[222:223], v[222:223], s[96:97] op_sel_hi:[1,0]
	v_pk_mul_f32 v[224:225], v[224:225], s[96:97] op_sel_hi:[1,0]
	v_pk_mul_f32 v[226:227], v[226:227], s[96:97] op_sel_hi:[1,0]
	v_pk_mul_f32 v[228:229], v[228:229], s[96:97] op_sel_hi:[1,0]
	v_pk_mul_f32 v[230:231], v[230:231], s[96:97] op_sel_hi:[1,0]
	v_cvt_scalef32_pk_fp4_f32 v232, v200, v201, 1.0
	v_cvt_scalef32_pk_fp4_f32 v233, v208, v209, 1.0
	v_cvt_scalef32_pk_fp4_f32 v234, v216, v217, 1.0
	v_cvt_scalef32_pk_fp4_f32 v235, v224, v225, 1.0
	v_cvt_scalef32_pk_fp4_f32 v232, v202, v203, 1.0 op_sel:[0,0,1,0]
	v_cvt_scalef32_pk_fp4_f32 v233, v210, v211, 1.0 op_sel:[0,0,1,0]
	v_cvt_scalef32_pk_fp4_f32 v234, v218, v219, 1.0 op_sel:[0,0,1,0]
	v_cvt_scalef32_pk_fp4_f32 v235, v226, v227, 1.0 op_sel:[0,0,1,0]
	v_cvt_scalef32_pk_fp4_f32 v232, v204, v205, 1.0 op_sel:[0,0,0,1]
	v_cvt_scalef32_pk_fp4_f32 v233, v212, v213, 1.0 op_sel:[0,0,0,1]
	v_cvt_scalef32_pk_fp4_f32 v234, v220, v221, 1.0 op_sel:[0,0,0,1]
	v_cvt_scalef32_pk_fp4_f32 v235, v228, v229, 1.0 op_sel:[0,0,0,1]
	v_cvt_scalef32_pk_fp4_f32 v232, v206, v207, 1.0 op_sel:[0,0,1,1]
	v_cvt_scalef32_pk_fp4_f32 v233, v214, v215, 1.0 op_sel:[0,0,1,1]
	v_cvt_scalef32_pk_fp4_f32 v234, v222, v223, 1.0 op_sel:[0,0,1,1]
	v_cvt_scalef32_pk_fp4_f32 v235, v230, v231, 1.0 op_sel:[0,0,1,1]
	s_nop 0
	global_store_dwordx4 v[240:241], v[232:235], off
	v_lshl_add_u64 v[240:241], v[240:241], 0, v[246:247]
	global_load_dwordx4 v[200:203], v[236:237], off
	global_load_dwordx4 v[204:207], v[236:237], off offset:16
	global_load_dwordx4 v[208:211], v[236:237], off offset:32
	global_load_dwordx4 v[212:215], v[236:237], off offset:48
	global_load_dwordx4 v[216:219], v[238:239], off
	global_load_dwordx4 v[220:223], v[238:239], off offset:16
	global_load_dwordx4 v[224:227], v[238:239], off offset:32
	global_load_dwordx4 v[228:231], v[238:239], off offset:48
	v_lshl_add_u64 v[236:237], v[236:237], 0, v[244:245]
	v_lshl_add_u64 v[238:239], v[238:239], 0, v[244:245]
	v_max3_u32 v12, v103, v12, v14
	v_max3_u32 v14, v35, v34, v60
	v_max3_u32 v3, v20, v18, v3
	v_max3_u32 v18, v57, v61, v81
	v_max3_u32 v8, v104, v8, v16
	v_max_u32_e32 v16, v37, v31
	v_min_u32_e32 v20, v37, v31
	v_max_u32_e32 v31, v32, v36
	v_min_u32_e32 v32, v32, v36
	v_max_u32_e32 v34, v4, v13
	v_min_u32_e32 v4, v4, v13
	v_max_u32_e32 v13, v28, v23
	v_min_u32_e32 v23, v28, v23
	v_max_u32_e32 v28, v9, v15
	v_min_u32_e32 v9, v9, v15
	v_max_u32_e32 v15, v30, v25
	v_min_u32_e32 v25, v30, v25
	v_max_u32_e32 v30, v7, v14
	v_min_u32_e32 v7, v7, v14
	v_max_u32_e32 v14, v29, v18
	v_min_u32_e32 v18, v29, v18
	v_max_u32_e32 v42, v24, v33
	v_min_u32_e32 v24, v24, v33
	v_max_u32_e32 v33, v2, v10
	v_min_u32_e32 v2, v2, v10
	v_max_u32_e32 v10, v19, v21
	v_min_u32_e32 v19, v19, v21
	v_max_u32_e32 v21, v6, v11
	v_min_u32_e32 v6, v6, v11
	v_max_u32_e32 v11, v27, v22
	v_min_u32_e32 v22, v27, v22
	v_max_u32_e32 v27, v5, v12
	v_min_u32_e32 v5, v5, v12
	v_max_u32_e32 v12, v26, v3
	v_min_u32_e32 v3, v26, v3
	v_max_u32_e32 v26, v17, v8
	v_min_u32_e32 v8, v17, v8
	v_max_u32_e32 v29, v16, v28
	v_min_u32_e32 v16, v16, v28
	v_max_u32_e32 v28, v31, v15
	v_min_u32_e32 v15, v31, v15
	v_max_u32_e32 v31, v34, v30
	v_min_u32_e32 v30, v34, v30
	v_max_u32_e32 v34, v13, v14
	v_min_u32_e32 v13, v13, v14
	v_max_u32_e32 v14, v20, v9
	v_min_u32_e32 v9, v20, v9
	v_max_u32_e32 v20, v32, v25
	v_min_u32_e32 v25, v32, v25
	v_max_u32_e32 v32, v4, v7
	v_min_u32_e32 v4, v4, v7
	v_max_u32_e32 v7, v23, v18
	v_min_u32_e32 v18, v23, v18
	v_max_u32_e32 v17, v42, v11
	v_min_u32_e32 v11, v42, v11
	v_max_u32_e32 v42, v33, v27
	v_min_u32_e32 v27, v33, v27
	v_max_u32_e32 v33, v10, v12
	v_min_u32_e32 v10, v10, v12
	v_max_u32_e32 v12, v21, v26
	v_min_u32_e32 v21, v21, v26
	v_max_u32_e32 v26, v24, v22
	v_min_u32_e32 v22, v24, v22
	v_max_u32_e32 v24, v2, v5
	v_min_u32_e32 v2, v2, v5
	v_max_u32_e32 v5, v19, v3
	v_min_u32_e32 v3, v19, v3
	v_max_u32_e32 v19, v6, v8
	v_min_u32_e32 v6, v6, v8
	v_max_u32_e32 v23, v29, v31
	v_min_u32_e32 v29, v29, v31
	v_max_u32_e32 v31, v28, v34
	v_min_u32_e32 v28, v28, v34
	v_max_u32_e32 v34, v16, v30
	v_min_u32_e32 v16, v16, v30
	v_max_u32_e32 v30, v15, v13
	v_min_u32_e32 v13, v15, v13
	v_max_u32_e32 v15, v14, v32
	v_min_u32_e32 v14, v14, v32
	v_max_u32_e32 v32, v20, v7
	v_min_u32_e32 v7, v20, v7
	v_max_u32_e32 v20, v9, v4
	v_min_u32_e32 v4, v9, v4
	v_max_u32_e32 v9, v25, v18
	v_min_u32_e32 v18, v25, v18
	v_max_u32_e32 v8, v17, v33
	v_min_u32_e32 v17, v17, v33
	v_max_u32_e32 v33, v42, v12
	v_min_u32_e32 v12, v42, v12
	v_max_u32_e32 v42, v11, v10
	v_min_u32_e32 v10, v11, v10
	v_max_u32_e32 v11, v27, v21
	v_min_u32_e32 v21, v27, v21
	v_max_u32_e32 v27, v26, v5
	v_min_u32_e32 v5, v26, v5
	v_max_u32_e32 v26, v24, v19
	v_min_u32_e32 v19, v24, v19
	v_max_u32_e32 v24, v22, v3
	v_min_u32_e32 v3, v22, v3
	v_max_u32_e32 v22, v2, v6
	v_min_u32_e32 v2, v2, v6
	v_min_u32_e32 v25, v23, v31
	v_min_u32_e32 v35, v29, v28
	v_min_u32_e32 v36, v34, v30
	v_min_u32_e32 v37, v16, v13
	v_min_u32_e32 v38, v15, v32
	v_min_u32_e32 v39, v14, v7
	v_min_u32_e32 v40, v20, v9
	v_min_u32_e32 v41, v4, v18
	v_min_u32_e32 v6, v8, v33
	v_min_u32_e32 v43, v17, v12
	v_min_u32_e32 v44, v42, v11
	v_min_u32_e32 v45, v10, v21
	v_min_u32_e32 v46, v27, v26
	v_min_u32_e32 v47, v5, v19
	v_min_u32_e32 v48, v24, v22
	v_min_u32_e32 v49, v3, v2
	v_max3_u32 v23, v23, v31, v49
	v_max3_u32 v2, v25, v3, v2
	v_max3_u32 v3, v29, v28, v48
	v_max3_u32 v22, v35, v24, v22
	v_max3_u32 v24, v34, v30, v47
	v_max3_u32 v5, v36, v5, v19
	v_max3_u32 v13, v16, v13, v46
	v_max3_u32 v16, v37, v27, v26
	v_max3_u32 v15, v15, v32, v45
	v_max3_u32 v10, v38, v10, v21
	v_max3_u32 v7, v14, v7, v44
	v_max3_u32 v11, v39, v42, v11
	v_max3_u32 v9, v20, v9, v43
	v_max3_u32 v12, v40, v17, v12
	v_max3_u32 v4, v4, v18, v6
	v_max3_u32 v6, v41, v8, v33
	v_max_u32_e32 v8, v23, v15
	v_min_u32_e32 v14, v23, v15
	v_max_u32_e32 v15, v2, v10
	v_min_u32_e32 v2, v2, v10
	v_max_u32_e32 v10, v3, v7
	v_min_u32_e32 v3, v3, v7
	v_max_u32_e32 v7, v22, v11
	v_min_u32_e32 v11, v22, v11
	v_max_u32_e32 v17, v24, v9
	v_min_u32_e32 v9, v24, v9
	v_max_u32_e32 v18, v5, v12
	v_min_u32_e32 v5, v5, v12
	v_max_u32_e32 v12, v13, v4
	v_min_u32_e32 v4, v13, v4
	v_max_u32_e32 v13, v16, v6
	v_min_u32_e32 v6, v16, v6
	v_max_u32_e32 v16, v8, v17
	v_min_u32_e32 v8, v8, v17
	v_max_u32_e32 v17, v15, v18
	v_min_u32_e32 v15, v15, v18
	v_max_u32_e32 v18, v10, v12
	v_min_u32_e32 v10, v10, v12
	v_max_u32_e32 v12, v7, v13
	v_min_u32_e32 v7, v7, v13
	v_max_u32_e32 v13, v14, v9
	v_min_u32_e32 v9, v14, v9
	v_max_u32_e32 v14, v2, v5
	v_min_u32_e32 v2, v2, v5
	v_max_u32_e32 v5, v3, v4
	v_min_u32_e32 v3, v3, v4
	v_max_u32_e32 v4, v11, v6
	v_min_u32_e32 v6, v11, v6
	v_max_u32_e32 v11, v16, v18
	v_min_u32_e32 v16, v16, v18
	v_max_u32_e32 v18, v17, v12
	v_min_u32_e32 v12, v17, v12
	v_max_u32_e32 v17, v8, v10
	v_min_u32_e32 v8, v8, v10
	v_max_u32_e32 v10, v15, v7
	v_min_u32_e32 v7, v15, v7
	v_max_u32_e32 v15, v13, v5
	v_min_u32_e32 v5, v13, v5
	v_max_u32_e32 v13, v14, v4
	v_min_u32_e32 v4, v14, v4
	v_max_u32_e32 v14, v9, v3
	v_min_u32_e32 v3, v9, v3
	v_max_u32_e32 v9, v2, v6
	v_min_u32_e32 v2, v2, v6
	v_max_u32_e32 v6, v11, v18
	v_min_u32_e32 v11, v11, v18
	v_max_u32_e32 v18, v16, v12
	v_min_u32_e32 v12, v16, v12
	v_max_u32_e32 v16, v17, v10
	v_min_u32_e32 v10, v17, v10
	v_max_u32_e32 v17, v8, v7
	v_min_u32_e32 v7, v8, v7
	v_max_u32_e32 v8, v15, v13
	v_min_u32_e32 v13, v15, v13
	v_max_u32_e32 v15, v5, v4
	ds_bpermute_b32 v23, v153, v15
	v_min_u32_e32 v19, v3, v2
	v_min_u32_e32 v4, v5, v4
	v_max_u32_e32 v5, v14, v9
	v_max_u32_e32 v2, v3, v2
	ds_bpermute_b32 v20, v153, v19
	v_min_u32_e32 v9, v14, v9
	ds_bpermute_b32 v14, v153, v2
	ds_bpermute_b32 v21, v153, v5
	ds_bpermute_b32 v22, v153, v4
	s_waitcnt lgkmcnt(4)
	v_max_u32_e32 v23, v10, v23
	ds_bpermute_b32 v10, v153, v10
	s_waitcnt lgkmcnt(4)
	v_max_u32_e32 v3, v6, v20
	ds_bpermute_b32 v20, v153, v9
	s_waitcnt lgkmcnt(4)
	v_max_u32_e32 v14, v11, v14
	s_waitcnt lgkmcnt(3)
	v_max_u32_e32 v21, v12, v21
	s_waitcnt lgkmcnt(2)
	v_max_u32_e32 v22, v16, v22
	ds_bpermute_b32 v24, v153, v13
	ds_bpermute_b32 v25, v153, v8
	ds_bpermute_b32 v26, v153, v7
	ds_bpermute_b32 v27, v153, v17
	s_waitcnt lgkmcnt(5)
	v_max_u32_e32 v10, v15, v10
	ds_bpermute_b32 v15, v153, v16
	ds_bpermute_b32 v12, v153, v12
	ds_bpermute_b32 v16, v153, v18
	ds_bpermute_b32 v11, v153, v11
	ds_bpermute_b32 v6, v153, v6
	s_waitcnt lgkmcnt(9)
	v_max_u32_e32 v20, v18, v20
	s_waitcnt lgkmcnt(8)
	v_max_u32_e32 v17, v17, v24
	s_waitcnt lgkmcnt(7)
	v_max_u32_e32 v7, v7, v25
	s_waitcnt lgkmcnt(6)
	v_max_u32_e32 v8, v8, v26
	s_waitcnt lgkmcnt(5)
	v_max_u32_e32 v13, v13, v27
	s_waitcnt lgkmcnt(4)
	v_max_u32_e32 v4, v4, v15
	s_waitcnt lgkmcnt(3)
	v_max_u32_e32 v5, v5, v12
	s_waitcnt lgkmcnt(2)
	v_max_u32_e32 v9, v9, v16
	s_waitcnt lgkmcnt(1)
	v_max_u32_e32 v2, v2, v11
	s_waitcnt lgkmcnt(0)
	v_max_u32_e32 v6, v19, v6
	v_max_u32_e32 v11, v3, v8
	v_min_u32_e32 v3, v3, v8
	v_max_u32_e32 v8, v14, v13
	v_min_u32_e32 v12, v14, v13
	v_max_u32_e32 v13, v20, v10
	v_min_u32_e32 v10, v20, v10
	v_max_u32_e32 v14, v21, v4
	v_min_u32_e32 v4, v21, v4
	v_max_u32_e32 v15, v22, v5
	v_min_u32_e32 v5, v22, v5
	v_max_u32_e32 v16, v23, v9
	v_min_u32_e32 v9, v23, v9
	v_max_u32_e32 v18, v17, v2
	v_min_u32_e32 v2, v17, v2
	v_max_u32_e32 v17, v7, v6
	v_min_u32_e32 v6, v7, v6
	v_max_u32_e32 v7, v11, v15
	v_min_u32_e32 v11, v11, v15
	v_max_u32_e32 v15, v8, v16
	v_min_u32_e32 v8, v8, v16
	v_max_u32_e32 v16, v13, v18
	v_min_u32_e32 v13, v13, v18
	v_max_u32_e32 v18, v14, v17
	v_min_u32_e32 v14, v14, v17
	v_max_u32_e32 v17, v3, v5
	v_min_u32_e32 v3, v3, v5
	v_max_u32_e32 v5, v12, v9
	v_min_u32_e32 v9, v12, v9
	v_max_u32_e32 v12, v10, v2
	v_min_u32_e32 v2, v10, v2
	v_max_u32_e32 v10, v4, v6
	v_min_u32_e32 v4, v4, v6
	v_max_u32_e32 v6, v7, v16
	v_min_u32_e32 v7, v7, v16
	v_max_u32_e32 v16, v15, v18
	s_waitcnt vmcnt(0)
	v_pk_mul_f32 v[200:201], v[200:201], s[96:97] op_sel_hi:[1,0]
	v_pk_mul_f32 v[202:203], v[202:203], s[96:97] op_sel_hi:[1,0]
	v_pk_mul_f32 v[204:205], v[204:205], s[96:97] op_sel_hi:[1,0]
	v_pk_mul_f32 v[206:207], v[206:207], s[96:97] op_sel_hi:[1,0]
	v_pk_mul_f32 v[208:209], v[208:209], s[96:97] op_sel_hi:[1,0]
	v_pk_mul_f32 v[210:211], v[210:211], s[96:97] op_sel_hi:[1,0]
	v_pk_mul_f32 v[212:213], v[212:213], s[96:97] op_sel_hi:[1,0]
	v_pk_mul_f32 v[214:215], v[214:215], s[96:97] op_sel_hi:[1,0]
	v_pk_mul_f32 v[216:217], v[216:217], s[96:97] op_sel_hi:[1,0]
	v_pk_mul_f32 v[218:219], v[218:219], s[96:97] op_sel_hi:[1,0]
	v_pk_mul_f32 v[220:221], v[220:221], s[96:97] op_sel_hi:[1,0]
	v_pk_mul_f32 v[222:223], v[222:223], s[96:97] op_sel_hi:[1,0]
	v_pk_mul_f32 v[224:225], v[224:225], s[96:97] op_sel_hi:[1,0]
	v_pk_mul_f32 v[226:227], v[226:227], s[96:97] op_sel_hi:[1,0]
	v_pk_mul_f32 v[228:229], v[228:229], s[96:97] op_sel_hi:[1,0]
	v_pk_mul_f32 v[230:231], v[230:231], s[96:97] op_sel_hi:[1,0]
	v_cvt_scalef32_pk_fp4_f32 v232, v200, v201, 1.0
	v_cvt_scalef32_pk_fp4_f32 v233, v208, v209, 1.0
	v_cvt_scalef32_pk_fp4_f32 v234, v216, v217, 1.0
	v_cvt_scalef32_pk_fp4_f32 v235, v224, v225, 1.0
	v_cvt_scalef32_pk_fp4_f32 v232, v202, v203, 1.0 op_sel:[0,0,1,0]
	v_cvt_scalef32_pk_fp4_f32 v233, v210, v211, 1.0 op_sel:[0,0,1,0]
	v_cvt_scalef32_pk_fp4_f32 v234, v218, v219, 1.0 op_sel:[0,0,1,0]
	v_cvt_scalef32_pk_fp4_f32 v235, v226, v227, 1.0 op_sel:[0,0,1,0]
	v_cvt_scalef32_pk_fp4_f32 v232, v204, v205, 1.0 op_sel:[0,0,0,1]
	v_cvt_scalef32_pk_fp4_f32 v233, v212, v213, 1.0 op_sel:[0,0,0,1]
	v_cvt_scalef32_pk_fp4_f32 v234, v220, v221, 1.0 op_sel:[0,0,0,1]
	v_cvt_scalef32_pk_fp4_f32 v235, v228, v229, 1.0 op_sel:[0,0,0,1]
	v_cvt_scalef32_pk_fp4_f32 v232, v206, v207, 1.0 op_sel:[0,0,1,1]
	v_cvt_scalef32_pk_fp4_f32 v233, v214, v215, 1.0 op_sel:[0,0,1,1]
	v_cvt_scalef32_pk_fp4_f32 v234, v222, v223, 1.0 op_sel:[0,0,1,1]
	v_cvt_scalef32_pk_fp4_f32 v235, v230, v231, 1.0 op_sel:[0,0,1,1]
	s_nop 0
	global_store_dwordx4 v[240:241], v[232:235], off
	v_lshl_add_u64 v[240:241], v[240:241], 0, v[246:247]
	global_load_dwordx4 v[200:203], v[236:237], off
	global_load_dwordx4 v[204:207], v[236:237], off offset:16
	global_load_dwordx4 v[208:211], v[236:237], off offset:32
	global_load_dwordx4 v[212:215], v[236:237], off offset:48
	global_load_dwordx4 v[216:219], v[238:239], off
	global_load_dwordx4 v[220:223], v[238:239], off offset:16
	global_load_dwordx4 v[224:227], v[238:239], off offset:32
	global_load_dwordx4 v[228:231], v[238:239], off offset:48
	v_lshl_add_u64 v[236:237], v[236:237], 0, v[244:245]
	v_lshl_add_u64 v[238:239], v[238:239], 0, v[244:245]
	v_max_u32_e32 v19, v17, v12
	v_min_u32_e32 v12, v17, v12
	v_max_u32_e32 v17, v5, v10
	v_min_u32_e32 v21, v3, v2
	v_max_u32_e32 v22, v9, v4
	v_min_u32_e32 v4, v9, v4
	v_min_u32_e32 v15, v15, v18
	v_max_u32_e32 v18, v11, v13
	v_min_u32_e32 v11, v11, v13
	v_max_u32_e32 v13, v8, v14
	v_min_u32_e32 v14, v8, v14
	v_min_u32_e32 v5, v5, v10
	v_max_u32_e32 v8, v6, v16
	v_min_u32_e32 v10, v6, v16
	v_max_u32_e32 v39, v19, v17
	v_min_u32_e32 v40, v19, v17
	v_max_u32_e32 v45, v21, v4
	v_min_u32_e32 v46, v21, v4
	v_bitop3_b32 v4, v82, s16, v82 bitop3:0xc
	v_lshl_add_u32 v19, v87, 2, s26
	v_bitop3_b32 v6, v152, s16, v152 bitop3:0xc
	v_max_u32_e32 v41, v12, v5
	v_min_u32_e32 v42, v12, v5
	v_bitop3_b32 v5, v8, s16, v8 bitop3:0xc
	ds_write2st64_b32 v19, v4, v6 offset1:1
	v_bitop3_b32 v4, v10, s16, v10 bitop3:0xc
	v_max_u32_e32 v20, v3, v2
	v_max_u32_e32 v3, v7, v15
	v_min_u32_e32 v2, v7, v15
	ds_write2st64_b32 v19, v5, v4 offset0:16 offset1:17
	v_bitop3_b32 v4, v156, s16, v156 bitop3:0xc
	v_bitop3_b32 v6, v157, s16, v157 bitop3:0xc
	v_bitop3_b32 v5, v3, s16, v3 bitop3:0xc
	ds_write2st64_b32 v19, v4, v6 offset0:2 offset1:3
	v_bitop3_b32 v4, v2, s16, v2 bitop3:0xc
	v_max_u32_e32 v35, v18, v13
	v_min_u32_e32 v36, v18, v13
	ds_write2st64_b32 v19, v5, v4 offset0:18 offset1:19
	v_bitop3_b32 v4, v158, s16, v158 bitop3:0xc
	v_bitop3_b32 v6, v159, s16, v159 bitop3:0xc
	v_bitop3_b32 v5, v35, s16, v35 bitop3:0xc
	ds_write2st64_b32 v19, v4, v6 offset0:4 offset1:5
	v_bitop3_b32 v4, v36, s16, v36 bitop3:0xc
	v_max_u32_e32 v37, v11, v14
	v_min_u32_e32 v38, v11, v14
	ds_write2st64_b32 v19, v5, v4 offset0:20 offset1:21
	v_bitop3_b32 v4, v160, s16, v160 bitop3:0xc
	v_bitop3_b32 v6, v161, s16, v161 bitop3:0xc
	v_bitop3_b32 v5, v37, s16, v37 bitop3:0xc
	ds_write2st64_b32 v19, v4, v6 offset0:6 offset1:7
	v_bitop3_b32 v4, v38, s16, v38 bitop3:0xc
	ds_write2st64_b32 v19, v5, v4 offset0:22 offset1:23
	v_bitop3_b32 v4, v83, s16, v83 bitop3:0xc
	v_bitop3_b32 v6, v147, s16, v147 bitop3:0xc
	v_bitop3_b32 v5, v39, s16, v39 bitop3:0xc
	ds_write2st64_b32 v19, v4, v6 offset0:8 offset1:9
	v_bitop3_b32 v4, v40, s16, v40 bitop3:0xc
	ds_write2st64_b32 v19, v5, v4 offset0:24 offset1:25
	v_bitop3_b32 v4, v148, s16, v148 bitop3:0xc
	v_bitop3_b32 v6, v149, s16, v149 bitop3:0xc
	v_bitop3_b32 v5, v41, s16, v41 bitop3:0xc
	ds_write2st64_b32 v19, v4, v6 offset0:10 offset1:11
	v_bitop3_b32 v4, v42, s16, v42 bitop3:0xc
	v_max_u32_e32 v43, v20, v22
	v_min_u32_e32 v44, v20, v22
	ds_write2st64_b32 v19, v5, v4 offset0:26 offset1:27
	v_bitop3_b32 v4, v150, s16, v150 bitop3:0xc
	v_bitop3_b32 v6, v151, s16, v151 bitop3:0xc
	v_bitop3_b32 v5, v43, s16, v43 bitop3:0xc
	ds_write2st64_b32 v19, v4, v6 offset0:12 offset1:13
	v_bitop3_b32 v4, v44, s16, v44 bitop3:0xc
	ds_write2st64_b32 v19, v5, v4 offset0:28 offset1:29
	v_bitop3_b32 v4, v154, s16, v154 bitop3:0xc
	v_bitop3_b32 v6, v155, s16, v155 bitop3:0xc
	v_bitop3_b32 v5, v45, s16, v45 bitop3:0xc
	ds_write2st64_b32 v19, v4, v6 offset0:14 offset1:15
	v_bitop3_b32 v4, v46, s16, v46 bitop3:0xc
	v_cmp_gt_u32_e32 vcc, 32, v87
	ds_write2st64_b32 v19, v5, v4 offset0:30 offset1:31
	s_and_saveexec_b64 s[14:15], vcc
	s_cbranch_execz .LBB0_801
	v_cmp_lt_i32_e32 vcc, -1, v161
	v_and_b32_e32 v6, 0xffffff80, v157
	v_and_b32_e32 v9, 0xffffff80, v8
	v_cndmask_b32_e64 v4, v86, -1, vcc
	v_cmp_lt_i32_e32 vcc, -1, v160
	v_bitop3_b32 v26, v4, v161, s17 bitop3:0x78
	v_and_b32_e32 v15, 0xffffff80, v152
	v_cndmask_b32_e64 v4, v86, -1, vcc
	v_cmp_lt_i32_e32 vcc, -1, v159
	v_bitop3_b32 v28, v4, v160, s17 bitop3:0x78
	v_and_b32_e32 v11, 0xffffff80, v155
	v_cndmask_b32_e64 v4, v86, -1, vcc
	v_cmp_lt_i32_e32 vcc, -1, v158
	v_bitop3_b32 v30, v4, v159, s17 bitop3:0x78
	v_and_b32_e32 v14, 0xffffff80, v154
	v_cndmask_b32_e64 v4, v86, -1, vcc
	v_cmp_lt_i32_e32 vcc, -1, v3
	v_bitop3_b32 v49, v4, v158, s17 bitop3:0x78
	v_and_b32_e32 v4, 0xffffff80, v3
	v_cndmask_b32_e64 v3, v86, -1, vcc
	v_cmp_lt_i32_e32 vcc, -1, v157
	v_xor_b32_e32 v5, v3, v4
	v_and_b32_e32 v3, 0xffffff80, v2
	v_cndmask_b32_e64 v7, v86, -1, vcc
	v_cmp_lt_i32_e32 vcc, -1, v2
	v_xor_b32_e32 v4, v7, v6
	v_and_b32_e32 v6, 0xffffff80, v156
	v_cndmask_b32_e64 v2, v86, -1, vcc
	v_cmp_lt_i32_e32 vcc, -1, v156
	v_xor_b32_e32 v7, v2, v3
	v_mov_b32_e32 v2, v5
	v_cndmask_b32_e64 v12, v86, -1, vcc
	v_xor_b32_e32 v6, v12, v6
	v_mov_b32_e32 v3, v7
	v_pk_add_f32 v[12:13], v[6:7], v[2:3] op_sel_hi:[0,1]
	v_not_b32_e32 v23, v13
	v_or_b32_e32 v24, 0x80000000, v13
	v_cmp_gt_i32_e32 vcc, 0, v13
	v_and_b32_e32 v16, 0xffffff80, v151
	v_and_b32_e32 v17, 0xffffff80, v150
	v_cndmask_b32_e32 v13, v24, v23, vcc
	v_and_b32_e32 v13, 0xffffff00, v13
	v_or_b32_e32 v31, 0xdc, v13
	v_not_b32_e32 v13, v12
	v_or_b32_e32 v23, 0x80000000, v12
	v_cmp_gt_i32_e32 vcc, 0, v12
	v_and_b32_e32 v18, 0xffffff80, v149
	v_and_b32_e32 v20, 0xffffff80, v148
	v_cndmask_b32_e32 v12, v23, v13, vcc
	v_cmp_lt_i32_e32 vcc, -1, v8
	v_and_b32_e32 v12, 0xffffff00, v12
	v_or_b32_e32 v32, 0xdd, v12
	v_cndmask_b32_e64 v8, v86, -1, vcc
	v_cmp_lt_i32_e32 vcc, -1, v152
	v_xor_b32_e32 v9, v8, v9
	v_and_b32_e32 v21, 0xffffff80, v147
	v_cndmask_b32_e64 v12, v86, -1, vcc
	v_cmp_lt_i32_e32 vcc, -1, v155
	v_xor_b32_e32 v8, v12, v15
	v_and_b32_e32 v22, 0xffffff80, v83
	v_cndmask_b32_e64 v12, v86, -1, vcc
	v_cmp_lt_i32_e32 vcc, -1, v154
	v_xor_b32_e32 v13, v12, v11
	v_mov_b32_e32 v48, v4
	v_cndmask_b32_e64 v15, v86, -1, vcc
	v_xor_b32_e32 v12, v15, v14
	v_pk_add_f32 v[12:13], v[8:9], v[12:13] op_sel:[1,0]
	v_and_b32_e32 v25, 0xffffff80, v10
	v_not_b32_e32 v11, v13
	v_or_b32_e32 v14, 0x80000000, v13
	v_cmp_gt_i32_e32 vcc, 0, v13
	v_or_b32_e32 v13, 0x80000000, v12
	v_and_b32_e32 v27, 0xffffff80, v82
	v_cndmask_b32_e32 v11, v14, v11, vcc
	v_and_or_b32 v14, v11, s29, 15
	v_not_b32_e32 v11, v12
	v_cmp_gt_i32_e32 vcc, 0, v12
	v_mov_b32_e32 v34, v49
	v_and_b32_e32 v54, 0xffffff80, v38
	v_cndmask_b32_e32 v11, v13, v11, vcc
	v_cmp_lt_i32_e32 vcc, -1, v151
	v_and_or_b32 v15, v11, s29, 31
	v_and_b32_e32 v55, 0xffffff80, v37
	v_cndmask_b32_e64 v11, v86, -1, vcc
	v_cmp_lt_i32_e32 vcc, -1, v150
	v_xor_b32_e32 v13, v11, v16
	v_and_b32_e32 v53, 0xffffff80, v35
	v_cndmask_b32_e64 v12, v86, -1, vcc
	v_xor_b32_e32 v12, v12, v17
	v_pk_add_f32 v[12:13], v[8:9], v[12:13] op_sel:[1,0]
	v_and_b32_e32 v52, 0xffffff80, v36
	v_not_b32_e32 v11, v13
	v_or_b32_e32 v16, 0x80000000, v13
	v_cmp_gt_i32_e32 vcc, 0, v13
	v_or_b32_e32 v13, 0x80000000, v12
	v_min_u32_e32 v88, v32, v31
	v_cndmask_b32_e32 v11, v16, v11, vcc
	v_and_or_b32 v16, v11, s29, 47
	v_not_b32_e32 v11, v12
	v_cmp_gt_i32_e32 vcc, 0, v12
	s_lshl_b32 s12, s30, 6
	s_nop 0
	v_cndmask_b32_e32 v11, v13, v11, vcc
	v_cmp_lt_i32_e32 vcc, -1, v149
	v_and_or_b32 v17, v11, s29, 63
	s_nop 0
	v_cndmask_b32_e64 v11, v86, -1, vcc
	v_cmp_lt_i32_e32 vcc, -1, v148
	v_xor_b32_e32 v13, v11, v18
	s_nop 0
	v_cndmask_b32_e64 v12, v86, -1, vcc
	v_xor_b32_e32 v12, v12, v20
	v_pk_add_f32 v[12:13], v[8:9], v[12:13] op_sel:[1,0]
	s_nop 0
	v_not_b32_e32 v11, v13
	v_or_b32_e32 v18, 0x80000000, v13
	v_cmp_gt_i32_e32 vcc, 0, v13
	v_or_b32_e32 v13, 0x80000000, v12
	s_nop 0
	v_cndmask_b32_e32 v11, v18, v11, vcc
	v_and_b32_e32 v11, 0xffffff00, v11
	v_or_b32_e32 v18, 0x4f, v11
	v_not_b32_e32 v11, v12
	v_cmp_gt_i32_e32 vcc, 0, v12
	s_nop 1
	v_cndmask_b32_e32 v11, v13, v11, vcc
	v_and_b32_e32 v11, 0xffffff00, v11
	v_cmp_lt_i32_e32 vcc, -1, v147
	v_or_b32_e32 v20, 0x5f, v11
	s_nop 0
	v_cndmask_b32_e64 v11, v86, -1, vcc
	v_cmp_lt_i32_e32 vcc, -1, v83
	v_xor_b32_e32 v13, v11, v21
	s_nop 0
	v_cndmask_b32_e64 v12, v86, -1, vcc
	v_xor_b32_e32 v12, v12, v22
	v_pk_add_f32 v[12:13], v[8:9], v[12:13] op_sel:[1,0]
	s_nop 0
	v_not_b32_e32 v11, v13
	v_or_b32_e32 v21, 0x80000000, v13
	v_cmp_gt_i32_e32 vcc, 0, v13
	v_or_b32_e32 v13, 0x80000000, v12
	s_nop 0
	v_cndmask_b32_e32 v11, v21, v11, vcc
	v_and_b32_e32 v11, 0xffffff00, v11
	v_or_b32_e32 v21, 0x6f, v11
	v_not_b32_e32 v11, v12
	v_cmp_gt_i32_e32 vcc, 0, v12
	v_mov_b32_e32 v12, v7
	s_nop 0
	v_cndmask_b32_e32 v11, v13, v11, vcc
	v_mov_b32_e32 v13, v9
	v_and_b32_e32 v11, 0xffffff00, v11
	v_pk_add_f32 v[12:13], v[48:49], v[12:13]
	v_or_b32_e32 v22, 0x7f, v11
	v_not_b32_e32 v11, v12
	v_or_b32_e32 v23, 0x80000000, v12
	v_cmp_gt_i32_e32 vcc, 0, v12
	v_or_b32_e32 v12, 0x80000000, v13
	v_mov_b32_e32 v49, v5
	v_cndmask_b32_e32 v11, v23, v11, vcc
	v_and_b32_e32 v11, 0xffffff00, v11
	v_or_b32_e32 v23, 0xcc, v11
	v_not_b32_e32 v11, v13
	v_cmp_gt_i32_e32 vcc, 0, v13
	s_nop 1
	v_cndmask_b32_e32 v11, v12, v11, vcc
	v_and_b32_e32 v11, 0xffffff00, v11
	v_pk_add_f32 v[12:13], v[8:9], v[2:3] op_sel_hi:[0,1]
	v_or_b32_e32 v24, 0xbf, v11
	v_not_b32_e32 v11, v13
	v_or_b32_e32 v29, 0x80000000, v13
	v_cmp_gt_i32_e32 vcc, 0, v13
	v_or_b32_e32 v13, 0x80000000, v12
	s_nop 0
	v_cndmask_b32_e32 v11, v29, v11, vcc
	v_and_b32_e32 v11, 0xffffff00, v11
	v_or_b32_e32 v56, 0xec, v11
	v_not_b32_e32 v11, v12
	v_cmp_gt_i32_e32 vcc, 0, v12
	s_nop 1
	v_cndmask_b32_e32 v11, v13, v11, vcc
	v_cmp_lt_i32_e32 vcc, -1, v10
	v_and_b32_e32 v11, 0xffffff00, v11
	v_or_b32_e32 v57, 0xed, v11
	v_cndmask_b32_e64 v10, v86, -1, vcc
	v_cmp_lt_i32_e32 vcc, -1, v82
	v_xor_b32_e32 v11, v10, v25
	v_mov_b32_e32 v13, v11
	v_cndmask_b32_e64 v12, v86, -1, vcc
	v_xor_b32_e32 v10, v12, v27
	v_mov_b32_e32 v12, v9
	v_pk_add_f32 v[26:27], v[26:27], v[12:13] op_sel_hi:[0,1]
	v_not_b32_e32 v25, v26
	v_or_b32_e32 v29, 0x80000000, v26
	v_cmp_gt_i32_e32 vcc, 0, v26
	v_not_b32_e32 v26, v27
	v_pk_add_f32 v[50:51], v[30:31], v[12:13] op_sel_hi:[0,1]
	v_cndmask_b32_e32 v25, v29, v25, vcc
	v_or_b32_e32 v29, 0x80000000, v27
	v_cmp_gt_i32_e32 vcc, 0, v27
	v_or_b32_e32 v30, 0x80000000, v50
	v_mov_b32_e32 v48, v11
	v_cndmask_b32_e32 v26, v29, v26, vcc
	v_pk_add_f32 v[28:29], v[28:29], v[12:13] op_sel_hi:[0,1]
	v_not_b32_e32 v27, v28
	v_or_b32_e32 v33, 0x80000000, v28
	v_cmp_gt_i32_e32 vcc, 0, v28
	v_not_b32_e32 v28, v29
	v_pk_add_f32 v[2:3], v[10:11], v[2:3] op_sel_hi:[0,1]
	v_cndmask_b32_e32 v27, v33, v27, vcc
	v_or_b32_e32 v33, 0x80000000, v29
	v_cmp_gt_i32_e32 vcc, 0, v29
	v_not_b32_e32 v29, v50
	v_min_u32_e32 v68, v57, v56
	v_cndmask_b32_e32 v28, v33, v28, vcc
	v_cmp_gt_i32_e32 vcc, 0, v50
	v_or_b32_e32 v33, 0x80000000, v51
	v_max_u32_e32 v31, v32, v31
	v_cndmask_b32_e32 v29, v30, v29, vcc
	v_not_b32_e32 v30, v51
	v_cmp_gt_i32_e32 vcc, 0, v51
	v_pk_add_f32 v[50:51], v[34:35], v[48:49] op_sel_hi:[0,1]
	v_or_b32_e32 v34, 0x80000000, v51
	v_cndmask_b32_e32 v30, v33, v30, vcc
	v_not_b32_e32 v33, v51
	v_cmp_gt_i32_e32 vcc, 0, v51
	v_or_b32_e32 v47, 0x80000000, v50
	v_pk_add_f32 v[48:49], v[4:5], v[48:49] op_sel_hi:[0,1]
	v_cndmask_b32_e32 v33, v34, v33, vcc
	v_not_b32_e32 v34, v50
	v_cmp_gt_i32_e32 vcc, 0, v50
	v_not_b32_e32 v5, v49
	v_and_b32_e32 v25, 0xffffff00, v25
	v_cndmask_b32_e32 v34, v47, v34, vcc
	v_or_b32_e32 v47, 0x80000000, v49
	v_cmp_gt_i32_e32 vcc, 0, v49
	v_and_b32_e32 v26, 0xffffff00, v26
	v_and_b32_e32 v27, 0xffffff00, v27
	v_cndmask_b32_e32 v5, v47, v5, vcc
	v_and_b32_e32 v5, 0xffffff00, v5
	v_or_b32_e32 v50, 0xcd, v5
	v_not_b32_e32 v5, v48
	v_or_b32_e32 v47, 0x80000000, v48
	v_cmp_gt_i32_e32 vcc, 0, v48
	v_pk_add_f32 v[48:49], v[6:7], v[12:13] op_sel_hi:[0,1]
	v_or_b32_e32 v7, 0x80000000, v48
	v_cndmask_b32_e32 v5, v47, v5, vcc
	v_and_b32_e32 v5, 0xffffff00, v5
	v_or_b32_e32 v51, 0xce, v5
	v_not_b32_e32 v5, v48
	v_cmp_gt_i32_e32 vcc, 0, v48
	v_min_u32_e32 v91, v51, v50
	v_and_b32_e32 v28, 0xffffff00, v28
	v_cndmask_b32_e32 v5, v7, v5, vcc
	v_and_b32_e32 v5, 0xffffff00, v5
	v_or_b32_e32 v58, 0xdf, v5
	v_not_b32_e32 v5, v49
	v_or_b32_e32 v7, 0x80000000, v49
	v_cmp_gt_i32_e32 vcc, 0, v49
	v_pk_add_f32 v[48:49], v[8:9], v[12:13] op_sel_hi:[0,1]
	v_and_b32_e32 v29, 0xffffff00, v29
	v_cndmask_b32_e32 v5, v7, v5, vcc
	v_and_b32_e32 v5, 0xffffff00, v5
	v_or_b32_e32 v59, 0xde, v5
	v_not_b32_e32 v5, v48
	v_or_b32_e32 v7, 0x80000000, v48
	v_cmp_gt_i32_e32 vcc, 0, v48
	v_max_u32_e32 v83, v58, v59
	v_min_u32_e32 v58, v58, v59
	v_cndmask_b32_e32 v5, v7, v5, vcc
	v_and_b32_e32 v5, 0xffffff00, v5
	v_or_b32_e32 v48, 0xef, v5
	v_not_b32_e32 v5, v49
	v_or_b32_e32 v7, 0x80000000, v49
	v_cmp_gt_i32_e32 vcc, 0, v49
	v_max_u32_e32 v89, v83, v88
	v_max_u32_e32 v32, v58, v31
	v_cndmask_b32_e32 v5, v7, v5, vcc
	v_and_b32_e32 v5, 0xffffff00, v5
	v_cmp_lt_i32_e32 vcc, -1, v46
	v_or_b32_e32 v49, 0xee, v5
	v_and_b32_e32 v5, 0xffffff80, v46
	v_cndmask_b32_e64 v46, v86, -1, vcc
	v_cmp_lt_i32_e32 vcc, -1, v45
	v_and_b32_e32 v7, 0xffffff80, v45
	v_xor_b32_e32 v47, v46, v5
	v_cndmask_b32_e64 v45, v86, -1, vcc
	v_xor_b32_e32 v46, v45, v7
	v_pk_add_f32 v[46:47], v[10:11], v[46:47] op_sel_hi:[0,1]
	v_not_b32_e32 v5, v47
	v_or_b32_e32 v7, 0x80000000, v47
	v_cmp_gt_i32_e32 vcc, 0, v47
	v_min_u32_e32 v83, v83, v88
	v_min_u32_e32 v31, v58, v31
	v_cndmask_b32_e32 v5, v7, v5, vcc
	v_and_b32_e32 v5, 0xffffff00, v5
	v_or_b32_e32 v47, 0xf0, v5
	v_not_b32_e32 v5, v46
	v_or_b32_e32 v7, 0x80000000, v46
	v_cmp_gt_i32_e32 vcc, 0, v46
	v_max_u32_e32 v59, v89, v32
	v_max_u32_e32 v58, v83, v31
	v_cndmask_b32_e32 v5, v7, v5, vcc
	v_and_b32_e32 v5, 0xffffff00, v5
	v_cmp_lt_i32_e32 vcc, -1, v44
	v_or_b32_e32 v46, 0xf1, v5
	v_and_b32_e32 v5, 0xffffff80, v44
	v_cndmask_b32_e64 v44, v86, -1, vcc
	v_cmp_lt_i32_e32 vcc, -1, v43
	v_and_b32_e32 v7, 0xffffff80, v43
	v_xor_b32_e32 v45, v44, v5
	v_cndmask_b32_e64 v43, v86, -1, vcc
	v_xor_b32_e32 v44, v43, v7
	v_pk_add_f32 v[44:45], v[10:11], v[44:45] op_sel_hi:[0,1]
	v_not_b32_e32 v5, v45
	v_or_b32_e32 v7, 0x80000000, v45
	v_cmp_gt_i32_e32 vcc, 0, v45
	v_min_u32_e32 v64, v46, v47
	v_min_u32_e32 v32, v89, v32
	v_cndmask_b32_e32 v5, v7, v5, vcc
	v_and_b32_e32 v5, 0xffffff00, v5
	v_or_b32_e32 v45, 0xf2, v5
	v_not_b32_e32 v5, v44
	v_or_b32_e32 v7, 0x80000000, v44
	v_cmp_gt_i32_e32 vcc, 0, v44
	v_min_u32_e32 v31, v83, v31
	v_and_b32_e32 v30, 0xffffff00, v30
	v_cndmask_b32_e32 v5, v7, v5, vcc
	v_and_b32_e32 v5, 0xffffff00, v5
	v_cmp_lt_i32_e32 vcc, -1, v42
	v_or_b32_e32 v44, 0xf3, v5
	v_and_b32_e32 v5, 0xffffff80, v42
	v_cndmask_b32_e64 v42, v86, -1, vcc
	v_cmp_lt_i32_e32 vcc, -1, v41
	v_and_b32_e32 v7, 0xffffff80, v41
	v_xor_b32_e32 v43, v42, v5
	v_cndmask_b32_e64 v41, v86, -1, vcc
	v_xor_b32_e32 v42, v41, v7
	v_pk_add_f32 v[42:43], v[10:11], v[42:43] op_sel_hi:[0,1]
	v_not_b32_e32 v5, v43
	v_or_b32_e32 v7, 0x80000000, v43
	v_cmp_gt_i32_e32 vcc, 0, v43
	v_max_u32_e32 v63, v44, v45
	v_min_u32_e32 v44, v44, v45
	v_cndmask_b32_e32 v5, v7, v5, vcc
	v_and_b32_e32 v5, 0xffffff00, v5
	v_or_b32_e32 v43, 0xf4, v5
	v_not_b32_e32 v5, v42
	v_or_b32_e32 v7, 0x80000000, v42
	v_cmp_gt_i32_e32 vcc, 0, v42
	v_max_u32_e32 v45, v46, v47
	v_min_u32_e32 v65, v63, v64
	v_cndmask_b32_e32 v5, v7, v5, vcc
	v_and_b32_e32 v5, 0xffffff00, v5
	v_cmp_lt_i32_e32 vcc, -1, v40
	v_or_b32_e32 v42, 0xf5, v5
	v_and_b32_e32 v5, 0xffffff80, v40
	v_cndmask_b32_e64 v40, v86, -1, vcc
	v_cmp_lt_i32_e32 vcc, -1, v39
	v_and_b32_e32 v7, 0xffffff80, v39
	v_xor_b32_e32 v41, v40, v5
	v_cndmask_b32_e64 v39, v86, -1, vcc
	v_xor_b32_e32 v40, v39, v7
	v_pk_add_f32 v[40:41], v[10:11], v[40:41] op_sel_hi:[0,1]
	v_not_b32_e32 v5, v41
	v_or_b32_e32 v7, 0x80000000, v41
	v_cmp_gt_i32_e32 vcc, 0, v41
	v_min_u32_e32 v46, v44, v45
	v_max_u32_e32 v44, v44, v45
	v_cndmask_b32_e32 v5, v7, v5, vcc
	v_and_b32_e32 v5, 0xffffff00, v5
	v_or_b32_e32 v60, 0xf6, v5
	v_not_b32_e32 v5, v40
	v_or_b32_e32 v7, 0x80000000, v40
	v_cmp_gt_i32_e32 vcc, 0, v40
	v_min_u32_e32 v47, v65, v46
	v_max_u32_e32 v46, v65, v46
	v_cndmask_b32_e32 v5, v7, v5, vcc
	v_and_b32_e32 v5, 0xffffff00, v5
	v_cmp_lt_i32_e32 vcc, -1, v38
	v_or_b32_e32 v61, 0xf7, v5
	v_and_b32_e32 v33, 0xffffff00, v33
	v_cndmask_b32_e64 v5, v86, -1, vcc
	v_cmp_lt_i32_e32 vcc, -1, v37
	v_xor_b32_e32 v39, v5, v54
	v_max_u32_e32 v54, v61, v60
	v_cndmask_b32_e64 v7, v86, -1, vcc
	v_xor_b32_e32 v38, v7, v55
	v_pk_add_f32 v[40:41], v[8:9], v[38:39] op_sel_hi:[0,1]
	v_not_b32_e32 v5, v41
	v_or_b32_e32 v7, 0x80000000, v41
	v_cmp_gt_i32_e32 vcc, 0, v41
	v_pk_add_f32 v[38:39], v[10:11], v[38:39] op_sel_hi:[0,1]
	v_min_u32_e32 v55, v42, v43
	v_cndmask_b32_e32 v5, v7, v5, vcc
	v_and_b32_e32 v5, 0xffffff00, v5
	v_or_b32_e32 v41, 0xe8, v5
	v_not_b32_e32 v5, v40
	v_or_b32_e32 v7, 0x80000000, v40
	v_cmp_gt_i32_e32 vcc, 0, v40
	v_min_u32_e32 v60, v61, v60
	v_max_u32_e32 v42, v42, v43
	v_cndmask_b32_e32 v5, v7, v5, vcc
	v_and_b32_e32 v5, 0xffffff00, v5
	v_or_b32_e32 v40, 0xe9, v5
	v_not_b32_e32 v5, v39
	v_or_b32_e32 v7, 0x80000000, v39
	v_cmp_gt_i32_e32 vcc, 0, v39
	v_max_u32_e32 v62, v54, v55
	v_max_u32_e32 v43, v60, v42
	v_cndmask_b32_e32 v5, v7, v5, vcc
	v_and_b32_e32 v5, 0xffffff00, v5
	v_or_b32_e32 v39, 0xf8, v5
	v_not_b32_e32 v5, v38
	v_or_b32_e32 v7, 0x80000000, v38
	v_cmp_gt_i32_e32 vcc, 0, v38
	v_min_u32_e32 v54, v54, v55
	v_min_u32_e32 v42, v60, v42
	v_cndmask_b32_e32 v5, v7, v5, vcc
	v_and_b32_e32 v5, 0xffffff00, v5
	v_cmp_lt_i32_e32 vcc, -1, v36
	v_or_b32_e32 v38, 0xf9, v5
	v_max_u32_e32 v60, v63, v64
	v_cndmask_b32_e64 v5, v86, -1, vcc
	v_cmp_lt_i32_e32 vcc, -1, v35
	v_xor_b32_e32 v37, v5, v52
	v_mov_b32_e32 v5, v9
	v_cndmask_b32_e64 v7, v86, -1, vcc
	v_xor_b32_e32 v36, v7, v53
	v_mov_b32_e32 v7, v4
	v_mov_b32_e32 v4, v36
	v_pk_add_f32 v[4:5], v[6:7], v[4:5]
	v_max_u32_e32 v61, v62, v43
	v_not_b32_e32 v6, v5
	v_or_b32_e32 v7, 0x80000000, v5
	v_cmp_gt_i32_e32 vcc, 0, v5
	v_max_u32_e32 v55, v54, v42
	v_min_u32_e32 v45, v60, v44
	v_cndmask_b32_e32 v5, v7, v6, vcc
	v_and_b32_e32 v5, 0xffffff00, v5
	v_or_b32_e32 v6, 0xcf, v5
	v_not_b32_e32 v5, v4
	v_or_b32_e32 v7, 0x80000000, v4
	v_cmp_gt_i32_e32 vcc, 0, v4
	v_min_u32_e32 v43, v62, v43
	v_min_u32_e32 v42, v54, v42
	v_cndmask_b32_e32 v4, v7, v5, vcc
	v_and_b32_e32 v4, 0xffffff00, v4
	v_or_b32_e32 v7, 0xdb, v4
	v_pk_add_f32 v[4:5], v[8:9], v[36:37] op_sel_hi:[0,1]
	v_not_b32_e32 v8, v5
	v_or_b32_e32 v9, 0x80000000, v5
	v_cmp_gt_i32_e32 vcc, 0, v5
	v_max_u32_e32 v44, v60, v44
	v_min_u32_e32 v66, v61, v47
	v_cndmask_b32_e32 v5, v9, v8, vcc
	v_and_b32_e32 v5, 0xffffff00, v5
	v_or_b32_e32 v8, 0xea, v5
	v_not_b32_e32 v5, v4
	v_or_b32_e32 v9, 0x80000000, v4
	v_cmp_gt_i32_e32 vcc, 0, v4
	v_min_u32_e32 v63, v55, v45
	v_min_u32_e32 v62, v43, v46
	v_cndmask_b32_e32 v4, v9, v5, vcc
	v_and_b32_e32 v4, 0xffffff00, v4
	v_or_b32_e32 v9, 0xeb, v4
	v_pk_add_f32 v[4:5], v[10:11], v[36:37] op_sel_hi:[0,1]
	v_not_b32_e32 v35, v5
	v_or_b32_e32 v36, 0x80000000, v5
	v_cmp_gt_i32_e32 vcc, 0, v5
	v_min_u32_e32 v37, v38, v39
	v_min_u32_e32 v54, v42, v44
	v_cndmask_b32_e32 v5, v36, v35, vcc
	v_not_b32_e32 v35, v4
	v_or_b32_e32 v36, 0x80000000, v4
	v_cmp_gt_i32_e32 vcc, 0, v4
	v_and_b32_e32 v5, 0xffffff00, v5
	v_or_b32_e32 v5, 0xfa, v5
	v_cndmask_b32_e32 v4, v36, v35, vcc
	v_not_b32_e32 v35, v3
	v_or_b32_e32 v36, 0x80000000, v3
	v_cmp_gt_i32_e32 vcc, 0, v3
	s_mov_b64 s[50:51], exec
	s_mov_b64 exec, -1
	s_waitcnt vmcnt(0)
	v_pk_mul_f32 v[200:201], v[200:201], s[96:97] op_sel_hi:[1,0]
	v_pk_mul_f32 v[202:203], v[202:203], s[96:97] op_sel_hi:[1,0]
	v_pk_mul_f32 v[204:205], v[204:205], s[96:97] op_sel_hi:[1,0]
	v_pk_mul_f32 v[206:207], v[206:207], s[96:97] op_sel_hi:[1,0]
	v_pk_mul_f32 v[208:209], v[208:209], s[96:97] op_sel_hi:[1,0]
	v_pk_mul_f32 v[210:211], v[210:211], s[96:97] op_sel_hi:[1,0]
	v_pk_mul_f32 v[212:213], v[212:213], s[96:97] op_sel_hi:[1,0]
	v_pk_mul_f32 v[214:215], v[214:215], s[96:97] op_sel_hi:[1,0]
	v_pk_mul_f32 v[216:217], v[216:217], s[96:97] op_sel_hi:[1,0]
	v_pk_mul_f32 v[218:219], v[218:219], s[96:97] op_sel_hi:[1,0]
	v_pk_mul_f32 v[220:221], v[220:221], s[96:97] op_sel_hi:[1,0]
	v_pk_mul_f32 v[222:223], v[222:223], s[96:97] op_sel_hi:[1,0]
	v_pk_mul_f32 v[224:225], v[224:225], s[96:97] op_sel_hi:[1,0]
	v_pk_mul_f32 v[226:227], v[226:227], s[96:97] op_sel_hi:[1,0]
	v_pk_mul_f32 v[228:229], v[228:229], s[96:97] op_sel_hi:[1,0]
	v_pk_mul_f32 v[230:231], v[230:231], s[96:97] op_sel_hi:[1,0]
	v_cvt_scalef32_pk_fp4_f32 v232, v200, v201, 1.0
	v_cvt_scalef32_pk_fp4_f32 v233, v208, v209, 1.0
	v_cvt_scalef32_pk_fp4_f32 v234, v216, v217, 1.0
	v_cvt_scalef32_pk_fp4_f32 v235, v224, v225, 1.0
	v_cvt_scalef32_pk_fp4_f32 v232, v202, v203, 1.0 op_sel:[0,0,1,0]
	v_cvt_scalef32_pk_fp4_f32 v233, v210, v211, 1.0 op_sel:[0,0,1,0]
	v_cvt_scalef32_pk_fp4_f32 v234, v218, v219, 1.0 op_sel:[0,0,1,0]
	v_cvt_scalef32_pk_fp4_f32 v235, v226, v227, 1.0 op_sel:[0,0,1,0]
	v_cvt_scalef32_pk_fp4_f32 v232, v204, v205, 1.0 op_sel:[0,0,0,1]
	v_cvt_scalef32_pk_fp4_f32 v233, v212, v213, 1.0 op_sel:[0,0,0,1]
	v_cvt_scalef32_pk_fp4_f32 v234, v220, v221, 1.0 op_sel:[0,0,0,1]
	v_cvt_scalef32_pk_fp4_f32 v235, v228, v229, 1.0 op_sel:[0,0,0,1]
	v_cvt_scalef32_pk_fp4_f32 v232, v206, v207, 1.0 op_sel:[0,0,1,1]
	v_cvt_scalef32_pk_fp4_f32 v233, v214, v215, 1.0 op_sel:[0,0,1,1]
	v_cvt_scalef32_pk_fp4_f32 v234, v222, v223, 1.0 op_sel:[0,0,1,1]
	v_cvt_scalef32_pk_fp4_f32 v235, v230, v231, 1.0 op_sel:[0,0,1,1]
	s_nop 0
	global_store_dwordx4 v[240:241], v[232:235], off
	v_lshl_add_u64 v[240:241], v[240:241], 0, v[246:247]
	global_load_dwordx4 v[200:203], v[236:237], off
	global_load_dwordx4 v[204:207], v[236:237], off offset:16
	global_load_dwordx4 v[208:211], v[236:237], off offset:32
	global_load_dwordx4 v[212:215], v[236:237], off offset:48
	global_load_dwordx4 v[216:219], v[238:239], off
	global_load_dwordx4 v[220:223], v[238:239], off offset:16
	global_load_dwordx4 v[224:227], v[238:239], off offset:32
	global_load_dwordx4 v[228:231], v[238:239], off offset:48
	v_lshl_add_u64 v[236:237], v[236:237], 0, v[244:245]
	v_lshl_add_u64 v[238:239], v[238:239], 0, v[244:245]
	s_mov_b64 exec, s[50:51]
	s_nop 4
	v_and_b32_e32 v4, 0xffffff00, v4
	v_or_b32_e32 v4, 0xfb, v4
	v_cndmask_b32_e32 v3, v36, v35, vcc
	v_and_b32_e32 v3, 0xffffff00, v3
	v_or_b32_e32 v35, 0xfc, v3
	v_not_b32_e32 v3, v2
	v_or_b32_e32 v36, 0x80000000, v2
	v_cmp_gt_i32_e32 vcc, 0, v2
	v_min_u32_e32 v64, v66, v63
	v_min_u32_e32 v60, v62, v54
	v_cndmask_b32_e32 v2, v36, v3, vcc
	v_and_b32_e32 v2, 0xffffff00, v2
	v_or_b32_e32 v36, 0xfd, v2
	v_pk_add_f32 v[2:3], v[10:11], v[12:13] op_sel_hi:[0,1]
	v_not_b32_e32 v10, v3
	v_or_b32_e32 v11, 0x80000000, v3
	v_cmp_gt_i32_e32 vcc, 0, v3
	v_min_u32_e32 v65, v64, v60
	v_max_u32_e32 v78, v9, v8
	v_cndmask_b32_e32 v3, v11, v10, vcc
	v_not_b32_e32 v10, v2
	v_or_b32_e32 v11, 0x80000000, v2
	v_cmp_gt_i32_e32 vcc, 0, v2
	v_and_b32_e32 v3, 0xffffff00, v3
	v_or_b32_e32 v3, 0xfe, v3
	v_cndmask_b32_e32 v2, v11, v10, vcc
	v_or_b32_e32 v2, 0xff, v2
	v_max_u32_e32 v10, v2, v3
	v_min_u32_e32 v11, v36, v35
	v_min_u32_e32 v2, v2, v3
	v_max_u32_e32 v3, v36, v35
	v_max_u32_e32 v36, v4, v5
	v_min_u32_e32 v4, v4, v5
	v_max_u32_e32 v5, v38, v39
	v_max_u32_e32 v12, v10, v11
	v_max_u32_e32 v13, v2, v3
	v_min_u32_e32 v52, v36, v37
	v_min_u32_e32 v38, v4, v5
	v_min_u32_e32 v10, v10, v11
	v_min_u32_e32 v2, v2, v3
	v_max_u32_e32 v11, v36, v37
	v_max_u32_e32 v4, v4, v5
	v_max_u32_e32 v35, v12, v13
	v_min_u32_e32 v39, v52, v38
	v_max_u32_e32 v3, v10, v2
	v_min_u32_e32 v5, v11, v4
	v_min_u32_e32 v12, v12, v13
	v_max_u32_e32 v13, v52, v38
	v_min_u32_e32 v2, v10, v2
	v_max_u32_e32 v4, v11, v4
	v_max_u32_e32 v53, v35, v39
	v_max_u32_e32 v36, v3, v5
	v_max_u32_e32 v38, v12, v13
	v_max_u32_e32 v10, v2, v4
	v_max_u32_e32 v37, v53, v36
	v_max_u32_e32 v11, v38, v10
	v_max_u32_e32 v52, v37, v11
	v_min_u32_e32 v11, v37, v11
	v_max_u32_e32 v37, v64, v60
	v_max_u32_e32 v64, v48, v49
	v_min_u32_e32 v48, v48, v49
	v_max_u32_e32 v49, v57, v56
	v_min_u32_e32 v80, v40, v41
	v_min_u32_e32 v8, v9, v8
	v_max_u32_e32 v9, v40, v41
	v_max_u32_e32 v90, v7, v6
	v_min_u32_e32 v6, v7, v6
	v_max_u32_e32 v7, v51, v50
	v_max_u32_e32 v69, v64, v68
	v_max_u32_e32 v56, v48, v49
	v_min_u32_e32 v81, v78, v80
	v_min_u32_e32 v40, v8, v9
	v_min_u32_e32 v64, v64, v68
	v_min_u32_e32 v48, v48, v49
	v_max_u32_e32 v68, v78, v80
	v_max_u32_e32 v8, v8, v9
	v_min_u32_e32 v92, v90, v91
	v_min_u32_e32 v50, v6, v7
	v_max_u32_e32 v88, v90, v91
	v_max_u32_e32 v6, v6, v7
	v_max_u32_e32 v57, v69, v56
	v_min_u32_e32 v41, v81, v40
	v_max_u32_e32 v49, v64, v48
	v_min_u32_e32 v9, v68, v8
	v_min_u32_e32 v56, v69, v56
	v_max_u32_e32 v40, v81, v40
	v_min_u32_e32 v48, v64, v48
	v_max_u32_e32 v8, v68, v8
	v_min_u32_e32 v51, v92, v50
	v_min_u32_e32 v7, v88, v6
	v_max_u32_e32 v50, v92, v50
	v_max_u32_e32 v6, v88, v6
	v_min_u32_e32 v35, v35, v39
	v_min_u32_e32 v3, v3, v5
	v_min_u32_e32 v12, v12, v13
	v_min_u32_e32 v2, v2, v4
	v_max_u32_e32 v39, v61, v47
	v_max_u32_e32 v45, v55, v45
	v_max_u32_e32 v43, v43, v46
	v_max_u32_e32 v42, v42, v44
	v_max_u32_e32 v82, v57, v41
	v_max_u32_e32 v78, v49, v9
	v_max_u32_e32 v69, v56, v40
	v_max_u32_e32 v64, v48, v8
	v_min_u32_e32 v93, v59, v51
	v_min_u32_e32 v90, v58, v7
	v_min_u32_e32 v89, v32, v50
	v_min_u32_e32 v83, v31, v6
	v_min_u32_e32 v41, v57, v41
	v_min_u32_e32 v9, v49, v9
	v_min_u32_e32 v40, v56, v40
	v_min_u32_e32 v8, v48, v8
	v_max_u32_e32 v51, v59, v51
	v_max_u32_e32 v7, v58, v7
	v_max_u32_e32 v32, v32, v50
	v_max_u32_e32 v6, v31, v6
	v_max_u32_e32 v5, v35, v3
	v_max_u32_e32 v4, v12, v2
	v_min_u32_e32 v47, v39, v45
	v_min_u32_e32 v44, v43, v42
	v_min_u32_e32 v36, v53, v36
	v_min_u32_e32 v10, v38, v10
	v_max_u32_e32 v53, v66, v63
	v_max_u32_e32 v54, v62, v54
	v_min_u32_e32 v3, v35, v3
	v_min_u32_e32 v2, v12, v2
	v_max_u32_e32 v35, v39, v45
	v_max_u32_e32 v39, v43, v42
	v_max_u32_e32 v80, v82, v78
	v_max_u32_e32 v68, v69, v64
	v_min_u32_e32 v91, v93, v90
	v_min_u32_e32 v88, v89, v83
	v_max_u32_e32 v49, v41, v9
	v_max_u32_e32 v48, v40, v8
	v_min_u32_e32 v57, v51, v7
	v_min_u32_e32 v31, v32, v6
	v_min_u32_e32 v78, v82, v78
	v_min_u32_e32 v64, v69, v64
	v_max_u32_e32 v82, v93, v90
	v_max_u32_e32 v83, v89, v83
	v_min_u32_e32 v9, v41, v9
	v_min_u32_e32 v8, v40, v8
	v_max_u32_e32 v7, v51, v7
	v_max_u32_e32 v6, v32, v6
	v_max_u32_e32 v13, v5, v4
	v_max_u32_e32 v38, v36, v10
	v_max_u32_e32 v12, v3, v2
	v_min_u32_e32 v4, v5, v4
	v_max_u32_e32 v5, v47, v44
	v_min_u32_e32 v10, v36, v10
	v_max_u32_e32 v36, v53, v54
	v_min_u32_e32 v2, v3, v2
	v_max_u32_e32 v3, v35, v39
	v_max_u32_e32 v81, v80, v68
	v_min_u32_e32 v92, v91, v88
	v_max_u32_e32 v56, v49, v48
	v_min_u32_e32 v50, v57, v31
	v_max_u32_e32 v69, v78, v64
	v_min_u32_e32 v89, v82, v83
	v_max_u32_e32 v40, v9, v8
	v_min_u32_e32 v32, v7, v6
	v_min_u32_e32 v68, v80, v68
	v_max_u32_e32 v80, v91, v88
	v_min_u32_e32 v48, v49, v48
	v_max_u32_e32 v31, v57, v31
	v_min_u32_e32 v64, v78, v64
	v_max_u32_e32 v78, v82, v83
	v_min_u32_e32 v8, v9, v8
	v_max_u32_e32 v6, v7, v6
	v_max_u32_e32 v67, v52, v65
	v_min_u32_e32 v46, v47, v44
	v_min_u32_e32 v62, v53, v54
	v_min_u32_e32 v42, v35, v39
	v_max_u32_e32 v60, v11, v37
	v_max_u32_e32 v44, v4, v5
	v_max_u32_e32 v53, v10, v36
	v_max_u32_e32 v35, v2, v3
	v_min_u32_e32 v58, v56, v50
	v_min_u32_e32 v41, v40, v32
	v_min_u32_e32 v88, v68, v80
	v_min_u32_e32 v49, v48, v31
	v_min_u32_e32 v82, v64, v78
	v_min_u32_e32 v7, v8, v6
	v_min_u32_e32 v52, v52, v65
	v_min_u32_e32 v11, v11, v37
	v_min_u32_e32 v4, v4, v5
	v_min_u32_e32 v10, v10, v36
	v_min_u32_e32 v2, v2, v3
	v_max_u32_e32 v37, v81, v92
	v_max_u32_e32 v50, v56, v50
	v_max_u32_e32 v65, v69, v89
	v_max_u32_e32 v32, v40, v32
	v_max_u32_e32 v68, v68, v80
	v_max_u32_e32 v31, v48, v31
	v_max_u32_e32 v64, v64, v78
	v_max_u32_e32 v6, v8, v6
	v_max_u32_e32 v55, v13, v46
	v_max_u32_e32 v63, v38, v62
	v_max_u32_e32 v43, v12, v42
	v_min_u32_e32 v94, v81, v92
	v_min_u32_e32 v90, v69, v89
	v_min_u32_e32 v13, v13, v46
	v_min_u32_e32 v38, v38, v62
	v_min_u32_e32 v12, v12, v42
	v_max_u32_e32 v5, v11, v4
	v_max_u32_e32 v3, v10, v2
	v_min_u32_e32 v56, v37, v50
	v_min_u32_e32 v40, v65, v32
	v_min_u32_e32 v48, v68, v31
	v_min_u32_e32 v8, v64, v6
	v_max_u32_e32 v47, v60, v44
	v_max_u32_e32 v39, v53, v35
	v_min_u32_e32 v59, v94, v58
	v_min_u32_e32 v51, v90, v41
	v_min_u32_e32 v57, v88, v49
	v_min_u32_e32 v9, v82, v7
	v_max_u32_e32 v46, v52, v13
	v_max_u32_e32 v42, v38, v12
	v_max_u32_e32 v36, v5, v3
	v_min_u32_e32 v78, v48, v8
	v_min_u32_e32 v4, v11, v4
	v_max_u32_e32 v11, v37, v50
	v_max_u32_e32 v32, v65, v32
	v_max_u32_e32 v31, v68, v31
	v_max_u32_e32 v6, v64, v6
	v_min_u32_e32 v3, v5, v3
	v_max_u32_e32 v5, v56, v40
	v_max_u32_e32 v8, v48, v8
	v_max_u32_e32 v61, v67, v55
	v_max_u32_e32 v45, v63, v43
	v_max_u32_e32 v54, v47, v39
	v_min_u32_e32 v83, v57, v9
	v_max_u32_e32 v62, v46, v42
	v_min_u32_e32 v69, v56, v40
	v_min_u32_e32 v55, v67, v55
	v_min_u32_e32 v43, v63, v43
	v_min_u32_e32 v44, v60, v44
	v_min_u32_e32 v35, v53, v35
	v_max_u32_e32 v58, v94, v58
	v_max_u32_e32 v41, v90, v41
	v_max_u32_e32 v49, v88, v49
	v_max_u32_e32 v7, v82, v7
	v_min_u32_e32 v13, v52, v13
	v_min_u32_e32 v12, v38, v12
	v_min_u32_e32 v2, v10, v2
	v_min_u32_e32 v37, v11, v32
	v_min_u32_e32 v50, v31, v6
	v_min_u32_e32 v39, v47, v39
	v_max_u32_e32 v47, v59, v51
	v_max_u32_e32 v9, v57, v9
	v_min_u32_e32 v42, v46, v42
	v_min_u32_e32 v40, v5, v8
	v_and_b32_e32 v34, 0xffffff00, v34
	v_max_u32_e32 v66, v61, v45
	v_min_u32_e32 v93, v59, v51
	v_max_u32_e32 v63, v55, v43
	v_max_u32_e32 v53, v44, v35
	v_min_u32_e32 v60, v58, v41
	v_min_u32_e32 v67, v49, v7
	v_max_u32_e32 v38, v13, v12
	v_max_u32_e32 v10, v4, v2
	v_min_u32_e32 v52, v37, v50
	v_min_u32_e32 v45, v61, v45
	v_min_u32_e32 v51, v47, v9
	v_max3_u32 v40, v42, v3, v40
	v_min_u32_e32 v43, v55, v43
	v_min_u32_e32 v35, v44, v35
	v_max_u32_e32 v41, v58, v41
	v_max_u32_e32 v7, v49, v7
	v_min_u32_e32 v2, v4, v2
	v_max_u32_e32 v4, v11, v32
	v_max_u32_e32 v6, v31, v6
	v_min_u32_e32 v3, v42, v3
	v_or_b32_e32 v25, 0x8f, v25
	v_or_b32_e32 v26, 0x8e, v26
	v_or_b32_e32 v27, 0x9f, v27
	v_or_b32_e32 v28, 0x9e, v28
	v_or_b32_e32 v29, 0xaf, v29
	v_or_b32_e32 v30, 0xae, v30
	v_or_b32_e32 v33, 0xbd, v33
	v_or_b32_e32 v34, 0xbe, v34
	v_max3_u32 v52, v38, v10, v52
	v_max3_u32 v51, v45, v39, v51
	v_min_u32_e32 v44, v41, v7
	v_min_u32_e32 v12, v13, v12
	v_min_u32_e32 v11, v4, v6
	v_min_u32_e32 v10, v38, v10
	v_min_u32_e32 v39, v45, v39
	v_max3_u32 v3, v3, v5, v8
	v_min_u32_e32 v8, v43, v35
	v_min_u32_e32 v91, v93, v83
	v_max3_u32 v44, v43, v35, v44
	v_max3_u32 v11, v12, v2, v11
	v_max3_u32 v10, v10, v37, v50
	v_max3_u32 v9, v39, v47, v9
	v_max3_u32 v7, v8, v41, v7
	v_min_u32_e32 v2, v12, v2
	v_max_u32_e32 v12, v23, v24
	v_min_u32_e32 v35, v34, v33
	v_min_u32_e32 v23, v23, v24
	v_max_u32_e32 v24, v34, v33
	v_max_u32_e32 v41, v29, v30
	v_min_u32_e32 v42, v27, v28
	v_min_u32_e32 v29, v29, v30
	v_max_u32_e32 v27, v27, v28
	v_max_u32_e32 v47, v25, v26
	v_min_u32_e32 v50, v22, v21
	v_min_u32_e32 v25, v25, v26
	v_max_u32_e32 v21, v22, v21
	v_max_u32_e32 v55, v20, v18
	v_min_u32_e32 v56, v17, v16
	v_min_u32_e32 v18, v20, v18
	v_max_u32_e32 v16, v17, v16
	v_max3_u32 v91, v66, v54, v91
	v_min_u32_e32 v48, v66, v54
	v_max_u32_e32 v39, v12, v35
	v_max_u32_e32 v33, v23, v24
	v_min_u32_e32 v43, v41, v42
	v_min_u32_e32 v28, v29, v27
	v_min_u32_e32 v12, v12, v35
	v_min_u32_e32 v23, v23, v24
	v_max_u32_e32 v35, v41, v42
	v_max_u32_e32 v27, v29, v27
	v_max_u32_e32 v54, v47, v50
	v_max_u32_e32 v22, v25, v21
	v_min_u32_e32 v57, v55, v56
	v_min_u32_e32 v17, v18, v16
	v_min_u32_e32 v47, v47, v50
	v_min_u32_e32 v21, v25, v21
	v_max_u32_e32 v50, v55, v56
	v_max_u32_e32 v16, v18, v16
	v_max_u32_e32 v34, v39, v33
	v_min_u32_e32 v30, v43, v28
	v_max_u32_e32 v24, v12, v23
	v_min_u32_e32 v29, v35, v27
	v_min_u32_e32 v33, v39, v33
	v_max_u32_e32 v28, v43, v28
	v_min_u32_e32 v12, v12, v23
	v_max_u32_e32 v23, v35, v27
	v_max_u32_e32 v26, v54, v22
	v_min_u32_e32 v20, v57, v17
	v_max_u32_e32 v25, v47, v21
	v_min_u32_e32 v18, v50, v16
	v_min_u32_e32 v22, v54, v22
	v_max_u32_e32 v17, v57, v17
	v_min_u32_e32 v21, v47, v21
	v_max_u32_e32 v16, v50, v16
	v_max_u32_e32 v45, v34, v30
	v_max_u32_e32 v41, v24, v29
	v_max_u32_e32 v39, v33, v28
	v_max_u32_e32 v27, v12, v23
	v_min_u32_e32 v58, v26, v20
	v_min_u32_e32 v55, v25, v18
	v_min_u32_e32 v54, v22, v17
	v_min_u32_e32 v47, v21, v16
	v_min_u32_e32 v30, v34, v30
	v_min_u32_e32 v24, v24, v29
	v_min_u32_e32 v28, v33, v28
	v_min_u32_e32 v12, v12, v23
	v_max_u32_e32 v20, v26, v20
	v_max_u32_e32 v18, v25, v18
	v_max_u32_e32 v17, v22, v17
	v_max_u32_e32 v16, v21, v16
	v_max_u32_e32 v42, v45, v41
	v_max_u32_e32 v35, v39, v27
	v_min_u32_e32 v56, v58, v55
	v_min_u32_e32 v50, v54, v47
	v_max_u32_e32 v29, v30, v24
	v_max_u32_e32 v23, v28, v12
	v_min_u32_e32 v25, v20, v18
	v_min_u32_e32 v21, v17, v16
	v_min_u32_e32 v41, v45, v41
	v_min_u32_e32 v27, v39, v27
	v_max_u32_e32 v45, v58, v55
	v_max_u32_e32 v47, v54, v47
	v_min_u32_e32 v24, v30, v24
	v_min_u32_e32 v12, v28, v12
	v_max_u32_e32 v18, v20, v18
	v_max_u32_e32 v16, v17, v16
	v_max_u32_e32 v43, v42, v35
	v_min_u32_e32 v57, v56, v50
	v_max_u32_e32 v33, v29, v23
	v_min_u32_e32 v22, v25, v21
	v_max_u32_e32 v39, v41, v27
	v_min_u32_e32 v54, v45, v47
	v_max_u32_e32 v28, v24, v12
	v_min_u32_e32 v17, v18, v16
	v_min_u32_e32 v35, v42, v35
	v_max_u32_e32 v42, v56, v50
	v_min_u32_e32 v23, v29, v23
	v_max_u32_e32 v21, v25, v21
	v_min_u32_e32 v27, v41, v27
	v_max_u32_e32 v41, v45, v47
	v_min_u32_e32 v12, v24, v12
	v_max_u32_e32 v16, v18, v16
	v_max_u32_e32 v59, v43, v57
	v_max_u32_e32 v26, v33, v22
	v_max_u32_e32 v55, v39, v54
	v_max_u32_e32 v20, v28, v17
	v_max_u32_e32 v50, v35, v42
	v_max_u32_e32 v25, v23, v21
	v_max_u32_e32 v45, v27, v41
	v_max_u32_e32 v18, v12, v16
	v_min_u32_e32 v43, v43, v57
	v_min_u32_e32 v22, v33, v22
	v_min_u32_e32 v39, v39, v54
	v_min_u32_e32 v17, v28, v17
	v_min_u32_e32 v35, v35, v42
	v_min_u32_e32 v21, v23, v21
	v_min_u32_e32 v27, v27, v41
	v_min_u32_e32 v12, v12, v16
	v_max_u32_e32 v33, v43, v22
	v_max_u32_e32 v28, v39, v17
	v_max_u32_e32 v23, v35, v21
	v_max_u32_e32 v16, v27, v12
	v_min_u32_e32 v22, v43, v22
	v_min_u32_e32 v17, v39, v17
	v_min_u32_e32 v21, v35, v21
	v_min_u32_e32 v12, v27, v12
	v_min_u32_e32 v80, v69, v78
	v_min_u32_e32 v82, v60, v67
	v_max_u32_e32 v34, v59, v26
	v_max_u32_e32 v30, v55, v20
	v_max_u32_e32 v29, v50, v25
	v_max_u32_e32 v24, v45, v18
	v_min_u32_e32 v26, v59, v26
	v_min_u32_e32 v20, v55, v20
	v_min_u32_e32 v25, v50, v25
	v_min_u32_e32 v18, v45, v18
	v_max_u32_e32 v39, v22, v17
	v_max_u32_e32 v27, v21, v12
	v_min_u32_e32 v17, v22, v17
	v_min_u32_e32 v12, v21, v12
	v_min_u32_e32 v21, v15, v14
	v_max3_u32 v80, v62, v36, v80
	v_max3_u32 v82, v63, v53, v82
	v_min_u32_e32 v36, v62, v36
	v_min_u32_e32 v53, v63, v53
	v_max_u32_e32 v58, v34, v30
	v_max_u32_e32 v47, v29, v24
	v_max_u32_e32 v54, v33, v28
	v_max_u32_e32 v41, v23, v16
	v_max_u32_e32 v55, v26, v20
	v_max_u32_e32 v45, v25, v18
	v_min_u32_e32 v30, v34, v30
	v_min_u32_e32 v24, v29, v24
	v_min_u32_e32 v28, v33, v28
	v_min_u32_e32 v16, v23, v16
	v_min_u32_e32 v20, v26, v20
	v_min_u32_e32 v18, v25, v18
	v_max3_u32 v21, v17, v12, v21
	v_min_u32_e32 v12, v17, v12
	v_max3_u32 v48, v48, v93, v83
	v_max3_u32 v36, v36, v69, v78
	v_max3_u32 v53, v53, v60, v67
	v_max3_u32 v2, v2, v4, v6
	v_max_u32_e32 v56, v58, v47
	v_max_u32_e32 v42, v54, v41
	v_max_u32_e32 v50, v55, v45
	v_max_u32_e32 v35, v39, v27
	v_max_u32_e32 v29, v30, v24
	v_max_u32_e32 v23, v28, v16
	v_max_u32_e32 v25, v20, v18
	v_min_u32_e32 v47, v58, v47
	v_min_u32_e32 v41, v54, v41
	v_min_u32_e32 v45, v55, v45
	v_min_u32_e32 v27, v39, v27
	v_min_u32_e32 v24, v30, v24
	v_min_u32_e32 v16, v28, v16
	v_min_u32_e32 v18, v20, v18
	v_max3_u32 v12, v12, v15, v14
	v_max_u32_e32 v49, v48, v36
	v_max_u32_e32 v37, v53, v10
	v_max_u32_e32 v5, v9, v3
	v_max_u32_e32 v4, v7, v2
	v_min_u32_e32 v57, v56, v42
	v_min_u32_e32 v43, v50, v35
	v_min_u32_e32 v33, v29, v23
	v_min_u32_e32 v22, v25, v21
	v_min_u32_e32 v54, v47, v41
	v_min_u32_e32 v39, v45, v27
	v_min_u32_e32 v28, v24, v16
	v_min_u32_e32 v14, v18, v12
	v_min_u32_e32 v36, v48, v36
	v_min_u32_e32 v10, v53, v10
	s_mov_b64 s[50:51], exec
	s_mov_b64 exec, -1
	s_waitcnt vmcnt(0)
	v_pk_mul_f32 v[200:201], v[200:201], s[96:97] op_sel_hi:[1,0]
	v_pk_mul_f32 v[202:203], v[202:203], s[96:97] op_sel_hi:[1,0]
	v_pk_mul_f32 v[204:205], v[204:205], s[96:97] op_sel_hi:[1,0]
	v_pk_mul_f32 v[206:207], v[206:207], s[96:97] op_sel_hi:[1,0]
	v_pk_mul_f32 v[208:209], v[208:209], s[96:97] op_sel_hi:[1,0]
	v_pk_mul_f32 v[210:211], v[210:211], s[96:97] op_sel_hi:[1,0]
	v_pk_mul_f32 v[212:213], v[212:213], s[96:97] op_sel_hi:[1,0]
	v_pk_mul_f32 v[214:215], v[214:215], s[96:97] op_sel_hi:[1,0]
	v_pk_mul_f32 v[216:217], v[216:217], s[96:97] op_sel_hi:[1,0]
	v_pk_mul_f32 v[218:219], v[218:219], s[96:97] op_sel_hi:[1,0]
	v_pk_mul_f32 v[220:221], v[220:221], s[96:97] op_sel_hi:[1,0]
	v_pk_mul_f32 v[222:223], v[222:223], s[96:97] op_sel_hi:[1,0]
	v_pk_mul_f32 v[224:225], v[224:225], s[96:97] op_sel_hi:[1,0]
	v_pk_mul_f32 v[226:227], v[226:227], s[96:97] op_sel_hi:[1,0]
	v_pk_mul_f32 v[228:229], v[228:229], s[96:97] op_sel_hi:[1,0]
	v_pk_mul_f32 v[230:231], v[230:231], s[96:97] op_sel_hi:[1,0]
	v_cvt_scalef32_pk_fp4_f32 v232, v200, v201, 1.0
	v_cvt_scalef32_pk_fp4_f32 v233, v208, v209, 1.0
	v_cvt_scalef32_pk_fp4_f32 v234, v216, v217, 1.0
	v_cvt_scalef32_pk_fp4_f32 v235, v224, v225, 1.0
	v_cvt_scalef32_pk_fp4_f32 v232, v202, v203, 1.0 op_sel:[0,0,1,0]
	v_cvt_scalef32_pk_fp4_f32 v233, v210, v211, 1.0 op_sel:[0,0,1,0]
	v_cvt_scalef32_pk_fp4_f32 v234, v218, v219, 1.0 op_sel:[0,0,1,0]
	v_cvt_scalef32_pk_fp4_f32 v235, v226, v227, 1.0 op_sel:[0,0,1,0]
	v_cvt_scalef32_pk_fp4_f32 v232, v204, v205, 1.0 op_sel:[0,0,0,1]
	v_cvt_scalef32_pk_fp4_f32 v233, v212, v213, 1.0 op_sel:[0,0,0,1]
	v_cvt_scalef32_pk_fp4_f32 v234, v220, v221, 1.0 op_sel:[0,0,0,1]
	v_cvt_scalef32_pk_fp4_f32 v235, v228, v229, 1.0 op_sel:[0,0,0,1]
	v_cvt_scalef32_pk_fp4_f32 v232, v206, v207, 1.0 op_sel:[0,0,1,1]
	v_cvt_scalef32_pk_fp4_f32 v233, v214, v215, 1.0 op_sel:[0,0,1,1]
	v_cvt_scalef32_pk_fp4_f32 v234, v222, v223, 1.0 op_sel:[0,0,1,1]
	v_cvt_scalef32_pk_fp4_f32 v235, v230, v231, 1.0 op_sel:[0,0,1,1]
	s_nop 0
	global_store_dwordx4 v[240:241], v[232:235], off
	v_lshl_add_u64 v[240:241], v[240:241], 0, v[246:247]
	s_mov_b64 exec, s[50:51]
	s_nop 4
	v_min_u32_e32 v3, v9, v3
	v_min_u32_e32 v2, v7, v2
	v_max_u32_e32 v42, v56, v42
	v_max_u32_e32 v35, v50, v35
	v_max_u32_e32 v23, v29, v23
	v_max_u32_e32 v21, v25, v21
	v_max_u32_e32 v41, v47, v41
	v_max_u32_e32 v27, v45, v27
	v_max_u32_e32 v16, v24, v16
	v_max_u32_e32 v12, v18, v12
	v_max_u32_e32 v81, v91, v80
	v_max_u32_e32 v64, v82, v52
	v_max_u32_e32 v46, v51, v40
	v_max_u32_e32 v13, v44, v11
	v_min_u32_e32 v59, v57, v43
	v_min_u32_e32 v26, v33, v22
	v_min_u32_e32 v55, v54, v39
	v_min_u32_e32 v15, v28, v14
	v_min_u32_e32 v30, v91, v80
	v_min_u32_e32 v52, v82, v52
	v_min_u32_e32 v40, v51, v40
	v_min_u32_e32 v11, v44, v11
	v_max_u32_e32 v48, v36, v10
	v_max_u32_e32 v7, v3, v2
	v_min_u32_e32 v50, v42, v35
	v_min_u32_e32 v25, v23, v21
	v_min_u32_e32 v45, v41, v27
	v_min_u32_e32 v18, v16, v12
	v_max_u32_e32 v43, v57, v43
	v_max_u32_e32 v22, v33, v22
	v_max_u32_e32 v39, v54, v39
	v_max_u32_e32 v14, v28, v14
	v_min_u32_e32 v10, v36, v10
	v_min_u32_e32 v2, v3, v2
	v_max_u32_e32 v35, v42, v35
	v_max_u32_e32 v21, v23, v21
	v_max_u32_e32 v27, v41, v27
	v_max_u32_e32 v12, v16, v12
	v_max_u32_e32 v65, v81, v64
	v_max_u32_e32 v31, v46, v13
	v_max_u32_e32 v38, v49, v37
	v_max_u32_e32 v6, v5, v4
	v_min_u32_e32 v34, v59, v26
	v_min_u32_e32 v17, v55, v15
	v_max_u32_e32 v58, v30, v52
	v_max_u32_e32 v44, v40, v11
	v_min_u32_e32 v29, v50, v25
	v_min_u32_e32 v24, v45, v18
	v_min_u32_e32 v56, v81, v64
	v_min_u32_e32 v13, v46, v13
	v_min_u32_e32 v37, v49, v37
	v_min_u32_e32 v4, v5, v4
	v_min_u32_e32 v33, v43, v22
	v_min_u32_e32 v28, v39, v14
	v_min_u32_e32 v30, v30, v52
	v_min_u32_e32 v11, v40, v11
	v_max_u32_e32 v3, v10, v2
	v_min_u32_e32 v23, v35, v21
	v_min_u32_e32 v16, v27, v12
	v_max_u32_e32 v26, v59, v26
	v_max_u32_e32 v15, v55, v15
	v_max_u32_e32 v25, v50, v25
	v_max_u32_e32 v18, v45, v18
	v_max_u32_e32 v22, v43, v22
	v_max_u32_e32 v14, v39, v14
	v_min_u32_e32 v2, v10, v2
	v_max_u32_e32 v10, v35, v21
	v_max_u32_e32 v12, v27, v12
	v_max_u32_e32 v32, v65, v31
	v_max_u32_e32 v8, v38, v6
	v_min_u32_e32 v20, v34, v17
	v_max_u32_e32 v51, v58, v44
	v_max_u32_e32 v9, v48, v7
	v_min_u32_e32 v47, v29, v24
	v_max_u32_e32 v46, v56, v13
	v_max_u32_e32 v5, v37, v4
	v_min_u32_e32 v49, v33, v28
	v_max_u32_e32 v40, v30, v11
	v_min_u32_e32 v36, v23, v16
	v_min_u32_e32 v31, v65, v31
	v_min_u32_e32 v6, v38, v6
	v_min_u32_e32 v38, v26, v15
	v_min_u32_e32 v44, v58, v44
	v_min_u32_e32 v7, v48, v7
	v_min_u32_e32 v45, v25, v18
	v_min_u32_e32 v13, v56, v13
	v_min_u32_e32 v4, v37, v4
	v_min_u32_e32 v37, v22, v14
	v_min_u32_e32 v11, v30, v11
	v_min_u32_e32 v21, v10, v12
	v_max3_u32 v20, v32, v8, v20
	v_max3_u32 v47, v51, v9, v47
	v_max3_u32 v49, v46, v5, v49
	v_max3_u32 v36, v40, v3, v36
	v_max3_u32 v38, v31, v6, v38
	v_max3_u32 v45, v44, v7, v45
	v_max3_u32 v37, v13, v4, v37
	v_max3_u32 v21, v11, v2, v21
	v_min_u32_e32 v8, v32, v8
	v_min_u32_e32 v9, v51, v9
	v_min_u32_e32 v5, v46, v5
	v_min_u32_e32 v3, v40, v3
	v_min_u32_e32 v6, v31, v6
	v_min_u32_e32 v7, v44, v7
	v_min_u32_e32 v4, v13, v4
	v_min_u32_e32 v2, v11, v2
	v_max3_u32 v8, v8, v34, v17
	v_max3_u32 v9, v9, v29, v24
	v_max3_u32 v5, v5, v33, v28
	v_max3_u32 v3, v3, v23, v16
	v_max3_u32 v6, v6, v26, v15
	v_max3_u32 v7, v7, v25, v18
	v_max3_u32 v4, v4, v22, v14
	v_max3_u32 v2, v2, v10, v12
	v_max_u32_e32 v53, v20, v47
	v_max_u32_e32 v41, v49, v36
	v_max_u32_e32 v48, v38, v45
	v_max_u32_e32 v27, v37, v21
	v_max_u32_e32 v17, v8, v9
	v_max_u32_e32 v16, v5, v3
	v_max_u32_e32 v15, v6, v7
	v_max_u32_e32 v10, v4, v2
	v_max_u32_e32 v42, v53, v41
	v_max_u32_e32 v30, v48, v27
	v_max_u32_e32 v23, v17, v16
	v_max_u32_e32 v11, v15, v10
	v_max_u32_e32 v35, v42, v30
	v_max_u32_e32 v12, v23, v11
	v_max_u32_e32 v13, v35, v12
	v_min_u32_e32 v12, v35, v12
	v_cmp_lt_i32_e32 vcc, -1, v12
	v_not_b32_e32 v32, v12
	v_min_u32_e32 v11, v23, v11
	v_cndmask_b32_e64 v14, v86, -1, vcc
	v_bitop3_b32 v12, v14, v12, s29 bitop3:0x78
	v_min_u32_e32 v14, v42, v30
	v_max_u32_e32 v18, v14, v11
	v_cmp_lt_i32_e32 vcc, -1, v18
	v_min_u32_e32 v11, v14, v11
	v_not_b32_e32 v33, v18
	v_cndmask_b32_e64 v22, v86, -1, vcc
	v_cmp_lt_i32_e32 vcc, -1, v11
	v_bitop3_b32 v18, v22, v18, s29 bitop3:0x78
	v_not_b32_e32 v34, v11
	v_cndmask_b32_e64 v14, v86, -1, vcc
	v_bitop3_b32 v11, v14, v11, s29 bitop3:0x78
	v_min_u32_e32 v14, v53, v41
	v_min_u32_e32 v22, v48, v27
	v_min_u32_e32 v16, v17, v16
	v_min_u32_e32 v10, v15, v10
	v_max_u32_e32 v23, v14, v22
	v_max_u32_e32 v15, v16, v10
	v_max_u32_e32 v17, v23, v15
	v_cmp_lt_i32_e32 vcc, -1, v17
	v_min_u32_e32 v15, v23, v15
	v_min_u32_e32 v14, v14, v22
	v_min_u32_e32 v10, v16, v10
	v_cndmask_b32_e64 v24, v86, -1, vcc
	v_cmp_lt_i32_e32 vcc, -1, v15
	v_max_u32_e32 v16, v14, v10
	v_min_u32_e32 v10, v14, v10
	v_cndmask_b32_e64 v23, v86, -1, vcc
	v_cmp_lt_i32_e32 vcc, -1, v16
	v_not_b32_e32 v30, v15
	v_bitop3_b32 v15, v23, v15, s29 bitop3:0x78
	v_cndmask_b32_e64 v22, v86, -1, vcc
	v_cmp_lt_i32_e32 vcc, -1, v10
	v_not_b32_e32 v35, v10
	v_min_u32_e32 v23, v38, v45
	v_cndmask_b32_e64 v14, v86, -1, vcc
	v_bitop3_b32 v14, v14, v10, s29 bitop3:0x78
	v_min_u32_e32 v10, v20, v47
	v_min_u32_e32 v20, v49, v36
	v_min_u32_e32 v21, v37, v21
	v_min_u32_e32 v8, v8, v9
	v_min_u32_e32 v3, v5, v3
	v_min_u32_e32 v6, v6, v7
	v_min_u32_e32 v2, v4, v2
	v_not_b32_e32 v29, v17
	v_bitop3_b32 v17, v24, v17, s29 bitop3:0x78
	v_not_b32_e32 v31, v16
	v_bitop3_b32 v16, v22, v16, s29 bitop3:0x78
	v_max_u32_e32 v22, v10, v20
	v_max_u32_e32 v24, v23, v21
	v_max_u32_e32 v5, v8, v3
	v_max_u32_e32 v4, v6, v2
	v_max_u32_e32 v25, v22, v24
	v_max_u32_e32 v7, v5, v4
	v_max_u32_e32 v9, v25, v7
	v_cmp_lt_i32_e32 vcc, -1, v9
	v_min_u32_e32 v7, v25, v7
	v_min_u32_e32 v22, v22, v24
	v_min_u32_e32 v4, v5, v4
	v_cndmask_b32_e64 v27, v86, -1, vcc
	v_cmp_lt_i32_e32 vcc, -1, v7
	v_max_u32_e32 v5, v22, v4
	v_not_b32_e32 v26, v9
	v_bitop3_b32 v9, v27, v9, s29 bitop3:0x78
	v_cndmask_b32_e64 v27, v86, -1, vcc
	v_cmp_lt_i32_e32 vcc, -1, v5
	v_min_u32_e32 v4, v22, v4
	v_not_b32_e32 v25, v7
	v_bitop3_b32 v7, v27, v7, s29 bitop3:0x78
	v_cndmask_b32_e64 v27, v86, -1, vcc
	v_cmp_lt_i32_e32 vcc, -1, v4
	v_not_b32_e32 v24, v5
	v_bitop3_b32 v27, v27, v5, s29 bitop3:0x78
	v_cndmask_b32_e64 v5, v86, -1, vcc
	v_not_b32_e32 v36, v4
	v_bitop3_b32 v22, v5, v4, s29 bitop3:0x78
	v_min_u32_e32 v4, v10, v20
	v_min_u32_e32 v5, v23, v21
	v_min_u32_e32 v3, v8, v3
	v_min_u32_e32 v2, v6, v2
	v_max_u32_e32 v10, v4, v5
	v_max_u32_e32 v6, v3, v2
	v_max_u32_e32 v8, v10, v6
	v_cmp_lt_i32_e32 vcc, -1, v8
	v_not_b32_e32 v20, v8
	v_min_u32_e32 v4, v4, v5
	v_cndmask_b32_e64 v21, v86, -1, vcc
	v_bitop3_b32 v8, v21, v8, s29 bitop3:0x78
	v_min_u32_e32 v21, v10, v6
	v_min_u32_e32 v2, v3, v2
	v_cmp_lt_i32_e32 vcc, -1, v21
	v_max_u32_e32 v37, v4, v2
	v_min_u32_e32 v39, v4, v2
	v_cndmask_b32_e64 v6, v86, -1, vcc
	v_cmp_lt_i32_e32 vcc, -1, v37
	v_and_b32_e32 v4, 0xffffff00, v13
	v_and_b32_e32 v5, 0xffffff00, v39
	v_cndmask_b32_e64 v3, v86, -1, vcc
	v_cmp_lt_i32_e32 vcc, -1, v13
	v_bitop3_b32 v38, v3, v37, s29 bitop3:0x78
	v_bitop3_b32 v23, v6, v21, s29 bitop3:0x78
	v_cndmask_b32_e64 v2, v86, -1, vcc
	v_cmp_lt_i32_e32 vcc, -1, v39
	v_xor_b32_e32 v40, v2, v4
	v_sub_f32_e32 v2, v40, v40
	v_cndmask_b32_e64 v3, v86, -1, vcc
	v_xor_b32_e32 v41, v3, v5
	v_mul_f32_e32 v2, 0x3fb8aa3b, v2
	v_sub_f32_e32 v3, v12, v40
	v_sub_f32_e32 v4, v18, v40
	v_exp_f32_e32 v2, v2
	v_mul_f32_e32 v3, 0x3fb8aa3b, v3
	v_mul_f32_e32 v4, 0x3fb8aa3b, v4
	v_exp_f32_e32 v3, v3
	v_exp_f32_e32 v10, v4
	v_sub_f32_e32 v4, v11, v40
	v_mul_f32_e32 v4, 0x3fb8aa3b, v4
	v_exp_f32_e32 v11, v4
	v_add_f32_e32 v4, 0, v2
	v_add_f32_e32 v4, v3, v4
	v_add_f32_e32 v4, v10, v4
	v_add_f32_e32 v6, v11, v4
	v_sub_f32_e32 v4, v17, v40
	v_mul_f32_e32 v4, 0x3fb8aa3b, v4
	v_sub_f32_e32 v5, v15, v40
	v_exp_f32_e32 v4, v4
	v_mul_f32_e32 v5, 0x3fb8aa3b, v5
	v_sub_f32_e32 v12, v16, v40
	v_not_b32_e32 v28, v13
	v_exp_f32_e32 v5, v5
	v_mul_f32_e32 v12, 0x3fb8aa3b, v12
	v_sub_f32_e32 v13, v14, v40
	v_exp_f32_e32 v12, v12
	v_mul_f32_e32 v13, 0x3fb8aa3b, v13
	v_exp_f32_e32 v13, v13
	v_add_f32_e32 v6, v4, v6
	v_add_f32_e32 v6, v5, v6
	v_add_f32_e32 v6, v12, v6
	v_add_f32_e32 v16, v13, v6
	v_sub_f32_e32 v6, v9, v40
	v_mul_f32_e32 v6, 0x3fb8aa3b, v6
	v_sub_f32_e32 v7, v7, v40
	v_sub_f32_e32 v9, v27, v40
	v_exp_f32_e32 v6, v6
	v_mul_f32_e32 v7, 0x3fb8aa3b, v7
	v_mul_f32_e32 v9, 0x3fb8aa3b, v9
	v_exp_f32_e32 v7, v7
	v_exp_f32_e32 v14, v9
	v_sub_f32_e32 v9, v22, v40
	v_mul_f32_e32 v9, 0x3fb8aa3b, v9
	v_exp_f32_e32 v15, v9
	v_add_f32_e32 v9, v6, v16
	v_add_f32_e32 v9, v7, v9
	v_add_f32_e32 v9, v14, v9
	v_sub_f32_e32 v8, v8, v40
	v_add_f32_e32 v18, v15, v9
	v_mul_f32_e32 v8, 0x3fb8aa3b, v8
	v_sub_f32_e32 v9, v23, v40
	v_exp_f32_e32 v8, v8
	v_mul_f32_e32 v9, 0x3fb8aa3b, v9
	v_sub_f32_e32 v16, v38, v40
	v_exp_f32_e32 v9, v9
	v_mul_f32_e32 v16, 0x3fb8aa3b, v16
	v_sub_f32_e32 v17, v41, v40
	v_exp_f32_e32 v16, v16
	v_mul_f32_e32 v17, 0x3fb8aa3b, v17
	v_exp_f32_e32 v17, v17
	v_add_f32_e32 v18, v8, v18
	v_add_f32_e32 v18, v9, v18
	v_add_f32_e32 v18, v16, v18
	v_add_f32_e32 v18, v17, v18
	v_div_scale_f32 v22, s[34:35], v18, v18, 1.0
	v_rcp_f32_e32 v23, v22
	v_not_b32_e32 v27, v37
	v_not_b32_e32 v37, v39
	v_not_b32_e32 v21, v21
	v_fma_f32 v38, -v22, v23, 1.0
	v_fmac_f32_e32 v23, v38, v23
	v_div_scale_f32 v38, vcc, 1.0, v18, 1.0
	v_mul_f32_e32 v39, v38, v23
	v_fma_f32 v40, -v22, v39, v38
	v_fmac_f32_e32 v39, v40, v23
	v_fma_f32 v22, -v22, v39, v38
	v_div_fmas_f32 v22, v22, v23, v39
	v_div_fixup_f32 v18, v22, v18, 1.0
	v_lshlrev_b32_e32 v22, 4, v37
	v_lshlrev_b32_e32 v23, 8, v37
	v_lshlrev_b32_e32 v38, 4, v27
	v_lshlrev_b32_e32 v27, 8, v27
	v_lshlrev_b32_e32 v39, 4, v21
	v_lshlrev_b32_e32 v21, 8, v21
	v_lshlrev_b32_e32 v40, 4, v20
	v_lshlrev_b32_e32 v20, 8, v20
	v_and_b32_e32 v22, 0xf00, v22
	v_and_b32_e32 v23, 0xf00, v23
	v_lshlrev_b32_e32 v37, 2, v87
	v_and_b32_e32 v38, 0xf00, v38
	v_and_b32_e32 v27, 0xf00, v27
	v_and_b32_e32 v39, 0xf00, v39
	v_and_b32_e32 v21, 0xf00, v21
	v_and_b32_e32 v40, 0xf00, v40
	v_and_b32_e32 v20, 0xf00, v20
	v_add_u32_e32 v22, v19, v22
	v_add3_u32 v23, s26, v23, v37
	v_add_u32_e32 v38, v19, v38
	v_add3_u32 v27, s26, v27, v37
	v_add_u32_e32 v39, v19, v39
	v_add3_u32 v21, s26, v21, v37
	v_add_u32_e32 v40, v19, v40
	v_add3_u32 v20, s26, v20, v37
	ds_read_b32 v22, v22
	ds_read_b32 v23, v23 offset:4096
	ds_read_b32 v38, v38
	ds_read_b32 v27, v27 offset:4096
	ds_read_b32 v39, v39
	ds_read_b32 v21, v21 offset:4096
	ds_read_b32 v40, v40
	ds_read_b32 v20, v20 offset:4096
	s_waitcnt lgkmcnt(6)
	v_lshl_add_u32 v23, v22, 7, v23
	s_waitcnt lgkmcnt(4)
	v_lshl_add_u32 v22, v38, 7, v27
	s_waitcnt lgkmcnt(2)
	v_lshl_add_u32 v21, v39, 7, v21
	v_lshlrev_b32_e32 v27, 4, v36
	v_lshlrev_b32_e32 v36, 8, v36
	v_lshlrev_b32_e32 v38, 4, v24
	v_lshlrev_b32_e32 v24, 8, v24
	v_lshlrev_b32_e32 v39, 4, v25
	v_lshlrev_b32_e32 v25, 8, v25
	v_lshlrev_b32_e32 v41, 4, v26
	v_and_b32_e32 v27, 0xf00, v27
	v_and_b32_e32 v36, 0xf00, v36
	v_and_b32_e32 v38, 0xf00, v38
	v_and_b32_e32 v24, 0xf00, v24
	v_and_b32_e32 v39, 0xf00, v39
	v_and_b32_e32 v25, 0xf00, v25
	v_and_b32_e32 v41, 0xf00, v41
	v_lshlrev_b32_e32 v26, 8, v26
	v_add_u32_e32 v27, v19, v27
	v_add3_u32 v36, s26, v36, v37
	v_add_u32_e32 v38, v19, v38
	v_add3_u32 v24, s26, v24, v37
	v_add_u32_e32 v39, v19, v39
	v_add3_u32 v25, s26, v25, v37
	v_add_u32_e32 v41, v19, v41
	v_and_b32_e32 v26, 0xf00, v26
	v_add3_u32 v26, s26, v26, v37
	ds_read_b32 v27, v27
	ds_read_b32 v36, v36 offset:4096
	ds_read_b32 v38, v38
	ds_read_b32 v24, v24 offset:4096
	ds_read_b32 v39, v39
	ds_read_b32 v25, v25 offset:4096
	ds_read_b32 v41, v41
	ds_read_b32 v42, v26 offset:4096
	s_waitcnt lgkmcnt(8)
	v_lshl_add_u32 v20, v40, 7, v20
	s_waitcnt lgkmcnt(6)
	v_lshl_add_u32 v27, v27, 7, v36
	s_waitcnt lgkmcnt(4)
	v_lshl_add_u32 v26, v38, 7, v24
	s_waitcnt lgkmcnt(2)
	v_lshl_add_u32 v25, v39, 7, v25
	v_lshlrev_b32_e32 v36, 4, v35
	v_lshlrev_b32_e32 v35, 8, v35
	v_lshlrev_b32_e32 v38, 4, v31
	v_lshlrev_b32_e32 v39, 4, v30
	v_lshlrev_b32_e32 v40, 4, v29
	v_and_b32_e32 v36, 0xf00, v36
	v_and_b32_e32 v35, 0xf00, v35
	v_and_b32_e32 v38, 0xf00, v38
	v_lshlrev_b32_e32 v31, 8, v31
	v_and_b32_e32 v39, 0xf00, v39
	v_lshlrev_b32_e32 v30, 8, v30
	v_and_b32_e32 v40, 0xf00, v40
	v_lshlrev_b32_e32 v29, 8, v29
	v_add_u32_e32 v36, v19, v36
	v_add3_u32 v35, s26, v35, v37
	v_add_u32_e32 v38, v19, v38
	v_and_b32_e32 v31, 0xf00, v31
	v_add_u32_e32 v39, v19, v39
	v_and_b32_e32 v30, 0xf00, v30
	v_add_u32_e32 v40, v19, v40
	v_and_b32_e32 v29, 0xf00, v29
	s_waitcnt lgkmcnt(0)
	v_lshl_add_u32 v24, v41, 7, v42
	v_add3_u32 v31, s26, v31, v37
	v_add3_u32 v30, s26, v30, v37
	v_add3_u32 v29, s26, v29, v37
	ds_read_b32 v36, v36
	ds_read_b32 v35, v35 offset:4096
	ds_read_b32 v38, v38
	ds_read_b32 v41, v31 offset:4096
	ds_read_b32 v39, v39
	ds_read_b32 v42, v30 offset:4096
	ds_read_b32 v40, v40
	ds_read_b32 v43, v29 offset:4096
	s_waitcnt lgkmcnt(6)
	v_lshl_add_u32 v31, v36, 7, v35
	s_waitcnt lgkmcnt(4)
	v_lshl_add_u32 v30, v38, 7, v41
	s_waitcnt lgkmcnt(2)
	v_lshl_add_u32 v29, v39, 7, v42
	v_lshlrev_b32_e32 v35, 4, v34
	v_lshlrev_b32_e32 v34, 8, v34
	v_lshlrev_b32_e32 v36, 4, v33
	v_lshlrev_b32_e32 v33, 8, v33
	v_lshlrev_b32_e32 v38, 4, v32
	v_lshlrev_b32_e32 v32, 8, v32
	v_lshlrev_b32_e32 v39, 4, v28
	v_and_b32_e32 v35, 0xf00, v35
	v_and_b32_e32 v34, 0xf00, v34
	v_and_b32_e32 v36, 0xf00, v36
	v_and_b32_e32 v33, 0xf00, v33
	v_and_b32_e32 v38, 0xf00, v38
	v_and_b32_e32 v32, 0xf00, v32
	v_and_b32_e32 v39, 0xf00, v39
	v_lshlrev_b32_e32 v28, 8, v28
	v_add_u32_e32 v35, v19, v35
	v_add3_u32 v34, s26, v34, v37
	v_add_u32_e32 v36, v19, v36
	v_add3_u32 v33, s26, v33, v37
	v_add_u32_e32 v38, v19, v38
	v_add3_u32 v32, s26, v32, v37
	v_add_u32_e32 v19, v19, v39
	v_and_b32_e32 v28, 0xf00, v28
	v_add3_u32 v28, s26, v28, v37
	ds_read_b32 v35, v35
	ds_read_b32 v34, v34 offset:4096
	ds_read_b32 v36, v36
	ds_read_b32 v33, v33 offset:4096
	ds_read_b32 v37, v38
	ds_read_b32 v32, v32 offset:4096
	ds_read_b32 v19, v19
	ds_read_b32 v38, v28 offset:4096
	s_waitcnt lgkmcnt(6)
	v_lshl_add_u32 v35, v35, 7, v34
	s_waitcnt lgkmcnt(4)
	v_lshl_add_u32 v34, v36, 7, v33
	v_or_b32_e32 v36, s31, v87
	s_waitcnt lgkmcnt(2)
	v_lshl_add_u32 v33, v37, 7, v32
	v_ashrrev_i32_e32 v37, 31, v36
	v_lshlrev_b64 v[36:37], 9, v[36:37]
	s_waitcnt lgkmcnt(0)
	v_lshl_add_u32 v32, v19, 7, v38
	v_lshl_add_u64 v[38:39], s[8:9], 0, v[36:37]
	v_lshl_add_u64 v[38:39], v[38:39], 0, s[12:13]
	v_lshl_add_u64 v[36:37], s[10:11], 0, v[36:37]
	v_lshl_add_u64 v[36:37], v[36:37], 0, s[12:13]
	global_store_dwordx4 v[38:39], v[32:35], off
	v_pk_mul_f32 v[12:13], v[12:13], v[18:19] op_sel_hi:[1,0]
	v_lshl_add_u32 v28, v40, 7, v43
	v_pk_mul_f32 v[34:35], v[10:11], v[18:19] op_sel_hi:[1,0]
	v_pk_mul_f32 v[32:33], v[2:3], v[18:19] op_sel_hi:[1,0]
	v_pk_mul_f32 v[10:11], v[4:5], v[18:19] op_sel_hi:[1,0]
	v_pk_mul_f32 v[4:5], v[14:15], v[18:19] op_sel_hi:[1,0]
	v_pk_mul_f32 v[2:3], v[6:7], v[18:19] op_sel_hi:[1,0]
	global_store_dwordx4 v[36:37], v[32:35], off
	global_store_dwordx4 v[38:39], v[28:31], off offset:16
	global_store_dwordx4 v[36:37], v[10:13], off offset:16
	global_store_dwordx4 v[38:39], v[24:27], off offset:32
	global_store_dwordx4 v[36:37], v[2:5], off offset:32
	global_store_dwordx4 v[38:39], v[20:23], off offset:48
	s_nop 0
	v_pk_mul_f32 v[4:5], v[16:17], v[18:19] op_sel_hi:[1,0]
	v_pk_mul_f32 v[2:3], v[8:9], v[18:19] op_sel_hi:[1,0]
	global_store_dwordx4 v[36:37], v[2:5], off offset:48
	s_branch .LBB0_801
